# rsq instead of IEEE 1/sqrt expansion in all GEMM epilogues (row rstd)
# speedup vs baseline: 1.0016x; 1.0016x over previous
.LBB0_614:
	v_lshl_add_u32 v188, s6, 8, v169
	v_ashrrev_i32_e32 v189, 31, v188
	v_lshl_add_u64 v[128:129], v[188:189], 3, s[30:31]
	global_load_dwordx2 v[182:183], v[128:129], off
	v_or_b32_e32 v194, 16, v188
	v_ashrrev_i32_e32 v195, 31, v194
	v_or_b32_e32 v192, 32, v188
	v_lshl_add_u64 v[128:129], v[194:195], 3, s[30:31]
	v_ashrrev_i32_e32 v193, 31, v192
	v_lshl_add_u64 v[130:131], v[192:193], 3, s[30:31]
	global_load_dwordx2 v[190:191], v[128:129], off
	global_load_dwordx2 v[198:199], v[130:131], off
	v_lshl_or_b32 v212, s7, 8, v187
	v_ashrrev_i32_e32 v213, 31, v212
	v_or_b32_e32 v184, 48, v188
	v_add_u32_e32 v180, 0x80, v188
	v_lshlrev_b64 v[128:129], 2, v[212:213]
	v_ashrrev_i32_e32 v185, 31, v184
	v_ashrrev_i32_e32 v181, 31, v180
	v_lshl_add_u64 v[130:131], s[68:69], 0, v[128:129]
	v_lshl_add_u64 v[136:137], s[70:71], 0, v[128:129]
	v_lshl_add_u64 v[200:201], v[184:185], 3, s[30:31]
	v_lshl_add_u64 v[202:203], v[180:181], 3, s[30:31]
	global_load_dwordx4 v[148:151], v[130:131], off offset:16
	global_load_dwordx4 v[156:159], v[130:131], off
	global_load_dwordx4 v[144:147], v[136:137], off offset:16
	global_load_dwordx4 v[152:155], v[136:137], off
	global_load_dwordx4 v[132:135], v[130:131], off offset:528
	global_load_dwordx4 v[140:143], v[130:131], off offset:512
	s_nop 0
	global_load_dwordx4 v[128:131], v[136:137], off offset:528
	s_nop 0
	global_load_dwordx4 v[136:139], v[136:137], off offset:512
	s_nop 0
	global_load_dwordx2 v[200:201], v[200:201], off
	s_nop 0
	global_load_dwordx2 v[206:207], v[202:203], off
	v_lshlrev_b64 v[212:213], 1, v[212:213]
	s_waitcnt vmcnt(0)
	v_pk_mul_f32 v[218:219], v[182:183], s[38:39] op_sel_hi:[1,0]
	s_nop 0
	v_fma_f32 v182, -v218, v218, v219
	v_add_f32_e32 v182, 0x3727c5ac, v182
	v_pk_mul_f32 v[208:209], v[190:191], s[38:39] op_sel_hi:[1,0]
	v_pk_mul_f32 v[198:199], v[198:199], s[38:39] op_sel_hi:[1,0]
	v_fma_f32 v183, -v208, v208, v209
	v_fma_f32 v186, -v198, v198, v199
	v_add_f32_e32 v183, 0x3727c5ac, v183
	v_add_f32_e32 v186, 0x3727c5ac, v186
	v_pk_mul_f32 v[206:207], v[206:207], s[38:39] op_sel_hi:[1,0]
	s_nop 0
	v_rsq_f32_e32 v222, v182
	v_rsq_f32_e32 v214, v183
	v_pk_mul_f32 v[202:203], v[200:201], s[38:39] op_sel_hi:[1,0]
	v_fma_f32 v200, -v202, v202, v203
	v_add_f32_e32 v200, 0x3727c5ac, v200
	v_rsq_f32_e32 v216, v200
	v_add_u32_e32 v182, 0x90, v188
	v_ashrrev_i32_e32 v183, 31, v182
	v_lshl_add_u64 v[182:183], v[182:183], 3, s[30:31]
	global_load_dwordx2 v[182:183], v[182:183], off
	v_rsq_f32_e32 v220, v186
	v_pk_fma_f32 v[104:105], v[148:149], v[208:209], v[104:105] op_sel_hi:[1,0,1] neg_lo:[1,0,0] neg_hi:[1,0,0]
	v_pk_fma_f32 v[108:109], v[156:157], v[208:209], v[108:109] op_sel_hi:[1,0,1] neg_lo:[1,0,0] neg_hi:[1,0,0]
	v_pk_fma_f32 v[104:105], v[104:105], v[214:215], v[144:145] op_sel_hi:[1,0,1]
	v_add_u32_e32 v190, 0xa0, v188
	v_ashrrev_i32_e32 v191, 31, v190
	v_lshl_add_u64 v[190:191], v[190:191], 3, s[30:31]
	global_load_dwordx2 v[190:191], v[190:191], off
	v_add_u32_e32 v200, 0xb0, v188
	v_ashrrev_i32_e32 v201, 31, v200
	v_lshl_add_u64 v[200:201], v[200:201], 3, s[30:31]
	global_load_dwordx2 v[224:225], v[200:201], off
	v_fma_f32 v200, -v206, v206, v207
	v_add_f32_e32 v200, 0x3727c5ac, v200
	v_rsq_f32_e32 v210, v200
	v_lshlrev_b64 v[188:189], 13, v[188:189]
	v_lshl_add_u64 v[188:189], s[24:25], 0, v[188:189]
	v_lshl_add_u64 v[188:189], v[188:189], 0, v[212:213]
	v_pk_fma_f32 v[108:109], v[108:109], v[214:215], v[152:153] op_sel_hi:[1,0,1]
	v_max_f32_e32 v104, 0, v104
	s_waitcnt vmcnt(2)
	v_pk_mul_f32 v[200:201], v[182:183], s[38:39] op_sel_hi:[1,0]
	v_fma_f32 v182, -v200, v200, v201
	v_add_f32_e32 v182, 0x3727c5ac, v182
	v_max_f32_e32 v105, 0, v105
	v_max_f32_e32 v108, 0, v108
	v_max_f32_e32 v109, 0, v109
	v_pk_fma_f32 v[96:97], v[132:133], v[208:209], v[96:97] op_sel_hi:[1,0,1] neg_lo:[1,0,0] neg_hi:[1,0,0]
	v_pk_mul_f32 v[108:109], v[108:109], v[108:109]
	s_waitcnt vmcnt(1)
	v_pk_mul_f32 v[190:191], v[190:191], s[38:39] op_sel_hi:[1,0]
	v_pk_fma_f32 v[100:101], v[140:141], v[208:209], v[100:101] op_sel_hi:[1,0,1] neg_lo:[1,0,0] neg_hi:[1,0,0]
	v_fma_f32 v204, -v190, v190, v191
	v_add_f32_e32 v204, 0x3727c5ac, v204
	v_rsq_f32_e32 v196, v204
	v_pk_fma_f32 v[96:97], v[96:97], v[214:215], v[128:129] op_sel_hi:[1,0,1]
	v_pk_fma_f32 v[100:101], v[100:101], v[214:215], v[136:137] op_sel_hi:[1,0,1]
	v_max_f32_e32 v96, 0, v96
	v_max_f32_e32 v97, 0, v97
	v_rsq_f32_e32 v204, v182
	s_waitcnt vmcnt(0)
	v_pk_mul_f32 v[182:183], v[224:225], s[38:39] op_sel_hi:[1,0]
	v_fma_f32 v224, -v182, v182, v183
	v_add_f32_e32 v224, 0x3727c5ac, v224
	v_rsq_f32_e32 v186, v224
	v_max_f32_e32 v100, 0, v100
	v_max_f32_e32 v101, 0, v101
	v_pk_fma_f32 v[88:89], v[148:149], v[198:199], v[88:89] op_sel_hi:[1,0,1] neg_lo:[1,0,0] neg_hi:[1,0,0]
	v_pk_mul_f32 v[100:101], v[100:101], v[100:101]
	v_pk_fma_f32 v[92:93], v[156:157], v[198:199], v[92:93] op_sel_hi:[1,0,1] neg_lo:[1,0,0] neg_hi:[1,0,0]
	v_pk_fma_f32 v[88:89], v[88:89], v[220:221], v[144:145] op_sel_hi:[1,0,1]
	v_pk_fma_f32 v[92:93], v[92:93], v[220:221], v[152:153] op_sel_hi:[1,0,1]
	v_max_f32_e32 v88, 0, v88
	v_pk_fma_f32 v[224:225], v[156:157], v[218:219], v[124:125] op_sel_hi:[1,0,1] neg_lo:[1,0,0] neg_hi:[1,0,0]
	v_xor_b32_e32 v125, 0x80000000, v159
	v_xor_b32_e32 v124, 0x80000000, v158
	v_pk_fma_f32 v[158:159], v[224:225], v[222:223], v[152:153] op_sel_hi:[1,0,1]
	v_pk_fma_f32 v[224:225], v[148:149], v[218:219], v[120:121] op_sel_hi:[1,0,1] neg_lo:[1,0,0] neg_hi:[1,0,0]
	v_xor_b32_e32 v121, 0x80000000, v151
	v_xor_b32_e32 v120, 0x80000000, v150
	v_pk_fma_f32 v[126:127], v[124:125], v[218:219], v[126:127] op_sel_hi:[1,0,1]
	v_pk_fma_f32 v[122:123], v[120:121], v[218:219], v[122:123] op_sel_hi:[1,0,1]
	v_pk_fma_f32 v[126:127], v[126:127], v[222:223], v[154:155] op_sel_hi:[1,0,1]
	v_pk_fma_f32 v[122:123], v[122:123], v[222:223], v[146:147] op_sel_hi:[1,0,1]
	v_max_f32_e32 v126, 0, v126
	v_max_f32_e32 v122, 0, v122
	v_max_f32_e32 v127, 0, v127
	v_max_f32_e32 v123, 0, v123
	v_pk_mul_f32 v[126:127], v[126:127], v[126:127]
	v_pk_mul_f32 v[122:123], v[122:123], v[122:123]
	v_pk_fma_f32 v[150:151], v[224:225], v[222:223], v[144:145] op_sel_hi:[1,0,1]
	v_cvt_pk_bf16_f32 v225, v126, v127
	v_cvt_pk_bf16_f32 v227, v122, v123
	v_pk_fma_f32 v[122:123], v[140:141], v[218:219], v[116:117] op_sel_hi:[1,0,1] neg_lo:[1,0,0] neg_hi:[1,0,0]
	v_xor_b32_e32 v117, 0x80000000, v143
	v_xor_b32_e32 v116, 0x80000000, v142
	v_pk_fma_f32 v[126:127], v[132:133], v[218:219], v[112:113] op_sel_hi:[1,0,1] neg_lo:[1,0,0] neg_hi:[1,0,0]
	v_xor_b32_e32 v113, 0x80000000, v135
	v_xor_b32_e32 v112, 0x80000000, v134
	v_pk_fma_f32 v[118:119], v[116:117], v[218:219], v[118:119] op_sel_hi:[1,0,1]
	v_pk_fma_f32 v[114:115], v[112:113], v[218:219], v[114:115] op_sel_hi:[1,0,1]
	v_max_f32_e32 v158, 0, v158
	v_max_f32_e32 v150, 0, v150
	v_max_f32_e32 v159, 0, v159
	v_max_f32_e32 v151, 0, v151
	v_pk_fma_f32 v[118:119], v[118:119], v[222:223], v[138:139] op_sel_hi:[1,0,1]
	v_pk_fma_f32 v[114:115], v[114:115], v[222:223], v[130:131] op_sel_hi:[1,0,1]
	v_pk_mul_f32 v[158:159], v[158:159], v[158:159]
	v_pk_mul_f32 v[150:151], v[150:151], v[150:151]
	v_pk_fma_f32 v[122:123], v[122:123], v[222:223], v[136:137] op_sel_hi:[1,0,1]
	v_max_f32_e32 v118, 0, v118
	v_max_f32_e32 v114, 0, v114
	v_max_f32_e32 v119, 0, v119
	v_max_f32_e32 v115, 0, v115
	v_pk_fma_f32 v[110:111], v[124:125], v[208:209], v[110:111] op_sel_hi:[1,0,1]
	v_pk_fma_f32 v[106:107], v[120:121], v[208:209], v[106:107] op_sel_hi:[1,0,1]
	v_cvt_pk_bf16_f32 v224, v158, v159
	v_cvt_pk_bf16_f32 v226, v150, v151
	v_max_f32_e32 v122, 0, v122
	v_max_f32_e32 v123, 0, v123
	v_pk_mul_f32 v[118:119], v[118:119], v[118:119]
	v_pk_mul_f32 v[114:115], v[114:115], v[114:115]
	v_pk_fma_f32 v[110:111], v[110:111], v[214:215], v[154:155] op_sel_hi:[1,0,1]
	v_pk_fma_f32 v[106:107], v[106:107], v[214:215], v[146:147] op_sel_hi:[1,0,1]
	global_store_dwordx4 v[188:189], v[224:227], off nt
	v_pk_fma_f32 v[126:127], v[126:127], v[222:223], v[128:129] op_sel_hi:[1,0,1]
	v_pk_mul_f32 v[122:123], v[122:123], v[122:123]
	v_cvt_pk_bf16_f32 v223, v118, v119
	v_cvt_pk_bf16_f32 v225, v114, v115
	v_lshlrev_b64 v[114:115], 13, v[194:195]
	v_pk_mul_f32 v[118:119], v[104:105], v[104:105]
	v_max_f32_e32 v104, 0, v110
	v_max_f32_e32 v106, 0, v106
	v_max_f32_e32 v105, 0, v111
	v_max_f32_e32 v107, 0, v107
	v_cvt_pk_bf16_f32 v222, v122, v123
	v_lshl_add_u64 v[114:115], s[24:25], 0, v[114:115]
	v_pk_mul_f32 v[110:111], v[104:105], v[104:105]
	v_pk_mul_f32 v[122:123], v[106:107], v[106:107]
	v_pk_fma_f32 v[102:103], v[116:117], v[208:209], v[102:103] op_sel_hi:[1,0,1]
	v_pk_fma_f32 v[98:99], v[112:113], v[208:209], v[98:99] op_sel_hi:[1,0,1]
	v_lshl_add_u64 v[114:115], v[114:115], 0, v[212:213]
	v_cvt_pk_bf16_f32 v104, v108, v109
	v_cvt_pk_bf16_f32 v105, v110, v111
	v_cvt_pk_bf16_f32 v106, v118, v119
	v_cvt_pk_bf16_f32 v107, v122, v123
	v_pk_fma_f32 v[102:103], v[102:103], v[214:215], v[138:139] op_sel_hi:[1,0,1]
	v_pk_fma_f32 v[98:99], v[98:99], v[214:215], v[130:131] op_sel_hi:[1,0,1]
	global_store_dwordx4 v[114:115], v[104:107], off nt
	v_max_f32_e32 v98, 0, v98
	v_max_f32_e32 v99, 0, v99
	v_pk_mul_f32 v[104:105], v[96:97], v[96:97]
	v_max_f32_e32 v96, 0, v102
	v_max_f32_e32 v97, 0, v103
	v_pk_mul_f32 v[102:103], v[96:97], v[96:97]
	v_pk_mul_f32 v[106:107], v[98:99], v[98:99]
	v_pk_fma_f32 v[94:95], v[124:125], v[198:199], v[94:95] op_sel_hi:[1,0,1]
	v_pk_fma_f32 v[90:91], v[120:121], v[198:199], v[90:91] op_sel_hi:[1,0,1]
	v_cvt_pk_bf16_f32 v96, v100, v101
	v_cvt_pk_bf16_f32 v97, v102, v103
	v_cvt_pk_bf16_f32 v98, v104, v105
	v_cvt_pk_bf16_f32 v99, v106, v107
	v_pk_fma_f32 v[94:95], v[94:95], v[220:221], v[154:155] op_sel_hi:[1,0,1]
	v_pk_fma_f32 v[90:91], v[90:91], v[220:221], v[146:147] op_sel_hi:[1,0,1]
	v_max_f32_e32 v89, 0, v89
	global_store_dwordx4 v[114:115], v[96:99], off offset:256 nt
	v_max_f32_e32 v92, 0, v92
	v_max_f32_e32 v93, 0, v93
	v_lshlrev_b64 v[96:97], 13, v[192:193]
	v_pk_mul_f32 v[98:99], v[88:89], v[88:89]
	v_max_f32_e32 v88, 0, v94
	v_max_f32_e32 v90, 0, v90
	v_max_f32_e32 v89, 0, v95
	v_max_f32_e32 v91, 0, v91
	v_pk_fma_f32 v[80:81], v[132:133], v[198:199], v[80:81] op_sel_hi:[1,0,1] neg_lo:[1,0,0] neg_hi:[1,0,0]
	v_lshl_add_u64 v[96:97], s[24:25], 0, v[96:97]
	v_pk_mul_f32 v[92:93], v[92:93], v[92:93]
	v_pk_mul_f32 v[94:95], v[88:89], v[88:89]
	v_pk_mul_f32 v[100:101], v[90:91], v[90:91]
	v_pk_fma_f32 v[84:85], v[140:141], v[198:199], v[84:85] op_sel_hi:[1,0,1] neg_lo:[1,0,0] neg_hi:[1,0,0]
	v_pk_fma_f32 v[86:87], v[116:117], v[198:199], v[86:87] op_sel_hi:[1,0,1]
	v_pk_fma_f32 v[82:83], v[112:113], v[198:199], v[82:83] op_sel_hi:[1,0,1]
	v_pk_fma_f32 v[80:81], v[80:81], v[220:221], v[128:129] op_sel_hi:[1,0,1]
	v_lshl_add_u64 v[96:97], v[96:97], 0, v[212:213]
	v_cvt_pk_bf16_f32 v88, v92, v93
	v_cvt_pk_bf16_f32 v89, v94, v95
	v_cvt_pk_bf16_f32 v90, v98, v99
	v_cvt_pk_bf16_f32 v91, v100, v101
	v_pk_fma_f32 v[86:87], v[86:87], v[220:221], v[138:139] op_sel_hi:[1,0,1]
	v_pk_fma_f32 v[84:85], v[84:85], v[220:221], v[136:137] op_sel_hi:[1,0,1]
	v_pk_fma_f32 v[82:83], v[82:83], v[220:221], v[130:131] op_sel_hi:[1,0,1]
	v_max_f32_e32 v80, 0, v80
	v_max_f32_e32 v81, 0, v81
	global_store_dwordx4 v[96:97], v[88:91], off nt
	v_max_f32_e32 v84, 0, v84
	v_max_f32_e32 v85, 0, v85
	v_pk_mul_f32 v[88:89], v[80:81], v[80:81]
	v_max_f32_e32 v80, 0, v86
	v_max_f32_e32 v82, 0, v82
	v_max_f32_e32 v81, 0, v87
	v_max_f32_e32 v83, 0, v83
	v_pk_fma_f32 v[72:73], v[148:149], v[202:203], v[72:73] op_sel_hi:[1,0,1] neg_lo:[1,0,0] neg_hi:[1,0,0]
	v_pk_mul_f32 v[84:85], v[84:85], v[84:85]
	v_pk_mul_f32 v[86:87], v[80:81], v[80:81]
	v_pk_mul_f32 v[90:91], v[82:83], v[82:83]
	v_pk_fma_f32 v[76:77], v[156:157], v[202:203], v[76:77] op_sel_hi:[1,0,1] neg_lo:[1,0,0] neg_hi:[1,0,0]
	v_pk_fma_f32 v[78:79], v[124:125], v[202:203], v[78:79] op_sel_hi:[1,0,1]
	v_pk_fma_f32 v[74:75], v[120:121], v[202:203], v[74:75] op_sel_hi:[1,0,1]
	v_pk_fma_f32 v[72:73], v[72:73], v[216:217], v[144:145] op_sel_hi:[1,0,1]
	v_cvt_pk_bf16_f32 v80, v84, v85
	v_cvt_pk_bf16_f32 v81, v86, v87
	v_cvt_pk_bf16_f32 v82, v88, v89
	v_cvt_pk_bf16_f32 v83, v90, v91
	v_pk_fma_f32 v[78:79], v[78:79], v[216:217], v[154:155] op_sel_hi:[1,0,1]
	v_pk_fma_f32 v[76:77], v[76:77], v[216:217], v[152:153] op_sel_hi:[1,0,1]
	v_pk_fma_f32 v[74:75], v[74:75], v[216:217], v[146:147] op_sel_hi:[1,0,1]
	v_max_f32_e32 v72, 0, v72
	v_max_f32_e32 v73, 0, v73
	global_store_dwordx4 v[96:97], v[80:83], off offset:256 nt
	v_max_f32_e32 v76, 0, v76
	v_max_f32_e32 v77, 0, v77
	v_lshlrev_b64 v[80:81], 13, v[184:185]
	v_pk_mul_f32 v[82:83], v[72:73], v[72:73]
	v_max_f32_e32 v72, 0, v78
	v_max_f32_e32 v74, 0, v74
	v_max_f32_e32 v73, 0, v79
	v_max_f32_e32 v75, 0, v75
	v_pk_fma_f32 v[64:65], v[132:133], v[202:203], v[64:65] op_sel_hi:[1,0,1] neg_lo:[1,0,0] neg_hi:[1,0,0]
	v_lshl_add_u64 v[80:81], s[24:25], 0, v[80:81]
	v_pk_mul_f32 v[76:77], v[76:77], v[76:77]
	v_pk_mul_f32 v[78:79], v[72:73], v[72:73]
	v_pk_mul_f32 v[84:85], v[74:75], v[74:75]
	v_pk_fma_f32 v[68:69], v[140:141], v[202:203], v[68:69] op_sel_hi:[1,0,1] neg_lo:[1,0,0] neg_hi:[1,0,0]
	v_pk_fma_f32 v[70:71], v[116:117], v[202:203], v[70:71] op_sel_hi:[1,0,1]
	v_pk_fma_f32 v[66:67], v[112:113], v[202:203], v[66:67] op_sel_hi:[1,0,1]
	v_pk_fma_f32 v[64:65], v[64:65], v[216:217], v[128:129] op_sel_hi:[1,0,1]
	v_lshl_add_u64 v[80:81], v[80:81], 0, v[212:213]
	v_cvt_pk_bf16_f32 v72, v76, v77
	v_cvt_pk_bf16_f32 v73, v78, v79
	v_cvt_pk_bf16_f32 v74, v82, v83
	v_cvt_pk_bf16_f32 v75, v84, v85
	v_pk_fma_f32 v[70:71], v[70:71], v[216:217], v[138:139] op_sel_hi:[1,0,1]
	v_pk_fma_f32 v[68:69], v[68:69], v[216:217], v[136:137] op_sel_hi:[1,0,1]
	v_pk_fma_f32 v[66:67], v[66:67], v[216:217], v[130:131] op_sel_hi:[1,0,1]
	v_max_f32_e32 v64, 0, v64
	v_max_f32_e32 v65, 0, v65
	global_store_dwordx4 v[80:81], v[72:75], off nt
	v_max_f32_e32 v68, 0, v68
	v_max_f32_e32 v69, 0, v69
	v_pk_mul_f32 v[72:73], v[64:65], v[64:65]
	v_max_f32_e32 v64, 0, v70
	v_max_f32_e32 v66, 0, v66
	v_max_f32_e32 v65, 0, v71
	v_max_f32_e32 v67, 0, v67
	v_pk_fma_f32 v[56:57], v[148:149], v[206:207], v[56:57] op_sel_hi:[1,0,1] neg_lo:[1,0,0] neg_hi:[1,0,0]
	v_pk_mul_f32 v[68:69], v[68:69], v[68:69]
	v_pk_mul_f32 v[70:71], v[64:65], v[64:65]
	v_pk_mul_f32 v[74:75], v[66:67], v[66:67]
	v_pk_fma_f32 v[60:61], v[156:157], v[206:207], v[60:61] op_sel_hi:[1,0,1] neg_lo:[1,0,0] neg_hi:[1,0,0]
	v_pk_fma_f32 v[62:63], v[124:125], v[206:207], v[62:63] op_sel_hi:[1,0,1]
	v_pk_fma_f32 v[58:59], v[120:121], v[206:207], v[58:59] op_sel_hi:[1,0,1]
	v_pk_fma_f32 v[56:57], v[56:57], v[210:211], v[144:145] op_sel_hi:[1,0,1]
	v_cvt_pk_bf16_f32 v64, v68, v69
	v_cvt_pk_bf16_f32 v65, v70, v71
	v_cvt_pk_bf16_f32 v66, v72, v73
	v_cvt_pk_bf16_f32 v67, v74, v75
	v_pk_fma_f32 v[62:63], v[62:63], v[210:211], v[154:155] op_sel_hi:[1,0,1]
	v_pk_fma_f32 v[60:61], v[60:61], v[210:211], v[152:153] op_sel_hi:[1,0,1]
	v_pk_fma_f32 v[58:59], v[58:59], v[210:211], v[146:147] op_sel_hi:[1,0,1]
	v_max_f32_e32 v56, 0, v56
	v_max_f32_e32 v57, 0, v57
	global_store_dwordx4 v[80:81], v[64:67], off offset:256 nt
	v_max_f32_e32 v60, 0, v60
	v_max_f32_e32 v61, 0, v61
	v_lshlrev_b64 v[64:65], 13, v[180:181]
	v_pk_mul_f32 v[66:67], v[56:57], v[56:57]
	v_max_f32_e32 v56, 0, v62
	v_max_f32_e32 v58, 0, v58
	v_max_f32_e32 v57, 0, v63
	v_max_f32_e32 v59, 0, v59
	v_pk_fma_f32 v[48:49], v[132:133], v[206:207], v[48:49] op_sel_hi:[1,0,1] neg_lo:[1,0,0] neg_hi:[1,0,0]
	v_lshl_add_u64 v[64:65], s[24:25], 0, v[64:65]
	v_pk_mul_f32 v[60:61], v[60:61], v[60:61]
	v_pk_mul_f32 v[62:63], v[56:57], v[56:57]
	v_pk_mul_f32 v[68:69], v[58:59], v[58:59]
	v_pk_fma_f32 v[52:53], v[140:141], v[206:207], v[52:53] op_sel_hi:[1,0,1] neg_lo:[1,0,0] neg_hi:[1,0,0]
	v_pk_fma_f32 v[54:55], v[116:117], v[206:207], v[54:55] op_sel_hi:[1,0,1]
	v_pk_fma_f32 v[50:51], v[112:113], v[206:207], v[50:51] op_sel_hi:[1,0,1]
	v_pk_fma_f32 v[48:49], v[48:49], v[210:211], v[128:129] op_sel_hi:[1,0,1]
	v_lshl_add_u64 v[64:65], v[64:65], 0, v[212:213]
	v_cvt_pk_bf16_f32 v56, v60, v61
	v_cvt_pk_bf16_f32 v57, v62, v63
	v_cvt_pk_bf16_f32 v58, v66, v67
	v_cvt_pk_bf16_f32 v59, v68, v69
	v_pk_fma_f32 v[54:55], v[54:55], v[210:211], v[138:139] op_sel_hi:[1,0,1]
	v_pk_fma_f32 v[52:53], v[52:53], v[210:211], v[136:137] op_sel_hi:[1,0,1]
	v_pk_fma_f32 v[50:51], v[50:51], v[210:211], v[130:131] op_sel_hi:[1,0,1]
	v_max_f32_e32 v48, 0, v48
	v_max_f32_e32 v49, 0, v49
	global_store_dwordx4 v[64:65], v[56:59], off nt
	v_max_f32_e32 v52, 0, v52
	v_max_f32_e32 v53, 0, v53
	v_pk_mul_f32 v[56:57], v[48:49], v[48:49]
	v_max_f32_e32 v48, 0, v54
	v_max_f32_e32 v50, 0, v50
	v_max_f32_e32 v49, 0, v55
	v_max_f32_e32 v51, 0, v51
	v_pk_fma_f32 v[44:45], v[156:157], v[200:201], v[44:45] op_sel_hi:[1,0,1] neg_lo:[1,0,0] neg_hi:[1,0,0]
	v_pk_fma_f32 v[40:41], v[148:149], v[200:201], v[40:41] op_sel_hi:[1,0,1] neg_lo:[1,0,0] neg_hi:[1,0,0]
	v_pk_mul_f32 v[52:53], v[52:53], v[52:53]
	v_pk_mul_f32 v[54:55], v[48:49], v[48:49]
	v_pk_mul_f32 v[58:59], v[50:51], v[50:51]
	v_pk_fma_f32 v[46:47], v[124:125], v[200:201], v[46:47] op_sel_hi:[1,0,1]
	v_pk_fma_f32 v[44:45], v[44:45], v[204:205], v[152:153] op_sel_hi:[1,0,1]
	v_pk_fma_f32 v[42:43], v[120:121], v[200:201], v[42:43] op_sel_hi:[1,0,1]
	v_pk_fma_f32 v[40:41], v[40:41], v[204:205], v[144:145] op_sel_hi:[1,0,1]
	v_cvt_pk_bf16_f32 v48, v52, v53
	v_cvt_pk_bf16_f32 v49, v54, v55
	v_cvt_pk_bf16_f32 v50, v56, v57
	v_cvt_pk_bf16_f32 v51, v58, v59
	s_mov_b64 s[2:3], 0x120000
	v_pk_fma_f32 v[46:47], v[46:47], v[204:205], v[154:155] op_sel_hi:[1,0,1]
	v_pk_fma_f32 v[42:43], v[42:43], v[204:205], v[146:147] op_sel_hi:[1,0,1]
	v_max_f32_e32 v44, 0, v44
	v_max_f32_e32 v40, 0, v40
	v_max_f32_e32 v45, 0, v45
	v_max_f32_e32 v41, 0, v41
	global_store_dwordx4 v[64:65], v[48:51], off offset:256 nt
	v_pk_mul_f32 v[44:45], v[44:45], v[44:45]
	v_max_f32_e32 v42, 0, v42
	v_lshl_add_u64 v[48:49], v[188:189], 0, s[2:3]
	v_pk_mul_f32 v[50:51], v[40:41], v[40:41]
	v_max_f32_e32 v40, 0, v46
	v_max_f32_e32 v41, 0, v47
	v_max_f32_e32 v43, 0, v43
	s_mov_b32 s2, 0x120000
	v_pk_fma_f32 v[32:33], v[132:133], v[200:201], v[32:33] op_sel_hi:[1,0,1] neg_lo:[1,0,0] neg_hi:[1,0,0]
	v_pk_mul_f32 v[46:47], v[40:41], v[40:41]
	v_pk_mul_f32 v[52:53], v[42:43], v[42:43]
	v_cvt_pk_bf16_f32 v40, v44, v45
	v_add_co_u32_e32 v44, vcc, s2, v188
	v_pk_fma_f32 v[36:37], v[140:141], v[200:201], v[36:37] op_sel_hi:[1,0,1] neg_lo:[1,0,0] neg_hi:[1,0,0]
	v_pk_fma_f32 v[38:39], v[116:117], v[200:201], v[38:39] op_sel_hi:[1,0,1]
	v_pk_fma_f32 v[34:35], v[112:113], v[200:201], v[34:35] op_sel_hi:[1,0,1]
	v_pk_fma_f32 v[32:33], v[32:33], v[204:205], v[128:129] op_sel_hi:[1,0,1]
	v_cvt_pk_bf16_f32 v41, v46, v47
	v_cvt_pk_bf16_f32 v42, v50, v51
	v_cvt_pk_bf16_f32 v43, v52, v53
	v_addc_co_u32_e32 v45, vcc, 0, v189, vcc
	v_pk_fma_f32 v[38:39], v[38:39], v[204:205], v[138:139] op_sel_hi:[1,0,1]
	v_pk_fma_f32 v[36:37], v[36:37], v[204:205], v[136:137] op_sel_hi:[1,0,1]
	v_pk_fma_f32 v[34:35], v[34:35], v[204:205], v[130:131] op_sel_hi:[1,0,1]
	v_max_f32_e32 v32, 0, v32
	v_max_f32_e32 v33, 0, v33
	global_store_dwordx4 v[44:45], v[40:43], off nt
	v_max_f32_e32 v36, 0, v36
	v_max_f32_e32 v37, 0, v37
	v_pk_mul_f32 v[40:41], v[32:33], v[32:33]
	v_max_f32_e32 v32, 0, v38
	v_max_f32_e32 v34, 0, v34
	v_max_f32_e32 v33, 0, v39
	v_max_f32_e32 v35, 0, v35
	v_pk_fma_f32 v[28:29], v[156:157], v[190:191], v[28:29] op_sel_hi:[1,0,1] neg_lo:[1,0,0] neg_hi:[1,0,0]
	v_pk_fma_f32 v[24:25], v[148:149], v[190:191], v[24:25] op_sel_hi:[1,0,1] neg_lo:[1,0,0] neg_hi:[1,0,0]
	v_pk_mul_f32 v[36:37], v[36:37], v[36:37]
	v_pk_mul_f32 v[38:39], v[32:33], v[32:33]
	v_pk_mul_f32 v[42:43], v[34:35], v[34:35]
	v_pk_fma_f32 v[30:31], v[124:125], v[190:191], v[30:31] op_sel_hi:[1,0,1]
	v_pk_fma_f32 v[28:29], v[28:29], v[196:197], v[152:153] op_sel_hi:[1,0,1]
	v_pk_fma_f32 v[26:27], v[120:121], v[190:191], v[26:27] op_sel_hi:[1,0,1]
	v_pk_fma_f32 v[24:25], v[24:25], v[196:197], v[144:145] op_sel_hi:[1,0,1]
	v_cvt_pk_bf16_f32 v32, v36, v37
	v_cvt_pk_bf16_f32 v33, v38, v39
	v_cvt_pk_bf16_f32 v34, v40, v41
	v_cvt_pk_bf16_f32 v35, v42, v43
	s_mov_b64 s[2:3], 0x140000
	v_pk_fma_f32 v[30:31], v[30:31], v[196:197], v[154:155] op_sel_hi:[1,0,1]
	v_pk_fma_f32 v[26:27], v[26:27], v[196:197], v[146:147] op_sel_hi:[1,0,1]
	v_max_f32_e32 v28, 0, v28
	v_max_f32_e32 v24, 0, v24
	v_max_f32_e32 v29, 0, v29
	v_max_f32_e32 v25, 0, v25
	global_store_dwordx4 v[48:49], v[32:35], off offset:256 nt
	v_pk_mul_f32 v[28:29], v[28:29], v[28:29]
	v_max_f32_e32 v26, 0, v26
	v_lshl_add_u64 v[32:33], v[188:189], 0, s[2:3]
	v_pk_mul_f32 v[34:35], v[24:25], v[24:25]
	v_max_f32_e32 v24, 0, v30
	v_max_f32_e32 v25, 0, v31
	v_max_f32_e32 v27, 0, v27
	s_mov_b32 s2, 0x140000
	v_pk_fma_f32 v[16:17], v[132:133], v[190:191], v[16:17] op_sel_hi:[1,0,1] neg_lo:[1,0,0] neg_hi:[1,0,0]
	v_pk_mul_f32 v[30:31], v[24:25], v[24:25]
	v_pk_mul_f32 v[36:37], v[26:27], v[26:27]
	v_cvt_pk_bf16_f32 v24, v28, v29
	v_add_co_u32_e32 v28, vcc, s2, v188
	v_pk_fma_f32 v[20:21], v[140:141], v[190:191], v[20:21] op_sel_hi:[1,0,1] neg_lo:[1,0,0] neg_hi:[1,0,0]
	v_pk_fma_f32 v[22:23], v[116:117], v[190:191], v[22:23] op_sel_hi:[1,0,1]
	v_pk_fma_f32 v[18:19], v[112:113], v[190:191], v[18:19] op_sel_hi:[1,0,1]
	v_pk_fma_f32 v[16:17], v[16:17], v[196:197], v[128:129] op_sel_hi:[1,0,1]
	v_cvt_pk_bf16_f32 v25, v30, v31
	v_cvt_pk_bf16_f32 v26, v34, v35
	v_cvt_pk_bf16_f32 v27, v36, v37
	v_addc_co_u32_e32 v29, vcc, 0, v189, vcc
	v_pk_fma_f32 v[22:23], v[22:23], v[196:197], v[138:139] op_sel_hi:[1,0,1]
	v_pk_fma_f32 v[20:21], v[20:21], v[196:197], v[136:137] op_sel_hi:[1,0,1]
	v_pk_fma_f32 v[18:19], v[18:19], v[196:197], v[130:131] op_sel_hi:[1,0,1]
	v_max_f32_e32 v16, 0, v16
	v_max_f32_e32 v17, 0, v17
	global_store_dwordx4 v[28:29], v[24:27], off nt
	v_max_f32_e32 v20, 0, v20
	v_max_f32_e32 v21, 0, v21
	v_pk_mul_f32 v[24:25], v[16:17], v[16:17]
	v_max_f32_e32 v16, 0, v22
	v_max_f32_e32 v18, 0, v18
	v_max_f32_e32 v17, 0, v23
	v_max_f32_e32 v19, 0, v19
	v_pk_fma_f32 v[12:13], v[156:157], v[182:183], v[12:13] op_sel_hi:[1,0,1] neg_lo:[1,0,0] neg_hi:[1,0,0]
	v_pk_fma_f32 v[8:9], v[148:149], v[182:183], v[8:9] op_sel_hi:[1,0,1] neg_lo:[1,0,0] neg_hi:[1,0,0]
	v_pk_mul_f32 v[20:21], v[20:21], v[20:21]
	v_pk_mul_f32 v[22:23], v[16:17], v[16:17]
	v_pk_mul_f32 v[26:27], v[18:19], v[18:19]
	v_pk_fma_f32 v[14:15], v[124:125], v[182:183], v[14:15] op_sel_hi:[1,0,1]
	v_pk_fma_f32 v[12:13], v[12:13], v[186:187], v[152:153] op_sel_hi:[1,0,1]
	v_pk_fma_f32 v[10:11], v[120:121], v[182:183], v[10:11] op_sel_hi:[1,0,1]
	v_pk_fma_f32 v[8:9], v[8:9], v[186:187], v[144:145] op_sel_hi:[1,0,1]
	v_cvt_pk_bf16_f32 v16, v20, v21
	v_cvt_pk_bf16_f32 v17, v22, v23
	v_cvt_pk_bf16_f32 v18, v24, v25
	v_cvt_pk_bf16_f32 v19, v26, v27
	s_mov_b64 s[2:3], 0x160000
	v_pk_fma_f32 v[14:15], v[14:15], v[186:187], v[154:155] op_sel_hi:[1,0,1]
	v_pk_fma_f32 v[10:11], v[10:11], v[186:187], v[146:147] op_sel_hi:[1,0,1]
	v_max_f32_e32 v12, 0, v12
	v_max_f32_e32 v8, 0, v8
	v_max_f32_e32 v13, 0, v13
	v_max_f32_e32 v9, 0, v9
	global_store_dwordx4 v[32:33], v[16:19], off offset:256 nt
	v_pk_mul_f32 v[12:13], v[12:13], v[12:13]
	v_max_f32_e32 v10, 0, v10
	v_lshl_add_u64 v[16:17], v[188:189], 0, s[2:3]
	v_pk_mul_f32 v[18:19], v[8:9], v[8:9]
	v_max_f32_e32 v8, 0, v14
	v_max_f32_e32 v9, 0, v15
	v_max_f32_e32 v11, 0, v11
	s_mov_b32 s2, 0x160000
	v_pk_fma_f32 v[0:1], v[132:133], v[182:183], v[0:1] op_sel_hi:[1,0,1] neg_lo:[1,0,0] neg_hi:[1,0,0]
	v_pk_mul_f32 v[14:15], v[8:9], v[8:9]
	v_pk_mul_f32 v[20:21], v[10:11], v[10:11]
	v_cvt_pk_bf16_f32 v8, v12, v13
	v_add_co_u32_e32 v12, vcc, s2, v188
	v_pk_fma_f32 v[4:5], v[140:141], v[182:183], v[4:5] op_sel_hi:[1,0,1] neg_lo:[1,0,0] neg_hi:[1,0,0]
	v_pk_fma_f32 v[6:7], v[116:117], v[182:183], v[6:7] op_sel_hi:[1,0,1]
	v_pk_fma_f32 v[2:3], v[112:113], v[182:183], v[2:3] op_sel_hi:[1,0,1]
	v_pk_fma_f32 v[0:1], v[0:1], v[186:187], v[128:129] op_sel_hi:[1,0,1]
	v_cvt_pk_bf16_f32 v9, v14, v15
	v_cvt_pk_bf16_f32 v10, v18, v19
	v_cvt_pk_bf16_f32 v11, v20, v21
	v_addc_co_u32_e32 v13, vcc, 0, v189, vcc
	v_pk_fma_f32 v[6:7], v[6:7], v[186:187], v[138:139] op_sel_hi:[1,0,1]
	v_pk_fma_f32 v[4:5], v[4:5], v[186:187], v[136:137] op_sel_hi:[1,0,1]
	v_pk_fma_f32 v[2:3], v[2:3], v[186:187], v[130:131] op_sel_hi:[1,0,1]
	v_max_f32_e32 v0, 0, v0
	v_max_f32_e32 v1, 0, v1
	v_max_f32_e32 v126, 0, v126
	v_max_f32_e32 v127, 0, v127
	global_store_dwordx4 v[12:13], v[8:11], off nt
	v_max_f32_e32 v4, 0, v4
	v_max_f32_e32 v5, 0, v5
	v_pk_mul_f32 v[8:9], v[0:1], v[0:1]
	v_max_f32_e32 v0, 0, v6
	v_max_f32_e32 v2, 0, v2
	v_max_f32_e32 v1, 0, v7
	v_max_f32_e32 v3, 0, v3
	v_pk_mul_f32 v[126:127], v[126:127], v[126:127]
	v_pk_mul_f32 v[4:5], v[4:5], v[4:5]
	v_pk_mul_f32 v[6:7], v[0:1], v[0:1]
	v_pk_mul_f32 v[10:11], v[2:3], v[2:3]
	v_cvt_pk_bf16_f32 v224, v126, v127
	v_cvt_pk_bf16_f32 v0, v4, v5
	v_cvt_pk_bf16_f32 v1, v6, v7
	v_cvt_pk_bf16_f32 v2, v8, v9
	v_cvt_pk_bf16_f32 v3, v10, v11
	s_andn2_b64 vcc, exec, s[0:1]
	s_mov_b64 s[0:1], -1
	global_store_dwordx4 v[188:189], v[222:225], off offset:256 nt
	global_store_dwordx4 v[16:17], v[0:3], off offset:256 nt
	s_cbranch_vccnz .LBB0_603
	s_andn2_b64 vcc, exec, s[4:5]
	s_cbranch_vccnz .LBB0_602
	s_barrier
	s_branch .LBB0_602

.LBB0_687:
	v_lshl_add_u32 v198, s0, 8, v169
	v_ashrrev_i32_e32 v199, 31, v198
	v_lshl_or_b32 v64, s1, 8, v211
	v_lshl_add_u64 v[68:69], v[198:199], 3, s[30:31]
	v_lshlrev_b64 v[66:67], 11, v[198:199]
	v_ashrrev_i32_e32 v65, 31, v64
	global_load_dwordx2 v[228:229], v[68:69], off
	v_lshl_add_u64 v[66:67], s[26:27], 0, v[66:67]
	v_lshlrev_b64 v[200:201], 1, v[64:65]
	v_lshl_add_u64 v[208:209], v[66:67], 0, v[200:201]
	global_load_dwordx4 v[220:223], v[208:209], off
	global_load_dwordx4 v[224:227], v[208:209], off offset:256
	v_readlane_b32 s64, v251, 1
	v_lshlrev_b64 v[64:65], 2, v[64:65]
	v_readlane_b32 s78, v251, 15
	v_readlane_b32 s79, v251, 16
	v_and_b32_e32 v66, 64, v216
	v_lshl_add_u64 v[76:77], s[12:13], 0, v[64:65]
	v_lshl_add_u64 v[68:69], s[78:79], 0, v[64:65]
	global_load_dwordx4 v[88:91], v[68:69], off offset:16
	global_load_dwordx4 v[96:99], v[68:69], off
	global_load_dwordx4 v[92:95], v[76:77], off offset:16
	global_load_dwordx4 v[100:103], v[76:77], off
	v_xor_b32_e32 v67, 16, v216
	v_add_u32_e32 v71, 64, v66
	v_xor_b32_e32 v70, 32, v216
	v_cmp_lt_i32_e32 vcc, v67, v71
	v_or_b32_e32 v66, 16, v198
	v_lshl_add_u64 v[202:203], s[26:27], 0, v[200:201]
	v_cndmask_b32_e32 v64, v216, v67, vcc
	v_cmp_lt_i32_e32 vcc, v70, v71
	v_ashrrev_i32_e32 v67, 31, v66
	v_lshlrev_b32_e32 v218, 2, v64
	v_cndmask_b32_e32 v65, v216, v70, vcc
	v_lshlrev_b32_e32 v199, 2, v65
	v_lshl_add_u64 v[160:161], v[66:67], 3, s[30:31]
	v_lshlrev_b64 v[204:205], 11, v[66:67]
	global_load_dwordx4 v[64:67], v[68:69], off offset:528
	global_load_dwordx4 v[72:75], v[68:69], off offset:512
	s_nop 0
	global_load_dwordx4 v[68:71], v[76:77], off offset:528
	s_nop 0
	global_load_dwordx4 v[76:79], v[76:77], off offset:512
	s_nop 0
	global_load_dwordx2 v[206:207], v[160:161], off
	v_lshl_add_u64 v[164:165], v[202:203], 0, v[204:205]
	global_load_dwordx4 v[160:163], v[164:165], off offset:256
	s_nop 0
	global_load_dwordx4 v[164:167], v[164:165], off
	v_readlane_b32 s65, v251, 2
	v_readlane_b32 s66, v251, 3
	v_readlane_b32 s67, v251, 4
	v_readlane_b32 s68, v251, 5
	v_readlane_b32 s69, v251, 6
	v_readlane_b32 s70, v251, 7
	v_readlane_b32 s71, v251, 8
	v_readlane_b32 s72, v251, 9
	v_readlane_b32 s73, v251, 10
	v_readlane_b32 s74, v251, 11
	v_readlane_b32 s75, v251, 12
	v_readlane_b32 s76, v251, 13
	v_readlane_b32 s77, v251, 14
	s_waitcnt vmcnt(0)
	v_pk_mul_f32 v[228:229], v[228:229], s[38:39] op_sel_hi:[1,0]
	s_nop 0
	v_fma_f32 v219, -v228, v228, v229
	v_add_f32_e32 v219, 0x3727c5ac, v219
	v_lshlrev_b32_e32 v236, 16, v224
	v_and_b32_e32 v237, 0xffff0000, v224
	v_lshlrev_b32_e32 v229, 16, v220
	v_and_b32_e32 v220, 0xffff0000, v220
	v_lshlrev_b32_e32 v230, 16, v221
	v_and_b32_e32 v231, 0xffff0000, v221
	v_sub_f32_e32 v221, v220, v228
	v_sub_f32_e32 v220, v229, v228
	v_lshlrev_b32_e32 v232, 16, v222
	v_and_b32_e32 v233, 0xffff0000, v222
	v_sub_f32_e32 v222, v230, v228
	v_lshlrev_b32_e32 v234, 16, v223
	v_and_b32_e32 v235, 0xffff0000, v223
	v_sub_f32_e32 v223, v231, v228
	v_sub_f32_e32 v224, v232, v228
	v_lshlrev_b32_e32 v238, 16, v225
	v_and_b32_e32 v239, 0xffff0000, v225
	v_sub_f32_e32 v225, v233, v228
	v_lshlrev_b32_e32 v240, 16, v226
	v_and_b32_e32 v241, 0xffff0000, v226
	v_sub_f32_e32 v226, v234, v228
	v_lshlrev_b32_e32 v242, 16, v227
	v_and_b32_e32 v243, 0xffff0000, v227
	v_sub_f32_e32 v227, v235, v228
	v_sub_f32_e32 v231, v237, v228
	v_rsq_f32_e32 v232, v219
	s_nop 0
	v_pk_mul_f32 v[220:221], v[220:221], v[232:233] op_sel_hi:[1,0]
	v_pk_mul_f32 v[222:223], v[222:223], v[232:233] op_sel_hi:[1,0]
	v_pk_mul_f32 v[226:227], v[226:227], v[232:233] op_sel_hi:[1,0]
	v_pk_mul_f32 v[224:225], v[224:225], v[232:233] op_sel_hi:[1,0]
	v_pk_fma_f32 v[220:221], v[96:97], v[220:221], v[100:101]
	v_pk_fma_f32 v[222:223], v[98:99], v[222:223], v[102:103]
	v_pk_fma_f32 v[224:225], v[88:89], v[224:225], v[92:93]
	v_pk_fma_f32 v[226:227], v[90:91], v[226:227], v[94:95]
	v_pk_fma_f32 v[156:157], v[220:221], s[40:41], v[156:157] op_sel_hi:[1,0,1]
	v_pk_fma_f32 v[158:159], v[222:223], s[40:41], v[158:159] op_sel_hi:[1,0,1]
	v_pk_fma_f32 v[220:221], v[226:227], s[40:41], v[154:155] op_sel_hi:[1,0,1]
	v_pk_fma_f32 v[154:155], v[224:225], s[40:41], v[152:153] op_sel_hi:[1,0,1]
	v_cvt_pk_bf16_f32 v152, v156, v157
	v_sub_f32_e32 v230, v236, v228
	v_sub_f32_e32 v157, v239, v228
	v_sub_f32_e32 v156, v238, v228
	v_cvt_pk_bf16_f32 v153, v158, v159
	v_cvt_pk_bf16_f32 v154, v154, v155
	v_cvt_pk_bf16_f32 v155, v220, v221
	v_pk_mul_f32 v[156:157], v[156:157], v[232:233] op_sel_hi:[1,0]
	v_pk_mul_f32 v[158:159], v[230:231], v[232:233] op_sel_hi:[1,0]
	v_sub_f32_e32 v221, v241, v228
	v_sub_f32_e32 v220, v240, v228
	v_sub_f32_e32 v223, v243, v228
	v_sub_f32_e32 v222, v242, v228
	v_pk_fma_f32 v[158:159], v[72:73], v[158:159], v[76:77]
	v_pk_fma_f32 v[156:157], v[74:75], v[156:157], v[78:79]
	v_pk_mul_f32 v[222:223], v[222:223], v[232:233] op_sel_hi:[1,0]
	v_pk_mul_f32 v[220:221], v[220:221], v[232:233] op_sel_hi:[1,0]
	v_pk_fma_f32 v[222:223], v[66:67], v[222:223], v[70:71]
	v_pk_fma_f32 v[220:221], v[64:65], v[220:221], v[68:69]
	v_pk_fma_f32 v[150:151], v[156:157], s[40:41], v[150:151] op_sel_hi:[1,0,1]
	v_pk_fma_f32 v[148:149], v[158:159], s[40:41], v[148:149] op_sel_hi:[1,0,1]
	v_pk_fma_f32 v[156:157], v[222:223], s[40:41], v[146:147] op_sel_hi:[1,0,1]
	v_pk_fma_f32 v[146:147], v[220:221], s[40:41], v[144:145] op_sel_hi:[1,0,1]
	v_cvt_pk_bf16_f32 v144, v148, v149
	v_cvt_pk_bf16_f32 v145, v150, v151
	global_store_dwordx4 v[208:209], v[152:155], off
	v_cvt_pk_bf16_f32 v146, v146, v147
	v_cvt_pk_bf16_f32 v147, v156, v157
	v_lshlrev_b32_e32 v149, 16, v152
	v_lshlrev_b32_e32 v148, 16, v144
	v_and_b32_e32 v151, 0xffff0000, v152
	v_and_b32_e32 v150, 0xffff0000, v144
	v_lshlrev_b32_e32 v157, 16, v153
	v_lshlrev_b32_e32 v156, 16, v145
	v_and_b32_e32 v153, 0xffff0000, v153
	v_and_b32_e32 v152, 0xffff0000, v145
	global_store_dwordx4 v[208:209], v[144:147], off offset:256
	v_and_b32_e32 v159, 0xffff0000, v154
	v_and_b32_e32 v158, 0xffff0000, v146
	v_lshlrev_b32_e32 v145, 16, v154
	v_lshlrev_b32_e32 v144, 16, v146
	v_lshlrev_b32_e32 v209, 16, v155
	v_lshlrev_b32_e32 v208, 16, v147
	v_and_b32_e32 v155, 0xffff0000, v155
	v_and_b32_e32 v154, 0xffff0000, v147
	v_pk_add_f32 v[146:147], v[148:149], v[150:151]
	v_pk_add_f32 v[220:221], v[156:157], v[152:153]
	v_pk_add_f32 v[222:223], v[208:209], v[154:155]
	v_pk_add_f32 v[146:147], v[146:147], v[220:221]
	v_pk_add_f32 v[220:221], v[144:145], v[158:159]
	s_nop 0
	v_pk_add_f32 v[220:221], v[220:221], v[222:223]
	v_lshlrev_b32_e32 v222, 16, v167
	v_pk_add_f32 v[220:221], v[146:147], v[220:221]
	v_pk_mul_f32 v[146:147], v[150:151], v[150:151]
	v_and_b32_e32 v223, 0xffff0000, v167
	v_pk_fma_f32 v[146:147], v[148:149], v[148:149], v[146:147]
	v_pk_mul_f32 v[148:149], v[152:153], v[152:153]
	s_nop 0
	v_pk_fma_f32 v[148:149], v[156:157], v[156:157], v[148:149]
	v_pk_mul_f32 v[156:157], v[206:207], s[38:39] op_sel_hi:[1,0]
	v_pk_add_f32 v[146:147], v[146:147], v[148:149]
	v_pk_mul_f32 v[148:149], v[158:159], v[158:159]
	v_sub_f32_e32 v223, v223, v156
	v_pk_fma_f32 v[144:145], v[144:145], v[144:145], v[148:149]
	v_pk_mul_f32 v[148:149], v[154:155], v[154:155]
	v_sub_f32_e32 v222, v222, v156
	v_pk_fma_f32 v[148:149], v[208:209], v[208:209], v[148:149]
	s_nop 0
	v_pk_add_f32 v[144:145], v[144:145], v[148:149]
	s_nop 0
	v_pk_add_f32 v[154:155], v[146:147], v[144:145]
	v_fma_f32 v146, -v156, v156, v157
	v_add_f32_e32 v146, 0x3727c5ac, v146
	v_rsq_f32_e32 v206, v146
	v_or_b32_e32 v144, 32, v198
	v_ashrrev_i32_e32 v145, 31, v144
	v_lshl_add_u64 v[148:149], v[144:145], 3, s[30:31]
	v_lshlrev_b64 v[152:153], 11, v[144:145]
	v_lshl_add_u64 v[150:151], v[202:203], 0, v[152:153]
	s_nop 0
	s_nop 1
	s_nop 1
	global_load_dwordx4 v[144:147], v[150:151], off offset:256
	global_load_dwordx2 v[158:159], v[148:149], off
	s_nop 0
	global_load_dwordx4 v[148:151], v[150:151], off
	s_nop 0
	v_lshlrev_b32_e32 v157, 16, v164
	v_and_b32_e32 v164, 0xffff0000, v164
	v_and_b32_e32 v208, 0xffff0000, v165
	v_lshlrev_b32_e32 v219, 16, v166
	v_and_b32_e32 v209, 0xffff0000, v166
	v_lshlrev_b32_e32 v207, 16, v165
	v_sub_f32_e32 v165, v164, v156
	v_sub_f32_e32 v164, v157, v156
	v_sub_f32_e32 v167, v208, v156
	v_sub_f32_e32 v209, v209, v156
	v_sub_f32_e32 v208, v219, v156
	v_sub_f32_e32 v166, v207, v156
	v_pk_mul_f32 v[164:165], v[206:207], v[164:165] op_sel_hi:[0,1]
	v_pk_mul_f32 v[222:223], v[206:207], v[222:223] op_sel_hi:[0,1]
	v_pk_mul_f32 v[208:209], v[206:207], v[208:209] op_sel_hi:[0,1]
	v_pk_mul_f32 v[166:167], v[206:207], v[166:167] op_sel_hi:[0,1]
	v_pk_fma_f32 v[164:165], v[96:97], v[164:165], v[100:101]
	v_pk_fma_f32 v[208:209], v[88:89], v[208:209], v[92:93]
	v_pk_fma_f32 v[222:223], v[90:91], v[222:223], v[94:95]
	v_pk_fma_f32 v[166:167], v[98:99], v[166:167], v[102:103]
	v_pk_fma_f32 v[140:141], v[164:165], s[40:41], v[140:141] op_sel_hi:[1,0,1]
	v_pk_fma_f32 v[164:165], v[222:223], s[40:41], v[138:139] op_sel_hi:[1,0,1]
	v_pk_fma_f32 v[138:139], v[208:209], s[40:41], v[136:137] op_sel_hi:[1,0,1]
	v_pk_fma_f32 v[142:143], v[166:167], s[40:41], v[142:143] op_sel_hi:[1,0,1]
	v_cvt_pk_bf16_f32 v136, v140, v141
	v_cvt_pk_bf16_f32 v138, v138, v139
	v_cvt_pk_bf16_f32 v137, v142, v143
	v_cvt_pk_bf16_f32 v139, v164, v165
	v_lshlrev_b32_e32 v143, 16, v138
	v_lshlrev_b32_e32 v142, 16, v136
	v_and_b32_e32 v165, 0xffff0000, v138
	v_and_b32_e32 v164, 0xffff0000, v136
	v_lshl_add_u64 v[140:141], s[26:27], 0, v[204:205]
	v_and_b32_e32 v205, 0xffff0000, v139
	v_and_b32_e32 v204, 0xffff0000, v137
	v_pk_add_f32 v[208:209], v[142:143], v[164:165]
	v_pk_mul_f32 v[164:165], v[164:165], v[164:165]
	v_lshlrev_b32_e32 v167, 16, v139
	v_lshlrev_b32_e32 v166, 16, v137
	v_pk_fma_f32 v[142:143], v[142:143], v[142:143], v[164:165]
	v_pk_mul_f32 v[164:165], v[204:205], v[204:205]
	v_pk_add_f32 v[222:223], v[166:167], v[204:205]
	v_pk_fma_f32 v[164:165], v[166:167], v[166:167], v[164:165]
	v_and_b32_e32 v157, 0xffff0000, v160
	v_pk_add_f32 v[142:143], v[142:143], v[164:165]
	v_lshlrev_b32_e32 v164, 16, v161
	v_pk_add_f32 v[142:143], v[142:143], v[142:143] op_sel_hi:[0,1]
	v_lshlrev_b32_e32 v142, 16, v160
	v_and_b32_e32 v165, 0xffff0000, v161
	v_lshlrev_b32_e32 v166, 16, v162
	v_and_b32_e32 v167, 0xffff0000, v162
	v_lshlrev_b32_e32 v204, 16, v163
	v_and_b32_e32 v205, 0xffff0000, v163
	v_sub_f32_e32 v161, v157, v156
	v_sub_f32_e32 v160, v142, v156
	v_sub_f32_e32 v163, v165, v156
	v_sub_f32_e32 v162, v164, v156
	v_sub_f32_e32 v165, v167, v156
	v_sub_f32_e32 v164, v166, v156
	v_sub_f32_e32 v157, v205, v156
	v_sub_f32_e32 v156, v204, v156
	v_pk_mul_f32 v[160:161], v[206:207], v[160:161] op_sel_hi:[0,1]
	v_pk_mul_f32 v[156:157], v[206:207], v[156:157] op_sel_hi:[0,1]
	v_pk_mul_f32 v[164:165], v[206:207], v[164:165] op_sel_hi:[0,1]
	v_pk_mul_f32 v[162:163], v[206:207], v[162:163] op_sel_hi:[0,1]
	v_pk_fma_f32 v[160:161], v[72:73], v[160:161], v[76:77]
	v_pk_fma_f32 v[164:165], v[64:65], v[164:165], v[68:69]
	v_pk_fma_f32 v[156:157], v[66:67], v[156:157], v[70:71]
	v_pk_fma_f32 v[162:163], v[74:75], v[162:163], v[78:79]
	v_pk_fma_f32 v[132:133], v[160:161], s[40:41], v[132:133] op_sel_hi:[1,0,1]
	v_pk_fma_f32 v[156:157], v[156:157], s[40:41], v[130:131] op_sel_hi:[1,0,1]
	v_pk_fma_f32 v[130:131], v[164:165], s[40:41], v[128:129] op_sel_hi:[1,0,1]
	v_pk_fma_f32 v[134:135], v[162:163], s[40:41], v[134:135] op_sel_hi:[1,0,1]
	v_cvt_pk_bf16_f32 v128, v132, v133
	v_cvt_pk_bf16_f32 v130, v130, v131
	v_cvt_pk_bf16_f32 v129, v134, v135
	v_cvt_pk_bf16_f32 v131, v156, v157
	v_lshlrev_b32_e32 v133, 16, v130
	v_lshlrev_b32_e32 v132, 16, v128
	v_and_b32_e32 v135, 0xffff0000, v130
	v_and_b32_e32 v134, 0xffff0000, v128
	v_and_b32_e32 v161, 0xffff0000, v131
	v_and_b32_e32 v160, 0xffff0000, v129
	v_pk_add_f32 v[162:163], v[132:133], v[134:135]
	v_pk_mul_f32 v[134:135], v[134:135], v[134:135]
	v_lshlrev_b32_e32 v157, 16, v131
	v_lshlrev_b32_e32 v156, 16, v129
	v_pk_fma_f32 v[132:133], v[132:133], v[132:133], v[134:135]
	v_pk_mul_f32 v[134:135], v[160:161], v[160:161]
	v_lshl_add_u64 v[140:141], v[140:141], 0, v[200:201]
	v_pk_fma_f32 v[134:135], v[156:157], v[156:157], v[134:135]
	global_store_dwordx4 v[140:141], v[136:139], off
	global_store_dwordx4 v[140:141], v[128:131], off offset:256
	v_pk_add_f32 v[132:133], v[132:133], v[134:135]
	v_pk_add_f32 v[208:209], v[208:209], v[222:223]
	v_pk_add_f32 v[132:133], v[132:133], v[132:133] op_sel_hi:[0,1]
	v_mov_b32_e32 v132, v155
	v_mov_b32_e32 v155, v143
	v_pk_add_f32 v[132:133], v[132:133], v[154:155]
	ds_bpermute_b32 v142, v218, v132
	ds_bpermute_b32 v143, v218, v133
	v_pk_add_f32 v[164:165], v[156:157], v[160:161]
	v_pk_add_f32 v[208:209], v[208:209], v[208:209] op_sel_hi:[0,1]
	v_pk_add_f32 v[162:163], v[162:163], v[164:165]
	v_or_b32_e32 v128, 48, v198
	s_waitcnt lgkmcnt(0)
	v_pk_add_f32 v[132:133], v[132:133], v[142:143]
	s_waitcnt vmcnt(3)
	v_pk_mul_f32 v[142:143], v[158:159], s[38:39] op_sel_hi:[1,0]
	v_pk_add_f32 v[162:163], v[162:163], v[162:163] op_sel_hi:[0,1]
	v_fma_f32 v130, -v142, v142, v143
	v_add_f32_e32 v130, 0x3727c5ac, v130
	v_rsq_f32_e32 v160, v130
	v_mov_b32_e32 v208, v221
	v_ashrrev_i32_e32 v129, 31, v128
	v_pk_add_f32 v[134:135], v[208:209], 0 op_sel_hi:[1,0]
	v_mov_b32_e32 v221, v163
	v_lshl_add_u64 v[154:155], v[128:129], 3, s[30:31]
	v_lshlrev_b64 v[140:141], 11, v[128:129]
	v_pk_add_f32 v[134:135], v[220:221], v[134:135]
	ds_bpermute_b32 v156, v218, v134
	ds_bpermute_b32 v157, v218, v135
	s_waitcnt vmcnt(2)
	v_lshlrev_b32_e32 v166, 16, v151
	s_waitcnt lgkmcnt(0)
	v_pk_add_f32 v[136:137], v[134:135], v[156:157]
	v_lshl_add_u64 v[156:157], v[202:203], 0, v[140:141]
	v_and_b32_e32 v165, 0xffff0000, v151
	v_sub_f32_e32 v165, v165, v142
	global_load_dwordx4 v[128:131], v[156:157], off offset:256
	global_load_dwordx2 v[158:159], v[154:155], off
	s_nop 0
	global_load_dwordx4 v[154:157], v[156:157], off
	ds_bpermute_b32 v138, v199, v136
	ds_bpermute_b32 v134, v199, v132
	ds_bpermute_b32 v139, v199, v137
	v_lshlrev_b32_e32 v143, 16, v148
	v_and_b32_e32 v148, 0xffff0000, v148
	v_lshlrev_b32_e32 v161, 16, v149
	v_and_b32_e32 v162, 0xffff0000, v149
	v_lshlrev_b32_e32 v164, 16, v150
	v_and_b32_e32 v163, 0xffff0000, v150
	v_sub_f32_e32 v149, v148, v142
	v_sub_f32_e32 v148, v143, v142
	v_sub_f32_e32 v151, v162, v142
	v_sub_f32_e32 v150, v161, v142
	v_sub_f32_e32 v163, v163, v142
	v_sub_f32_e32 v162, v164, v142
	v_sub_f32_e32 v164, v166, v142
	v_pk_mul_f32 v[150:151], v[160:161], v[150:151] op_sel_hi:[0,1]
	v_pk_mul_f32 v[148:149], v[160:161], v[148:149] op_sel_hi:[0,1]
	v_pk_mul_f32 v[164:165], v[160:161], v[164:165] op_sel_hi:[0,1]
	v_pk_mul_f32 v[162:163], v[160:161], v[162:163] op_sel_hi:[0,1]
	v_pk_fma_f32 v[148:149], v[96:97], v[148:149], v[100:101]
	v_pk_fma_f32 v[150:151], v[98:99], v[150:151], v[102:103]
	v_pk_fma_f32 v[162:163], v[88:89], v[162:163], v[92:93]
	v_pk_fma_f32 v[164:165], v[90:91], v[164:165], v[94:95]
	v_pk_fma_f32 v[126:127], v[150:151], s[40:41], v[126:127] op_sel_hi:[1,0,1]
	v_pk_fma_f32 v[124:125], v[148:149], s[40:41], v[124:125] op_sel_hi:[1,0,1]
	v_pk_fma_f32 v[148:149], v[164:165], s[40:41], v[122:123] op_sel_hi:[1,0,1]
	v_pk_fma_f32 v[122:123], v[162:163], s[40:41], v[120:121] op_sel_hi:[1,0,1]
	v_cvt_pk_bf16_f32 v121, v126, v127
	v_cvt_pk_bf16_f32 v122, v122, v123
	v_cvt_pk_bf16_f32 v123, v148, v149
	v_lshlrev_b32_e32 v126, 16, v144
	v_and_b32_e32 v127, 0xffff0000, v144
	v_lshlrev_b32_e32 v143, 16, v145
	v_and_b32_e32 v144, 0xffff0000, v145
	v_lshlrev_b32_e32 v148, 16, v146
	v_and_b32_e32 v146, 0xffff0000, v146
	v_lshlrev_b32_e32 v149, 16, v147
	v_and_b32_e32 v150, 0xffff0000, v147
	v_sub_f32_e32 v127, v127, v142
	v_sub_f32_e32 v126, v126, v142
	v_sub_f32_e32 v145, v144, v142
	v_sub_f32_e32 v144, v143, v142
	v_sub_f32_e32 v147, v146, v142
	v_sub_f32_e32 v146, v148, v142
	v_sub_f32_e32 v143, v150, v142
	v_sub_f32_e32 v142, v149, v142
	v_pk_mul_f32 v[144:145], v[160:161], v[144:145] op_sel_hi:[0,1]
	v_pk_mul_f32 v[126:127], v[160:161], v[126:127] op_sel_hi:[0,1]
	v_pk_mul_f32 v[142:143], v[160:161], v[142:143] op_sel_hi:[0,1]
	v_pk_mul_f32 v[146:147], v[160:161], v[146:147] op_sel_hi:[0,1]
	v_pk_fma_f32 v[126:127], v[72:73], v[126:127], v[76:77]
	v_pk_fma_f32 v[144:145], v[74:75], v[144:145], v[78:79]
	v_pk_fma_f32 v[146:147], v[64:65], v[146:147], v[68:69]
	v_pk_fma_f32 v[142:143], v[66:67], v[142:143], v[70:71]
	v_cvt_pk_bf16_f32 v120, v124, v125
	v_lshl_add_u64 v[124:125], s[26:27], 0, v[152:153]
	v_pk_fma_f32 v[118:119], v[144:145], s[40:41], v[118:119] op_sel_hi:[1,0,1]
	v_pk_fma_f32 v[116:117], v[126:127], s[40:41], v[116:117] op_sel_hi:[1,0,1]
	v_pk_fma_f32 v[126:127], v[142:143], s[40:41], v[114:115] op_sel_hi:[1,0,1]
	v_pk_fma_f32 v[114:115], v[146:147], s[40:41], v[112:113] op_sel_hi:[1,0,1]
	v_lshl_add_u64 v[124:125], v[124:125], 0, v[200:201]
	v_cvt_pk_bf16_f32 v112, v116, v117
	v_cvt_pk_bf16_f32 v113, v118, v119
	v_cvt_pk_bf16_f32 v114, v114, v115
	v_cvt_pk_bf16_f32 v115, v126, v127
	global_store_dwordx4 v[124:125], v[120:123], off
	global_store_dwordx4 v[124:125], v[112:115], off offset:256
	v_lshlrev_b32_e32 v117, 16, v120
	v_lshlrev_b32_e32 v116, 16, v112
	v_and_b32_e32 v119, 0xffff0000, v120
	v_and_b32_e32 v118, 0xffff0000, v112
	v_lshlrev_b32_e32 v125, 16, v121
	v_lshlrev_b32_e32 v124, 16, v113
	v_and_b32_e32 v121, 0xffff0000, v121
	v_and_b32_e32 v120, 0xffff0000, v113
	v_lshlrev_b32_e32 v113, 16, v122
	v_lshlrev_b32_e32 v112, 16, v114
	v_and_b32_e32 v127, 0xffff0000, v122
	v_and_b32_e32 v126, 0xffff0000, v114
	v_lshlrev_b32_e32 v143, 16, v123
	v_lshlrev_b32_e32 v142, 16, v115
	v_and_b32_e32 v123, 0xffff0000, v123
	v_and_b32_e32 v122, 0xffff0000, v115
	v_pk_add_f32 v[114:115], v[116:117], v[118:119]
	v_pk_add_f32 v[144:145], v[124:125], v[120:121]
	v_pk_add_f32 v[146:147], v[142:143], v[122:123]
	v_pk_add_f32 v[114:115], v[114:115], v[144:145]
	v_pk_add_f32 v[144:145], v[112:113], v[126:127]
	s_waitcnt vmcnt(2)
	v_lshlrev_b32_e32 v150, 16, v156
	v_pk_add_f32 v[144:145], v[144:145], v[146:147]
	v_and_b32_e32 v151, 0xffff0000, v156
	v_pk_add_f32 v[144:145], v[114:115], v[144:145]
	v_pk_mul_f32 v[114:115], v[118:119], v[118:119]
	v_lshlrev_b32_e32 v152, 16, v157
	v_pk_fma_f32 v[114:115], v[116:117], v[116:117], v[114:115]
	v_pk_mul_f32 v[116:117], v[120:121], v[120:121]
	v_and_b32_e32 v153, 0xffff0000, v157
	v_pk_fma_f32 v[116:117], v[124:125], v[124:125], v[116:117]
	v_pk_mul_f32 v[124:125], v[158:159], s[38:39] op_sel_hi:[1,0]
	v_pk_add_f32 v[114:115], v[114:115], v[116:117]
	v_pk_mul_f32 v[116:117], v[126:127], v[126:127]
	v_and_b32_e32 v149, 0xffff0000, v155
	v_pk_fma_f32 v[112:113], v[112:113], v[112:113], v[116:117]
	v_pk_mul_f32 v[116:117], v[122:123], v[122:123]
	v_sub_f32_e32 v151, v151, v124
	v_pk_fma_f32 v[116:117], v[142:143], v[142:143], v[116:117]
	v_sub_f32_e32 v150, v150, v124
	v_pk_add_f32 v[112:113], v[112:113], v[116:117]
	v_sub_f32_e32 v153, v153, v124
	v_pk_add_f32 v[122:123], v[114:115], v[112:113]
	v_fma_f32 v114, -v124, v124, v125
	v_add_f32_e32 v114, 0x3727c5ac, v114
	v_rsq_f32_e32 v142, v114
	v_add_u32_e32 v112, 0x80, v198
	v_ashrrev_i32_e32 v113, 31, v112
	v_lshl_add_u64 v[116:117], v[112:113], 3, s[30:31]
	v_lshlrev_b64 v[120:121], 11, v[112:113]
	v_lshl_add_u64 v[118:119], v[202:203], 0, v[120:121]
	v_sub_f32_e32 v152, v152, v124
	v_sub_f32_e32 v149, v149, v124
	ds_bpermute_b32 v135, v199, v133
	s_nop 1
	global_load_dwordx4 v[112:115], v[118:119], off offset:256
	global_load_dwordx2 v[126:127], v[116:117], off
	s_nop 0
	global_load_dwordx4 v[116:119], v[118:119], off
	s_nop 0
	v_lshlrev_b32_e32 v125, 16, v154
	v_and_b32_e32 v143, 0xffff0000, v154
	v_lshlrev_b32_e32 v148, 16, v155
	v_sub_f32_e32 v147, v143, v124
	v_sub_f32_e32 v146, v125, v124
	v_sub_f32_e32 v148, v148, v124
	v_pk_mul_f32 v[146:147], v[142:143], v[146:147] op_sel_hi:[0,1]
	v_pk_mul_f32 v[152:153], v[142:143], v[152:153] op_sel_hi:[0,1]
	v_pk_mul_f32 v[150:151], v[142:143], v[150:151] op_sel_hi:[0,1]
	v_pk_mul_f32 v[148:149], v[142:143], v[148:149] op_sel_hi:[0,1]
	v_pk_fma_f32 v[146:147], v[96:97], v[146:147], v[100:101]
	v_pk_fma_f32 v[150:151], v[88:89], v[150:151], v[92:93]
	v_pk_fma_f32 v[152:153], v[90:91], v[152:153], v[94:95]
	v_pk_fma_f32 v[148:149], v[98:99], v[148:149], v[102:103]
	v_pk_fma_f32 v[108:109], v[146:147], s[40:41], v[108:109] op_sel_hi:[1,0,1]
	v_pk_fma_f32 v[146:147], v[152:153], s[40:41], v[106:107] op_sel_hi:[1,0,1]
	v_pk_fma_f32 v[106:107], v[150:151], s[40:41], v[104:105] op_sel_hi:[1,0,1]
	v_pk_fma_f32 v[110:111], v[148:149], s[40:41], v[110:111] op_sel_hi:[1,0,1]
	v_cvt_pk_bf16_f32 v104, v108, v109
	v_cvt_pk_bf16_f32 v106, v106, v107
	v_cvt_pk_bf16_f32 v105, v110, v111
	v_cvt_pk_bf16_f32 v107, v146, v147
	v_lshl_add_u64 v[108:109], s[26:27], 0, v[140:141]
	v_lshlrev_b32_e32 v111, 16, v106
	v_lshlrev_b32_e32 v110, 16, v104
	v_and_b32_e32 v141, 0xffff0000, v106
	v_and_b32_e32 v140, 0xffff0000, v104
	v_and_b32_e32 v149, 0xffff0000, v107
	v_and_b32_e32 v148, 0xffff0000, v105
	v_pk_add_f32 v[150:151], v[110:111], v[140:141]
	v_pk_mul_f32 v[140:141], v[140:141], v[140:141]
	v_lshlrev_b32_e32 v147, 16, v107
	v_lshlrev_b32_e32 v146, 16, v105
	v_pk_fma_f32 v[110:111], v[110:111], v[110:111], v[140:141]
	v_pk_mul_f32 v[140:141], v[148:149], v[148:149]
	v_pk_add_f32 v[152:153], v[146:147], v[148:149]
	v_pk_fma_f32 v[140:141], v[146:147], v[146:147], v[140:141]
	v_and_b32_e32 v125, 0xffff0000, v128
	v_pk_add_f32 v[110:111], v[110:111], v[140:141]
	v_lshlrev_b32_e32 v140, 16, v129
	v_pk_add_f32 v[110:111], v[110:111], v[110:111] op_sel_hi:[0,1]
	v_lshlrev_b32_e32 v110, 16, v128
	v_and_b32_e32 v141, 0xffff0000, v129
	v_lshlrev_b32_e32 v143, 16, v130
	v_and_b32_e32 v146, 0xffff0000, v130
	v_lshlrev_b32_e32 v147, 16, v131
	v_and_b32_e32 v148, 0xffff0000, v131
	v_sub_f32_e32 v129, v125, v124
	v_sub_f32_e32 v128, v110, v124
	v_sub_f32_e32 v131, v141, v124
	v_sub_f32_e32 v130, v140, v124
	v_sub_f32_e32 v141, v146, v124
	v_sub_f32_e32 v140, v143, v124
	v_sub_f32_e32 v125, v148, v124
	v_sub_f32_e32 v124, v147, v124
	v_pk_mul_f32 v[128:129], v[142:143], v[128:129] op_sel_hi:[0,1]
	v_pk_mul_f32 v[124:125], v[142:143], v[124:125] op_sel_hi:[0,1]
	v_pk_mul_f32 v[140:141], v[142:143], v[140:141] op_sel_hi:[0,1]
	v_pk_mul_f32 v[130:131], v[142:143], v[130:131] op_sel_hi:[0,1]
	v_pk_fma_f32 v[128:129], v[72:73], v[128:129], v[76:77]
	v_pk_fma_f32 v[140:141], v[64:65], v[140:141], v[68:69]
	v_pk_fma_f32 v[124:125], v[66:67], v[124:125], v[70:71]
	v_pk_fma_f32 v[130:131], v[74:75], v[130:131], v[78:79]
	v_pk_fma_f32 v[84:85], v[128:129], s[40:41], v[84:85] op_sel_hi:[1,0,1]
	v_pk_fma_f32 v[124:125], v[124:125], s[40:41], v[82:83] op_sel_hi:[1,0,1]
	v_pk_fma_f32 v[82:83], v[140:141], s[40:41], v[80:81] op_sel_hi:[1,0,1]
	v_pk_fma_f32 v[86:87], v[130:131], s[40:41], v[86:87] op_sel_hi:[1,0,1]
	v_cvt_pk_bf16_f32 v80, v84, v85
	v_cvt_pk_bf16_f32 v82, v82, v83
	v_cvt_pk_bf16_f32 v81, v86, v87
	v_cvt_pk_bf16_f32 v83, v124, v125
	v_lshlrev_b32_e32 v85, 16, v82
	v_lshlrev_b32_e32 v84, 16, v80
	v_and_b32_e32 v87, 0xffff0000, v82
	v_and_b32_e32 v86, 0xffff0000, v80
	v_and_b32_e32 v129, 0xffff0000, v83
	v_and_b32_e32 v128, 0xffff0000, v81
	v_pk_add_f32 v[130:131], v[84:85], v[86:87]
	v_pk_mul_f32 v[86:87], v[86:87], v[86:87]
	v_lshlrev_b32_e32 v125, 16, v83
	v_lshlrev_b32_e32 v124, 16, v81
	v_pk_fma_f32 v[84:85], v[84:85], v[84:85], v[86:87]
	v_pk_mul_f32 v[86:87], v[128:129], v[128:129]
	v_mov_b32_e32 v110, v123
	v_pk_fma_f32 v[86:87], v[124:125], v[124:125], v[86:87]
	v_lshl_add_u64 v[108:109], v[108:109], 0, v[200:201]
	v_pk_add_f32 v[84:85], v[84:85], v[86:87]
	global_store_dwordx4 v[108:109], v[104:107], off
	global_store_dwordx4 v[108:109], v[80:83], off offset:256
	v_pk_add_f32 v[84:85], v[84:85], v[84:85] op_sel_hi:[0,1]
	v_mov_b32_e32 v84, v122
	v_pk_add_f32 v[84:85], v[84:85], v[110:111]
	ds_bpermute_b32 v110, v218, v84
	ds_bpermute_b32 v111, v218, v85
	v_pk_add_f32 v[150:151], v[150:151], v[152:153]
	v_pk_add_f32 v[140:141], v[124:125], v[128:129]
	v_pk_add_f32 v[150:151], v[150:151], v[150:151] op_sel_hi:[0,1]
	v_pk_add_f32 v[130:131], v[130:131], v[140:141]
	s_waitcnt lgkmcnt(0)
	v_pk_add_f32 v[84:85], v[84:85], v[110:111]
	s_waitcnt vmcnt(3)
	v_pk_mul_f32 v[110:111], v[126:127], s[38:39] op_sel_hi:[1,0]
	v_add_u32_e32 v80, 0x90, v198
	v_fma_f32 v82, -v110, v110, v111
	v_add_f32_e32 v82, 0x3727c5ac, v82
	v_rsq_f32_e32 v128, v82
	v_pk_add_f32 v[130:131], v[130:131], v[130:131] op_sel_hi:[0,1]
	v_mov_b32_e32 v150, v145
	v_ashrrev_i32_e32 v81, 31, v80
	v_pk_add_f32 v[86:87], v[150:151], 0 op_sel_hi:[1,0]
	v_mov_b32_e32 v145, v131
	v_lshl_add_u64 v[122:123], v[80:81], 3, s[30:31]
	v_lshlrev_b64 v[108:109], 11, v[80:81]
	v_pk_add_f32 v[86:87], v[144:145], v[86:87]
	ds_bpermute_b32 v124, v218, v86
	ds_bpermute_b32 v125, v218, v87
	s_waitcnt vmcnt(2)
	v_lshlrev_b32_e32 v142, 16, v119
	s_waitcnt lgkmcnt(0)
	v_pk_add_f32 v[104:105], v[86:87], v[124:125]
	v_lshl_add_u64 v[124:125], v[202:203], 0, v[108:109]
	v_and_b32_e32 v141, 0xffff0000, v119
	v_sub_f32_e32 v141, v141, v110
	global_load_dwordx4 v[80:83], v[124:125], off offset:256
	global_load_dwordx2 v[126:127], v[122:123], off
	s_nop 0
	global_load_dwordx4 v[122:125], v[124:125], off
	ds_bpermute_b32 v106, v199, v104
	ds_bpermute_b32 v86, v199, v84
	ds_bpermute_b32 v107, v199, v105
	v_lshlrev_b32_e32 v111, 16, v116
	v_and_b32_e32 v116, 0xffff0000, v116
	v_lshlrev_b32_e32 v129, 16, v117
	v_and_b32_e32 v130, 0xffff0000, v117
	v_lshlrev_b32_e32 v140, 16, v118
	v_and_b32_e32 v131, 0xffff0000, v118
	v_sub_f32_e32 v117, v116, v110
	v_sub_f32_e32 v116, v111, v110
	v_sub_f32_e32 v119, v130, v110
	v_sub_f32_e32 v118, v129, v110
	v_sub_f32_e32 v131, v131, v110
	v_sub_f32_e32 v130, v140, v110
	v_sub_f32_e32 v140, v142, v110
	v_pk_mul_f32 v[118:119], v[128:129], v[118:119] op_sel_hi:[0,1]
	v_pk_mul_f32 v[116:117], v[128:129], v[116:117] op_sel_hi:[0,1]
	v_pk_mul_f32 v[140:141], v[128:129], v[140:141] op_sel_hi:[0,1]
	v_pk_mul_f32 v[130:131], v[128:129], v[130:131] op_sel_hi:[0,1]
	v_pk_fma_f32 v[116:117], v[96:97], v[116:117], v[100:101]
	v_pk_fma_f32 v[118:119], v[98:99], v[118:119], v[102:103]
	v_pk_fma_f32 v[130:131], v[88:89], v[130:131], v[92:93]
	v_pk_fma_f32 v[140:141], v[90:91], v[140:141], v[94:95]
	v_pk_fma_f32 v[62:63], v[118:119], s[40:41], v[62:63] op_sel_hi:[1,0,1]
	v_pk_fma_f32 v[60:61], v[116:117], s[40:41], v[60:61] op_sel_hi:[1,0,1]
	v_pk_fma_f32 v[116:117], v[140:141], s[40:41], v[58:59] op_sel_hi:[1,0,1]
	v_pk_fma_f32 v[58:59], v[130:131], s[40:41], v[56:57] op_sel_hi:[1,0,1]
	v_cvt_pk_bf16_f32 v57, v62, v63
	v_cvt_pk_bf16_f32 v58, v58, v59
	v_cvt_pk_bf16_f32 v59, v116, v117
	v_lshlrev_b32_e32 v62, 16, v112
	v_and_b32_e32 v63, 0xffff0000, v112
	v_lshlrev_b32_e32 v111, 16, v113
	v_and_b32_e32 v112, 0xffff0000, v113
	v_lshlrev_b32_e32 v116, 16, v114
	v_and_b32_e32 v114, 0xffff0000, v114
	v_lshlrev_b32_e32 v117, 16, v115
	v_and_b32_e32 v118, 0xffff0000, v115
	v_sub_f32_e32 v63, v63, v110
	v_sub_f32_e32 v62, v62, v110
	v_sub_f32_e32 v113, v112, v110
	v_sub_f32_e32 v112, v111, v110
	v_sub_f32_e32 v115, v114, v110
	v_sub_f32_e32 v114, v116, v110
	v_sub_f32_e32 v111, v118, v110
	v_sub_f32_e32 v110, v117, v110
	v_pk_mul_f32 v[112:113], v[128:129], v[112:113] op_sel_hi:[0,1]
	v_pk_mul_f32 v[62:63], v[128:129], v[62:63] op_sel_hi:[0,1]
	v_pk_mul_f32 v[110:111], v[128:129], v[110:111] op_sel_hi:[0,1]
	v_pk_mul_f32 v[114:115], v[128:129], v[114:115] op_sel_hi:[0,1]
	v_pk_fma_f32 v[62:63], v[72:73], v[62:63], v[76:77]
	v_pk_fma_f32 v[112:113], v[74:75], v[112:113], v[78:79]
	v_pk_fma_f32 v[114:115], v[64:65], v[114:115], v[68:69]
	v_pk_fma_f32 v[110:111], v[66:67], v[110:111], v[70:71]
	v_cvt_pk_bf16_f32 v56, v60, v61
	v_lshl_add_u64 v[60:61], s[26:27], 0, v[120:121]
	v_pk_fma_f32 v[54:55], v[112:113], s[40:41], v[54:55] op_sel_hi:[1,0,1]
	v_pk_fma_f32 v[52:53], v[62:63], s[40:41], v[52:53] op_sel_hi:[1,0,1]
	v_pk_fma_f32 v[62:63], v[110:111], s[40:41], v[50:51] op_sel_hi:[1,0,1]
	v_pk_fma_f32 v[50:51], v[114:115], s[40:41], v[48:49] op_sel_hi:[1,0,1]
	v_lshl_add_u64 v[60:61], v[60:61], 0, v[200:201]
	v_cvt_pk_bf16_f32 v48, v52, v53
	v_cvt_pk_bf16_f32 v49, v54, v55
	v_cvt_pk_bf16_f32 v50, v50, v51
	v_cvt_pk_bf16_f32 v51, v62, v63
	global_store_dwordx4 v[60:61], v[56:59], off
	global_store_dwordx4 v[60:61], v[48:51], off offset:256
	v_lshlrev_b32_e32 v53, 16, v56
	v_lshlrev_b32_e32 v52, 16, v48
	v_and_b32_e32 v55, 0xffff0000, v56
	v_and_b32_e32 v54, 0xffff0000, v48
	v_lshlrev_b32_e32 v61, 16, v57
	v_lshlrev_b32_e32 v60, 16, v49
	v_and_b32_e32 v57, 0xffff0000, v57
	v_and_b32_e32 v56, 0xffff0000, v49
	v_lshlrev_b32_e32 v49, 16, v58
	v_lshlrev_b32_e32 v48, 16, v50
	v_and_b32_e32 v63, 0xffff0000, v58
	v_and_b32_e32 v62, 0xffff0000, v50
	v_lshlrev_b32_e32 v111, 16, v59
	v_lshlrev_b32_e32 v110, 16, v51
	v_and_b32_e32 v59, 0xffff0000, v59
	v_and_b32_e32 v58, 0xffff0000, v51
	v_pk_add_f32 v[50:51], v[52:53], v[54:55]
	v_pk_add_f32 v[112:113], v[60:61], v[56:57]
	v_pk_add_f32 v[114:115], v[110:111], v[58:59]
	v_pk_add_f32 v[50:51], v[50:51], v[112:113]
	v_pk_add_f32 v[112:113], v[48:49], v[62:63]
	s_waitcnt vmcnt(2)
	v_lshlrev_b32_e32 v118, 16, v124
	v_pk_add_f32 v[112:113], v[112:113], v[114:115]
	v_and_b32_e32 v119, 0xffff0000, v124
	v_pk_add_f32 v[112:113], v[50:51], v[112:113]
	v_pk_mul_f32 v[50:51], v[54:55], v[54:55]
	v_lshlrev_b32_e32 v120, 16, v125
	v_pk_fma_f32 v[50:51], v[52:53], v[52:53], v[50:51]
	v_pk_mul_f32 v[52:53], v[56:57], v[56:57]
	v_and_b32_e32 v121, 0xffff0000, v125
	v_pk_fma_f32 v[52:53], v[60:61], v[60:61], v[52:53]
	v_pk_mul_f32 v[60:61], v[126:127], s[38:39] op_sel_hi:[1,0]
	v_pk_add_f32 v[50:51], v[50:51], v[52:53]
	v_pk_mul_f32 v[52:53], v[62:63], v[62:63]
	v_and_b32_e32 v117, 0xffff0000, v123
	v_pk_fma_f32 v[48:49], v[48:49], v[48:49], v[52:53]
	v_pk_mul_f32 v[52:53], v[58:59], v[58:59]
	v_sub_f32_e32 v119, v119, v60
	v_pk_fma_f32 v[52:53], v[110:111], v[110:111], v[52:53]
	v_sub_f32_e32 v118, v118, v60
	v_pk_add_f32 v[48:49], v[48:49], v[52:53]
	v_sub_f32_e32 v121, v121, v60
	v_pk_add_f32 v[58:59], v[50:51], v[48:49]
	v_fma_f32 v50, -v60, v60, v61
	v_add_f32_e32 v50, 0x3727c5ac, v50
	v_rsq_f32_e32 v110, v50
	v_add_u32_e32 v48, 0xa0, v198
	v_ashrrev_i32_e32 v49, 31, v48
	v_lshl_add_u64 v[52:53], v[48:49], 3, s[30:31]
	v_lshlrev_b64 v[56:57], 11, v[48:49]
	v_lshl_add_u64 v[54:55], v[202:203], 0, v[56:57]
	v_sub_f32_e32 v120, v120, v60
	v_sub_f32_e32 v117, v117, v60
	ds_bpermute_b32 v87, v199, v85
	s_nop 1
	global_load_dwordx4 v[48:51], v[54:55], off offset:256
	global_load_dwordx2 v[62:63], v[52:53], off
	s_nop 0
	global_load_dwordx4 v[52:55], v[54:55], off
	s_nop 0
	v_lshlrev_b32_e32 v61, 16, v122
	v_and_b32_e32 v111, 0xffff0000, v122
	v_lshlrev_b32_e32 v116, 16, v123
	v_sub_f32_e32 v115, v111, v60
	v_sub_f32_e32 v114, v61, v60
	v_sub_f32_e32 v116, v116, v60
	v_pk_mul_f32 v[114:115], v[110:111], v[114:115] op_sel_hi:[0,1]
	v_pk_mul_f32 v[120:121], v[110:111], v[120:121] op_sel_hi:[0,1]
	v_pk_mul_f32 v[118:119], v[110:111], v[118:119] op_sel_hi:[0,1]
	v_pk_mul_f32 v[116:117], v[110:111], v[116:117] op_sel_hi:[0,1]
	v_pk_fma_f32 v[114:115], v[96:97], v[114:115], v[100:101]
	v_pk_fma_f32 v[118:119], v[88:89], v[118:119], v[92:93]
	v_pk_fma_f32 v[120:121], v[90:91], v[120:121], v[94:95]
	v_pk_fma_f32 v[116:117], v[98:99], v[116:117], v[102:103]
	v_pk_fma_f32 v[44:45], v[114:115], s[40:41], v[44:45] op_sel_hi:[1,0,1]
	v_pk_fma_f32 v[114:115], v[120:121], s[40:41], v[42:43] op_sel_hi:[1,0,1]
	v_pk_fma_f32 v[42:43], v[118:119], s[40:41], v[40:41] op_sel_hi:[1,0,1]
	v_pk_fma_f32 v[46:47], v[116:117], s[40:41], v[46:47] op_sel_hi:[1,0,1]
	v_cvt_pk_bf16_f32 v40, v44, v45
	v_cvt_pk_bf16_f32 v42, v42, v43
	v_cvt_pk_bf16_f32 v41, v46, v47
	v_cvt_pk_bf16_f32 v43, v114, v115
	v_lshl_add_u64 v[44:45], s[26:27], 0, v[108:109]
	v_lshlrev_b32_e32 v47, 16, v42
	v_lshlrev_b32_e32 v46, 16, v40
	v_and_b32_e32 v109, 0xffff0000, v42
	v_and_b32_e32 v108, 0xffff0000, v40
	v_and_b32_e32 v117, 0xffff0000, v43
	v_and_b32_e32 v116, 0xffff0000, v41
	v_pk_add_f32 v[118:119], v[46:47], v[108:109]
	v_pk_mul_f32 v[108:109], v[108:109], v[108:109]
	v_lshlrev_b32_e32 v115, 16, v43
	v_lshlrev_b32_e32 v114, 16, v41
	v_pk_fma_f32 v[46:47], v[46:47], v[46:47], v[108:109]
	v_pk_mul_f32 v[108:109], v[116:117], v[116:117]
	v_pk_add_f32 v[120:121], v[114:115], v[116:117]
	v_pk_fma_f32 v[108:109], v[114:115], v[114:115], v[108:109]
	v_and_b32_e32 v61, 0xffff0000, v80
	v_pk_add_f32 v[46:47], v[46:47], v[108:109]
	v_lshlrev_b32_e32 v108, 16, v81
	v_pk_add_f32 v[46:47], v[46:47], v[46:47] op_sel_hi:[0,1]
	v_lshlrev_b32_e32 v46, 16, v80
	v_and_b32_e32 v109, 0xffff0000, v81
	v_lshlrev_b32_e32 v111, 16, v82
	v_and_b32_e32 v114, 0xffff0000, v82
	v_lshlrev_b32_e32 v115, 16, v83
	v_and_b32_e32 v116, 0xffff0000, v83
	v_sub_f32_e32 v81, v61, v60
	v_sub_f32_e32 v80, v46, v60
	v_sub_f32_e32 v83, v109, v60
	v_sub_f32_e32 v82, v108, v60
	v_sub_f32_e32 v109, v114, v60
	v_sub_f32_e32 v108, v111, v60
	v_sub_f32_e32 v61, v116, v60
	v_sub_f32_e32 v60, v115, v60
	v_pk_mul_f32 v[80:81], v[110:111], v[80:81] op_sel_hi:[0,1]
	v_pk_mul_f32 v[60:61], v[110:111], v[60:61] op_sel_hi:[0,1]
	v_pk_mul_f32 v[108:109], v[110:111], v[108:109] op_sel_hi:[0,1]
	v_pk_mul_f32 v[82:83], v[110:111], v[82:83] op_sel_hi:[0,1]
	v_pk_fma_f32 v[80:81], v[72:73], v[80:81], v[76:77]
	v_pk_fma_f32 v[108:109], v[64:65], v[108:109], v[68:69]
	v_pk_fma_f32 v[60:61], v[66:67], v[60:61], v[70:71]
	v_pk_fma_f32 v[82:83], v[74:75], v[82:83], v[78:79]
	v_pk_fma_f32 v[36:37], v[80:81], s[40:41], v[36:37] op_sel_hi:[1,0,1]
	v_pk_fma_f32 v[60:61], v[60:61], s[40:41], v[34:35] op_sel_hi:[1,0,1]
	v_pk_fma_f32 v[34:35], v[108:109], s[40:41], v[32:33] op_sel_hi:[1,0,1]
	v_pk_fma_f32 v[38:39], v[82:83], s[40:41], v[38:39] op_sel_hi:[1,0,1]
	v_cvt_pk_bf16_f32 v32, v36, v37
	v_cvt_pk_bf16_f32 v34, v34, v35
	v_cvt_pk_bf16_f32 v33, v38, v39
	v_cvt_pk_bf16_f32 v35, v60, v61
	v_lshlrev_b32_e32 v37, 16, v34
	v_lshlrev_b32_e32 v36, 16, v32
	v_and_b32_e32 v39, 0xffff0000, v34
	v_and_b32_e32 v38, 0xffff0000, v32
	v_and_b32_e32 v81, 0xffff0000, v35
	v_and_b32_e32 v80, 0xffff0000, v33
	v_pk_add_f32 v[82:83], v[36:37], v[38:39]
	v_pk_mul_f32 v[38:39], v[38:39], v[38:39]
	v_lshlrev_b32_e32 v61, 16, v35
	v_lshlrev_b32_e32 v60, 16, v33
	v_pk_fma_f32 v[36:37], v[36:37], v[36:37], v[38:39]
	v_pk_mul_f32 v[38:39], v[80:81], v[80:81]
	v_mov_b32_e32 v46, v59
	v_pk_fma_f32 v[38:39], v[60:61], v[60:61], v[38:39]
	v_lshl_add_u64 v[44:45], v[44:45], 0, v[200:201]
	v_pk_add_f32 v[36:37], v[36:37], v[38:39]
	global_store_dwordx4 v[44:45], v[40:43], off
	global_store_dwordx4 v[44:45], v[32:35], off offset:256
	v_pk_add_f32 v[36:37], v[36:37], v[36:37] op_sel_hi:[0,1]
	v_mov_b32_e32 v36, v58
	v_pk_add_f32 v[36:37], v[36:37], v[46:47]
	ds_bpermute_b32 v46, v218, v36
	ds_bpermute_b32 v47, v218, v37
	v_pk_add_f32 v[118:119], v[118:119], v[120:121]
	v_pk_add_f32 v[108:109], v[60:61], v[80:81]
	v_pk_add_f32 v[118:119], v[118:119], v[118:119] op_sel_hi:[0,1]
	v_pk_add_f32 v[82:83], v[82:83], v[108:109]
	s_waitcnt lgkmcnt(0)
	v_pk_add_f32 v[36:37], v[36:37], v[46:47]
	s_waitcnt vmcnt(3)
	v_pk_mul_f32 v[46:47], v[62:63], s[38:39] op_sel_hi:[1,0]
	v_add_u32_e32 v32, 0xb0, v198
	v_fma_f32 v34, -v46, v46, v47
	v_add_f32_e32 v34, 0x3727c5ac, v34
	v_rsq_f32_e32 v80, v34
	v_pk_add_f32 v[82:83], v[82:83], v[82:83] op_sel_hi:[0,1]
	v_mov_b32_e32 v118, v113
	v_ashrrev_i32_e32 v33, 31, v32
	v_pk_add_f32 v[38:39], v[118:119], 0 op_sel_hi:[1,0]
	v_mov_b32_e32 v113, v83
	v_lshl_add_u64 v[58:59], v[32:33], 3, s[30:31]
	v_lshlrev_b64 v[44:45], 11, v[32:33]
	v_pk_add_f32 v[38:39], v[112:113], v[38:39]
	ds_bpermute_b32 v60, v218, v38
	ds_bpermute_b32 v61, v218, v39
	s_waitcnt vmcnt(2)
	v_lshlrev_b32_e32 v110, 16, v55
	s_waitcnt lgkmcnt(0)
	v_pk_add_f32 v[40:41], v[38:39], v[60:61]
	v_lshl_add_u64 v[60:61], v[202:203], 0, v[44:45]
	v_and_b32_e32 v109, 0xffff0000, v55
	v_sub_f32_e32 v109, v109, v46
	global_load_dwordx4 v[32:35], v[60:61], off offset:256
	global_load_dwordx2 v[62:63], v[58:59], off
	s_nop 0
	global_load_dwordx4 v[58:61], v[60:61], off
	ds_bpermute_b32 v42, v199, v40
	ds_bpermute_b32 v38, v199, v36
	ds_bpermute_b32 v43, v199, v41
	v_lshlrev_b32_e32 v81, 16, v53
	v_and_b32_e32 v82, 0xffff0000, v53
	v_lshlrev_b32_e32 v47, 16, v52
	v_and_b32_e32 v52, 0xffff0000, v52
	v_lshlrev_b32_e32 v108, 16, v54
	v_and_b32_e32 v83, 0xffff0000, v54
	v_sub_f32_e32 v55, v82, v46
	v_sub_f32_e32 v54, v81, v46
	v_sub_f32_e32 v53, v52, v46
	v_sub_f32_e32 v52, v47, v46
	v_pk_mul_f32 v[54:55], v[80:81], v[54:55] op_sel_hi:[0,1]
	v_sub_f32_e32 v83, v83, v46
	v_sub_f32_e32 v82, v108, v46
	v_sub_f32_e32 v108, v110, v46
	v_pk_mul_f32 v[52:53], v[80:81], v[52:53] op_sel_hi:[0,1]
	v_pk_fma_f32 v[54:55], v[98:99], v[54:55], v[102:103]
	v_pk_mul_f32 v[108:109], v[80:81], v[108:109] op_sel_hi:[0,1]
	v_pk_mul_f32 v[82:83], v[80:81], v[82:83] op_sel_hi:[0,1]
	v_pk_fma_f32 v[52:53], v[96:97], v[52:53], v[100:101]
	v_pk_fma_f32 v[82:83], v[88:89], v[82:83], v[92:93]
	v_pk_fma_f32 v[108:109], v[90:91], v[108:109], v[94:95]
	v_pk_fma_f32 v[30:31], v[54:55], s[40:41], v[30:31] op_sel_hi:[1,0,1]
	v_pk_fma_f32 v[28:29], v[52:53], s[40:41], v[28:29] op_sel_hi:[1,0,1]
	v_pk_fma_f32 v[52:53], v[108:109], s[40:41], v[26:27] op_sel_hi:[1,0,1]
	v_pk_fma_f32 v[26:27], v[82:83], s[40:41], v[24:25] op_sel_hi:[1,0,1]
	v_cvt_pk_bf16_f32 v25, v30, v31
	v_lshlrev_b32_e32 v30, 16, v48
	v_and_b32_e32 v31, 0xffff0000, v48
	v_cvt_pk_bf16_f32 v26, v26, v27
	v_cvt_pk_bf16_f32 v27, v52, v53
	v_lshlrev_b32_e32 v47, 16, v49
	v_and_b32_e32 v48, 0xffff0000, v49
	v_lshlrev_b32_e32 v52, 16, v50
	v_and_b32_e32 v50, 0xffff0000, v50
	v_lshlrev_b32_e32 v53, 16, v51
	v_and_b32_e32 v54, 0xffff0000, v51
	v_sub_f32_e32 v31, v31, v46
	v_sub_f32_e32 v30, v30, v46
	v_sub_f32_e32 v49, v48, v46
	v_sub_f32_e32 v48, v47, v46
	v_pk_mul_f32 v[30:31], v[80:81], v[30:31] op_sel_hi:[0,1]
	v_sub_f32_e32 v51, v50, v46
	v_sub_f32_e32 v50, v52, v46
	v_sub_f32_e32 v47, v54, v46
	v_sub_f32_e32 v46, v53, v46
	v_pk_mul_f32 v[48:49], v[80:81], v[48:49] op_sel_hi:[0,1]
	v_pk_fma_f32 v[30:31], v[72:73], v[30:31], v[76:77]
	v_pk_mul_f32 v[46:47], v[80:81], v[46:47] op_sel_hi:[0,1]
	v_pk_mul_f32 v[50:51], v[80:81], v[50:51] op_sel_hi:[0,1]
	v_pk_fma_f32 v[48:49], v[74:75], v[48:49], v[78:79]
	v_pk_fma_f32 v[50:51], v[64:65], v[50:51], v[68:69]
	v_pk_fma_f32 v[46:47], v[66:67], v[46:47], v[70:71]
	v_pk_fma_f32 v[20:21], v[30:31], s[40:41], v[20:21] op_sel_hi:[1,0,1]
	v_cvt_pk_bf16_f32 v24, v28, v29
	v_lshl_add_u64 v[28:29], s[26:27], 0, v[56:57]
	v_pk_fma_f32 v[22:23], v[48:49], s[40:41], v[22:23] op_sel_hi:[1,0,1]
	v_pk_fma_f32 v[30:31], v[46:47], s[40:41], v[18:19] op_sel_hi:[1,0,1]
	v_pk_fma_f32 v[18:19], v[50:51], s[40:41], v[16:17] op_sel_hi:[1,0,1]
	v_cvt_pk_bf16_f32 v16, v20, v21
	v_lshl_add_u64 v[28:29], v[28:29], 0, v[200:201]
	v_cvt_pk_bf16_f32 v17, v22, v23
	v_cvt_pk_bf16_f32 v18, v18, v19
	v_cvt_pk_bf16_f32 v19, v30, v31
	v_lshlrev_b32_e32 v21, 16, v24
	v_lshlrev_b32_e32 v20, 16, v16
	v_and_b32_e32 v23, 0xffff0000, v24
	v_and_b32_e32 v22, 0xffff0000, v16
	global_store_dwordx4 v[28:29], v[24:27], off
	global_store_dwordx4 v[28:29], v[16:19], off offset:256
	v_lshlrev_b32_e32 v29, 16, v25
	v_lshlrev_b32_e32 v28, 16, v17
	v_and_b32_e32 v25, 0xffff0000, v25
	v_and_b32_e32 v24, 0xffff0000, v17
	v_lshlrev_b32_e32 v17, 16, v26
	v_lshlrev_b32_e32 v16, 16, v18
	v_and_b32_e32 v31, 0xffff0000, v26
	v_and_b32_e32 v30, 0xffff0000, v18
	v_lshlrev_b32_e32 v46, 16, v19
	v_and_b32_e32 v26, 0xffff0000, v19
	v_pk_add_f32 v[18:19], v[20:21], v[22:23]
	v_pk_mul_f32 v[22:23], v[22:23], v[22:23]
	v_pk_add_f32 v[48:49], v[28:29], v[24:25]
	v_pk_fma_f32 v[20:21], v[20:21], v[20:21], v[22:23]
	v_pk_mul_f32 v[22:23], v[24:25], v[24:25]
	s_waitcnt vmcnt(3)
	v_pk_mul_f32 v[24:25], v[62:63], s[38:39] op_sel_hi:[1,0]
	v_pk_fma_f32 v[22:23], v[28:29], v[28:29], v[22:23]
	v_fma_f32 v25, -v24, v24, v25
	v_add_f32_e32 v25, 0x3727c5ac, v25
	v_lshlrev_b32_e32 v47, 16, v27
	v_and_b32_e32 v27, 0xffff0000, v27
	v_pk_add_f32 v[20:21], v[20:21], v[22:23]
	v_pk_mul_f32 v[22:23], v[30:31], v[30:31]
	v_pk_add_f32 v[18:19], v[18:19], v[48:49]
	v_pk_add_f32 v[48:49], v[16:17], v[30:31]
	v_pk_add_f32 v[50:51], v[46:47], v[26:27]
	v_pk_fma_f32 v[16:17], v[16:17], v[16:17], v[22:23]
	v_pk_mul_f32 v[22:23], v[26:27], v[26:27]
	v_pk_fma_f32 v[22:23], v[46:47], v[46:47], v[22:23]
	v_pk_add_f32 v[16:17], v[16:17], v[22:23]
	s_waitcnt vmcnt(2)
	v_lshlrev_b32_e32 v28, 16, v60
	v_pk_add_f32 v[16:17], v[20:21], v[16:17]
	v_and_b32_e32 v29, 0xffff0000, v60
	v_lshlrev_b32_e32 v30, 16, v61
	v_and_b32_e32 v31, 0xffff0000, v61
	v_sub_f32_e32 v29, v29, v24
	v_lshlrev_b32_e32 v21, 16, v58
	v_and_b32_e32 v22, 0xffff0000, v58
	v_rsq_f32_e32 v20, v25
	v_lshlrev_b32_e32 v25, 16, v59
	v_and_b32_e32 v26, 0xffff0000, v59
	v_sub_f32_e32 v23, v22, v24
	v_sub_f32_e32 v22, v21, v24
	v_sub_f32_e32 v28, v28, v24
	v_sub_f32_e32 v31, v31, v24
	v_sub_f32_e32 v30, v30, v24
	v_sub_f32_e32 v27, v26, v24
	v_sub_f32_e32 v26, v25, v24
	v_pk_mul_f32 v[22:23], v[20:21], v[22:23] op_sel_hi:[0,1]
	v_pk_mul_f32 v[30:31], v[20:21], v[30:31] op_sel_hi:[0,1]
	v_pk_mul_f32 v[28:29], v[20:21], v[28:29] op_sel_hi:[0,1]
	v_pk_mul_f32 v[26:27], v[20:21], v[26:27] op_sel_hi:[0,1]
	v_pk_fma_f32 v[22:23], v[96:97], v[22:23], v[100:101]
	v_pk_fma_f32 v[28:29], v[88:89], v[28:29], v[92:93]
	v_pk_fma_f32 v[30:31], v[90:91], v[30:31], v[94:95]
	v_pk_fma_f32 v[26:27], v[98:99], v[26:27], v[102:103]
	v_pk_fma_f32 v[12:13], v[22:23], s[40:41], v[12:13] op_sel_hi:[1,0,1]
	v_pk_fma_f32 v[22:23], v[30:31], s[40:41], v[10:11] op_sel_hi:[1,0,1]
	v_pk_fma_f32 v[10:11], v[28:29], s[40:41], v[8:9] op_sel_hi:[1,0,1]
	v_pk_fma_f32 v[14:15], v[26:27], s[40:41], v[14:15] op_sel_hi:[1,0,1]
	v_cvt_pk_bf16_f32 v8, v12, v13
	v_cvt_pk_bf16_f32 v10, v10, v11
	v_cvt_pk_bf16_f32 v9, v14, v15
	v_cvt_pk_bf16_f32 v11, v22, v23
	v_lshlrev_b32_e32 v15, 16, v10
	v_lshlrev_b32_e32 v14, 16, v8
	v_and_b32_e32 v23, 0xffff0000, v10
	v_and_b32_e32 v22, 0xffff0000, v8
	v_and_b32_e32 v29, 0xffff0000, v11
	v_and_b32_e32 v28, 0xffff0000, v9
	v_pk_add_f32 v[30:31], v[14:15], v[22:23]
	v_pk_mul_f32 v[22:23], v[22:23], v[22:23]
	v_lshlrev_b32_e32 v27, 16, v11
	v_lshlrev_b32_e32 v26, 16, v9
	v_pk_fma_f32 v[14:15], v[14:15], v[14:15], v[22:23]
	v_pk_mul_f32 v[22:23], v[28:29], v[28:29]
	v_lshl_add_u64 v[12:13], s[26:27], 0, v[44:45]
	v_pk_add_f32 v[44:45], v[26:27], v[28:29]
	v_pk_fma_f32 v[22:23], v[26:27], v[26:27], v[22:23]
	v_pk_add_f32 v[30:31], v[30:31], v[44:45]
	v_pk_add_f32 v[14:15], v[14:15], v[22:23]
	v_pk_add_f32 v[30:31], v[30:31], v[30:31] op_sel_hi:[0,1]
	v_pk_add_f32 v[14:15], v[14:15], v[14:15] op_sel_hi:[0,1]
	v_lshlrev_b32_e32 v14, 16, v32
	v_and_b32_e32 v21, 0xffff0000, v32
	v_lshlrev_b32_e32 v25, 16, v33
	v_and_b32_e32 v26, 0xffff0000, v33
	v_lshlrev_b32_e32 v28, 16, v34
	v_and_b32_e32 v29, 0xffff0000, v34
	v_lshlrev_b32_e32 v30, 16, v35
	v_and_b32_e32 v32, 0xffff0000, v35
	v_sub_f32_e32 v23, v21, v24
	v_sub_f32_e32 v22, v14, v24
	v_sub_f32_e32 v27, v26, v24
	v_sub_f32_e32 v26, v25, v24
	v_sub_f32_e32 v29, v29, v24
	v_sub_f32_e32 v28, v28, v24
	v_sub_f32_e32 v25, v32, v24
	v_sub_f32_e32 v24, v30, v24
	v_pk_mul_f32 v[26:27], v[20:21], v[26:27] op_sel_hi:[0,1]
	v_pk_mul_f32 v[22:23], v[20:21], v[22:23] op_sel_hi:[0,1]
	v_pk_mul_f32 v[24:25], v[20:21], v[24:25] op_sel_hi:[0,1]
	v_pk_mul_f32 v[20:21], v[20:21], v[28:29] op_sel_hi:[0,1]
	v_pk_fma_f32 v[22:23], v[72:73], v[22:23], v[76:77]
	v_pk_fma_f32 v[20:21], v[64:65], v[20:21], v[68:69]
	v_pk_fma_f32 v[24:25], v[66:67], v[24:25], v[70:71]
	v_pk_fma_f32 v[26:27], v[74:75], v[26:27], v[78:79]
	v_pk_fma_f32 v[4:5], v[22:23], s[40:41], v[4:5] op_sel_hi:[1,0,1]
	v_pk_fma_f32 v[22:23], v[24:25], s[40:41], v[2:3] op_sel_hi:[1,0,1]
	v_pk_fma_f32 v[2:3], v[20:21], s[40:41], v[0:1] op_sel_hi:[1,0,1]
	v_pk_fma_f32 v[6:7], v[26:27], s[40:41], v[6:7] op_sel_hi:[1,0,1]
	v_cvt_pk_bf16_f32 v0, v4, v5
	v_cvt_pk_bf16_f32 v2, v2, v3
	v_cvt_pk_bf16_f32 v1, v6, v7
	v_cvt_pk_bf16_f32 v3, v22, v23
	v_lshlrev_b32_e32 v5, 16, v2
	v_lshlrev_b32_e32 v4, 16, v0
	v_and_b32_e32 v7, 0xffff0000, v2
	v_and_b32_e32 v6, 0xffff0000, v0
	v_lshlrev_b32_e32 v21, 16, v3
	v_lshlrev_b32_e32 v20, 16, v1
	v_and_b32_e32 v23, 0xffff0000, v3
	v_and_b32_e32 v22, 0xffff0000, v1
	v_pk_add_f32 v[24:25], v[4:5], v[6:7]
	v_pk_mul_f32 v[6:7], v[6:7], v[6:7]
	v_pk_add_f32 v[48:49], v[48:49], v[50:51]
	v_pk_add_f32 v[26:27], v[20:21], v[22:23]
	v_pk_fma_f32 v[4:5], v[4:5], v[4:5], v[6:7]
	v_pk_mul_f32 v[6:7], v[22:23], v[22:23]
	v_pk_add_f32 v[18:19], v[18:19], v[48:49]
	v_pk_add_f32 v[24:25], v[24:25], v[26:27]
	v_pk_fma_f32 v[6:7], v[20:21], v[20:21], v[6:7]
	v_pk_add_f32 v[24:25], v[24:25], v[24:25] op_sel_hi:[0,1]
	v_pk_add_f32 v[4:5], v[4:5], v[6:7]
	v_mov_b32_e32 v30, v19
	v_pk_add_f32 v[4:5], v[4:5], v[4:5] op_sel_hi:[0,1]
	v_pk_add_f32 v[6:7], v[30:31], 0 op_sel_hi:[1,0]
	v_mov_b32_e32 v19, v25
	v_pk_add_f32 v[6:7], v[18:19], v[6:7]
	v_mov_b32_e32 v4, v16
	v_mov_b32_e32 v14, v17
	ds_bpermute_b32 v18, v218, v6
	ds_bpermute_b32 v19, v218, v7
	v_pk_add_f32 v[4:5], v[4:5], v[14:15]
	ds_bpermute_b32 v14, v218, v4
	ds_bpermute_b32 v15, v218, v5
	v_lshl_add_u64 v[12:13], v[12:13], 0, v[200:201]
	global_store_dwordx4 v[12:13], v[8:11], off
	global_store_dwordx4 v[12:13], v[0:3], off offset:256
	ds_bpermute_b32 v39, v199, v37
	s_waitcnt lgkmcnt(1)
	v_pk_add_f32 v[4:5], v[4:5], v[14:15]
	v_pk_add_f32 v[0:1], v[6:7], v[18:19]
	ds_bpermute_b32 v2, v199, v0
	ds_bpermute_b32 v3, v199, v1
	ds_bpermute_b32 v6, v199, v4
	ds_bpermute_b32 v7, v199, v5
	v_pk_add_f32 v[8:9], v[136:137], v[138:139]
	v_pk_add_f32 v[10:11], v[104:105], v[106:107]
	s_waitcnt lgkmcnt(2)
	v_pk_add_f32 v[0:1], v[0:1], v[2:3]
	v_pk_add_f32 v[2:3], v[132:133], v[134:135]
	v_pk_add_f32 v[14:15], v[84:85], v[86:87]
	s_waitcnt lgkmcnt(0)
	v_pk_add_f32 v[4:5], v[4:5], v[6:7]
	v_cndmask_b32_e64 v3, v3, v9, s[6:7]
	v_cndmask_b32_e64 v2, v2, v8, s[6:7]
	v_cmp_ne_u64_e32 vcc, 0, v[180:181]
	v_cndmask_b32_e64 v4, v4, v0, s[6:7]
	v_cndmask_b32_e64 v10, v14, v10, s[6:7]
	v_cndmask_b32_e32 v0, v2, v3, vcc
	v_cmp_eq_u32_e32 vcc, 2, v180
	v_pk_add_f32 v[12:13], v[40:41], v[42:43]
	v_pk_add_f32 v[16:17], v[36:37], v[38:39]
	v_cndmask_b32_e64 v11, v15, v11, s[6:7]
	v_cndmask_b32_e32 v0, v0, v10, vcc
	v_cmp_eq_u32_e32 vcc, 3, v180
	v_cndmask_b32_e64 v7, v16, v12, s[6:7]
	v_cndmask_b32_e64 v6, v17, v13, s[6:7]
	v_cndmask_b32_e32 v0, v0, v11, vcc
	v_cmp_eq_u32_e32 vcc, 4, v180
	v_cndmask_b32_e64 v5, v5, v1, s[6:7]
	s_mov_b64 s[0:1], -1
	v_cndmask_b32_e32 v0, v0, v7, vcc
	v_cmp_eq_u32_e32 vcc, 5, v180
	s_nop 1
	v_cndmask_b32_e32 v0, v0, v6, vcc
	v_cmp_eq_u32_e32 vcc, 6, v180
	s_nop 1
	v_cndmask_b32_e32 v0, v0, v4, vcc
	v_cmp_eq_u32_e32 vcc, 7, v180
	s_nop 1
	v_cndmask_b32_e32 v8, v0, v5, vcc
	v_or_b32_e32 v0, v198, v183
	v_ashrrev_i32_e32 v1, 31, v0
	v_lshl_add_u64 v[0:1], v[0:1], 3, v[188:189]
	v_cmp_eq_u32_e32 vcc, 1, v182
	global_atomic_add_f32 v[0:1], v8, off
	s_nop 0
	v_cndmask_b32_e32 v0, v2, v3, vcc
	v_cmp_eq_u32_e32 vcc, 2, v182
	s_nop 1
	v_cndmask_b32_e32 v0, v0, v10, vcc
	v_cmp_eq_u32_e32 vcc, 3, v182
	s_nop 1
	v_cndmask_b32_e32 v0, v0, v11, vcc
	v_cmp_eq_u32_e32 vcc, 4, v182
	s_nop 1
	v_cndmask_b32_e32 v0, v0, v7, vcc
	v_cmp_eq_u32_e32 vcc, 5, v182
	s_nop 1
	v_cndmask_b32_e32 v0, v0, v6, vcc
	v_cmp_eq_u32_e32 vcc, 6, v182
	s_nop 1
	v_cndmask_b32_e32 v0, v0, v4, vcc
	v_cmp_eq_u32_e32 vcc, 7, v182
	s_nop 1
	v_cndmask_b32_e32 v8, v0, v5, vcc
	v_or_b32_e32 v0, v198, v185
	v_ashrrev_i32_e32 v1, 31, v0
	v_lshl_add_u64 v[0:1], v[0:1], 3, v[188:189]
	v_cmp_eq_u32_e32 vcc, 1, v184
	global_atomic_add_f32 v[0:1], v8, off
	s_nop 0
	v_cndmask_b32_e32 v0, v2, v3, vcc
	v_cmp_eq_u32_e32 vcc, 2, v184
	s_nop 1
	v_cndmask_b32_e32 v0, v0, v10, vcc
	v_cmp_eq_u32_e32 vcc, 3, v184
	s_nop 1
	v_cndmask_b32_e32 v0, v0, v11, vcc
	v_cmp_eq_u32_e32 vcc, 4, v184
	s_nop 1
	v_cndmask_b32_e32 v0, v0, v7, vcc
	v_cmp_eq_u32_e32 vcc, 5, v184
	s_nop 1
	v_cndmask_b32_e32 v0, v0, v6, vcc
	v_cmp_eq_u32_e32 vcc, 6, v184
	s_nop 1
	v_cndmask_b32_e32 v0, v0, v4, vcc
	v_cmp_eq_u32_e32 vcc, 7, v184
	s_nop 1
	v_cndmask_b32_e32 v8, v0, v5, vcc
	v_add_u32_e32 v0, v198, v187
	v_ashrrev_i32_e32 v1, 31, v0
	v_lshl_add_u64 v[0:1], v[0:1], 3, v[188:189]
	v_cmp_eq_u32_e32 vcc, 1, v186
	global_atomic_add_f32 v[0:1], v8, off
	s_nop 0
	v_cndmask_b32_e32 v0, v2, v3, vcc
	v_cmp_eq_u32_e32 vcc, 2, v186
	s_nop 1
	v_cndmask_b32_e32 v0, v0, v10, vcc
	v_cmp_eq_u32_e32 vcc, 3, v186
	s_nop 1
	v_cndmask_b32_e32 v0, v0, v11, vcc
	v_cmp_eq_u32_e32 vcc, 4, v186
	s_nop 1
	v_cndmask_b32_e32 v0, v0, v7, vcc
	v_cmp_eq_u32_e32 vcc, 5, v186
	s_nop 1
	v_cndmask_b32_e32 v0, v0, v6, vcc
	v_cmp_eq_u32_e32 vcc, 6, v186
	s_nop 1
	v_cndmask_b32_e32 v0, v0, v4, vcc
	v_cmp_eq_u32_e32 vcc, 7, v186
	s_nop 1
	v_cndmask_b32_e32 v2, v0, v5, vcc
	v_add_u32_e32 v0, v198, v210
	v_ashrrev_i32_e32 v1, 31, v0
	v_lshl_add_u64 v[0:1], v[0:1], 3, v[188:189]
	global_atomic_add_f32 v[0:1], v2, off
	s_andn2_b64 vcc, exec, s[8:9]
	s_cbranch_vccnz .LBB0_676
	s_andn2_b64 vcc, exec, s[4:5]
	s_cbranch_vccnz .LBB0_675
	s_barrier
	s_branch .LBB0_675

.LBB0_756:
	s_lshl_b32 s3, s0, 8
	v_lshl_or_b32 v120, s83, 8, v199
	s_add_i32 s3, s3, s63
	v_ashrrev_i32_e32 v121, 31, v120
	v_or_b32_e32 v112, 0x80, v120
	v_lshlrev_b64 v[100:101], 2, v[120:121]
	v_ashrrev_i32_e32 v113, 31, v112
	v_or_b32_e32 v120, 0x84, v120
	v_or_b32_e32 v194, s3, v169
	v_lshlrev_b64 v[112:113], 2, v[112:113]
	v_ashrrev_i32_e32 v121, 31, v120
	v_ashrrev_i32_e32 v195, 31, v194
	v_lshl_add_u64 v[102:103], s[30:31], 0, v[100:101]
	v_lshl_add_u64 v[108:109], s[34:35], 0, v[100:101]
	v_lshl_add_u64 v[114:115], s[30:31], 0, v[112:113]
	v_lshl_add_u64 v[122:123], s[34:35], 0, v[112:113]
	v_lshl_add_u64 v[124:125], v[120:121], 2, s[30:31]
	v_lshl_add_u64 v[160:161], v[194:195], 3, s[10:11]
	global_load_dwordx4 v[96:99], v[102:103], off offset:16
	global_load_dwordx4 v[104:107], v[102:103], off
	s_nop 0
	global_load_dwordx4 v[100:103], v[108:109], off offset:16
	s_nop 0
	global_load_dwordx4 v[108:111], v[108:109], off
	s_nop 0
	global_load_dwordx4 v[112:115], v[114:115], off
	s_nop 0
	global_load_dwordx4 v[116:119], v[122:123], off
	s_nop 0
	global_load_dwordx4 v[120:123], v[122:123], off offset:16
	s_nop 0
	global_load_dwordx4 v[124:127], v[124:125], off
	s_mul_hi_i32 s0, s83, 0x55555556
	global_load_dwordx2 v[196:197], v[160:161], off
	s_lshr_b32 s1, s0, 31
	s_add_i32 s0, s0, s1
	s_mul_i32 s0, s0, 3
	s_sub_i32 s0, s83, s0
	s_lshl_b32 s1, s0, 2
	s_or_b32 s43, s1, s62
	s_lshl_b32 s2, s0, 1
	s_cmp_lt_i32 s83, 6
	s_mov_b64 s[0:1], -1
	s_cbranch_scc1 .LBB0_758
	s_sub_i32 s45, 13, s2
	v_and_b32_e32 v162, 0x1fcf, v194
	v_lshlrev_b32_e32 v160, s45, v194
	v_and_b32_e32 v163, 0x1ffe, v160
	v_lshrrev_b32_e32 v176, s2, v162
	v_or_b32_e32 v193, v163, v176
	v_bitop3_b32 v163, v163, s72, v176 bitop3:0xc8
	v_lshlrev_b32_e32 v176, 1, v193
	v_lshrrev_b32_e32 v193, 1, v193
	v_and_b32_e32 v176, 8, v176
	v_and_b32_e32 v193, 4, v193
	v_or3_b32 v163, v176, v163, v193
	s_waitcnt vmcnt(0)
	v_mul_f32_e32 v193, 0x3a800000, v196
	v_mul_f32_e32 v176, v193, v193
	v_fma_f32 v176, v197, s40, -v176
	v_or_b32_e32 v208, 16, v194
	v_add_f32_e32 v176, 0x3727c5ac, v176
	v_rsq_f32_e32 v247, v176
	v_ashrrev_i32_e32 v209, 31, v208
	v_lshl_add_u64 v[208:209], v[208:209], 3, s[10:11]
	s_ashr_i32 s0, s3, 13
	global_load_dwordx2 v[208:209], v[208:209], off
	s_mul_i32 s0, s0, 12
	s_add_i32 s0, s0, s43
	s_ashr_i32 s1, s0, 31
	s_lshl_b64 s[0:1], s[0:1], 20
	v_lshl_add_u64 v[160:161], v[182:183], 0, s[0:1]
	v_lshlrev_b32_e32 v176, 1, v163
	v_lshl_add_u64 v[200:201], v[160:161], 0, v[176:177]
	s_nop 0
	s_nop 1
	s_nop 1
	s_nop 0
	v_mov_b32_e32 v163, v247
	v_fma_f32 v176, -v104, v193, v156
	v_fma_f32 v176, v176, v163, v108
	v_cvt_pk_bf16_f32 v176, v176, s0
	global_store_short v[200:201], v176, off
	v_fma_f32 v176, -v105, v193, v157
	v_fma_f32 v176, v176, v163, v109
	v_add_co_u32_e32 v210, vcc, s61, v200
	v_cvt_pk_bf16_f32 v176, v176, s0
	s_nop 0
	v_addc_co_u32_e32 v211, vcc, 0, v201, vcc
	global_store_short v[210:211], v176, off
	v_fma_f32 v176, -v106, v193, v158
	v_fma_f32 v176, v176, v163, v110
	v_add_co_u32_e32 v210, vcc, s67, v200
	v_cvt_pk_bf16_f32 v176, v176, s0
	s_nop 0
	v_addc_co_u32_e32 v211, vcc, 0, v201, vcc
	global_store_short v[210:211], v176, off
	v_fma_f32 v176, -v107, v193, v159
	v_fma_f32 v176, v176, v163, v111
	v_add_co_u32_e32 v210, vcc, s71, v200
	v_cvt_pk_bf16_f32 v176, v176, s0
	s_nop 0
	v_addc_co_u32_e32 v211, vcc, 0, v201, vcc
	global_store_short v[210:211], v176, off
	v_fma_f32 v176, -v96, v193, v152
	v_fma_f32 v176, v176, v163, v100
	v_add_co_u32_e32 v210, vcc, s59, v200
	v_cvt_pk_bf16_f32 v176, v176, s0
	s_nop 0
	v_addc_co_u32_e32 v211, vcc, 0, v201, vcc
	global_store_short v[210:211], v176, off
	v_fma_f32 v176, -v97, v193, v153
	v_fma_f32 v176, v176, v163, v101
	v_add_co_u32_e32 v210, vcc, s60, v200
	v_cvt_pk_bf16_f32 v176, v176, s0
	s_nop 0
	v_addc_co_u32_e32 v211, vcc, 0, v201, vcc
	global_store_short v[210:211], v176, off
	v_fma_f32 v176, -v98, v193, v154
	v_fma_f32 v176, v176, v163, v102
	v_add_co_u32_e32 v210, vcc, s66, v200
	v_cvt_pk_bf16_f32 v176, v176, s0
	s_nop 0
	v_addc_co_u32_e32 v211, vcc, 0, v201, vcc
	global_store_short v[210:211], v176, off
	v_fma_f32 v176, -v99, v193, v155
	v_fma_f32 v176, v176, v163, v103
	v_add_co_u32_e32 v210, vcc, s68, v200
	v_cvt_pk_bf16_f32 v176, v176, s0
	s_nop 0
	v_addc_co_u32_e32 v211, vcc, 0, v201, vcc
	global_store_short v[210:211], v176, off
	v_fma_f32 v176, -v112, v193, v148
	v_fma_f32 v176, v176, v163, v116
	v_add_co_u32_e32 v210, vcc, s74, v200
	v_cvt_pk_bf16_f32 v176, v176, s0
	s_nop 0
	v_addc_co_u32_e32 v211, vcc, 0, v201, vcc
	global_store_short v[210:211], v176, off
	v_fma_f32 v176, -v113, v193, v149
	v_fma_f32 v176, v176, v163, v117
	v_add_co_u32_e32 v210, vcc, s75, v200
	v_cvt_pk_bf16_f32 v176, v176, s0
	s_nop 0
	v_addc_co_u32_e32 v211, vcc, 0, v201, vcc
	global_store_short v[210:211], v176, off
	v_fma_f32 v176, -v114, v193, v150
	v_fma_f32 v176, v176, v163, v118
	v_add_co_u32_e32 v210, vcc, s76, v200
	v_cvt_pk_bf16_f32 v176, v176, s0
	s_nop 0
	v_addc_co_u32_e32 v211, vcc, 0, v201, vcc
	global_store_short v[210:211], v176, off
	v_fma_f32 v176, -v115, v193, v151
	v_fma_f32 v176, v176, v163, v119
	v_add_co_u32_e32 v210, vcc, s77, v200
	v_cvt_pk_bf16_f32 v176, v176, s0
	s_nop 0
	v_addc_co_u32_e32 v211, vcc, 0, v201, vcc
	global_store_short v[210:211], v176, off
	v_fma_f32 v176, -v124, v193, v144
	v_fma_f32 v176, v176, v163, v120
	v_add_co_u32_e32 v210, vcc, s78, v200
	v_cvt_pk_bf16_f32 v176, v176, s0
	s_nop 0
	v_addc_co_u32_e32 v211, vcc, 0, v201, vcc
	global_store_short v[210:211], v176, off
	v_fma_f32 v176, -v125, v193, v145
	v_fma_f32 v176, v176, v163, v121
	v_add_co_u32_e32 v210, vcc, s79, v200
	v_cvt_pk_bf16_f32 v176, v176, s0
	s_nop 0
	v_addc_co_u32_e32 v211, vcc, 0, v201, vcc
	global_store_short v[210:211], v176, off
	v_fma_f32 v176, -v126, v193, v146
	v_fma_f32 v176, v176, v163, v122
	v_add_co_u32_e32 v210, vcc, s80, v200
	v_cvt_pk_bf16_f32 v176, v176, s0
	s_nop 0
	v_addc_co_u32_e32 v211, vcc, 0, v201, vcc
	global_store_short v[210:211], v176, off
	v_fma_f32 v176, -v127, v193, v147
	v_fma_f32 v163, v176, v163, v123
	v_add_co_u32_e32 v200, vcc, s81, v200
	v_cvt_pk_bf16_f32 v163, v163, s0
	s_nop 0
	v_addc_co_u32_e32 v201, vcc, 0, v201, vcc
	global_store_short v[200:201], v163, off
	v_or_b32_e32 v163, 16, v162
	v_lshlrev_b32_e32 v176, s45, v163
	v_and_b32_e32 v176, 0x1ffe, v176
	v_lshrrev_b32_e32 v163, s2, v163
	v_or_b32_e32 v193, v176, v163
	v_bitop3_b32 v163, v176, s72, v163 bitop3:0xc8
	v_lshlrev_b32_e32 v176, 1, v193
	v_lshrrev_b32_e32 v193, 1, v193
	v_and_b32_e32 v176, 8, v176
	v_and_b32_e32 v193, 4, v193
	v_or3_b32 v163, v176, v163, v193
	s_waitcnt vmcnt(16)
	v_mul_f32_e32 v193, 0x3a800000, v208
	v_mul_f32_e32 v176, v193, v193
	v_fma_f32 v176, v209, s40, -v176
	v_or_b32_e32 v208, 32, v194
	v_add_f32_e32 v176, 0x3727c5ac, v176
	v_rsq_f32_e32 v248, v176
	v_ashrrev_i32_e32 v209, 31, v208
	v_lshl_add_u64 v[208:209], v[208:209], 3, s[10:11]
	global_load_dwordx2 v[208:209], v[208:209], off
	v_lshlrev_b32_e32 v176, 1, v163
	v_lshl_add_u64 v[200:201], v[160:161], 0, v[176:177]
	s_nop 0
	s_nop 1
	s_nop 1
	s_nop 0
	v_mov_b32_e32 v163, v248
	v_fma_f32 v176, -v104, v193, v140
	v_fma_f32 v176, v176, v163, v108
	v_cvt_pk_bf16_f32 v176, v176, s0
	global_store_short v[200:201], v176, off
	v_fma_f32 v176, -v105, v193, v141
	v_fma_f32 v176, v176, v163, v109
	v_add_co_u32_e32 v210, vcc, s61, v200
	v_cvt_pk_bf16_f32 v176, v176, s0
	s_nop 0
	v_addc_co_u32_e32 v211, vcc, 0, v201, vcc
	global_store_short v[210:211], v176, off
	v_fma_f32 v176, -v106, v193, v142
	v_fma_f32 v176, v176, v163, v110
	v_add_co_u32_e32 v210, vcc, s67, v200
	v_cvt_pk_bf16_f32 v176, v176, s0
	s_nop 0
	v_addc_co_u32_e32 v211, vcc, 0, v201, vcc
	global_store_short v[210:211], v176, off
	v_fma_f32 v176, -v107, v193, v143
	v_fma_f32 v176, v176, v163, v111
	v_add_co_u32_e32 v210, vcc, s71, v200
	v_cvt_pk_bf16_f32 v176, v176, s0
	s_nop 0
	v_addc_co_u32_e32 v211, vcc, 0, v201, vcc
	global_store_short v[210:211], v176, off
	v_fma_f32 v176, -v96, v193, v136
	v_fma_f32 v176, v176, v163, v100
	v_add_co_u32_e32 v210, vcc, s59, v200
	v_cvt_pk_bf16_f32 v176, v176, s0
	s_nop 0
	v_addc_co_u32_e32 v211, vcc, 0, v201, vcc
	global_store_short v[210:211], v176, off
	v_fma_f32 v176, -v97, v193, v137
	v_fma_f32 v176, v176, v163, v101
	v_add_co_u32_e32 v210, vcc, s60, v200
	v_cvt_pk_bf16_f32 v176, v176, s0
	s_nop 0
	v_addc_co_u32_e32 v211, vcc, 0, v201, vcc
	global_store_short v[210:211], v176, off
	v_fma_f32 v176, -v98, v193, v138
	v_fma_f32 v176, v176, v163, v102
	v_add_co_u32_e32 v210, vcc, s66, v200
	v_cvt_pk_bf16_f32 v176, v176, s0
	s_nop 0
	v_addc_co_u32_e32 v211, vcc, 0, v201, vcc
	global_store_short v[210:211], v176, off
	v_fma_f32 v176, -v99, v193, v139
	v_fma_f32 v176, v176, v163, v103
	v_add_co_u32_e32 v210, vcc, s68, v200
	v_cvt_pk_bf16_f32 v176, v176, s0
	s_nop 0
	v_addc_co_u32_e32 v211, vcc, 0, v201, vcc
	global_store_short v[210:211], v176, off
	v_fma_f32 v176, -v112, v193, v132
	v_fma_f32 v176, v176, v163, v116
	v_add_co_u32_e32 v210, vcc, s74, v200
	v_cvt_pk_bf16_f32 v176, v176, s0
	s_nop 0
	v_addc_co_u32_e32 v211, vcc, 0, v201, vcc
	global_store_short v[210:211], v176, off
	v_fma_f32 v176, -v113, v193, v133
	v_fma_f32 v176, v176, v163, v117
	v_add_co_u32_e32 v210, vcc, s75, v200
	v_cvt_pk_bf16_f32 v176, v176, s0
	s_nop 0
	v_addc_co_u32_e32 v211, vcc, 0, v201, vcc
	global_store_short v[210:211], v176, off
	v_fma_f32 v176, -v114, v193, v134
	v_fma_f32 v176, v176, v163, v118
	v_add_co_u32_e32 v210, vcc, s76, v200
	v_cvt_pk_bf16_f32 v176, v176, s0
	s_nop 0
	v_addc_co_u32_e32 v211, vcc, 0, v201, vcc
	global_store_short v[210:211], v176, off
	v_fma_f32 v176, -v115, v193, v135
	v_fma_f32 v176, v176, v163, v119
	v_add_co_u32_e32 v210, vcc, s77, v200
	v_cvt_pk_bf16_f32 v176, v176, s0
	s_nop 0
	v_addc_co_u32_e32 v211, vcc, 0, v201, vcc
	global_store_short v[210:211], v176, off
	v_fma_f32 v176, -v124, v193, v128
	v_fma_f32 v176, v176, v163, v120
	v_add_co_u32_e32 v210, vcc, s78, v200
	v_cvt_pk_bf16_f32 v176, v176, s0
	s_nop 0
	v_addc_co_u32_e32 v211, vcc, 0, v201, vcc
	global_store_short v[210:211], v176, off
	v_fma_f32 v176, -v125, v193, v129
	v_fma_f32 v176, v176, v163, v121
	v_add_co_u32_e32 v210, vcc, s79, v200
	v_cvt_pk_bf16_f32 v176, v176, s0
	s_nop 0
	v_addc_co_u32_e32 v211, vcc, 0, v201, vcc
	global_store_short v[210:211], v176, off
	v_fma_f32 v176, -v126, v193, v130
	v_fma_f32 v176, v176, v163, v122
	v_add_co_u32_e32 v210, vcc, s80, v200
	v_cvt_pk_bf16_f32 v176, v176, s0
	s_nop 0
	v_addc_co_u32_e32 v211, vcc, 0, v201, vcc
	global_store_short v[210:211], v176, off
	v_fma_f32 v176, -v127, v193, v131
	v_fma_f32 v163, v176, v163, v123
	v_add_co_u32_e32 v200, vcc, s81, v200
	v_cvt_pk_bf16_f32 v163, v163, s0
	s_nop 0
	v_addc_co_u32_e32 v201, vcc, 0, v201, vcc
	global_store_short v[200:201], v163, off
	v_or_b32_e32 v163, 32, v162
	v_lshlrev_b32_e32 v176, s45, v163
	v_and_b32_e32 v176, 0x1ffe, v176
	v_lshrrev_b32_e32 v163, s2, v163
	v_or_b32_e32 v193, v176, v163
	v_bitop3_b32 v163, v176, s72, v163 bitop3:0xc8
	v_lshlrev_b32_e32 v176, 1, v193
	v_lshrrev_b32_e32 v193, 1, v193
	v_and_b32_e32 v176, 8, v176
	v_and_b32_e32 v193, 4, v193
	v_or3_b32 v163, v176, v163, v193
	s_waitcnt vmcnt(16)
	v_mul_f32_e32 v193, 0x3a800000, v208
	v_mul_f32_e32 v176, v193, v193
	v_or_b32_e32 v208, 48, v194
	v_fma_f32 v176, v209, s40, -v176
	v_ashrrev_i32_e32 v209, 31, v208
	v_lshl_add_u64 v[208:209], v[208:209], 3, s[10:11]
	v_add_f32_e32 v176, 0x3727c5ac, v176
	v_rsq_f32_e32 v249, v176
	global_load_dwordx2 v[208:209], v[208:209], off
	v_or_b32_e32 v162, 48, v162
	s_nop 0
	v_lshlrev_b32_e32 v176, 1, v163
	v_lshl_add_u64 v[200:201], v[160:161], 0, v[176:177]
	s_nop 0
	s_nop 1
	s_nop 1
	s_nop 0
	v_mov_b32_e32 v163, v249
	v_fma_f32 v176, -v104, v193, v92
	v_fma_f32 v176, v176, v163, v108
	v_cvt_pk_bf16_f32 v176, v176, s0
	global_store_short v[200:201], v176, off
	v_fma_f32 v176, -v105, v193, v93
	v_fma_f32 v176, v176, v163, v109
	v_add_co_u32_e32 v210, vcc, s61, v200
	v_cvt_pk_bf16_f32 v176, v176, s0
	s_nop 0
	v_addc_co_u32_e32 v211, vcc, 0, v201, vcc
	global_store_short v[210:211], v176, off
	v_fma_f32 v176, -v106, v193, v94
	v_fma_f32 v176, v176, v163, v110
	v_add_co_u32_e32 v210, vcc, s67, v200
	v_cvt_pk_bf16_f32 v176, v176, s0
	s_nop 0
	v_addc_co_u32_e32 v211, vcc, 0, v201, vcc
	global_store_short v[210:211], v176, off
	v_fma_f32 v176, -v107, v193, v95
	v_fma_f32 v176, v176, v163, v111
	v_add_co_u32_e32 v210, vcc, s71, v200
	v_cvt_pk_bf16_f32 v176, v176, s0
	s_nop 0
	v_addc_co_u32_e32 v211, vcc, 0, v201, vcc
	global_store_short v[210:211], v176, off
	v_fma_f32 v176, -v96, v193, v88
	v_fma_f32 v176, v176, v163, v100
	v_add_co_u32_e32 v210, vcc, s59, v200
	v_cvt_pk_bf16_f32 v176, v176, s0
	s_nop 0
	v_addc_co_u32_e32 v211, vcc, 0, v201, vcc
	global_store_short v[210:211], v176, off
	v_fma_f32 v176, -v97, v193, v89
	v_fma_f32 v176, v176, v163, v101
	v_add_co_u32_e32 v210, vcc, s60, v200
	v_cvt_pk_bf16_f32 v176, v176, s0
	s_nop 0
	v_addc_co_u32_e32 v211, vcc, 0, v201, vcc
	global_store_short v[210:211], v176, off
	v_fma_f32 v176, -v98, v193, v90
	v_fma_f32 v176, v176, v163, v102
	v_add_co_u32_e32 v210, vcc, s66, v200
	v_cvt_pk_bf16_f32 v176, v176, s0
	s_nop 0
	v_addc_co_u32_e32 v211, vcc, 0, v201, vcc
	global_store_short v[210:211], v176, off
	v_fma_f32 v176, -v99, v193, v91
	v_fma_f32 v176, v176, v163, v103
	v_add_co_u32_e32 v210, vcc, s68, v200
	v_cvt_pk_bf16_f32 v176, v176, s0
	s_nop 0
	v_addc_co_u32_e32 v211, vcc, 0, v201, vcc
	global_store_short v[210:211], v176, off
	v_fma_f32 v176, -v112, v193, v84
	v_fma_f32 v176, v176, v163, v116
	v_add_co_u32_e32 v210, vcc, s74, v200
	v_cvt_pk_bf16_f32 v176, v176, s0
	s_nop 0
	v_addc_co_u32_e32 v211, vcc, 0, v201, vcc
	global_store_short v[210:211], v176, off
	v_fma_f32 v176, -v113, v193, v85
	v_fma_f32 v176, v176, v163, v117
	v_add_co_u32_e32 v210, vcc, s75, v200
	v_cvt_pk_bf16_f32 v176, v176, s0
	s_nop 0
	v_addc_co_u32_e32 v211, vcc, 0, v201, vcc
	global_store_short v[210:211], v176, off
	v_fma_f32 v176, -v114, v193, v86
	v_fma_f32 v176, v176, v163, v118
	v_add_co_u32_e32 v210, vcc, s76, v200
	v_cvt_pk_bf16_f32 v176, v176, s0
	s_nop 0
	v_addc_co_u32_e32 v211, vcc, 0, v201, vcc
	global_store_short v[210:211], v176, off
	v_fma_f32 v176, -v115, v193, v87
	v_fma_f32 v176, v176, v163, v119
	v_add_co_u32_e32 v210, vcc, s77, v200
	v_cvt_pk_bf16_f32 v176, v176, s0
	s_nop 0
	v_addc_co_u32_e32 v211, vcc, 0, v201, vcc
	global_store_short v[210:211], v176, off
	v_fma_f32 v176, -v124, v193, v80
	v_fma_f32 v176, v176, v163, v120
	v_add_co_u32_e32 v210, vcc, s78, v200
	v_cvt_pk_bf16_f32 v176, v176, s0
	s_nop 0
	v_addc_co_u32_e32 v211, vcc, 0, v201, vcc
	global_store_short v[210:211], v176, off
	v_fma_f32 v176, -v125, v193, v81
	v_fma_f32 v176, v176, v163, v121
	v_add_co_u32_e32 v210, vcc, s79, v200
	v_cvt_pk_bf16_f32 v176, v176, s0
	s_nop 0
	v_addc_co_u32_e32 v211, vcc, 0, v201, vcc
	global_store_short v[210:211], v176, off
	v_fma_f32 v176, -v126, v193, v82
	v_fma_f32 v176, v176, v163, v122
	v_add_co_u32_e32 v210, vcc, s80, v200
	v_cvt_pk_bf16_f32 v176, v176, s0
	s_nop 0
	v_addc_co_u32_e32 v211, vcc, 0, v201, vcc
	global_store_short v[210:211], v176, off
	v_fma_f32 v176, -v127, v193, v83
	v_fma_f32 v163, v176, v163, v123
	v_add_co_u32_e32 v200, vcc, s81, v200
	v_cvt_pk_bf16_f32 v163, v163, s0
	s_nop 0
	v_addc_co_u32_e32 v201, vcc, 0, v201, vcc
	global_store_short v[200:201], v163, off
	v_lshlrev_b32_e32 v163, s45, v162
	v_and_b32_e32 v163, 0x1ffe, v163
	v_lshrrev_b32_e32 v162, s2, v162
	v_or_b32_e32 v176, v163, v162
	v_bitop3_b32 v162, v163, s72, v162 bitop3:0xc8
	v_lshlrev_b32_e32 v163, 1, v176
	v_lshrrev_b32_e32 v176, 1, v176
	v_and_b32_e32 v163, 8, v163
	v_and_b32_e32 v176, 4, v176
	s_waitcnt vmcnt(16)
	v_mul_f32_e32 v193, 0x3a800000, v208
	v_or3_b32 v162, v163, v162, v176
	v_mul_f32_e32 v163, v193, v193
	v_fma_f32 v163, v209, s40, -v163
	v_add_f32_e32 v163, 0x3727c5ac, v163
	v_rsq_f32_e32 v252, v163
	s_nop 1
	v_lshlrev_b32_e32 v176, 1, v162
	v_lshl_add_u64 v[160:161], v[160:161], 0, v[176:177]
	v_add_u32_e32 v162, 0x80, v194
	s_nop 0
	s_nop 1
	s_nop 1
	v_ashrrev_i32_e32 v163, 31, v162
	v_lshl_add_u64 v[200:201], v[162:163], 3, s[10:11]
	global_load_dwordx2 v[200:201], v[200:201], off
	s_nop 0
	v_mov_b32_e32 v163, v252
	v_fma_f32 v176, -v104, v193, v76
	v_fma_f32 v176, v176, v163, v108
	v_cvt_pk_bf16_f32 v176, v176, s0
	global_store_short v[160:161], v176, off
	v_fma_f32 v176, -v105, v193, v77
	v_fma_f32 v176, v176, v163, v109
	v_add_co_u32_e32 v208, vcc, s61, v160
	v_cvt_pk_bf16_f32 v176, v176, s0
	s_nop 0
	v_addc_co_u32_e32 v209, vcc, 0, v161, vcc
	global_store_short v[208:209], v176, off
	v_fma_f32 v176, -v106, v193, v78
	v_fma_f32 v176, v176, v163, v110
	v_add_co_u32_e32 v208, vcc, s67, v160
	v_cvt_pk_bf16_f32 v176, v176, s0
	s_nop 0
	v_addc_co_u32_e32 v209, vcc, 0, v161, vcc
	global_store_short v[208:209], v176, off
	v_fma_f32 v176, -v107, v193, v79
	v_fma_f32 v176, v176, v163, v111
	v_add_co_u32_e32 v208, vcc, s71, v160
	v_cvt_pk_bf16_f32 v176, v176, s0
	s_nop 0
	v_addc_co_u32_e32 v209, vcc, 0, v161, vcc
	global_store_short v[208:209], v176, off
	v_fma_f32 v176, -v96, v193, v72
	v_fma_f32 v176, v176, v163, v100
	v_add_co_u32_e32 v208, vcc, s59, v160
	v_cvt_pk_bf16_f32 v176, v176, s0
	s_nop 0
	v_addc_co_u32_e32 v209, vcc, 0, v161, vcc
	global_store_short v[208:209], v176, off
	v_fma_f32 v176, -v97, v193, v73
	v_fma_f32 v176, v176, v163, v101
	v_add_co_u32_e32 v208, vcc, s60, v160
	v_cvt_pk_bf16_f32 v176, v176, s0
	s_nop 0
	v_addc_co_u32_e32 v209, vcc, 0, v161, vcc
	global_store_short v[208:209], v176, off
	v_fma_f32 v176, -v98, v193, v74
	v_fma_f32 v176, v176, v163, v102
	v_add_co_u32_e32 v208, vcc, s66, v160
	v_cvt_pk_bf16_f32 v176, v176, s0
	s_nop 0
	v_addc_co_u32_e32 v209, vcc, 0, v161, vcc
	global_store_short v[208:209], v176, off
	v_fma_f32 v176, -v99, v193, v75
	v_fma_f32 v176, v176, v163, v103
	v_add_co_u32_e32 v208, vcc, s68, v160
	v_cvt_pk_bf16_f32 v176, v176, s0
	s_nop 0
	v_addc_co_u32_e32 v209, vcc, 0, v161, vcc
	global_store_short v[208:209], v176, off
	v_fma_f32 v176, -v112, v193, v68
	v_fma_f32 v176, v176, v163, v116
	v_add_co_u32_e32 v208, vcc, s74, v160
	v_cvt_pk_bf16_f32 v176, v176, s0
	s_nop 0
	v_addc_co_u32_e32 v209, vcc, 0, v161, vcc
	global_store_short v[208:209], v176, off
	v_fma_f32 v176, -v113, v193, v69
	v_fma_f32 v176, v176, v163, v117
	v_add_co_u32_e32 v208, vcc, s75, v160
	v_cvt_pk_bf16_f32 v176, v176, s0
	s_nop 0
	v_addc_co_u32_e32 v209, vcc, 0, v161, vcc
	global_store_short v[208:209], v176, off
	v_fma_f32 v176, -v114, v193, v70
	v_fma_f32 v176, v176, v163, v118
	v_add_co_u32_e32 v208, vcc, s76, v160
	v_cvt_pk_bf16_f32 v176, v176, s0
	s_nop 0
	v_addc_co_u32_e32 v209, vcc, 0, v161, vcc
	global_store_short v[208:209], v176, off
	v_fma_f32 v176, -v115, v193, v71
	v_fma_f32 v176, v176, v163, v119
	v_add_co_u32_e32 v208, vcc, s77, v160
	v_cvt_pk_bf16_f32 v176, v176, s0
	s_nop 0
	v_addc_co_u32_e32 v209, vcc, 0, v161, vcc
	global_store_short v[208:209], v176, off
	v_fma_f32 v176, -v124, v193, v64
	v_fma_f32 v176, v176, v163, v120
	v_add_co_u32_e32 v208, vcc, s78, v160
	v_cvt_pk_bf16_f32 v176, v176, s0
	s_nop 0
	v_addc_co_u32_e32 v209, vcc, 0, v161, vcc
	global_store_short v[208:209], v176, off
	v_fma_f32 v176, -v125, v193, v65
	v_fma_f32 v176, v176, v163, v121
	v_add_co_u32_e32 v208, vcc, s79, v160
	v_cvt_pk_bf16_f32 v176, v176, s0
	s_nop 0
	v_addc_co_u32_e32 v209, vcc, 0, v161, vcc
	global_store_short v[208:209], v176, off
	v_fma_f32 v176, -v126, v193, v66
	v_fma_f32 v176, v176, v163, v122
	v_add_co_u32_e32 v208, vcc, s80, v160
	v_cvt_pk_bf16_f32 v176, v176, s0
	s_nop 0
	v_addc_co_u32_e32 v209, vcc, 0, v161, vcc
	global_store_short v[208:209], v176, off
	v_fma_f32 v176, -v127, v193, v67
	v_fma_f32 v163, v176, v163, v123
	v_add_co_u32_e32 v160, vcc, s81, v160
	v_cvt_pk_bf16_f32 v163, v163, s0
	s_nop 0
	v_addc_co_u32_e32 v161, vcc, 0, v161, vcc
	global_store_short v[160:161], v163, off
	v_ashrrev_i32_e32 v160, 13, v162
	v_and_b32_e32 v162, 0x1fcf, v162
	v_lshlrev_b32_e32 v161, s45, v162
	v_and_b32_e32 v163, 0x1ffe, v161
	v_lshrrev_b32_e32 v176, s2, v162
	v_or_b32_e32 v193, v163, v176
	v_bitop3_b32 v163, v163, s72, v176 bitop3:0xc8
	v_lshlrev_b32_e32 v176, 1, v193
	v_lshrrev_b32_e32 v193, 1, v193
	v_and_b32_e32 v176, 8, v176
	v_and_b32_e32 v193, 4, v193
	v_or3_b32 v163, v176, v163, v193
	s_waitcnt vmcnt(16)
	v_mul_f32_e32 v193, 0x3a800000, v200
	v_mul_f32_e32 v176, v193, v193
	v_fma_f32 v176, v201, s40, -v176
	v_add_u32_e32 v208, 0x90, v194
	v_add_f32_e32 v176, 0x3727c5ac, v176
	v_rsq_f32_e32 v253, v176
	v_ashrrev_i32_e32 v209, 31, v208
	v_lshl_add_u64 v[208:209], v[208:209], 3, s[10:11]
	global_load_dwordx2 v[208:209], v[208:209], off
	v_mad_i32_i24 v160, v160, 12, s43
	v_ashrrev_i32_e32 v161, 31, v160
	v_lshlrev_b64 v[160:161], 20, v[160:161]
	v_lshl_add_u64 v[160:161], v[182:183], 0, v[160:161]
	v_lshlrev_b32_e32 v176, 1, v163
	v_lshl_add_u64 v[200:201], v[160:161], 0, v[176:177]
	s_nop 0
	s_nop 1
	s_nop 1
	s_nop 0
	v_mov_b32_e32 v163, v253
	v_fma_f32 v176, -v104, v193, v60
	v_fma_f32 v176, v176, v163, v108
	v_cvt_pk_bf16_f32 v176, v176, s0
	global_store_short v[200:201], v176, off
	v_fma_f32 v176, -v105, v193, v61
	v_fma_f32 v176, v176, v163, v109
	v_add_co_u32_e32 v210, vcc, s61, v200
	v_cvt_pk_bf16_f32 v176, v176, s0
	s_nop 0
	v_addc_co_u32_e32 v211, vcc, 0, v201, vcc
	global_store_short v[210:211], v176, off
	v_fma_f32 v176, -v106, v193, v62
	v_fma_f32 v176, v176, v163, v110
	v_add_co_u32_e32 v210, vcc, s67, v200
	v_cvt_pk_bf16_f32 v176, v176, s0
	s_nop 0
	v_addc_co_u32_e32 v211, vcc, 0, v201, vcc
	global_store_short v[210:211], v176, off
	v_fma_f32 v176, -v107, v193, v63
	v_fma_f32 v176, v176, v163, v111
	v_add_co_u32_e32 v210, vcc, s71, v200
	v_cvt_pk_bf16_f32 v176, v176, s0
	s_nop 0
	v_addc_co_u32_e32 v211, vcc, 0, v201, vcc
	global_store_short v[210:211], v176, off
	v_fma_f32 v176, -v96, v193, v56
	v_fma_f32 v176, v176, v163, v100
	v_add_co_u32_e32 v210, vcc, s59, v200
	v_cvt_pk_bf16_f32 v176, v176, s0
	s_nop 0
	v_addc_co_u32_e32 v211, vcc, 0, v201, vcc
	global_store_short v[210:211], v176, off
	v_fma_f32 v176, -v97, v193, v57
	v_fma_f32 v176, v176, v163, v101
	v_add_co_u32_e32 v210, vcc, s60, v200
	v_cvt_pk_bf16_f32 v176, v176, s0
	s_nop 0
	v_addc_co_u32_e32 v211, vcc, 0, v201, vcc
	global_store_short v[210:211], v176, off
	v_fma_f32 v176, -v98, v193, v58
	v_fma_f32 v176, v176, v163, v102
	v_add_co_u32_e32 v210, vcc, s66, v200
	v_cvt_pk_bf16_f32 v176, v176, s0
	s_nop 0
	v_addc_co_u32_e32 v211, vcc, 0, v201, vcc
	global_store_short v[210:211], v176, off
	v_fma_f32 v176, -v99, v193, v59
	v_fma_f32 v176, v176, v163, v103
	v_add_co_u32_e32 v210, vcc, s68, v200
	v_cvt_pk_bf16_f32 v176, v176, s0
	s_nop 0
	v_addc_co_u32_e32 v211, vcc, 0, v201, vcc
	global_store_short v[210:211], v176, off
	v_fma_f32 v176, -v112, v193, v52
	v_fma_f32 v176, v176, v163, v116
	v_add_co_u32_e32 v210, vcc, s74, v200
	v_cvt_pk_bf16_f32 v176, v176, s0
	s_nop 0
	v_addc_co_u32_e32 v211, vcc, 0, v201, vcc
	global_store_short v[210:211], v176, off
	v_fma_f32 v176, -v113, v193, v53
	v_fma_f32 v176, v176, v163, v117
	v_add_co_u32_e32 v210, vcc, s75, v200
	v_cvt_pk_bf16_f32 v176, v176, s0
	s_nop 0
	v_addc_co_u32_e32 v211, vcc, 0, v201, vcc
	global_store_short v[210:211], v176, off
	v_fma_f32 v176, -v114, v193, v54
	v_fma_f32 v176, v176, v163, v118
	v_add_co_u32_e32 v210, vcc, s76, v200
	v_cvt_pk_bf16_f32 v176, v176, s0
	s_nop 0
	v_addc_co_u32_e32 v211, vcc, 0, v201, vcc
	global_store_short v[210:211], v176, off
	v_fma_f32 v176, -v115, v193, v55
	v_fma_f32 v176, v176, v163, v119
	v_add_co_u32_e32 v210, vcc, s77, v200
	v_cvt_pk_bf16_f32 v176, v176, s0
	s_nop 0
	v_addc_co_u32_e32 v211, vcc, 0, v201, vcc
	global_store_short v[210:211], v176, off
	v_fma_f32 v176, -v124, v193, v48
	v_fma_f32 v176, v176, v163, v120
	v_add_co_u32_e32 v210, vcc, s78, v200
	v_cvt_pk_bf16_f32 v176, v176, s0
	s_nop 0
	v_addc_co_u32_e32 v211, vcc, 0, v201, vcc
	global_store_short v[210:211], v176, off
	v_fma_f32 v176, -v125, v193, v49
	v_fma_f32 v176, v176, v163, v121
	v_add_co_u32_e32 v210, vcc, s79, v200
	v_cvt_pk_bf16_f32 v176, v176, s0
	s_nop 0
	v_addc_co_u32_e32 v211, vcc, 0, v201, vcc
	global_store_short v[210:211], v176, off
	v_fma_f32 v176, -v126, v193, v50
	v_fma_f32 v176, v176, v163, v122
	v_add_co_u32_e32 v210, vcc, s80, v200
	v_cvt_pk_bf16_f32 v176, v176, s0
	s_nop 0
	v_addc_co_u32_e32 v211, vcc, 0, v201, vcc
	global_store_short v[210:211], v176, off
	v_fma_f32 v176, -v127, v193, v51
	v_fma_f32 v163, v176, v163, v123
	v_add_co_u32_e32 v200, vcc, s81, v200
	v_cvt_pk_bf16_f32 v163, v163, s0
	s_nop 0
	v_addc_co_u32_e32 v201, vcc, 0, v201, vcc
	global_store_short v[200:201], v163, off
	v_or_b32_e32 v163, 16, v162
	v_lshlrev_b32_e32 v176, s45, v163
	v_and_b32_e32 v176, 0x1ffe, v176
	v_lshrrev_b32_e32 v163, s2, v163
	v_or_b32_e32 v193, v176, v163
	v_bitop3_b32 v163, v176, s72, v163 bitop3:0xc8
	v_lshlrev_b32_e32 v176, 1, v193
	v_lshrrev_b32_e32 v193, 1, v193
	v_and_b32_e32 v176, 8, v176
	v_and_b32_e32 v193, 4, v193
	v_or3_b32 v163, v176, v163, v193
	s_waitcnt vmcnt(16)
	v_mul_f32_e32 v193, 0x3a800000, v208
	v_mul_f32_e32 v176, v193, v193
	v_fma_f32 v176, v209, s40, -v176
	v_add_u32_e32 v208, 0xa0, v194
	v_add_f32_e32 v176, 0x3727c5ac, v176
	v_rsq_f32_e32 v254, v176
	v_ashrrev_i32_e32 v209, 31, v208
	v_lshl_add_u64 v[208:209], v[208:209], 3, s[10:11]
	global_load_dwordx2 v[208:209], v[208:209], off
	v_lshlrev_b32_e32 v176, 1, v163
	v_lshl_add_u64 v[200:201], v[160:161], 0, v[176:177]
	s_nop 0
	s_nop 1
	s_nop 1
	s_nop 0
	v_mov_b32_e32 v163, v254
	v_fma_f32 v176, -v104, v193, v44
	v_fma_f32 v176, v176, v163, v108
	v_cvt_pk_bf16_f32 v176, v176, s0
	global_store_short v[200:201], v176, off
	v_fma_f32 v176, -v105, v193, v45
	v_fma_f32 v176, v176, v163, v109
	v_add_co_u32_e32 v210, vcc, s61, v200
	v_cvt_pk_bf16_f32 v176, v176, s0
	s_nop 0
	v_addc_co_u32_e32 v211, vcc, 0, v201, vcc
	global_store_short v[210:211], v176, off
	v_fma_f32 v176, -v106, v193, v46
	v_fma_f32 v176, v176, v163, v110
	v_add_co_u32_e32 v210, vcc, s67, v200
	v_cvt_pk_bf16_f32 v176, v176, s0
	s_nop 0
	v_addc_co_u32_e32 v211, vcc, 0, v201, vcc
	global_store_short v[210:211], v176, off
	v_fma_f32 v176, -v107, v193, v47
	v_fma_f32 v176, v176, v163, v111
	v_add_co_u32_e32 v210, vcc, s71, v200
	v_cvt_pk_bf16_f32 v176, v176, s0
	s_nop 0
	v_addc_co_u32_e32 v211, vcc, 0, v201, vcc
	global_store_short v[210:211], v176, off
	v_fma_f32 v176, -v96, v193, v40
	v_fma_f32 v176, v176, v163, v100
	v_add_co_u32_e32 v210, vcc, s59, v200
	v_cvt_pk_bf16_f32 v176, v176, s0
	s_nop 0
	v_addc_co_u32_e32 v211, vcc, 0, v201, vcc
	global_store_short v[210:211], v176, off
	v_fma_f32 v176, -v97, v193, v41
	v_fma_f32 v176, v176, v163, v101
	v_add_co_u32_e32 v210, vcc, s60, v200
	v_cvt_pk_bf16_f32 v176, v176, s0
	s_nop 0
	v_addc_co_u32_e32 v211, vcc, 0, v201, vcc
	global_store_short v[210:211], v176, off
	v_fma_f32 v176, -v98, v193, v42
	v_fma_f32 v176, v176, v163, v102
	v_add_co_u32_e32 v210, vcc, s66, v200
	v_cvt_pk_bf16_f32 v176, v176, s0
	s_nop 0
	v_addc_co_u32_e32 v211, vcc, 0, v201, vcc
	global_store_short v[210:211], v176, off
	v_fma_f32 v176, -v99, v193, v43
	v_fma_f32 v176, v176, v163, v103
	v_add_co_u32_e32 v210, vcc, s68, v200
	v_cvt_pk_bf16_f32 v176, v176, s0
	s_nop 0
	v_addc_co_u32_e32 v211, vcc, 0, v201, vcc
	global_store_short v[210:211], v176, off
	v_fma_f32 v176, -v112, v193, v36
	v_fma_f32 v176, v176, v163, v116
	v_add_co_u32_e32 v210, vcc, s74, v200
	v_cvt_pk_bf16_f32 v176, v176, s0
	s_nop 0
	v_addc_co_u32_e32 v211, vcc, 0, v201, vcc
	global_store_short v[210:211], v176, off
	v_fma_f32 v176, -v113, v193, v37
	v_fma_f32 v176, v176, v163, v117
	v_add_co_u32_e32 v210, vcc, s75, v200
	v_cvt_pk_bf16_f32 v176, v176, s0
	s_nop 0
	v_addc_co_u32_e32 v211, vcc, 0, v201, vcc
	global_store_short v[210:211], v176, off
	v_fma_f32 v176, -v114, v193, v38
	v_fma_f32 v176, v176, v163, v118
	v_add_co_u32_e32 v210, vcc, s76, v200
	v_cvt_pk_bf16_f32 v176, v176, s0
	s_nop 0
	v_addc_co_u32_e32 v211, vcc, 0, v201, vcc
	global_store_short v[210:211], v176, off
	v_fma_f32 v176, -v115, v193, v39
	v_fma_f32 v176, v176, v163, v119
	v_add_co_u32_e32 v210, vcc, s77, v200
	v_cvt_pk_bf16_f32 v176, v176, s0
	s_nop 0
	v_addc_co_u32_e32 v211, vcc, 0, v201, vcc
	global_store_short v[210:211], v176, off
	v_fma_f32 v176, -v124, v193, v32
	v_fma_f32 v176, v176, v163, v120
	v_add_co_u32_e32 v210, vcc, s78, v200
	v_cvt_pk_bf16_f32 v176, v176, s0
	s_nop 0
	v_addc_co_u32_e32 v211, vcc, 0, v201, vcc
	global_store_short v[210:211], v176, off
	v_fma_f32 v176, -v125, v193, v33
	v_fma_f32 v176, v176, v163, v121
	v_add_co_u32_e32 v210, vcc, s79, v200
	v_cvt_pk_bf16_f32 v176, v176, s0
	s_nop 0
	v_addc_co_u32_e32 v211, vcc, 0, v201, vcc
	global_store_short v[210:211], v176, off
	v_fma_f32 v176, -v126, v193, v34
	v_fma_f32 v176, v176, v163, v122
	v_add_co_u32_e32 v210, vcc, s80, v200
	v_cvt_pk_bf16_f32 v176, v176, s0
	s_nop 0
	v_addc_co_u32_e32 v211, vcc, 0, v201, vcc
	global_store_short v[210:211], v176, off
	v_fma_f32 v176, -v127, v193, v35
	v_fma_f32 v163, v176, v163, v123
	v_add_co_u32_e32 v200, vcc, s81, v200
	v_cvt_pk_bf16_f32 v163, v163, s0
	s_nop 0
	v_addc_co_u32_e32 v201, vcc, 0, v201, vcc
	global_store_short v[200:201], v163, off
	v_or_b32_e32 v163, 32, v162
	v_lshlrev_b32_e32 v176, s45, v163
	v_and_b32_e32 v176, 0x1ffe, v176
	v_lshrrev_b32_e32 v163, s2, v163
	v_or_b32_e32 v193, v176, v163
	v_bitop3_b32 v163, v176, s72, v163 bitop3:0xc8
	v_lshlrev_b32_e32 v176, 1, v193
	v_lshrrev_b32_e32 v193, 1, v193
	v_and_b32_e32 v176, 8, v176
	v_and_b32_e32 v193, 4, v193
	v_or3_b32 v163, v176, v163, v193
	s_waitcnt vmcnt(16)
	v_mul_f32_e32 v193, 0x3a800000, v208
	v_mul_f32_e32 v176, v193, v193
	v_add_u32_e32 v208, 0xb0, v194
	v_fma_f32 v176, v209, s40, -v176
	v_ashrrev_i32_e32 v209, 31, v208
	v_lshl_add_u64 v[208:209], v[208:209], 3, s[10:11]
	global_load_dwordx2 v[208:209], v[208:209], off
	v_add_f32_e32 v176, 0x3727c5ac, v176
	v_rsq_f32_e32 v255, v176
	v_or_b32_e32 v162, 48, v162
	s_nop 0
	v_lshlrev_b32_e32 v176, 1, v163
	v_lshl_add_u64 v[200:201], v[160:161], 0, v[176:177]
	s_nop 0
	s_nop 1
	s_nop 1
	s_nop 0
	v_mov_b32_e32 v163, v255
	v_fma_f32 v176, -v104, v193, v28
	v_fma_f32 v176, v176, v163, v108
	v_cvt_pk_bf16_f32 v176, v176, s0
	global_store_short v[200:201], v176, off
	v_fma_f32 v176, -v105, v193, v29
	v_fma_f32 v176, v176, v163, v109
	v_add_co_u32_e32 v210, vcc, s61, v200
	v_cvt_pk_bf16_f32 v176, v176, s0
	s_nop 0
	v_addc_co_u32_e32 v211, vcc, 0, v201, vcc
	global_store_short v[210:211], v176, off
	v_fma_f32 v176, -v106, v193, v30
	v_fma_f32 v176, v176, v163, v110
	v_add_co_u32_e32 v210, vcc, s67, v200
	v_cvt_pk_bf16_f32 v176, v176, s0
	s_nop 0
	v_addc_co_u32_e32 v211, vcc, 0, v201, vcc
	global_store_short v[210:211], v176, off
	v_fma_f32 v176, -v107, v193, v31
	v_fma_f32 v176, v176, v163, v111
	v_add_co_u32_e32 v210, vcc, s71, v200
	v_cvt_pk_bf16_f32 v176, v176, s0
	s_nop 0
	v_addc_co_u32_e32 v211, vcc, 0, v201, vcc
	global_store_short v[210:211], v176, off
	v_fma_f32 v176, -v96, v193, v24
	v_fma_f32 v176, v176, v163, v100
	v_add_co_u32_e32 v210, vcc, s59, v200
	v_cvt_pk_bf16_f32 v176, v176, s0
	s_nop 0
	v_addc_co_u32_e32 v211, vcc, 0, v201, vcc
	global_store_short v[210:211], v176, off
	v_fma_f32 v176, -v97, v193, v25
	v_fma_f32 v176, v176, v163, v101
	v_add_co_u32_e32 v210, vcc, s60, v200
	v_cvt_pk_bf16_f32 v176, v176, s0
	s_nop 0
	v_addc_co_u32_e32 v211, vcc, 0, v201, vcc
	global_store_short v[210:211], v176, off
	v_fma_f32 v176, -v98, v193, v26
	v_fma_f32 v176, v176, v163, v102
	v_add_co_u32_e32 v210, vcc, s66, v200
	v_cvt_pk_bf16_f32 v176, v176, s0
	s_nop 0
	v_addc_co_u32_e32 v211, vcc, 0, v201, vcc
	global_store_short v[210:211], v176, off
	v_fma_f32 v176, -v99, v193, v27
	v_fma_f32 v176, v176, v163, v103
	v_add_co_u32_e32 v210, vcc, s68, v200
	v_cvt_pk_bf16_f32 v176, v176, s0
	s_nop 0
	v_addc_co_u32_e32 v211, vcc, 0, v201, vcc
	global_store_short v[210:211], v176, off
	v_fma_f32 v176, -v112, v193, v20
	v_fma_f32 v176, v176, v163, v116
	v_add_co_u32_e32 v210, vcc, s74, v200
	v_cvt_pk_bf16_f32 v176, v176, s0
	s_nop 0
	v_addc_co_u32_e32 v211, vcc, 0, v201, vcc
	global_store_short v[210:211], v176, off
	v_fma_f32 v176, -v113, v193, v21
	v_fma_f32 v176, v176, v163, v117
	v_add_co_u32_e32 v210, vcc, s75, v200
	v_cvt_pk_bf16_f32 v176, v176, s0
	s_nop 0
	v_addc_co_u32_e32 v211, vcc, 0, v201, vcc
	global_store_short v[210:211], v176, off
	v_fma_f32 v176, -v114, v193, v22
	v_fma_f32 v176, v176, v163, v118
	v_add_co_u32_e32 v210, vcc, s76, v200
	v_cvt_pk_bf16_f32 v176, v176, s0
	s_nop 0
	v_addc_co_u32_e32 v211, vcc, 0, v201, vcc
	global_store_short v[210:211], v176, off
	v_fma_f32 v176, -v115, v193, v23
	v_fma_f32 v176, v176, v163, v119
	v_add_co_u32_e32 v210, vcc, s77, v200
	v_cvt_pk_bf16_f32 v176, v176, s0
	s_nop 0
	v_addc_co_u32_e32 v211, vcc, 0, v201, vcc
	global_store_short v[210:211], v176, off
	v_fma_f32 v176, -v124, v193, v16
	v_fma_f32 v176, v176, v163, v120
	v_add_co_u32_e32 v210, vcc, s78, v200
	v_cvt_pk_bf16_f32 v176, v176, s0
	s_nop 0
	v_addc_co_u32_e32 v211, vcc, 0, v201, vcc
	global_store_short v[210:211], v176, off
	v_fma_f32 v176, -v125, v193, v17
	v_fma_f32 v176, v176, v163, v121
	v_add_co_u32_e32 v210, vcc, s79, v200
	v_cvt_pk_bf16_f32 v176, v176, s0
	s_nop 0
	v_addc_co_u32_e32 v211, vcc, 0, v201, vcc
	global_store_short v[210:211], v176, off
	v_fma_f32 v176, -v126, v193, v18
	v_fma_f32 v176, v176, v163, v122
	v_add_co_u32_e32 v210, vcc, s80, v200
	v_cvt_pk_bf16_f32 v176, v176, s0
	s_nop 0
	v_addc_co_u32_e32 v211, vcc, 0, v201, vcc
	s_waitcnt vmcnt(14)
	v_mul_f32_e32 v195, 0x3a800000, v208
	global_store_short v[210:211], v176, off
	v_fma_f32 v176, -v127, v193, v19
	v_mul_f32_e32 v198, v195, v195
	v_fma_f32 v163, v176, v163, v123
	v_add_co_u32_e32 v200, vcc, s81, v200
	v_fma_f32 v198, v209, s40, -v198
	v_cvt_pk_bf16_f32 v163, v163, s0
	v_addc_co_u32_e32 v201, vcc, 0, v201, vcc
	v_add_f32_e32 v198, 0x3727c5ac, v198
	global_store_short v[200:201], v163, off
	v_lshlrev_b32_e32 v163, s45, v162
	v_and_b32_e32 v163, 0x1ffe, v163
	v_lshrrev_b32_e32 v162, s2, v162
	v_or_b32_e32 v176, v163, v162
	v_lshlrev_b32_e32 v193, 1, v176
	v_bitop3_b32 v162, v163, s72, v162 bitop3:0xc8
	v_lshrrev_b32_e32 v163, 1, v176
	v_and_b32_e32 v193, 8, v193
	v_and_b32_e32 v163, 4, v163
	v_or3_b32 v162, v193, v162, v163
	s_nop 1
	v_lshlrev_b32_e32 v176, 1, v162
	v_lshl_add_u64 v[160:161], v[160:161], 0, v[176:177]
	v_rsq_f32_e32 v176, v198
	v_fma_f32 v162, -v104, v195, v12
	v_fma_f32 v162, v162, v176, v108
	v_cvt_pk_bf16_f32 v162, v162, s0
	global_store_short v[160:161], v162, off
	v_fma_f32 v162, -v105, v195, v13
	v_fma_f32 v162, v162, v176, v109
	v_cvt_pk_bf16_f32 v193, v162, s0
	v_add_co_u32_e32 v162, vcc, s61, v160
	s_nop 1
	v_addc_co_u32_e32 v163, vcc, 0, v161, vcc
	global_store_short v[162:163], v193, off
	v_fma_f32 v162, -v106, v195, v14
	v_fma_f32 v162, v162, v176, v110
	v_cvt_pk_bf16_f32 v193, v162, s0
	v_add_co_u32_e32 v162, vcc, s67, v160
	s_nop 1
	v_addc_co_u32_e32 v163, vcc, 0, v161, vcc
	global_store_short v[162:163], v193, off
	v_fma_f32 v162, -v107, v195, v15
	v_fma_f32 v162, v162, v176, v111
	v_cvt_pk_bf16_f32 v193, v162, s0
	v_add_co_u32_e32 v162, vcc, s71, v160
	s_nop 1
	v_addc_co_u32_e32 v163, vcc, 0, v161, vcc
	global_store_short v[162:163], v193, off
	v_fma_f32 v162, -v96, v195, v8
	v_fma_f32 v162, v162, v176, v100
	v_cvt_pk_bf16_f32 v193, v162, s0
	v_add_co_u32_e32 v162, vcc, s59, v160
	s_nop 1
	v_addc_co_u32_e32 v163, vcc, 0, v161, vcc
	global_store_short v[162:163], v193, off
	v_fma_f32 v162, -v97, v195, v9
	v_fma_f32 v162, v162, v176, v101
	v_cvt_pk_bf16_f32 v193, v162, s0
	v_add_co_u32_e32 v162, vcc, s60, v160
	s_nop 1
	v_addc_co_u32_e32 v163, vcc, 0, v161, vcc
	global_store_short v[162:163], v193, off
	v_fma_f32 v162, -v98, v195, v10
	v_fma_f32 v162, v162, v176, v102
	v_cvt_pk_bf16_f32 v193, v162, s0
	v_add_co_u32_e32 v162, vcc, s66, v160
	s_nop 1
	v_addc_co_u32_e32 v163, vcc, 0, v161, vcc
	global_store_short v[162:163], v193, off
	v_fma_f32 v162, -v99, v195, v11
	v_fma_f32 v162, v162, v176, v103
	v_cvt_pk_bf16_f32 v193, v162, s0
	v_add_co_u32_e32 v162, vcc, s68, v160
	s_nop 1
	v_addc_co_u32_e32 v163, vcc, 0, v161, vcc
	global_store_short v[162:163], v193, off
	v_fma_f32 v162, -v112, v195, v4
	v_fma_f32 v162, v162, v176, v116
	v_cvt_pk_bf16_f32 v193, v162, s0
	v_add_co_u32_e32 v162, vcc, s74, v160
	s_nop 1
	v_addc_co_u32_e32 v163, vcc, 0, v161, vcc
	global_store_short v[162:163], v193, off
	v_fma_f32 v162, -v113, v195, v5
	v_fma_f32 v162, v162, v176, v117
	v_cvt_pk_bf16_f32 v193, v162, s0
	v_add_co_u32_e32 v162, vcc, s75, v160
	s_nop 1
	v_addc_co_u32_e32 v163, vcc, 0, v161, vcc
	global_store_short v[162:163], v193, off
	v_fma_f32 v162, -v114, v195, v6
	v_fma_f32 v162, v162, v176, v118
	v_cvt_pk_bf16_f32 v193, v162, s0
	v_add_co_u32_e32 v162, vcc, s76, v160
	s_nop 1
	v_addc_co_u32_e32 v163, vcc, 0, v161, vcc
	global_store_short v[162:163], v193, off
	v_fma_f32 v162, -v115, v195, v7
	v_fma_f32 v162, v162, v176, v119
	v_cvt_pk_bf16_f32 v193, v162, s0
	v_add_co_u32_e32 v162, vcc, s77, v160
	s_nop 1
	v_addc_co_u32_e32 v163, vcc, 0, v161, vcc
	global_store_short v[162:163], v193, off
	v_fma_f32 v162, -v124, v195, v0
	v_fma_f32 v162, v162, v176, v120
	v_cvt_pk_bf16_f32 v193, v162, s0
	v_add_co_u32_e32 v162, vcc, s78, v160
	s_nop 1
	v_addc_co_u32_e32 v163, vcc, 0, v161, vcc
	global_store_short v[162:163], v193, off
	v_fma_f32 v162, -v125, v195, v1
	v_fma_f32 v162, v162, v176, v121
	v_cvt_pk_bf16_f32 v193, v162, s0
	v_add_co_u32_e32 v162, vcc, s79, v160
	s_nop 1
	v_addc_co_u32_e32 v163, vcc, 0, v161, vcc
	global_store_short v[162:163], v193, off
	v_fma_f32 v162, -v126, v195, v2
	v_fma_f32 v162, v162, v176, v122
	v_cvt_pk_bf16_f32 v193, v162, s0
	v_add_co_u32_e32 v162, vcc, 0x98000, v160
	s_nop 1
	v_addc_co_u32_e32 v163, vcc, 0, v161, vcc
	global_store_short v[162:163], v193, off
	v_fma_f32 v162, -v127, v195, v3
	v_fma_f32 v162, v162, v176, v123
	v_add_co_u32_e32 v160, vcc, 0x9c000, v160
	v_cvt_pk_bf16_f32 v162, v162, s0
	s_nop 0
	v_addc_co_u32_e32 v161, vcc, 0, v161, vcc
	s_mov_b64 s[0:1], 0
	global_store_short v[160:161], v162, off
.LBB0_758:
	s_andn2_b64 vcc, exec, s[0:1]
	v_readlane_b32 s84, v251, 36
	v_readlane_b32 s85, v251, 40
	s_cbranch_vccnz .LBB0_760
	v_lshlrev_b32_e32 v160, 7, v194
	v_and_b32_e32 v176, 0xfe780, v160
	v_lshl_add_u64 v[160:161], v[178:179], 0, v[176:177]
	global_load_dwordx4 v[208:211], v[160:161], off offset:16
	global_load_dwordx4 v[216:219], v[160:161], off
	v_lshl_add_u64 v[160:161], v[180:181], 0, v[176:177]
	global_load_dwordx4 v[220:223], v[160:161], off offset:16
	global_load_dwordx4 v[224:227], v[160:161], off
	v_or_b32_e32 v160, 16, v194
	v_ashrrev_i32_e32 v161, 31, v160
	v_lshl_add_u64 v[162:163], v[160:161], 3, s[10:11]
	v_lshlrev_b32_e32 v160, 7, v160
	v_and_b32_e32 v176, 0xfef80, v160
	v_lshl_add_u64 v[212:213], v[178:179], 0, v[176:177]
	global_load_dwordx2 v[240:241], v[162:163], off
	s_nop 0
	global_load_dwordx4 v[160:163], v[212:213], off
	s_add_i32 s0, s83, 2
	s_waitcnt vmcnt(0)
	v_pk_mul_f32 v[196:197], v[196:197], s[40:41] op_sel_hi:[1,0]
	s_cmp_lt_u32 s0, 5
	v_lshl_add_u64 v[236:237], v[180:181], 0, v[176:177]
	v_fma_f32 v176, -v196, v196, v197
	s_cselect_b64 vcc, -1, 0
	v_add_f32_e32 v176, 0x3727c5ac, v176
	v_cndmask_b32_e32 v198, 1.0, v206, vcc
	s_and_b64 s[0:1], vcc, exec
	global_load_dwordx4 v[228:231], v[236:237], off offset:16
	global_load_dwordx4 v[232:235], v[212:213], off offset:16
	s_nop 0
	global_load_dwordx4 v[236:239], v[236:237], off
	s_cselect_b32 s50, s25, s5
	s_cselect_b32 s51, s24, s4
	s_lshl_b32 s0, s43, 6
	s_ashr_i32 s1, s0, 31
	s_sub_i32 s45, 13, s2
	s_lshl_b64 s[0:1], s[0:1], 1
	s_add_u32 s0, s51, s0
	s_addc_u32 s1, s50, s1
	v_mov_b32_e32 v193, v177
	v_lshl_add_u64 v[200:201], s[0:1], 0, v[192:193]
	v_xor_b32_e32 v115, 0x80000000, v115
	v_xor_b32_e32 v114, 0x80000000, v114
	v_xor_b32_e32 v127, 0x80000000, v127
	v_lshlrev_b32_e32 v212, s45, v194
	v_and_b32_e32 v214, 0x1ffe, v212
	v_xor_b32_e32 v126, 0x80000000, v126
	v_pk_fma_f32 v[144:145], v[124:125], v[196:197], v[144:145] op_sel_hi:[1,0,1] neg_lo:[1,0,0] neg_hi:[1,0,0]
	v_xor_b32_e32 v107, 0x80000000, v107
	v_rsq_f32_e32 v176, v176
	v_xor_b32_e32 v106, 0x80000000, v106
	v_xor_b32_e32 v99, 0x80000000, v99
	v_xor_b32_e32 v98, 0x80000000, v98
	v_pk_fma_f32 v[152:153], v[96:97], v[196:197], v[152:153] op_sel_hi:[1,0,1] neg_lo:[1,0,0] neg_hi:[1,0,0]
	v_pk_fma_f32 v[150:151], v[114:115], v[196:197], v[150:151] op_sel_hi:[1,0,1]
	v_pk_fma_f32 v[148:149], v[112:113], v[196:197], v[148:149] op_sel_hi:[1,0,1] neg_lo:[1,0,0] neg_hi:[1,0,0]
	v_pk_fma_f32 v[146:147], v[126:127], v[196:197], v[146:147] op_sel_hi:[1,0,1]
	v_pk_fma_f32 v[144:145], v[144:145], v[176:177], v[120:121] op_sel_hi:[1,0,1]
	v_pk_fma_f32 v[158:159], v[106:107], v[196:197], v[158:159] op_sel_hi:[1,0,1]
	v_pk_fma_f32 v[156:157], v[104:105], v[196:197], v[156:157] op_sel_hi:[1,0,1] neg_lo:[1,0,0] neg_hi:[1,0,0]
	v_pk_fma_f32 v[154:155], v[98:99], v[196:197], v[154:155] op_sel_hi:[1,0,1]
	v_pk_fma_f32 v[152:153], v[152:153], v[176:177], v[100:101] op_sel_hi:[1,0,1]
	v_pk_fma_f32 v[148:149], v[148:149], v[176:177], v[116:117] op_sel_hi:[1,0,1]
	v_pk_fma_f32 v[150:151], v[150:151], v[176:177], v[118:119] op_sel_hi:[1,0,1]
	v_pk_fma_f32 v[146:147], v[146:147], v[176:177], v[122:123] op_sel_hi:[1,0,1]
	v_pk_mul_f32 v[244:245], v[144:145], v[220:221]
	v_and_b32_e32 v193, 0x1fcf, v194
	v_pk_fma_f32 v[158:159], v[158:159], v[176:177], v[110:111] op_sel_hi:[1,0,1]
	v_pk_fma_f32 v[156:157], v[156:157], v[176:177], v[108:109] op_sel_hi:[1,0,1]
	v_pk_fma_f32 v[154:155], v[154:155], v[176:177], v[102:103] op_sel_hi:[1,0,1]
	v_pk_mul_f32 v[196:197], v[150:151], v[226:227]
	v_pk_mul_f32 v[212:213], v[148:149], v[224:225]
	v_pk_mul_f32 v[242:243], v[146:147], v[222:223]
	v_pk_fma_f32 v[244:245], v[152:153], v[208:209], v[244:245] neg_lo:[0,0,1] neg_hi:[0,0,1]
	v_pk_mul_f32 v[152:153], v[152:153], v[220:221]
	v_lshrrev_b32_e32 v246, s2, v193
	v_pk_fma_f32 v[212:213], v[156:157], v[216:217], v[212:213] neg_lo:[0,0,1] neg_hi:[0,0,1]
	v_pk_fma_f32 v[196:197], v[158:159], v[218:219], v[196:197] neg_lo:[0,0,1] neg_hi:[0,0,1]
	v_pk_fma_f32 v[242:243], v[154:155], v[210:211], v[242:243] neg_lo:[0,0,1] neg_hi:[0,0,1]
	v_pk_mul_f32 v[158:159], v[158:159], v[226:227]
	v_pk_mul_f32 v[156:157], v[156:157], v[224:225]
	v_pk_mul_f32 v[154:155], v[154:155], v[222:223]
	v_pk_fma_f32 v[144:145], v[144:145], v[208:209], v[152:153]
	s_and_b32 s3, s3, 0xffffe000
	v_pk_mul_f32 v[196:197], v[198:199], v[196:197] op_sel_hi:[0,1]
	v_pk_mul_f32 v[212:213], v[198:199], v[212:213] op_sel_hi:[0,1]
	v_pk_mul_f32 v[242:243], v[198:199], v[242:243] op_sel_hi:[0,1]
	v_pk_mul_f32 v[244:245], v[198:199], v[244:245] op_sel_hi:[0,1]
	v_pk_fma_f32 v[148:149], v[148:149], v[216:217], v[156:157]
	v_pk_fma_f32 v[150:151], v[150:151], v[218:219], v[158:159]
	v_pk_fma_f32 v[146:147], v[146:147], v[210:211], v[154:155]
	v_pk_mul_f32 v[154:155], v[198:199], v[144:145] op_sel_hi:[0,1]
	v_or3_b32 v144, v246, v214, s3
	v_pk_mul_f32 v[150:151], v[198:199], v[150:151] op_sel_hi:[0,1]
	v_pk_mul_f32 v[148:149], v[198:199], v[148:149] op_sel_hi:[0,1]
	v_pk_mul_f32 v[152:153], v[198:199], v[146:147] op_sel_hi:[0,1]
	v_mad_i64_i32 v[156:157], s[0:1], v144, s82, v[200:201]
	v_cvt_pk_bf16_f32 v144, v212, v213
	v_cvt_pk_bf16_f32 v145, v196, v197
	v_cvt_pk_bf16_f32 v146, v244, v245
	v_cvt_pk_bf16_f32 v147, v242, v243
	global_store_dwordx4 v[156:157], v[144:147], off
	v_pk_mul_f32 v[208:209], v[240:241], s[40:41] op_sel_hi:[1,0]
	v_or_b32_e32 v195, 16, v193
	v_cvt_pk_bf16_f32 v144, v148, v149
	v_cvt_pk_bf16_f32 v145, v150, v151
	v_cvt_pk_bf16_f32 v146, v154, v155
	v_cvt_pk_bf16_f32 v147, v152, v153
	global_store_dwordx4 v[156:157], v[144:147], off offset:64
	v_fma_f32 v148, -v208, v208, v209
	v_add_f32_e32 v148, 0x3727c5ac, v148
	v_or_b32_e32 v144, 32, v194
	v_ashrrev_i32_e32 v145, 31, v144
	v_lshl_add_u64 v[146:147], v[144:145], 3, s[10:11]
	v_lshlrev_b32_e32 v144, 7, v144
	v_and_b32_e32 v176, 0xff780, v144
	v_lshl_add_u64 v[152:153], v[178:179], 0, v[176:177]
	global_load_dwordx2 v[196:197], v[146:147], off
	s_nop 0
	global_load_dwordx4 v[144:147], v[152:153], off
	v_lshl_add_u64 v[156:157], v[180:181], 0, v[176:177]
	v_rsq_f32_e32 v176, v148
	v_pk_fma_f32 v[134:135], v[114:115], v[208:209], v[134:135] op_sel_hi:[1,0,1]
	global_load_dwordx4 v[148:151], v[156:157], off offset:16
	s_nop 0
	global_load_dwordx4 v[152:155], v[152:153], off offset:16
	s_nop 0
	global_load_dwordx4 v[156:159], v[156:157], off
	v_pk_fma_f32 v[132:133], v[112:113], v[208:209], v[132:133] op_sel_hi:[1,0,1] neg_lo:[1,0,0] neg_hi:[1,0,0]
	v_pk_fma_f32 v[130:131], v[126:127], v[208:209], v[130:131] op_sel_hi:[1,0,1]
	v_pk_fma_f32 v[128:129], v[124:125], v[208:209], v[128:129] op_sel_hi:[1,0,1] neg_lo:[1,0,0] neg_hi:[1,0,0]
	v_pk_fma_f32 v[142:143], v[106:107], v[208:209], v[142:143] op_sel_hi:[1,0,1]
	v_pk_fma_f32 v[140:141], v[104:105], v[208:209], v[140:141] op_sel_hi:[1,0,1] neg_lo:[1,0,0] neg_hi:[1,0,0]
	v_lshlrev_b32_e32 v211, s45, v195
	v_and_b32_e32 v214, 0x1ffe, v211
	v_pk_fma_f32 v[138:139], v[98:99], v[208:209], v[138:139] op_sel_hi:[1,0,1]
	v_pk_fma_f32 v[136:137], v[96:97], v[208:209], v[136:137] op_sel_hi:[1,0,1] neg_lo:[1,0,0] neg_hi:[1,0,0]
	v_lshrrev_b32_e32 v195, s2, v195
	v_pk_fma_f32 v[132:133], v[132:133], v[176:177], v[116:117] op_sel_hi:[1,0,1]
	v_pk_fma_f32 v[134:135], v[134:135], v[176:177], v[118:119] op_sel_hi:[1,0,1]
	v_pk_fma_f32 v[128:129], v[128:129], v[176:177], v[120:121] op_sel_hi:[1,0,1]
	v_pk_fma_f32 v[130:131], v[130:131], v[176:177], v[122:123] op_sel_hi:[1,0,1]
	v_pk_fma_f32 v[142:143], v[142:143], v[176:177], v[110:111] op_sel_hi:[1,0,1]
	v_pk_fma_f32 v[140:141], v[140:141], v[176:177], v[108:109] op_sel_hi:[1,0,1]
	v_pk_fma_f32 v[138:139], v[138:139], v[176:177], v[102:103] op_sel_hi:[1,0,1]
	v_pk_fma_f32 v[136:137], v[136:137], v[176:177], v[100:101] op_sel_hi:[1,0,1]
	s_waitcnt vmcnt(7)
	v_pk_mul_f32 v[208:209], v[238:239], v[134:135]
	v_pk_mul_f32 v[210:211], v[236:237], v[132:133]
	v_pk_mul_f32 v[212:213], v[230:231], v[130:131]
	v_pk_mul_f32 v[216:217], v[228:229], v[128:129]
	v_pk_mul_f32 v[128:129], v[232:233], v[128:129]
	v_pk_fma_f32 v[210:211], v[160:161], v[140:141], v[210:211] neg_lo:[0,0,1] neg_hi:[0,0,1]
	v_pk_fma_f32 v[208:209], v[162:163], v[142:143], v[208:209] neg_lo:[0,0,1] neg_hi:[0,0,1]
	v_pk_fma_f32 v[216:217], v[232:233], v[136:137], v[216:217] neg_lo:[0,0,1] neg_hi:[0,0,1]
	v_pk_fma_f32 v[212:213], v[234:235], v[138:139], v[212:213] neg_lo:[0,0,1] neg_hi:[0,0,1]
	v_pk_mul_f32 v[134:135], v[162:163], v[134:135]
	v_pk_mul_f32 v[132:133], v[160:161], v[132:133]
	v_pk_mul_f32 v[130:131], v[234:235], v[130:131]
	v_pk_fma_f32 v[128:129], v[228:229], v[136:137], v[128:129]
	v_pk_mul_f32 v[208:209], v[198:199], v[208:209] op_sel_hi:[0,1]
	v_pk_mul_f32 v[210:211], v[198:199], v[210:211] op_sel_hi:[0,1]
	v_pk_mul_f32 v[212:213], v[198:199], v[212:213] op_sel_hi:[0,1]
	v_pk_mul_f32 v[216:217], v[198:199], v[216:217] op_sel_hi:[0,1]
	v_pk_fma_f32 v[132:133], v[236:237], v[140:141], v[132:133]
	v_pk_fma_f32 v[134:135], v[238:239], v[142:143], v[134:135]
	v_pk_fma_f32 v[130:131], v[230:231], v[138:139], v[130:131]
	v_pk_mul_f32 v[138:139], v[198:199], v[128:129] op_sel_hi:[0,1]
	v_or3_b32 v128, v195, v214, s3
	v_pk_mul_f32 v[134:135], v[198:199], v[134:135] op_sel_hi:[0,1]
	v_pk_mul_f32 v[132:133], v[198:199], v[132:133] op_sel_hi:[0,1]
	v_pk_mul_f32 v[136:137], v[198:199], v[130:131] op_sel_hi:[0,1]
	v_mad_i64_i32 v[140:141], s[0:1], v128, s82, v[200:201]
	v_cvt_pk_bf16_f32 v128, v210, v211
	v_cvt_pk_bf16_f32 v129, v208, v209
	v_cvt_pk_bf16_f32 v130, v216, v217
	v_cvt_pk_bf16_f32 v131, v212, v213
	global_store_dwordx4 v[140:141], v[128:131], off
	s_waitcnt vmcnt(5)
	v_pk_mul_f32 v[162:163], v[196:197], s[40:41] op_sel_hi:[1,0]
	v_or_b32_e32 v195, 32, v193
	v_cvt_pk_bf16_f32 v128, v132, v133
	v_cvt_pk_bf16_f32 v129, v134, v135
	v_cvt_pk_bf16_f32 v130, v138, v139
	v_cvt_pk_bf16_f32 v131, v136, v137
	global_store_dwordx4 v[140:141], v[128:131], off offset:64
	v_fma_f32 v132, -v162, v162, v163
	v_add_f32_e32 v132, 0x3727c5ac, v132
	v_or_b32_e32 v128, 48, v194
	v_ashrrev_i32_e32 v129, 31, v128
	v_lshl_add_u64 v[130:131], v[128:129], 3, s[10:11]
	v_lshlrev_b32_e32 v128, 7, v128
	v_and_b32_e32 v176, 0xfff80, v128
	v_lshl_add_u64 v[136:137], v[178:179], 0, v[176:177]
	global_load_dwordx2 v[160:161], v[130:131], off
	s_nop 0
	global_load_dwordx4 v[128:131], v[136:137], off
	v_lshl_add_u64 v[140:141], v[180:181], 0, v[176:177]
	v_rsq_f32_e32 v176, v132
	v_pk_fma_f32 v[86:87], v[114:115], v[162:163], v[86:87] op_sel_hi:[1,0,1]
	v_pk_fma_f32 v[84:85], v[112:113], v[162:163], v[84:85] op_sel_hi:[1,0,1] neg_lo:[1,0,0] neg_hi:[1,0,0]
	global_load_dwordx4 v[132:135], v[140:141], off offset:16
	s_nop 0
	global_load_dwordx4 v[136:139], v[136:137], off offset:16
	s_nop 0
	global_load_dwordx4 v[140:143], v[140:141], off
	v_pk_fma_f32 v[82:83], v[126:127], v[162:163], v[82:83] op_sel_hi:[1,0,1]
	v_pk_fma_f32 v[80:81], v[124:125], v[162:163], v[80:81] op_sel_hi:[1,0,1] neg_lo:[1,0,0] neg_hi:[1,0,0]
	v_pk_fma_f32 v[94:95], v[106:107], v[162:163], v[94:95] op_sel_hi:[1,0,1]
	v_pk_fma_f32 v[92:93], v[104:105], v[162:163], v[92:93] op_sel_hi:[1,0,1] neg_lo:[1,0,0] neg_hi:[1,0,0]
	v_pk_fma_f32 v[90:91], v[98:99], v[162:163], v[90:91] op_sel_hi:[1,0,1]
	v_pk_fma_f32 v[88:89], v[96:97], v[162:163], v[88:89] op_sel_hi:[1,0,1] neg_lo:[1,0,0] neg_hi:[1,0,0]
	v_lshlrev_b32_e32 v207, s45, v195
	v_and_b32_e32 v207, 0x1ffe, v207
	v_lshrrev_b32_e32 v195, s2, v195
	v_pk_fma_f32 v[84:85], v[84:85], v[176:177], v[116:117] op_sel_hi:[1,0,1]
	v_pk_fma_f32 v[86:87], v[86:87], v[176:177], v[118:119] op_sel_hi:[1,0,1]
	v_pk_fma_f32 v[80:81], v[80:81], v[176:177], v[120:121] op_sel_hi:[1,0,1]
	v_pk_fma_f32 v[82:83], v[82:83], v[176:177], v[122:123] op_sel_hi:[1,0,1]
	v_pk_fma_f32 v[94:95], v[94:95], v[176:177], v[110:111] op_sel_hi:[1,0,1]
	v_pk_fma_f32 v[92:93], v[92:93], v[176:177], v[108:109] op_sel_hi:[1,0,1]
	v_pk_fma_f32 v[90:91], v[90:91], v[176:177], v[102:103] op_sel_hi:[1,0,1]
	v_pk_fma_f32 v[88:89], v[88:89], v[176:177], v[100:101] op_sel_hi:[1,0,1]
	s_waitcnt vmcnt(7)
	v_pk_mul_f32 v[162:163], v[158:159], v[86:87]
	v_pk_mul_f32 v[196:197], v[156:157], v[84:85]
	v_pk_mul_f32 v[208:209], v[150:151], v[82:83]
	v_pk_mul_f32 v[210:211], v[148:149], v[80:81]
	v_pk_mul_f32 v[80:81], v[152:153], v[80:81]
	v_pk_fma_f32 v[196:197], v[144:145], v[92:93], v[196:197] neg_lo:[0,0,1] neg_hi:[0,0,1]
	v_pk_fma_f32 v[162:163], v[146:147], v[94:95], v[162:163] neg_lo:[0,0,1] neg_hi:[0,0,1]
	v_pk_fma_f32 v[210:211], v[152:153], v[88:89], v[210:211] neg_lo:[0,0,1] neg_hi:[0,0,1]
	v_pk_fma_f32 v[208:209], v[154:155], v[90:91], v[208:209] neg_lo:[0,0,1] neg_hi:[0,0,1]
	v_pk_mul_f32 v[86:87], v[146:147], v[86:87]
	v_pk_mul_f32 v[84:85], v[144:145], v[84:85]
	v_pk_mul_f32 v[82:83], v[154:155], v[82:83]
	v_pk_fma_f32 v[80:81], v[148:149], v[88:89], v[80:81]
	v_pk_mul_f32 v[162:163], v[198:199], v[162:163] op_sel_hi:[0,1]
	v_pk_mul_f32 v[196:197], v[198:199], v[196:197] op_sel_hi:[0,1]
	v_pk_mul_f32 v[208:209], v[198:199], v[208:209] op_sel_hi:[0,1]
	v_pk_mul_f32 v[210:211], v[198:199], v[210:211] op_sel_hi:[0,1]
	v_pk_fma_f32 v[84:85], v[156:157], v[92:93], v[84:85]
	v_pk_fma_f32 v[86:87], v[158:159], v[94:95], v[86:87]
	v_pk_fma_f32 v[82:83], v[150:151], v[90:91], v[82:83]
	v_pk_mul_f32 v[90:91], v[198:199], v[80:81] op_sel_hi:[0,1]
	v_or3_b32 v80, v195, v207, s3
	v_pk_mul_f32 v[86:87], v[198:199], v[86:87] op_sel_hi:[0,1]
	v_pk_mul_f32 v[84:85], v[198:199], v[84:85] op_sel_hi:[0,1]
	v_pk_mul_f32 v[88:89], v[198:199], v[82:83] op_sel_hi:[0,1]
	v_mad_i64_i32 v[92:93], s[0:1], v80, s82, v[200:201]
	v_cvt_pk_bf16_f32 v80, v196, v197
	v_cvt_pk_bf16_f32 v81, v162, v163
	v_cvt_pk_bf16_f32 v82, v210, v211
	v_cvt_pk_bf16_f32 v83, v208, v209
	global_store_dwordx4 v[92:93], v[80:83], off
	s_waitcnt vmcnt(5)
	v_pk_mul_f32 v[148:149], v[160:161], s[40:41] op_sel_hi:[1,0]
	v_or_b32_e32 v150, 48, v193
	v_cvt_pk_bf16_f32 v80, v84, v85
	v_cvt_pk_bf16_f32 v81, v86, v87
	v_cvt_pk_bf16_f32 v82, v90, v91
	v_cvt_pk_bf16_f32 v83, v88, v89
	global_store_dwordx4 v[92:93], v[80:83], off offset:64
	v_lshrrev_b32_e32 v157, s2, v150
	v_pk_fma_f32 v[70:71], v[114:115], v[148:149], v[70:71] op_sel_hi:[1,0,1]
	v_add_u32_e32 v80, 0x80, v194
	v_ashrrev_i32_e32 v81, 31, v80
	v_lshl_add_u64 v[82:83], v[80:81], 3, s[10:11]
	v_lshlrev_b32_e32 v81, 7, v80
	v_and_b32_e32 v176, 0xfe780, v81
	v_lshl_add_u64 v[90:91], v[178:179], 0, v[176:177]
	global_load_dwordx2 v[94:95], v[82:83], off
	s_nop 0
	global_load_dwordx4 v[82:85], v[90:91], off
	v_fma_f32 v81, -v148, v148, v149
	v_add_f32_e32 v81, 0x3727c5ac, v81
	v_lshl_add_u64 v[144:145], v[180:181], 0, v[176:177]
	v_pk_fma_f32 v[68:69], v[112:113], v[148:149], v[68:69] op_sel_hi:[1,0,1] neg_lo:[1,0,0] neg_hi:[1,0,0]
	global_load_dwordx4 v[86:89], v[144:145], off offset:16
	s_nop 0
	global_load_dwordx4 v[90:93], v[90:91], off offset:16
	s_nop 0
	global_load_dwordx4 v[144:147], v[144:145], off
	v_pk_fma_f32 v[66:67], v[126:127], v[148:149], v[66:67] op_sel_hi:[1,0,1]
	v_pk_fma_f32 v[64:65], v[124:125], v[148:149], v[64:65] op_sel_hi:[1,0,1] neg_lo:[1,0,0] neg_hi:[1,0,0]
	v_pk_fma_f32 v[78:79], v[106:107], v[148:149], v[78:79] op_sel_hi:[1,0,1]
	v_pk_fma_f32 v[76:77], v[104:105], v[148:149], v[76:77] op_sel_hi:[1,0,1] neg_lo:[1,0,0] neg_hi:[1,0,0]
	v_pk_fma_f32 v[74:75], v[98:99], v[148:149], v[74:75] op_sel_hi:[1,0,1]
	v_lshlrev_b32_e32 v153, s45, v150
	v_and_b32_e32 v156, 0x1ffe, v153
	v_pk_fma_f32 v[72:73], v[96:97], v[148:149], v[72:73] op_sel_hi:[1,0,1] neg_lo:[1,0,0] neg_hi:[1,0,0]
	v_rsq_f32_e32 v150, v81
	s_nop 0
	v_pk_fma_f32 v[68:69], v[68:69], v[150:151], v[116:117] op_sel_hi:[1,0,1]
	v_pk_fma_f32 v[70:71], v[70:71], v[150:151], v[118:119] op_sel_hi:[1,0,1]
	v_pk_fma_f32 v[64:65], v[64:65], v[150:151], v[120:121] op_sel_hi:[1,0,1]
	v_pk_fma_f32 v[66:67], v[66:67], v[150:151], v[122:123] op_sel_hi:[1,0,1]
	v_pk_fma_f32 v[78:79], v[78:79], v[150:151], v[110:111] op_sel_hi:[1,0,1]
	v_pk_fma_f32 v[76:77], v[76:77], v[150:151], v[108:109] op_sel_hi:[1,0,1]
	v_pk_fma_f32 v[74:75], v[74:75], v[150:151], v[102:103] op_sel_hi:[1,0,1]
	v_pk_fma_f32 v[72:73], v[72:73], v[150:151], v[100:101] op_sel_hi:[1,0,1]
	s_waitcnt vmcnt(7)
	v_pk_mul_f32 v[148:149], v[142:143], v[70:71]
	v_pk_mul_f32 v[150:151], v[140:141], v[68:69]
	v_pk_mul_f32 v[152:153], v[134:135], v[66:67]
	v_pk_mul_f32 v[154:155], v[132:133], v[64:65]
	v_pk_mul_f32 v[64:65], v[136:137], v[64:65]
	v_pk_fma_f32 v[150:151], v[128:129], v[76:77], v[150:151] neg_lo:[0,0,1] neg_hi:[0,0,1]
	v_pk_fma_f32 v[148:149], v[130:131], v[78:79], v[148:149] neg_lo:[0,0,1] neg_hi:[0,0,1]
	v_pk_fma_f32 v[154:155], v[136:137], v[72:73], v[154:155] neg_lo:[0,0,1] neg_hi:[0,0,1]
	v_pk_fma_f32 v[152:153], v[138:139], v[74:75], v[152:153] neg_lo:[0,0,1] neg_hi:[0,0,1]
	v_pk_mul_f32 v[70:71], v[130:131], v[70:71]
	v_pk_mul_f32 v[68:69], v[128:129], v[68:69]
	v_pk_mul_f32 v[66:67], v[138:139], v[66:67]
	v_pk_fma_f32 v[64:65], v[132:133], v[72:73], v[64:65]
	v_pk_mul_f32 v[148:149], v[198:199], v[148:149] op_sel_hi:[0,1]
	v_pk_mul_f32 v[150:151], v[198:199], v[150:151] op_sel_hi:[0,1]
	v_pk_mul_f32 v[152:153], v[198:199], v[152:153] op_sel_hi:[0,1]
	v_pk_mul_f32 v[154:155], v[198:199], v[154:155] op_sel_hi:[0,1]
	v_pk_fma_f32 v[68:69], v[140:141], v[76:77], v[68:69]
	v_pk_fma_f32 v[70:71], v[142:143], v[78:79], v[70:71]
	v_pk_fma_f32 v[66:67], v[134:135], v[74:75], v[66:67]
	v_pk_mul_f32 v[74:75], v[198:199], v[64:65] op_sel_hi:[0,1]
	v_or3_b32 v64, v157, v156, s3
	v_pk_mul_f32 v[70:71], v[198:199], v[70:71] op_sel_hi:[0,1]
	v_pk_mul_f32 v[68:69], v[198:199], v[68:69] op_sel_hi:[0,1]
	v_pk_mul_f32 v[72:73], v[198:199], v[66:67] op_sel_hi:[0,1]
	v_mad_i64_i32 v[76:77], s[0:1], v64, s82, v[200:201]
	v_cvt_pk_bf16_f32 v64, v150, v151
	v_cvt_pk_bf16_f32 v65, v148, v149
	v_cvt_pk_bf16_f32 v66, v154, v155
	v_cvt_pk_bf16_f32 v67, v152, v153
	global_store_dwordx4 v[76:77], v[64:67], off
	s_waitcnt vmcnt(5)
	v_pk_mul_f32 v[94:95], v[94:95], s[40:41] op_sel_hi:[1,0]
	v_and_b32_e32 v136, 0x1fcf, v80
	v_cvt_pk_bf16_f32 v64, v68, v69
	v_cvt_pk_bf16_f32 v65, v70, v71
	v_cvt_pk_bf16_f32 v66, v74, v75
	v_cvt_pk_bf16_f32 v67, v72, v73
	global_store_dwordx4 v[76:77], v[64:67], off offset:64
	v_fma_f32 v68, -v94, v94, v95
	v_add_f32_e32 v68, 0x3727c5ac, v68
	v_rsq_f32_e32 v130, v68
	v_add_u32_e32 v64, 0x90, v194
	v_ashrrev_i32_e32 v65, 31, v64
	v_lshl_add_u64 v[66:67], v[64:65], 3, s[10:11]
	v_lshlrev_b32_e32 v64, 7, v64
	v_and_b32_e32 v176, 0xfff80, v64
	v_lshl_add_u64 v[72:73], v[178:179], 0, v[176:177]
	global_load_dwordx2 v[128:129], v[66:67], off
	s_nop 0
	global_load_dwordx4 v[64:67], v[72:73], off
	v_lshl_add_u64 v[76:77], v[180:181], 0, v[176:177]
	v_pk_fma_f32 v[54:55], v[114:115], v[94:95], v[54:55] op_sel_hi:[1,0,1]
	v_pk_fma_f32 v[52:53], v[112:113], v[94:95], v[52:53] op_sel_hi:[1,0,1] neg_lo:[1,0,0] neg_hi:[1,0,0]
	global_load_dwordx4 v[68:71], v[76:77], off offset:16
	s_nop 0
	global_load_dwordx4 v[72:75], v[72:73], off offset:16
	s_nop 0
	global_load_dwordx4 v[76:79], v[76:77], off
	v_pk_fma_f32 v[50:51], v[126:127], v[94:95], v[50:51] op_sel_hi:[1,0,1]
	v_pk_fma_f32 v[48:49], v[124:125], v[94:95], v[48:49] op_sel_hi:[1,0,1] neg_lo:[1,0,0] neg_hi:[1,0,0]
	v_pk_fma_f32 v[62:63], v[106:107], v[94:95], v[62:63] op_sel_hi:[1,0,1]
	v_pk_fma_f32 v[60:61], v[104:105], v[94:95], v[60:61] op_sel_hi:[1,0,1] neg_lo:[1,0,0] neg_hi:[1,0,0]
	v_pk_fma_f32 v[58:59], v[98:99], v[94:95], v[58:59] op_sel_hi:[1,0,1]
	v_pk_fma_f32 v[56:57], v[96:97], v[94:95], v[56:57] op_sel_hi:[1,0,1] neg_lo:[1,0,0] neg_hi:[1,0,0]
	v_lshlrev_b32_e32 v132, s45, v136
	v_and_b32_e32 v137, 0x1ffe, v132
	v_lshrrev_b32_e32 v138, s2, v136
	v_pk_fma_f32 v[52:53], v[52:53], v[130:131], v[116:117] op_sel_hi:[1,0,1]
	v_pk_fma_f32 v[54:55], v[54:55], v[130:131], v[118:119] op_sel_hi:[1,0,1]
	v_pk_fma_f32 v[48:49], v[48:49], v[130:131], v[120:121] op_sel_hi:[1,0,1]
	v_pk_fma_f32 v[50:51], v[50:51], v[130:131], v[122:123] op_sel_hi:[1,0,1]
	v_pk_fma_f32 v[62:63], v[62:63], v[130:131], v[110:111] op_sel_hi:[1,0,1]
	v_pk_fma_f32 v[60:61], v[60:61], v[130:131], v[108:109] op_sel_hi:[1,0,1]
	v_pk_fma_f32 v[58:59], v[58:59], v[130:131], v[102:103] op_sel_hi:[1,0,1]
	v_pk_fma_f32 v[56:57], v[56:57], v[130:131], v[100:101] op_sel_hi:[1,0,1]
	s_waitcnt vmcnt(7)
	v_pk_mul_f32 v[94:95], v[146:147], v[54:55]
	v_pk_mul_f32 v[130:131], v[144:145], v[52:53]
	v_pk_mul_f32 v[132:133], v[88:89], v[50:51]
	v_pk_mul_f32 v[134:135], v[86:87], v[48:49]
	v_pk_mul_f32 v[48:49], v[90:91], v[48:49]
	v_pk_fma_f32 v[130:131], v[82:83], v[60:61], v[130:131] neg_lo:[0,0,1] neg_hi:[0,0,1]
	v_pk_fma_f32 v[94:95], v[84:85], v[62:63], v[94:95] neg_lo:[0,0,1] neg_hi:[0,0,1]
	v_pk_fma_f32 v[134:135], v[90:91], v[56:57], v[134:135] neg_lo:[0,0,1] neg_hi:[0,0,1]
	v_pk_fma_f32 v[132:133], v[92:93], v[58:59], v[132:133] neg_lo:[0,0,1] neg_hi:[0,0,1]
	v_pk_mul_f32 v[54:55], v[84:85], v[54:55]
	v_pk_mul_f32 v[52:53], v[82:83], v[52:53]
	v_pk_mul_f32 v[50:51], v[92:93], v[50:51]
	v_pk_fma_f32 v[48:49], v[86:87], v[56:57], v[48:49]
	v_and_b32_e32 v90, 0xffffe000, v80
	v_pk_mul_f32 v[94:95], v[198:199], v[94:95] op_sel_hi:[0,1]
	v_pk_mul_f32 v[130:131], v[198:199], v[130:131] op_sel_hi:[0,1]
	v_pk_mul_f32 v[132:133], v[198:199], v[132:133] op_sel_hi:[0,1]
	v_pk_mul_f32 v[134:135], v[198:199], v[134:135] op_sel_hi:[0,1]
	v_pk_fma_f32 v[52:53], v[144:145], v[60:61], v[52:53]
	v_pk_fma_f32 v[54:55], v[146:147], v[62:63], v[54:55]
	v_pk_fma_f32 v[50:51], v[88:89], v[58:59], v[50:51]
	v_pk_mul_f32 v[58:59], v[198:199], v[48:49] op_sel_hi:[0,1]
	v_or3_b32 v48, v138, v137, v90
	v_pk_mul_f32 v[54:55], v[198:199], v[54:55] op_sel_hi:[0,1]
	v_pk_mul_f32 v[52:53], v[198:199], v[52:53] op_sel_hi:[0,1]
	v_pk_mul_f32 v[56:57], v[198:199], v[50:51] op_sel_hi:[0,1]
	v_mad_i64_i32 v[60:61], s[0:1], v48, s82, v[200:201]
	v_cvt_pk_bf16_f32 v48, v130, v131
	v_cvt_pk_bf16_f32 v49, v94, v95
	v_cvt_pk_bf16_f32 v50, v134, v135
	v_cvt_pk_bf16_f32 v51, v132, v133
	global_store_dwordx4 v[60:61], v[48:51], off
	s_waitcnt vmcnt(5)
	v_pk_mul_f32 v[82:83], v[128:129], s[40:41] op_sel_hi:[1,0]
	v_or_b32_e32 v84, 16, v136
	v_cvt_pk_bf16_f32 v48, v52, v53
	v_cvt_pk_bf16_f32 v49, v54, v55
	v_cvt_pk_bf16_f32 v50, v58, v59
	v_cvt_pk_bf16_f32 v51, v56, v57
	global_store_dwordx4 v[60:61], v[48:51], off offset:64
	v_fma_f32 v52, -v82, v82, v83
	v_add_f32_e32 v52, 0x3727c5ac, v52
	v_add_u32_e32 v48, 0xa0, v194
	v_ashrrev_i32_e32 v49, 31, v48
	v_lshl_add_u64 v[50:51], v[48:49], 3, s[10:11]
	v_lshlrev_b32_e32 v48, 7, v48
	v_and_b32_e32 v176, 0xfff80, v48
	v_lshl_add_u64 v[56:57], v[178:179], 0, v[176:177]
	global_load_dwordx2 v[80:81], v[50:51], off
	s_nop 0
	global_load_dwordx4 v[48:51], v[56:57], off
	v_lshrrev_b32_e32 v92, s2, v84
	v_pk_fma_f32 v[38:39], v[114:115], v[82:83], v[38:39] op_sel_hi:[1,0,1]
	v_pk_fma_f32 v[36:37], v[112:113], v[82:83], v[36:37] op_sel_hi:[1,0,1] neg_lo:[1,0,0] neg_hi:[1,0,0]
	v_pk_fma_f32 v[34:35], v[126:127], v[82:83], v[34:35] op_sel_hi:[1,0,1]
	v_pk_fma_f32 v[32:33], v[124:125], v[82:83], v[32:33] op_sel_hi:[1,0,1] neg_lo:[1,0,0] neg_hi:[1,0,0]
	v_pk_fma_f32 v[46:47], v[106:107], v[82:83], v[46:47] op_sel_hi:[1,0,1]
	v_pk_fma_f32 v[44:45], v[104:105], v[82:83], v[44:45] op_sel_hi:[1,0,1] neg_lo:[1,0,0] neg_hi:[1,0,0]
	v_pk_fma_f32 v[42:43], v[98:99], v[82:83], v[42:43] op_sel_hi:[1,0,1]
	v_lshlrev_b32_e32 v88, s45, v84
	v_rsq_f32_e32 v84, v52
	v_and_b32_e32 v91, 0x1ffe, v88
	v_pk_fma_f32 v[40:41], v[96:97], v[82:83], v[40:41] op_sel_hi:[1,0,1] neg_lo:[1,0,0] neg_hi:[1,0,0]
	v_lshl_add_u64 v[60:61], v[180:181], 0, v[176:177]
	global_load_dwordx4 v[52:55], v[60:61], off offset:16
	s_nop 0
	global_load_dwordx4 v[56:59], v[56:57], off offset:16
	s_nop 0
	global_load_dwordx4 v[60:63], v[60:61], off
	v_pk_fma_f32 v[36:37], v[36:37], v[84:85], v[116:117] op_sel_hi:[1,0,1]
	v_pk_fma_f32 v[38:39], v[38:39], v[84:85], v[118:119] op_sel_hi:[1,0,1]
	v_pk_fma_f32 v[32:33], v[32:33], v[84:85], v[120:121] op_sel_hi:[1,0,1]
	v_pk_fma_f32 v[34:35], v[34:35], v[84:85], v[122:123] op_sel_hi:[1,0,1]
	v_pk_fma_f32 v[46:47], v[46:47], v[84:85], v[110:111] op_sel_hi:[1,0,1]
	v_pk_fma_f32 v[44:45], v[44:45], v[84:85], v[108:109] op_sel_hi:[1,0,1]
	v_pk_fma_f32 v[42:43], v[42:43], v[84:85], v[102:103] op_sel_hi:[1,0,1]
	v_pk_fma_f32 v[40:41], v[40:41], v[84:85], v[100:101] op_sel_hi:[1,0,1]
	s_waitcnt vmcnt(7)
	v_pk_mul_f32 v[82:83], v[78:79], v[38:39]
	v_pk_mul_f32 v[84:85], v[76:77], v[36:37]
	v_pk_mul_f32 v[86:87], v[70:71], v[34:35]
	v_pk_mul_f32 v[88:89], v[68:69], v[32:33]
	v_pk_mul_f32 v[32:33], v[72:73], v[32:33]
	v_pk_fma_f32 v[84:85], v[64:65], v[44:45], v[84:85] neg_lo:[0,0,1] neg_hi:[0,0,1]
	v_pk_fma_f32 v[82:83], v[66:67], v[46:47], v[82:83] neg_lo:[0,0,1] neg_hi:[0,0,1]
	v_pk_fma_f32 v[88:89], v[72:73], v[40:41], v[88:89] neg_lo:[0,0,1] neg_hi:[0,0,1]
	v_pk_fma_f32 v[86:87], v[74:75], v[42:43], v[86:87] neg_lo:[0,0,1] neg_hi:[0,0,1]
	v_pk_mul_f32 v[38:39], v[66:67], v[38:39]
	v_pk_mul_f32 v[36:37], v[64:65], v[36:37]
	v_pk_mul_f32 v[34:35], v[74:75], v[34:35]
	v_pk_fma_f32 v[32:33], v[68:69], v[40:41], v[32:33]
	v_pk_mul_f32 v[82:83], v[198:199], v[82:83] op_sel_hi:[0,1]
	v_pk_mul_f32 v[84:85], v[198:199], v[84:85] op_sel_hi:[0,1]
	v_pk_mul_f32 v[86:87], v[198:199], v[86:87] op_sel_hi:[0,1]
	v_pk_mul_f32 v[88:89], v[198:199], v[88:89] op_sel_hi:[0,1]
	v_pk_fma_f32 v[36:37], v[76:77], v[44:45], v[36:37]
	v_pk_fma_f32 v[38:39], v[78:79], v[46:47], v[38:39]
	v_pk_fma_f32 v[34:35], v[70:71], v[42:43], v[34:35]
	v_pk_mul_f32 v[42:43], v[198:199], v[32:33] op_sel_hi:[0,1]
	v_or3_b32 v32, v92, v91, v90
	v_pk_mul_f32 v[38:39], v[198:199], v[38:39] op_sel_hi:[0,1]
	v_pk_mul_f32 v[36:37], v[198:199], v[36:37] op_sel_hi:[0,1]
	v_pk_mul_f32 v[40:41], v[198:199], v[34:35] op_sel_hi:[0,1]
	v_mad_i64_i32 v[44:45], s[0:1], v32, s82, v[200:201]
	v_cvt_pk_bf16_f32 v32, v84, v85
	v_cvt_pk_bf16_f32 v33, v82, v83
	v_cvt_pk_bf16_f32 v34, v88, v89
	v_cvt_pk_bf16_f32 v35, v86, v87
	global_store_dwordx4 v[44:45], v[32:35], off
	s_waitcnt vmcnt(5)
	v_pk_mul_f32 v[66:67], v[80:81], s[40:41] op_sel_hi:[1,0]
	v_or_b32_e32 v68, 32, v136
	v_cvt_pk_bf16_f32 v32, v36, v37
	v_cvt_pk_bf16_f32 v33, v38, v39
	v_cvt_pk_bf16_f32 v34, v42, v43
	v_cvt_pk_bf16_f32 v35, v40, v41
	global_store_dwordx4 v[44:45], v[32:35], off offset:64
	v_fma_f32 v36, -v66, v66, v67
	v_add_f32_e32 v36, 0x3727c5ac, v36
	v_rsq_f32_e32 v252, v36
	v_add_u32_e32 v32, 0xb0, v194
	v_ashrrev_i32_e32 v33, 31, v32
	v_lshl_add_u64 v[34:35], v[32:33], 3, s[10:11]
	v_lshlrev_b32_e32 v32, 7, v32
	v_and_b32_e32 v176, 0xfff80, v32
	v_lshl_add_u64 v[40:41], v[178:179], 0, v[176:177]
	global_load_dwordx2 v[64:65], v[34:35], off
	s_nop 0
	global_load_dwordx4 v[32:35], v[40:41], off
	v_lshl_add_u64 v[44:45], v[180:181], 0, v[176:177]
	v_lshrrev_b32_e32 v75, s2, v68
	v_pk_fma_f32 v[22:23], v[114:115], v[66:67], v[22:23] op_sel_hi:[1,0,1]
	global_load_dwordx4 v[36:39], v[44:45], off offset:16
	s_nop 0
	global_load_dwordx4 v[40:43], v[40:41], off offset:16
	s_nop 0
	global_load_dwordx4 v[44:47], v[44:45], off
	v_pk_fma_f32 v[20:21], v[112:113], v[66:67], v[20:21] op_sel_hi:[1,0,1] neg_lo:[1,0,0] neg_hi:[1,0,0]
	v_pk_fma_f32 v[18:19], v[126:127], v[66:67], v[18:19] op_sel_hi:[1,0,1]
	v_pk_fma_f32 v[16:17], v[124:125], v[66:67], v[16:17] op_sel_hi:[1,0,1] neg_lo:[1,0,0] neg_hi:[1,0,0]
	v_pk_fma_f32 v[30:31], v[106:107], v[66:67], v[30:31] op_sel_hi:[1,0,1]
	v_pk_fma_f32 v[28:29], v[104:105], v[66:67], v[28:29] op_sel_hi:[1,0,1] neg_lo:[1,0,0] neg_hi:[1,0,0]
	v_pk_fma_f32 v[26:27], v[98:99], v[66:67], v[26:27] op_sel_hi:[1,0,1]
	v_lshlrev_b32_e32 v72, s45, v68
	v_and_b32_e32 v74, 0x1ffe, v72
	v_pk_fma_f32 v[24:25], v[96:97], v[66:67], v[24:25] op_sel_hi:[1,0,1] neg_lo:[1,0,0] neg_hi:[1,0,0]
	v_mov_b32_e32 v68, v252
	v_pk_fma_f32 v[20:21], v[20:21], v[68:69], v[116:117] op_sel_hi:[1,0,1]
	v_pk_fma_f32 v[22:23], v[22:23], v[68:69], v[118:119] op_sel_hi:[1,0,1]
	v_pk_fma_f32 v[16:17], v[16:17], v[68:69], v[120:121] op_sel_hi:[1,0,1]
	v_pk_fma_f32 v[18:19], v[18:19], v[68:69], v[122:123] op_sel_hi:[1,0,1]
	v_pk_fma_f32 v[30:31], v[30:31], v[68:69], v[110:111] op_sel_hi:[1,0,1]
	v_pk_fma_f32 v[28:29], v[28:29], v[68:69], v[108:109] op_sel_hi:[1,0,1]
	v_pk_fma_f32 v[26:27], v[26:27], v[68:69], v[102:103] op_sel_hi:[1,0,1]
	v_pk_fma_f32 v[24:25], v[24:25], v[68:69], v[100:101] op_sel_hi:[1,0,1]
	s_waitcnt vmcnt(7)
	v_pk_mul_f32 v[66:67], v[62:63], v[22:23]
	v_pk_mul_f32 v[68:69], v[60:61], v[20:21]
	v_pk_mul_f32 v[70:71], v[54:55], v[18:19]
	v_pk_mul_f32 v[72:73], v[52:53], v[16:17]
	v_pk_mul_f32 v[16:17], v[56:57], v[16:17]
	v_pk_fma_f32 v[68:69], v[48:49], v[28:29], v[68:69] neg_lo:[0,0,1] neg_hi:[0,0,1]
	v_pk_fma_f32 v[66:67], v[50:51], v[30:31], v[66:67] neg_lo:[0,0,1] neg_hi:[0,0,1]
	v_pk_fma_f32 v[72:73], v[56:57], v[24:25], v[72:73] neg_lo:[0,0,1] neg_hi:[0,0,1]
	v_pk_fma_f32 v[70:71], v[58:59], v[26:27], v[70:71] neg_lo:[0,0,1] neg_hi:[0,0,1]
	v_pk_mul_f32 v[20:21], v[48:49], v[20:21]
	v_pk_mul_f32 v[18:19], v[58:59], v[18:19]
	v_pk_fma_f32 v[16:17], v[52:53], v[24:25], v[16:17]
	v_pk_mul_f32 v[66:67], v[198:199], v[66:67] op_sel_hi:[0,1]
	v_pk_mul_f32 v[68:69], v[198:199], v[68:69] op_sel_hi:[0,1]
	v_pk_mul_f32 v[70:71], v[198:199], v[70:71] op_sel_hi:[0,1]
	v_pk_mul_f32 v[72:73], v[198:199], v[72:73] op_sel_hi:[0,1]
	v_pk_mul_f32 v[22:23], v[50:51], v[22:23]
	v_pk_fma_f32 v[20:21], v[60:61], v[28:29], v[20:21]
	v_pk_fma_f32 v[18:19], v[54:55], v[26:27], v[18:19]
	v_pk_mul_f32 v[26:27], v[198:199], v[16:17] op_sel_hi:[0,1]
	v_or3_b32 v16, v75, v74, v90
	v_pk_fma_f32 v[22:23], v[62:63], v[30:31], v[22:23]
	v_pk_mul_f32 v[20:21], v[198:199], v[20:21] op_sel_hi:[0,1]
	v_pk_mul_f32 v[24:25], v[198:199], v[18:19] op_sel_hi:[0,1]
	v_mad_i64_i32 v[28:29], s[0:1], v16, s82, v[200:201]
	v_cvt_pk_bf16_f32 v16, v68, v69
	v_cvt_pk_bf16_f32 v17, v66, v67
	v_cvt_pk_bf16_f32 v18, v72, v73
	v_cvt_pk_bf16_f32 v19, v70, v71
	v_pk_mul_f32 v[22:23], v[198:199], v[22:23] op_sel_hi:[0,1]
	global_store_dwordx4 v[28:29], v[16:19], off
	s_nop 1
	v_cvt_pk_bf16_f32 v16, v20, v21
	s_waitcnt vmcnt(5)
	v_pk_mul_f32 v[20:21], v[64:65], s[40:41] op_sel_hi:[1,0]
	v_cvt_pk_bf16_f32 v17, v22, v23
	v_fma_f32 v22, -v20, v20, v21
	v_add_f32_e32 v22, 0x3727c5ac, v22
	v_rsq_f32_e32 v253, v22
	v_cvt_pk_bf16_f32 v18, v26, v27
	v_cvt_pk_bf16_f32 v19, v24, v25
	global_store_dwordx4 v[28:29], v[16:19], off offset:64
	v_pk_fma_f32 v[6:7], v[114:115], v[20:21], v[6:7] op_sel_hi:[1,0,1]
	v_pk_fma_f32 v[4:5], v[112:113], v[20:21], v[4:5] op_sel_hi:[1,0,1] neg_lo:[1,0,0] neg_hi:[1,0,0]
	v_or_b32_e32 v16, 48, v136
	v_lshrrev_b32_e32 v25, s2, v16
	v_pk_fma_f32 v[2:3], v[126:127], v[20:21], v[2:3] op_sel_hi:[1,0,1]
	v_pk_fma_f32 v[0:1], v[124:125], v[20:21], v[0:1] op_sel_hi:[1,0,1] neg_lo:[1,0,0] neg_hi:[1,0,0]
	v_lshlrev_b32_e32 v22, s45, v16
	v_and_b32_e32 v24, 0x1ffe, v22
	v_pk_fma_f32 v[14:15], v[106:107], v[20:21], v[14:15] op_sel_hi:[1,0,1]
	v_mov_b32_e32 v16, v253
	v_pk_fma_f32 v[12:13], v[104:105], v[20:21], v[12:13] op_sel_hi:[1,0,1] neg_lo:[1,0,0] neg_hi:[1,0,0]
	v_pk_fma_f32 v[10:11], v[98:99], v[20:21], v[10:11] op_sel_hi:[1,0,1]
	v_pk_fma_f32 v[8:9], v[96:97], v[20:21], v[8:9] op_sel_hi:[1,0,1] neg_lo:[1,0,0] neg_hi:[1,0,0]
	v_pk_fma_f32 v[4:5], v[4:5], v[16:17], v[116:117] op_sel_hi:[1,0,1]
	v_pk_fma_f32 v[6:7], v[6:7], v[16:17], v[118:119] op_sel_hi:[1,0,1]
	v_pk_fma_f32 v[0:1], v[0:1], v[16:17], v[120:121] op_sel_hi:[1,0,1]
	v_pk_fma_f32 v[2:3], v[2:3], v[16:17], v[122:123] op_sel_hi:[1,0,1]
	v_pk_fma_f32 v[14:15], v[14:15], v[16:17], v[110:111] op_sel_hi:[1,0,1]
	v_pk_fma_f32 v[12:13], v[12:13], v[16:17], v[108:109] op_sel_hi:[1,0,1]
	v_pk_fma_f32 v[10:11], v[10:11], v[16:17], v[102:103] op_sel_hi:[1,0,1]
	v_pk_fma_f32 v[8:9], v[8:9], v[16:17], v[100:101] op_sel_hi:[1,0,1]
	s_waitcnt vmcnt(2)
	v_pk_mul_f32 v[16:17], v[46:47], v[6:7]
	v_pk_mul_f32 v[18:19], v[44:45], v[4:5]
	v_pk_mul_f32 v[20:21], v[38:39], v[2:3]
	v_pk_mul_f32 v[22:23], v[36:37], v[0:1]
	v_pk_mul_f32 v[0:1], v[40:41], v[0:1]
	v_pk_fma_f32 v[18:19], v[32:33], v[12:13], v[18:19] neg_lo:[0,0,1] neg_hi:[0,0,1]
	v_pk_fma_f32 v[16:17], v[34:35], v[14:15], v[16:17] neg_lo:[0,0,1] neg_hi:[0,0,1]
	v_pk_fma_f32 v[22:23], v[40:41], v[8:9], v[22:23] neg_lo:[0,0,1] neg_hi:[0,0,1]
	v_pk_fma_f32 v[20:21], v[42:43], v[10:11], v[20:21] neg_lo:[0,0,1] neg_hi:[0,0,1]
	v_pk_mul_f32 v[6:7], v[34:35], v[6:7]
	v_pk_mul_f32 v[4:5], v[32:33], v[4:5]
	v_pk_mul_f32 v[2:3], v[42:43], v[2:3]
	v_pk_fma_f32 v[0:1], v[36:37], v[8:9], v[0:1]
	v_pk_mul_f32 v[16:17], v[198:199], v[16:17] op_sel_hi:[0,1]
	v_pk_mul_f32 v[18:19], v[198:199], v[18:19] op_sel_hi:[0,1]
	v_pk_mul_f32 v[20:21], v[198:199], v[20:21] op_sel_hi:[0,1]
	v_pk_mul_f32 v[22:23], v[198:199], v[22:23] op_sel_hi:[0,1]
	v_pk_fma_f32 v[4:5], v[44:45], v[12:13], v[4:5]
	v_pk_fma_f32 v[6:7], v[46:47], v[14:15], v[6:7]
	v_pk_fma_f32 v[2:3], v[38:39], v[10:11], v[2:3]
	v_pk_mul_f32 v[10:11], v[198:199], v[0:1] op_sel_hi:[0,1]
	v_or3_b32 v0, v25, v24, v90
	v_pk_mul_f32 v[6:7], v[198:199], v[6:7] op_sel_hi:[0,1]
	v_pk_mul_f32 v[4:5], v[198:199], v[4:5] op_sel_hi:[0,1]
	v_pk_mul_f32 v[8:9], v[198:199], v[2:3] op_sel_hi:[0,1]
	v_mad_i64_i32 v[12:13], s[0:1], v0, s82, v[200:201]
	v_cvt_pk_bf16_f32 v0, v18, v19
	v_cvt_pk_bf16_f32 v1, v16, v17
	v_cvt_pk_bf16_f32 v2, v22, v23
	v_cvt_pk_bf16_f32 v3, v20, v21
	global_store_dwordx4 v[12:13], v[0:3], off
	s_nop 1
	v_cvt_pk_bf16_f32 v0, v4, v5
	v_cvt_pk_bf16_f32 v1, v6, v7
	v_cvt_pk_bf16_f32 v2, v10, v11
	v_cvt_pk_bf16_f32 v3, v8, v9
	global_store_dwordx4 v[12:13], v[0:3], off offset:64

.LBB0_1013:
	v_lshl_add_u32 v198, s58, 8, v169
	v_ashrrev_i32_e32 v199, 31, v198
	v_lshl_or_b32 v64, s59, 8, v209
	v_lshl_add_u64 v[68:69], v[198:199], 3, s[10:11]
	v_lshlrev_b64 v[66:67], 11, v[198:199]
	v_ashrrev_i32_e32 v65, 31, v64
	global_load_dwordx2 v[226:227], v[68:69], off
	v_lshl_add_u64 v[66:67], s[26:27], 0, v[66:67]
	v_lshlrev_b64 v[200:201], 1, v[64:65]
	v_lshl_add_u64 v[228:229], v[66:67], 0, v[200:201]
	global_load_dwordx4 v[218:221], v[228:229], off
	global_load_dwordx4 v[222:225], v[228:229], off offset:256
	v_lshlrev_b64 v[64:65], 2, v[64:65]
	v_lshl_add_u64 v[68:69], s[14:15], 0, v[64:65]
	v_and_b32_e32 v66, 64, v213
	v_lshl_add_u64 v[76:77], s[16:17], 0, v[64:65]
	global_load_dwordx4 v[88:91], v[68:69], off offset:16
	global_load_dwordx4 v[96:99], v[68:69], off
	global_load_dwordx4 v[92:95], v[76:77], off offset:16
	global_load_dwordx4 v[100:103], v[76:77], off
	v_xor_b32_e32 v67, 16, v213
	v_add_u32_e32 v71, 64, v66
	v_xor_b32_e32 v70, 32, v213
	v_cmp_lt_i32_e32 vcc, v67, v71
	v_or_b32_e32 v66, 16, v198
	v_lshl_add_u64 v[202:203], s[26:27], 0, v[200:201]
	v_cndmask_b32_e32 v64, v213, v67, vcc
	v_cmp_lt_i32_e32 vcc, v70, v71
	v_ashrrev_i32_e32 v67, 31, v66
	v_lshlrev_b32_e32 v216, 2, v64
	v_cndmask_b32_e32 v65, v213, v70, vcc
	v_lshlrev_b32_e32 v199, 2, v65
	v_lshl_add_u64 v[160:161], v[66:67], 3, s[10:11]
	v_lshlrev_b64 v[204:205], 11, v[66:67]
	global_load_dwordx4 v[64:67], v[68:69], off offset:528
	global_load_dwordx4 v[72:75], v[68:69], off offset:512
	s_nop 0
	global_load_dwordx4 v[68:71], v[76:77], off offset:528
	s_nop 0
	global_load_dwordx4 v[76:79], v[76:77], off offset:512
	s_nop 0
	global_load_dwordx2 v[206:207], v[160:161], off
	v_lshl_add_u64 v[164:165], v[202:203], 0, v[204:205]
	global_load_dwordx4 v[160:163], v[164:165], off offset:256
	s_nop 0
	global_load_dwordx4 v[164:167], v[164:165], off
	s_waitcnt vmcnt(0)
	v_pk_mul_f32 v[226:227], v[226:227], s[36:37] op_sel_hi:[1,0]
	s_nop 0
	v_fma_f32 v217, -v226, v226, v227
	v_add_f32_e32 v217, 0x3727c5ac, v217
	v_lshlrev_b32_e32 v236, 16, v222
	v_and_b32_e32 v237, 0xffff0000, v222
	v_lshlrev_b32_e32 v227, 16, v218
	v_and_b32_e32 v218, 0xffff0000, v218
	v_lshlrev_b32_e32 v230, 16, v219
	v_and_b32_e32 v231, 0xffff0000, v219
	v_sub_f32_e32 v219, v218, v226
	v_sub_f32_e32 v218, v227, v226
	v_lshlrev_b32_e32 v232, 16, v220
	v_and_b32_e32 v233, 0xffff0000, v220
	v_sub_f32_e32 v220, v230, v226
	v_lshlrev_b32_e32 v234, 16, v221
	v_and_b32_e32 v235, 0xffff0000, v221
	v_sub_f32_e32 v221, v231, v226
	v_sub_f32_e32 v222, v232, v226
	v_lshlrev_b32_e32 v238, 16, v223
	v_and_b32_e32 v239, 0xffff0000, v223
	v_sub_f32_e32 v223, v233, v226
	v_lshlrev_b32_e32 v240, 16, v224
	v_and_b32_e32 v241, 0xffff0000, v224
	v_sub_f32_e32 v224, v234, v226
	v_lshlrev_b32_e32 v242, 16, v225
	v_and_b32_e32 v243, 0xffff0000, v225
	v_sub_f32_e32 v225, v235, v226
	v_sub_f32_e32 v231, v237, v226
	v_rsq_f32_e32 v232, v217
	s_nop 0
	v_pk_mul_f32 v[218:219], v[218:219], v[232:233] op_sel_hi:[1,0]
	v_pk_mul_f32 v[220:221], v[220:221], v[232:233] op_sel_hi:[1,0]
	v_pk_mul_f32 v[224:225], v[224:225], v[232:233] op_sel_hi:[1,0]
	v_pk_mul_f32 v[222:223], v[222:223], v[232:233] op_sel_hi:[1,0]
	v_pk_fma_f32 v[218:219], v[96:97], v[218:219], v[100:101]
	v_pk_fma_f32 v[220:221], v[98:99], v[220:221], v[102:103]
	v_pk_fma_f32 v[222:223], v[88:89], v[222:223], v[92:93]
	v_pk_fma_f32 v[224:225], v[90:91], v[224:225], v[94:95]
	v_pk_fma_f32 v[156:157], v[218:219], s[38:39], v[156:157] op_sel_hi:[1,0,1]
	v_pk_fma_f32 v[158:159], v[220:221], s[38:39], v[158:159] op_sel_hi:[1,0,1]
	v_pk_fma_f32 v[218:219], v[224:225], s[38:39], v[154:155] op_sel_hi:[1,0,1]
	v_pk_fma_f32 v[154:155], v[222:223], s[38:39], v[152:153] op_sel_hi:[1,0,1]
	v_cvt_pk_bf16_f32 v152, v156, v157
	v_sub_f32_e32 v230, v236, v226
	v_sub_f32_e32 v157, v239, v226
	v_sub_f32_e32 v156, v238, v226
	v_cvt_pk_bf16_f32 v153, v158, v159
	v_cvt_pk_bf16_f32 v154, v154, v155
	v_cvt_pk_bf16_f32 v155, v218, v219
	v_pk_mul_f32 v[156:157], v[156:157], v[232:233] op_sel_hi:[1,0]
	v_pk_mul_f32 v[158:159], v[230:231], v[232:233] op_sel_hi:[1,0]
	v_sub_f32_e32 v219, v241, v226
	v_sub_f32_e32 v218, v240, v226
	v_sub_f32_e32 v221, v243, v226
	v_sub_f32_e32 v220, v242, v226
	v_pk_fma_f32 v[158:159], v[72:73], v[158:159], v[76:77]
	v_pk_fma_f32 v[156:157], v[74:75], v[156:157], v[78:79]
	v_pk_mul_f32 v[220:221], v[220:221], v[232:233] op_sel_hi:[1,0]
	v_pk_mul_f32 v[218:219], v[218:219], v[232:233] op_sel_hi:[1,0]
	v_pk_fma_f32 v[220:221], v[66:67], v[220:221], v[70:71]
	v_pk_fma_f32 v[218:219], v[64:65], v[218:219], v[68:69]
	v_pk_fma_f32 v[150:151], v[156:157], s[38:39], v[150:151] op_sel_hi:[1,0,1]
	v_pk_fma_f32 v[148:149], v[158:159], s[38:39], v[148:149] op_sel_hi:[1,0,1]
	v_pk_fma_f32 v[156:157], v[220:221], s[38:39], v[146:147] op_sel_hi:[1,0,1]
	v_pk_fma_f32 v[146:147], v[218:219], s[38:39], v[144:145] op_sel_hi:[1,0,1]
	v_cvt_pk_bf16_f32 v144, v148, v149
	v_cvt_pk_bf16_f32 v145, v150, v151
	global_store_dwordx4 v[228:229], v[152:155], off
	v_cvt_pk_bf16_f32 v146, v146, v147
	v_cvt_pk_bf16_f32 v147, v156, v157
	v_lshlrev_b32_e32 v149, 16, v152
	v_lshlrev_b32_e32 v148, 16, v144
	v_and_b32_e32 v151, 0xffff0000, v152
	v_and_b32_e32 v150, 0xffff0000, v144
	v_lshlrev_b32_e32 v157, 16, v153
	v_lshlrev_b32_e32 v156, 16, v145
	v_and_b32_e32 v153, 0xffff0000, v153
	v_and_b32_e32 v152, 0xffff0000, v145
	global_store_dwordx4 v[228:229], v[144:147], off offset:256
	v_and_b32_e32 v159, 0xffff0000, v154
	v_and_b32_e32 v158, 0xffff0000, v146
	v_lshlrev_b32_e32 v145, 16, v154
	v_lshlrev_b32_e32 v144, 16, v146
	v_lshlrev_b32_e32 v219, 16, v155
	v_lshlrev_b32_e32 v218, 16, v147
	v_and_b32_e32 v155, 0xffff0000, v155
	v_and_b32_e32 v154, 0xffff0000, v147
	v_pk_add_f32 v[146:147], v[148:149], v[150:151]
	v_pk_add_f32 v[220:221], v[156:157], v[152:153]
	v_pk_add_f32 v[222:223], v[218:219], v[154:155]
	v_pk_add_f32 v[146:147], v[146:147], v[220:221]
	v_pk_add_f32 v[220:221], v[144:145], v[158:159]
	s_nop 0
	v_pk_add_f32 v[220:221], v[220:221], v[222:223]
	v_lshlrev_b32_e32 v222, 16, v167
	v_pk_add_f32 v[220:221], v[146:147], v[220:221]
	v_pk_mul_f32 v[146:147], v[150:151], v[150:151]
	v_and_b32_e32 v223, 0xffff0000, v167
	v_pk_fma_f32 v[146:147], v[148:149], v[148:149], v[146:147]
	v_pk_mul_f32 v[148:149], v[152:153], v[152:153]
	s_nop 0
	v_pk_fma_f32 v[148:149], v[156:157], v[156:157], v[148:149]
	v_pk_mul_f32 v[156:157], v[206:207], s[36:37] op_sel_hi:[1,0]
	v_pk_add_f32 v[146:147], v[146:147], v[148:149]
	v_pk_mul_f32 v[148:149], v[158:159], v[158:159]
	v_sub_f32_e32 v223, v223, v156
	v_pk_fma_f32 v[144:145], v[144:145], v[144:145], v[148:149]
	v_pk_mul_f32 v[148:149], v[154:155], v[154:155]
	v_sub_f32_e32 v222, v222, v156
	v_pk_fma_f32 v[148:149], v[218:219], v[218:219], v[148:149]
	s_nop 0
	v_pk_add_f32 v[144:145], v[144:145], v[148:149]
	s_nop 0
	v_pk_add_f32 v[154:155], v[146:147], v[144:145]
	v_fma_f32 v146, -v156, v156, v157
	v_add_f32_e32 v146, 0x3727c5ac, v146
	v_rsq_f32_e32 v206, v146
	v_or_b32_e32 v144, 32, v198
	v_ashrrev_i32_e32 v145, 31, v144
	v_lshl_add_u64 v[148:149], v[144:145], 3, s[10:11]
	v_lshlrev_b64 v[152:153], 11, v[144:145]
	v_lshl_add_u64 v[150:151], v[202:203], 0, v[152:153]
	s_nop 0
	s_nop 1
	s_nop 1
	global_load_dwordx4 v[144:147], v[150:151], off offset:256
	global_load_dwordx2 v[158:159], v[148:149], off
	s_nop 0
	global_load_dwordx4 v[148:151], v[150:151], off
	s_nop 0
	v_lshlrev_b32_e32 v157, 16, v164
	v_and_b32_e32 v164, 0xffff0000, v164
	v_lshlrev_b32_e32 v218, 16, v166
	v_and_b32_e32 v219, 0xffff0000, v166
	v_lshlrev_b32_e32 v207, 16, v165
	v_and_b32_e32 v217, 0xffff0000, v165
	v_sub_f32_e32 v165, v164, v156
	v_sub_f32_e32 v164, v157, v156
	v_sub_f32_e32 v219, v219, v156
	v_sub_f32_e32 v218, v218, v156
	v_sub_f32_e32 v167, v217, v156
	v_sub_f32_e32 v166, v207, v156
	v_pk_mul_f32 v[164:165], v[206:207], v[164:165] op_sel_hi:[0,1]
	v_pk_mul_f32 v[222:223], v[206:207], v[222:223] op_sel_hi:[0,1]
	v_pk_mul_f32 v[218:219], v[206:207], v[218:219] op_sel_hi:[0,1]
	v_pk_mul_f32 v[166:167], v[206:207], v[166:167] op_sel_hi:[0,1]
	v_pk_fma_f32 v[164:165], v[96:97], v[164:165], v[100:101]
	v_pk_fma_f32 v[218:219], v[88:89], v[218:219], v[92:93]
	v_pk_fma_f32 v[222:223], v[90:91], v[222:223], v[94:95]
	v_pk_fma_f32 v[166:167], v[98:99], v[166:167], v[102:103]
	v_pk_fma_f32 v[140:141], v[164:165], s[38:39], v[140:141] op_sel_hi:[1,0,1]
	v_pk_fma_f32 v[164:165], v[222:223], s[38:39], v[138:139] op_sel_hi:[1,0,1]
	v_pk_fma_f32 v[138:139], v[218:219], s[38:39], v[136:137] op_sel_hi:[1,0,1]
	v_pk_fma_f32 v[142:143], v[166:167], s[38:39], v[142:143] op_sel_hi:[1,0,1]
	v_cvt_pk_bf16_f32 v136, v140, v141
	v_cvt_pk_bf16_f32 v138, v138, v139
	v_cvt_pk_bf16_f32 v137, v142, v143
	v_cvt_pk_bf16_f32 v139, v164, v165
	v_lshlrev_b32_e32 v143, 16, v138
	v_lshlrev_b32_e32 v142, 16, v136
	v_and_b32_e32 v165, 0xffff0000, v138
	v_and_b32_e32 v164, 0xffff0000, v136
	v_lshl_add_u64 v[140:141], s[26:27], 0, v[204:205]
	v_and_b32_e32 v205, 0xffff0000, v139
	v_and_b32_e32 v204, 0xffff0000, v137
	v_pk_add_f32 v[218:219], v[142:143], v[164:165]
	v_pk_mul_f32 v[164:165], v[164:165], v[164:165]
	v_lshlrev_b32_e32 v167, 16, v139
	v_lshlrev_b32_e32 v166, 16, v137
	v_pk_fma_f32 v[142:143], v[142:143], v[142:143], v[164:165]
	v_pk_mul_f32 v[164:165], v[204:205], v[204:205]
	v_pk_add_f32 v[222:223], v[166:167], v[204:205]
	v_pk_fma_f32 v[164:165], v[166:167], v[166:167], v[164:165]
	v_and_b32_e32 v157, 0xffff0000, v160
	v_pk_add_f32 v[142:143], v[142:143], v[164:165]
	v_lshlrev_b32_e32 v164, 16, v161
	v_pk_add_f32 v[142:143], v[142:143], v[142:143] op_sel_hi:[0,1]
	v_lshlrev_b32_e32 v142, 16, v160
	v_and_b32_e32 v165, 0xffff0000, v161
	v_lshlrev_b32_e32 v166, 16, v162
	v_and_b32_e32 v167, 0xffff0000, v162
	v_lshlrev_b32_e32 v204, 16, v163
	v_and_b32_e32 v205, 0xffff0000, v163
	v_sub_f32_e32 v161, v157, v156
	v_sub_f32_e32 v160, v142, v156
	v_sub_f32_e32 v163, v165, v156
	v_sub_f32_e32 v162, v164, v156
	v_sub_f32_e32 v165, v167, v156
	v_sub_f32_e32 v164, v166, v156
	v_sub_f32_e32 v157, v205, v156
	v_sub_f32_e32 v156, v204, v156
	v_pk_mul_f32 v[160:161], v[206:207], v[160:161] op_sel_hi:[0,1]
	v_pk_mul_f32 v[156:157], v[206:207], v[156:157] op_sel_hi:[0,1]
	v_pk_mul_f32 v[164:165], v[206:207], v[164:165] op_sel_hi:[0,1]
	v_pk_mul_f32 v[162:163], v[206:207], v[162:163] op_sel_hi:[0,1]
	v_pk_fma_f32 v[160:161], v[72:73], v[160:161], v[76:77]
	v_pk_fma_f32 v[164:165], v[64:65], v[164:165], v[68:69]
	v_pk_fma_f32 v[156:157], v[66:67], v[156:157], v[70:71]
	v_pk_fma_f32 v[162:163], v[74:75], v[162:163], v[78:79]
	v_pk_fma_f32 v[132:133], v[160:161], s[38:39], v[132:133] op_sel_hi:[1,0,1]
	v_pk_fma_f32 v[156:157], v[156:157], s[38:39], v[130:131] op_sel_hi:[1,0,1]
	v_pk_fma_f32 v[130:131], v[164:165], s[38:39], v[128:129] op_sel_hi:[1,0,1]
	v_pk_fma_f32 v[134:135], v[162:163], s[38:39], v[134:135] op_sel_hi:[1,0,1]
	v_cvt_pk_bf16_f32 v128, v132, v133
	v_cvt_pk_bf16_f32 v130, v130, v131
	v_cvt_pk_bf16_f32 v129, v134, v135
	v_cvt_pk_bf16_f32 v131, v156, v157
	v_lshlrev_b32_e32 v133, 16, v130
	v_lshlrev_b32_e32 v132, 16, v128
	v_and_b32_e32 v135, 0xffff0000, v130
	v_and_b32_e32 v134, 0xffff0000, v128
	v_and_b32_e32 v161, 0xffff0000, v131
	v_and_b32_e32 v160, 0xffff0000, v129
	v_pk_add_f32 v[162:163], v[132:133], v[134:135]
	v_pk_mul_f32 v[134:135], v[134:135], v[134:135]
	v_lshlrev_b32_e32 v157, 16, v131
	v_lshlrev_b32_e32 v156, 16, v129
	v_pk_fma_f32 v[132:133], v[132:133], v[132:133], v[134:135]
	v_pk_mul_f32 v[134:135], v[160:161], v[160:161]
	v_lshl_add_u64 v[140:141], v[140:141], 0, v[200:201]
	v_pk_fma_f32 v[134:135], v[156:157], v[156:157], v[134:135]
	global_store_dwordx4 v[140:141], v[136:139], off
	global_store_dwordx4 v[140:141], v[128:131], off offset:256
	v_pk_add_f32 v[132:133], v[132:133], v[134:135]
	v_pk_add_f32 v[218:219], v[218:219], v[222:223]
	v_pk_add_f32 v[132:133], v[132:133], v[132:133] op_sel_hi:[0,1]
	v_mov_b32_e32 v132, v155
	v_mov_b32_e32 v155, v143
	v_pk_add_f32 v[132:133], v[132:133], v[154:155]
	ds_bpermute_b32 v142, v216, v132
	ds_bpermute_b32 v143, v216, v133
	v_pk_add_f32 v[164:165], v[156:157], v[160:161]
	v_pk_add_f32 v[218:219], v[218:219], v[218:219] op_sel_hi:[0,1]
	v_pk_add_f32 v[162:163], v[162:163], v[164:165]
	v_or_b32_e32 v128, 48, v198
	s_waitcnt lgkmcnt(0)
	v_pk_add_f32 v[132:133], v[132:133], v[142:143]
	s_waitcnt vmcnt(3)
	v_pk_mul_f32 v[142:143], v[158:159], s[36:37] op_sel_hi:[1,0]
	v_pk_add_f32 v[162:163], v[162:163], v[162:163] op_sel_hi:[0,1]
	v_fma_f32 v130, -v142, v142, v143
	v_add_f32_e32 v130, 0x3727c5ac, v130
	v_rsq_f32_e32 v160, v130
	v_mov_b32_e32 v218, v221
	v_ashrrev_i32_e32 v129, 31, v128
	v_pk_add_f32 v[134:135], v[218:219], 0 op_sel_hi:[1,0]
	v_mov_b32_e32 v221, v163
	v_lshl_add_u64 v[154:155], v[128:129], 3, s[10:11]
	v_lshlrev_b64 v[140:141], 11, v[128:129]
	v_pk_add_f32 v[134:135], v[220:221], v[134:135]
	ds_bpermute_b32 v156, v216, v134
	ds_bpermute_b32 v157, v216, v135
	s_waitcnt vmcnt(2)
	v_lshlrev_b32_e32 v166, 16, v151
	s_waitcnt lgkmcnt(0)
	v_pk_add_f32 v[136:137], v[134:135], v[156:157]
	v_lshl_add_u64 v[156:157], v[202:203], 0, v[140:141]
	v_and_b32_e32 v165, 0xffff0000, v151
	v_sub_f32_e32 v165, v165, v142
	global_load_dwordx4 v[128:131], v[156:157], off offset:256
	global_load_dwordx2 v[158:159], v[154:155], off
	s_nop 0
	global_load_dwordx4 v[154:157], v[156:157], off
	ds_bpermute_b32 v138, v199, v136
	ds_bpermute_b32 v134, v199, v132
	ds_bpermute_b32 v139, v199, v137
	v_lshlrev_b32_e32 v143, 16, v148
	v_and_b32_e32 v148, 0xffff0000, v148
	v_lshlrev_b32_e32 v161, 16, v149
	v_and_b32_e32 v162, 0xffff0000, v149
	v_lshlrev_b32_e32 v164, 16, v150
	v_and_b32_e32 v163, 0xffff0000, v150
	v_sub_f32_e32 v149, v148, v142
	v_sub_f32_e32 v148, v143, v142
	v_sub_f32_e32 v151, v162, v142
	v_sub_f32_e32 v150, v161, v142
	v_sub_f32_e32 v163, v163, v142
	v_sub_f32_e32 v162, v164, v142
	v_sub_f32_e32 v164, v166, v142
	v_pk_mul_f32 v[150:151], v[160:161], v[150:151] op_sel_hi:[0,1]
	v_pk_mul_f32 v[148:149], v[160:161], v[148:149] op_sel_hi:[0,1]
	v_pk_mul_f32 v[164:165], v[160:161], v[164:165] op_sel_hi:[0,1]
	v_pk_mul_f32 v[162:163], v[160:161], v[162:163] op_sel_hi:[0,1]
	v_pk_fma_f32 v[148:149], v[96:97], v[148:149], v[100:101]
	v_pk_fma_f32 v[150:151], v[98:99], v[150:151], v[102:103]
	v_pk_fma_f32 v[162:163], v[88:89], v[162:163], v[92:93]
	v_pk_fma_f32 v[164:165], v[90:91], v[164:165], v[94:95]
	v_pk_fma_f32 v[126:127], v[150:151], s[38:39], v[126:127] op_sel_hi:[1,0,1]
	v_pk_fma_f32 v[124:125], v[148:149], s[38:39], v[124:125] op_sel_hi:[1,0,1]
	v_pk_fma_f32 v[148:149], v[164:165], s[38:39], v[122:123] op_sel_hi:[1,0,1]
	v_pk_fma_f32 v[122:123], v[162:163], s[38:39], v[120:121] op_sel_hi:[1,0,1]
	v_cvt_pk_bf16_f32 v121, v126, v127
	v_cvt_pk_bf16_f32 v122, v122, v123
	v_cvt_pk_bf16_f32 v123, v148, v149
	v_lshlrev_b32_e32 v126, 16, v144
	v_and_b32_e32 v127, 0xffff0000, v144
	v_lshlrev_b32_e32 v143, 16, v145
	v_and_b32_e32 v144, 0xffff0000, v145
	v_lshlrev_b32_e32 v148, 16, v146
	v_and_b32_e32 v146, 0xffff0000, v146
	v_lshlrev_b32_e32 v149, 16, v147
	v_and_b32_e32 v150, 0xffff0000, v147
	v_sub_f32_e32 v127, v127, v142
	v_sub_f32_e32 v126, v126, v142
	v_sub_f32_e32 v145, v144, v142
	v_sub_f32_e32 v144, v143, v142
	v_sub_f32_e32 v147, v146, v142
	v_sub_f32_e32 v146, v148, v142
	v_sub_f32_e32 v143, v150, v142
	v_sub_f32_e32 v142, v149, v142
	v_pk_mul_f32 v[144:145], v[160:161], v[144:145] op_sel_hi:[0,1]
	v_pk_mul_f32 v[126:127], v[160:161], v[126:127] op_sel_hi:[0,1]
	v_pk_mul_f32 v[142:143], v[160:161], v[142:143] op_sel_hi:[0,1]
	v_pk_mul_f32 v[146:147], v[160:161], v[146:147] op_sel_hi:[0,1]
	v_pk_fma_f32 v[126:127], v[72:73], v[126:127], v[76:77]
	v_pk_fma_f32 v[144:145], v[74:75], v[144:145], v[78:79]
	v_pk_fma_f32 v[146:147], v[64:65], v[146:147], v[68:69]
	v_pk_fma_f32 v[142:143], v[66:67], v[142:143], v[70:71]
	v_cvt_pk_bf16_f32 v120, v124, v125
	v_lshl_add_u64 v[124:125], s[26:27], 0, v[152:153]
	v_pk_fma_f32 v[118:119], v[144:145], s[38:39], v[118:119] op_sel_hi:[1,0,1]
	v_pk_fma_f32 v[116:117], v[126:127], s[38:39], v[116:117] op_sel_hi:[1,0,1]
	v_pk_fma_f32 v[126:127], v[142:143], s[38:39], v[114:115] op_sel_hi:[1,0,1]
	v_pk_fma_f32 v[114:115], v[146:147], s[38:39], v[112:113] op_sel_hi:[1,0,1]
	v_lshl_add_u64 v[124:125], v[124:125], 0, v[200:201]
	v_cvt_pk_bf16_f32 v112, v116, v117
	v_cvt_pk_bf16_f32 v113, v118, v119
	v_cvt_pk_bf16_f32 v114, v114, v115
	v_cvt_pk_bf16_f32 v115, v126, v127
	global_store_dwordx4 v[124:125], v[120:123], off
	global_store_dwordx4 v[124:125], v[112:115], off offset:256
	v_lshlrev_b32_e32 v117, 16, v120
	v_lshlrev_b32_e32 v116, 16, v112
	v_and_b32_e32 v119, 0xffff0000, v120
	v_and_b32_e32 v118, 0xffff0000, v112
	v_lshlrev_b32_e32 v125, 16, v121
	v_lshlrev_b32_e32 v124, 16, v113
	v_and_b32_e32 v121, 0xffff0000, v121
	v_and_b32_e32 v120, 0xffff0000, v113
	v_lshlrev_b32_e32 v113, 16, v122
	v_lshlrev_b32_e32 v112, 16, v114
	v_and_b32_e32 v127, 0xffff0000, v122
	v_and_b32_e32 v126, 0xffff0000, v114
	v_lshlrev_b32_e32 v143, 16, v123
	v_lshlrev_b32_e32 v142, 16, v115
	v_and_b32_e32 v123, 0xffff0000, v123
	v_and_b32_e32 v122, 0xffff0000, v115
	v_pk_add_f32 v[114:115], v[116:117], v[118:119]
	v_pk_add_f32 v[144:145], v[124:125], v[120:121]
	v_pk_add_f32 v[146:147], v[142:143], v[122:123]
	v_pk_add_f32 v[114:115], v[114:115], v[144:145]
	v_pk_add_f32 v[144:145], v[112:113], v[126:127]
	s_waitcnt vmcnt(2)
	v_lshlrev_b32_e32 v150, 16, v156
	v_pk_add_f32 v[144:145], v[144:145], v[146:147]
	v_and_b32_e32 v151, 0xffff0000, v156
	v_pk_add_f32 v[144:145], v[114:115], v[144:145]
	v_pk_mul_f32 v[114:115], v[118:119], v[118:119]
	v_lshlrev_b32_e32 v152, 16, v157
	v_pk_fma_f32 v[114:115], v[116:117], v[116:117], v[114:115]
	v_pk_mul_f32 v[116:117], v[120:121], v[120:121]
	v_and_b32_e32 v153, 0xffff0000, v157
	v_pk_fma_f32 v[116:117], v[124:125], v[124:125], v[116:117]
	v_pk_mul_f32 v[124:125], v[158:159], s[36:37] op_sel_hi:[1,0]
	v_pk_add_f32 v[114:115], v[114:115], v[116:117]
	v_pk_mul_f32 v[116:117], v[126:127], v[126:127]
	v_and_b32_e32 v149, 0xffff0000, v155
	v_pk_fma_f32 v[112:113], v[112:113], v[112:113], v[116:117]
	v_pk_mul_f32 v[116:117], v[122:123], v[122:123]
	v_sub_f32_e32 v151, v151, v124
	v_pk_fma_f32 v[116:117], v[142:143], v[142:143], v[116:117]
	v_sub_f32_e32 v150, v150, v124
	v_pk_add_f32 v[112:113], v[112:113], v[116:117]
	v_sub_f32_e32 v153, v153, v124
	v_pk_add_f32 v[122:123], v[114:115], v[112:113]
	v_fma_f32 v114, -v124, v124, v125
	v_add_f32_e32 v114, 0x3727c5ac, v114
	v_rsq_f32_e32 v142, v114
	v_add_u32_e32 v112, 0x80, v198
	v_ashrrev_i32_e32 v113, 31, v112
	v_lshl_add_u64 v[116:117], v[112:113], 3, s[10:11]
	v_lshlrev_b64 v[120:121], 11, v[112:113]
	v_lshl_add_u64 v[118:119], v[202:203], 0, v[120:121]
	v_sub_f32_e32 v152, v152, v124
	v_sub_f32_e32 v149, v149, v124
	ds_bpermute_b32 v135, v199, v133
	s_nop 1
	global_load_dwordx4 v[112:115], v[118:119], off offset:256
	global_load_dwordx2 v[126:127], v[116:117], off
	s_nop 0
	global_load_dwordx4 v[116:119], v[118:119], off
	s_nop 0
	v_lshlrev_b32_e32 v125, 16, v154
	v_and_b32_e32 v143, 0xffff0000, v154
	v_lshlrev_b32_e32 v148, 16, v155
	v_sub_f32_e32 v147, v143, v124
	v_sub_f32_e32 v146, v125, v124
	v_sub_f32_e32 v148, v148, v124
	v_pk_mul_f32 v[146:147], v[142:143], v[146:147] op_sel_hi:[0,1]
	v_pk_mul_f32 v[152:153], v[142:143], v[152:153] op_sel_hi:[0,1]
	v_pk_mul_f32 v[150:151], v[142:143], v[150:151] op_sel_hi:[0,1]
	v_pk_mul_f32 v[148:149], v[142:143], v[148:149] op_sel_hi:[0,1]
	v_pk_fma_f32 v[146:147], v[96:97], v[146:147], v[100:101]
	v_pk_fma_f32 v[150:151], v[88:89], v[150:151], v[92:93]
	v_pk_fma_f32 v[152:153], v[90:91], v[152:153], v[94:95]
	v_pk_fma_f32 v[148:149], v[98:99], v[148:149], v[102:103]
	v_pk_fma_f32 v[108:109], v[146:147], s[38:39], v[108:109] op_sel_hi:[1,0,1]
	v_pk_fma_f32 v[146:147], v[152:153], s[38:39], v[106:107] op_sel_hi:[1,0,1]
	v_pk_fma_f32 v[106:107], v[150:151], s[38:39], v[104:105] op_sel_hi:[1,0,1]
	v_pk_fma_f32 v[110:111], v[148:149], s[38:39], v[110:111] op_sel_hi:[1,0,1]
	v_cvt_pk_bf16_f32 v104, v108, v109
	v_cvt_pk_bf16_f32 v106, v106, v107
	v_cvt_pk_bf16_f32 v105, v110, v111
	v_cvt_pk_bf16_f32 v107, v146, v147
	v_lshl_add_u64 v[108:109], s[26:27], 0, v[140:141]
	v_lshlrev_b32_e32 v111, 16, v106
	v_lshlrev_b32_e32 v110, 16, v104
	v_and_b32_e32 v141, 0xffff0000, v106
	v_and_b32_e32 v140, 0xffff0000, v104
	v_and_b32_e32 v149, 0xffff0000, v107
	v_and_b32_e32 v148, 0xffff0000, v105
	v_pk_add_f32 v[150:151], v[110:111], v[140:141]
	v_pk_mul_f32 v[140:141], v[140:141], v[140:141]
	v_lshlrev_b32_e32 v147, 16, v107
	v_lshlrev_b32_e32 v146, 16, v105
	v_pk_fma_f32 v[110:111], v[110:111], v[110:111], v[140:141]
	v_pk_mul_f32 v[140:141], v[148:149], v[148:149]
	v_pk_add_f32 v[152:153], v[146:147], v[148:149]
	v_pk_fma_f32 v[140:141], v[146:147], v[146:147], v[140:141]
	v_and_b32_e32 v125, 0xffff0000, v128
	v_pk_add_f32 v[110:111], v[110:111], v[140:141]
	v_lshlrev_b32_e32 v140, 16, v129
	v_pk_add_f32 v[110:111], v[110:111], v[110:111] op_sel_hi:[0,1]
	v_lshlrev_b32_e32 v110, 16, v128
	v_and_b32_e32 v141, 0xffff0000, v129
	v_lshlrev_b32_e32 v143, 16, v130
	v_and_b32_e32 v146, 0xffff0000, v130
	v_lshlrev_b32_e32 v147, 16, v131
	v_and_b32_e32 v148, 0xffff0000, v131
	v_sub_f32_e32 v129, v125, v124
	v_sub_f32_e32 v128, v110, v124
	v_sub_f32_e32 v131, v141, v124
	v_sub_f32_e32 v130, v140, v124
	v_sub_f32_e32 v141, v146, v124
	v_sub_f32_e32 v140, v143, v124
	v_sub_f32_e32 v125, v148, v124
	v_sub_f32_e32 v124, v147, v124
	v_pk_mul_f32 v[128:129], v[142:143], v[128:129] op_sel_hi:[0,1]
	v_pk_mul_f32 v[124:125], v[142:143], v[124:125] op_sel_hi:[0,1]
	v_pk_mul_f32 v[140:141], v[142:143], v[140:141] op_sel_hi:[0,1]
	v_pk_mul_f32 v[130:131], v[142:143], v[130:131] op_sel_hi:[0,1]
	v_pk_fma_f32 v[128:129], v[72:73], v[128:129], v[76:77]
	v_pk_fma_f32 v[140:141], v[64:65], v[140:141], v[68:69]
	v_pk_fma_f32 v[124:125], v[66:67], v[124:125], v[70:71]
	v_pk_fma_f32 v[130:131], v[74:75], v[130:131], v[78:79]
	v_pk_fma_f32 v[84:85], v[128:129], s[38:39], v[84:85] op_sel_hi:[1,0,1]
	v_pk_fma_f32 v[124:125], v[124:125], s[38:39], v[82:83] op_sel_hi:[1,0,1]
	v_pk_fma_f32 v[82:83], v[140:141], s[38:39], v[80:81] op_sel_hi:[1,0,1]
	v_pk_fma_f32 v[86:87], v[130:131], s[38:39], v[86:87] op_sel_hi:[1,0,1]
	v_cvt_pk_bf16_f32 v80, v84, v85
	v_cvt_pk_bf16_f32 v82, v82, v83
	v_cvt_pk_bf16_f32 v81, v86, v87
	v_cvt_pk_bf16_f32 v83, v124, v125
	v_lshlrev_b32_e32 v85, 16, v82
	v_lshlrev_b32_e32 v84, 16, v80
	v_and_b32_e32 v87, 0xffff0000, v82
	v_and_b32_e32 v86, 0xffff0000, v80
	v_and_b32_e32 v129, 0xffff0000, v83
	v_and_b32_e32 v128, 0xffff0000, v81
	v_pk_add_f32 v[130:131], v[84:85], v[86:87]
	v_pk_mul_f32 v[86:87], v[86:87], v[86:87]
	v_lshlrev_b32_e32 v125, 16, v83
	v_lshlrev_b32_e32 v124, 16, v81
	v_pk_fma_f32 v[84:85], v[84:85], v[84:85], v[86:87]
	v_pk_mul_f32 v[86:87], v[128:129], v[128:129]
	v_mov_b32_e32 v110, v123
	v_pk_fma_f32 v[86:87], v[124:125], v[124:125], v[86:87]
	v_lshl_add_u64 v[108:109], v[108:109], 0, v[200:201]
	v_pk_add_f32 v[84:85], v[84:85], v[86:87]
	global_store_dwordx4 v[108:109], v[104:107], off
	global_store_dwordx4 v[108:109], v[80:83], off offset:256
	v_pk_add_f32 v[84:85], v[84:85], v[84:85] op_sel_hi:[0,1]
	v_mov_b32_e32 v84, v122
	v_pk_add_f32 v[84:85], v[84:85], v[110:111]
	ds_bpermute_b32 v110, v216, v84
	ds_bpermute_b32 v111, v216, v85
	v_pk_add_f32 v[150:151], v[150:151], v[152:153]
	v_pk_add_f32 v[140:141], v[124:125], v[128:129]
	v_pk_add_f32 v[150:151], v[150:151], v[150:151] op_sel_hi:[0,1]
	v_pk_add_f32 v[130:131], v[130:131], v[140:141]
	s_waitcnt lgkmcnt(0)
	v_pk_add_f32 v[84:85], v[84:85], v[110:111]
	s_waitcnt vmcnt(3)
	v_pk_mul_f32 v[110:111], v[126:127], s[36:37] op_sel_hi:[1,0]
	v_add_u32_e32 v80, 0x90, v198
	v_fma_f32 v82, -v110, v110, v111
	v_add_f32_e32 v82, 0x3727c5ac, v82
	v_rsq_f32_e32 v128, v82
	v_pk_add_f32 v[130:131], v[130:131], v[130:131] op_sel_hi:[0,1]
	v_mov_b32_e32 v150, v145
	v_ashrrev_i32_e32 v81, 31, v80
	v_pk_add_f32 v[86:87], v[150:151], 0 op_sel_hi:[1,0]
	v_mov_b32_e32 v145, v131
	v_lshl_add_u64 v[122:123], v[80:81], 3, s[10:11]
	v_lshlrev_b64 v[108:109], 11, v[80:81]
	v_pk_add_f32 v[86:87], v[144:145], v[86:87]
	ds_bpermute_b32 v124, v216, v86
	ds_bpermute_b32 v125, v216, v87
	s_waitcnt vmcnt(2)
	v_lshlrev_b32_e32 v142, 16, v119
	s_waitcnt lgkmcnt(0)
	v_pk_add_f32 v[104:105], v[86:87], v[124:125]
	v_lshl_add_u64 v[124:125], v[202:203], 0, v[108:109]
	v_and_b32_e32 v141, 0xffff0000, v119
	v_sub_f32_e32 v141, v141, v110
	global_load_dwordx4 v[80:83], v[124:125], off offset:256
	global_load_dwordx2 v[126:127], v[122:123], off
	s_nop 0
	global_load_dwordx4 v[122:125], v[124:125], off
	ds_bpermute_b32 v106, v199, v104
	ds_bpermute_b32 v86, v199, v84
	ds_bpermute_b32 v107, v199, v105
	v_lshlrev_b32_e32 v111, 16, v116
	v_and_b32_e32 v116, 0xffff0000, v116
	v_lshlrev_b32_e32 v129, 16, v117
	v_and_b32_e32 v130, 0xffff0000, v117
	v_lshlrev_b32_e32 v140, 16, v118
	v_and_b32_e32 v131, 0xffff0000, v118
	v_sub_f32_e32 v117, v116, v110
	v_sub_f32_e32 v116, v111, v110
	v_sub_f32_e32 v119, v130, v110
	v_sub_f32_e32 v118, v129, v110
	v_sub_f32_e32 v131, v131, v110
	v_sub_f32_e32 v130, v140, v110
	v_sub_f32_e32 v140, v142, v110
	v_pk_mul_f32 v[118:119], v[128:129], v[118:119] op_sel_hi:[0,1]
	v_pk_mul_f32 v[116:117], v[128:129], v[116:117] op_sel_hi:[0,1]
	v_pk_mul_f32 v[140:141], v[128:129], v[140:141] op_sel_hi:[0,1]
	v_pk_mul_f32 v[130:131], v[128:129], v[130:131] op_sel_hi:[0,1]
	v_pk_fma_f32 v[116:117], v[96:97], v[116:117], v[100:101]
	v_pk_fma_f32 v[118:119], v[98:99], v[118:119], v[102:103]
	v_pk_fma_f32 v[130:131], v[88:89], v[130:131], v[92:93]
	v_pk_fma_f32 v[140:141], v[90:91], v[140:141], v[94:95]
	v_pk_fma_f32 v[62:63], v[118:119], s[38:39], v[62:63] op_sel_hi:[1,0,1]
	v_pk_fma_f32 v[60:61], v[116:117], s[38:39], v[60:61] op_sel_hi:[1,0,1]
	v_pk_fma_f32 v[116:117], v[140:141], s[38:39], v[58:59] op_sel_hi:[1,0,1]
	v_pk_fma_f32 v[58:59], v[130:131], s[38:39], v[56:57] op_sel_hi:[1,0,1]
	v_cvt_pk_bf16_f32 v57, v62, v63
	v_cvt_pk_bf16_f32 v58, v58, v59
	v_cvt_pk_bf16_f32 v59, v116, v117
	v_lshlrev_b32_e32 v62, 16, v112
	v_and_b32_e32 v63, 0xffff0000, v112
	v_lshlrev_b32_e32 v111, 16, v113
	v_and_b32_e32 v112, 0xffff0000, v113
	v_lshlrev_b32_e32 v116, 16, v114
	v_and_b32_e32 v114, 0xffff0000, v114
	v_lshlrev_b32_e32 v117, 16, v115
	v_and_b32_e32 v118, 0xffff0000, v115
	v_sub_f32_e32 v63, v63, v110
	v_sub_f32_e32 v62, v62, v110
	v_sub_f32_e32 v113, v112, v110
	v_sub_f32_e32 v112, v111, v110
	v_sub_f32_e32 v115, v114, v110
	v_sub_f32_e32 v114, v116, v110
	v_sub_f32_e32 v111, v118, v110
	v_sub_f32_e32 v110, v117, v110
	v_pk_mul_f32 v[112:113], v[128:129], v[112:113] op_sel_hi:[0,1]
	v_pk_mul_f32 v[62:63], v[128:129], v[62:63] op_sel_hi:[0,1]
	v_pk_mul_f32 v[110:111], v[128:129], v[110:111] op_sel_hi:[0,1]
	v_pk_mul_f32 v[114:115], v[128:129], v[114:115] op_sel_hi:[0,1]
	v_pk_fma_f32 v[62:63], v[72:73], v[62:63], v[76:77]
	v_pk_fma_f32 v[112:113], v[74:75], v[112:113], v[78:79]
	v_pk_fma_f32 v[114:115], v[64:65], v[114:115], v[68:69]
	v_pk_fma_f32 v[110:111], v[66:67], v[110:111], v[70:71]
	v_cvt_pk_bf16_f32 v56, v60, v61
	v_lshl_add_u64 v[60:61], s[26:27], 0, v[120:121]
	v_pk_fma_f32 v[54:55], v[112:113], s[38:39], v[54:55] op_sel_hi:[1,0,1]
	v_pk_fma_f32 v[52:53], v[62:63], s[38:39], v[52:53] op_sel_hi:[1,0,1]
	v_pk_fma_f32 v[62:63], v[110:111], s[38:39], v[50:51] op_sel_hi:[1,0,1]
	v_pk_fma_f32 v[50:51], v[114:115], s[38:39], v[48:49] op_sel_hi:[1,0,1]
	v_lshl_add_u64 v[60:61], v[60:61], 0, v[200:201]
	v_cvt_pk_bf16_f32 v48, v52, v53
	v_cvt_pk_bf16_f32 v49, v54, v55
	v_cvt_pk_bf16_f32 v50, v50, v51
	v_cvt_pk_bf16_f32 v51, v62, v63
	global_store_dwordx4 v[60:61], v[56:59], off
	global_store_dwordx4 v[60:61], v[48:51], off offset:256
	v_lshlrev_b32_e32 v53, 16, v56
	v_lshlrev_b32_e32 v52, 16, v48
	v_and_b32_e32 v55, 0xffff0000, v56
	v_and_b32_e32 v54, 0xffff0000, v48
	v_lshlrev_b32_e32 v61, 16, v57
	v_lshlrev_b32_e32 v60, 16, v49
	v_and_b32_e32 v57, 0xffff0000, v57
	v_and_b32_e32 v56, 0xffff0000, v49
	v_lshlrev_b32_e32 v49, 16, v58
	v_lshlrev_b32_e32 v48, 16, v50
	v_and_b32_e32 v63, 0xffff0000, v58
	v_and_b32_e32 v62, 0xffff0000, v50
	v_lshlrev_b32_e32 v111, 16, v59
	v_lshlrev_b32_e32 v110, 16, v51
	v_and_b32_e32 v59, 0xffff0000, v59
	v_and_b32_e32 v58, 0xffff0000, v51
	v_pk_add_f32 v[50:51], v[52:53], v[54:55]
	v_pk_add_f32 v[112:113], v[60:61], v[56:57]
	v_pk_add_f32 v[114:115], v[110:111], v[58:59]
	v_pk_add_f32 v[50:51], v[50:51], v[112:113]
	v_pk_add_f32 v[112:113], v[48:49], v[62:63]
	s_waitcnt vmcnt(2)
	v_lshlrev_b32_e32 v118, 16, v124
	v_pk_add_f32 v[112:113], v[112:113], v[114:115]
	v_and_b32_e32 v119, 0xffff0000, v124
	v_pk_add_f32 v[112:113], v[50:51], v[112:113]
	v_pk_mul_f32 v[50:51], v[54:55], v[54:55]
	v_lshlrev_b32_e32 v120, 16, v125
	v_pk_fma_f32 v[50:51], v[52:53], v[52:53], v[50:51]
	v_pk_mul_f32 v[52:53], v[56:57], v[56:57]
	v_and_b32_e32 v121, 0xffff0000, v125
	v_pk_fma_f32 v[52:53], v[60:61], v[60:61], v[52:53]
	v_pk_mul_f32 v[60:61], v[126:127], s[36:37] op_sel_hi:[1,0]
	v_pk_add_f32 v[50:51], v[50:51], v[52:53]
	v_pk_mul_f32 v[52:53], v[62:63], v[62:63]
	v_and_b32_e32 v117, 0xffff0000, v123
	v_pk_fma_f32 v[48:49], v[48:49], v[48:49], v[52:53]
	v_pk_mul_f32 v[52:53], v[58:59], v[58:59]
	v_sub_f32_e32 v119, v119, v60
	v_pk_fma_f32 v[52:53], v[110:111], v[110:111], v[52:53]
	v_sub_f32_e32 v118, v118, v60
	v_pk_add_f32 v[48:49], v[48:49], v[52:53]
	v_sub_f32_e32 v121, v121, v60
	v_pk_add_f32 v[58:59], v[50:51], v[48:49]
	v_fma_f32 v50, -v60, v60, v61
	v_add_f32_e32 v50, 0x3727c5ac, v50
	v_rsq_f32_e32 v110, v50
	v_add_u32_e32 v48, 0xa0, v198
	v_ashrrev_i32_e32 v49, 31, v48
	v_lshl_add_u64 v[52:53], v[48:49], 3, s[10:11]
	v_lshlrev_b64 v[56:57], 11, v[48:49]
	v_lshl_add_u64 v[54:55], v[202:203], 0, v[56:57]
	v_sub_f32_e32 v120, v120, v60
	v_sub_f32_e32 v117, v117, v60
	ds_bpermute_b32 v87, v199, v85
	s_nop 1
	global_load_dwordx4 v[48:51], v[54:55], off offset:256
	global_load_dwordx2 v[62:63], v[52:53], off
	s_nop 0
	global_load_dwordx4 v[52:55], v[54:55], off
	s_nop 0
	v_lshlrev_b32_e32 v61, 16, v122
	v_and_b32_e32 v111, 0xffff0000, v122
	v_lshlrev_b32_e32 v116, 16, v123
	v_sub_f32_e32 v115, v111, v60
	v_sub_f32_e32 v114, v61, v60
	v_sub_f32_e32 v116, v116, v60
	v_pk_mul_f32 v[114:115], v[110:111], v[114:115] op_sel_hi:[0,1]
	v_pk_mul_f32 v[120:121], v[110:111], v[120:121] op_sel_hi:[0,1]
	v_pk_mul_f32 v[118:119], v[110:111], v[118:119] op_sel_hi:[0,1]
	v_pk_mul_f32 v[116:117], v[110:111], v[116:117] op_sel_hi:[0,1]
	v_pk_fma_f32 v[114:115], v[96:97], v[114:115], v[100:101]
	v_pk_fma_f32 v[118:119], v[88:89], v[118:119], v[92:93]
	v_pk_fma_f32 v[120:121], v[90:91], v[120:121], v[94:95]
	v_pk_fma_f32 v[116:117], v[98:99], v[116:117], v[102:103]
	v_pk_fma_f32 v[44:45], v[114:115], s[38:39], v[44:45] op_sel_hi:[1,0,1]
	v_pk_fma_f32 v[114:115], v[120:121], s[38:39], v[42:43] op_sel_hi:[1,0,1]
	v_pk_fma_f32 v[42:43], v[118:119], s[38:39], v[40:41] op_sel_hi:[1,0,1]
	v_pk_fma_f32 v[46:47], v[116:117], s[38:39], v[46:47] op_sel_hi:[1,0,1]
	v_cvt_pk_bf16_f32 v40, v44, v45
	v_cvt_pk_bf16_f32 v42, v42, v43
	v_cvt_pk_bf16_f32 v41, v46, v47
	v_cvt_pk_bf16_f32 v43, v114, v115
	v_lshl_add_u64 v[44:45], s[26:27], 0, v[108:109]
	v_lshlrev_b32_e32 v47, 16, v42
	v_lshlrev_b32_e32 v46, 16, v40
	v_and_b32_e32 v109, 0xffff0000, v42
	v_and_b32_e32 v108, 0xffff0000, v40
	v_and_b32_e32 v117, 0xffff0000, v43
	v_and_b32_e32 v116, 0xffff0000, v41
	v_pk_add_f32 v[118:119], v[46:47], v[108:109]
	v_pk_mul_f32 v[108:109], v[108:109], v[108:109]
	v_lshlrev_b32_e32 v115, 16, v43
	v_lshlrev_b32_e32 v114, 16, v41
	v_pk_fma_f32 v[46:47], v[46:47], v[46:47], v[108:109]
	v_pk_mul_f32 v[108:109], v[116:117], v[116:117]
	v_pk_add_f32 v[120:121], v[114:115], v[116:117]
	v_pk_fma_f32 v[108:109], v[114:115], v[114:115], v[108:109]
	v_and_b32_e32 v61, 0xffff0000, v80
	v_pk_add_f32 v[46:47], v[46:47], v[108:109]
	v_lshlrev_b32_e32 v108, 16, v81
	v_pk_add_f32 v[46:47], v[46:47], v[46:47] op_sel_hi:[0,1]
	v_lshlrev_b32_e32 v46, 16, v80
	v_and_b32_e32 v109, 0xffff0000, v81
	v_lshlrev_b32_e32 v111, 16, v82
	v_and_b32_e32 v114, 0xffff0000, v82
	v_lshlrev_b32_e32 v115, 16, v83
	v_and_b32_e32 v116, 0xffff0000, v83
	v_sub_f32_e32 v81, v61, v60
	v_sub_f32_e32 v80, v46, v60
	v_sub_f32_e32 v83, v109, v60
	v_sub_f32_e32 v82, v108, v60
	v_sub_f32_e32 v109, v114, v60
	v_sub_f32_e32 v108, v111, v60
	v_sub_f32_e32 v61, v116, v60
	v_sub_f32_e32 v60, v115, v60
	v_pk_mul_f32 v[80:81], v[110:111], v[80:81] op_sel_hi:[0,1]
	v_pk_mul_f32 v[60:61], v[110:111], v[60:61] op_sel_hi:[0,1]
	v_pk_mul_f32 v[108:109], v[110:111], v[108:109] op_sel_hi:[0,1]
	v_pk_mul_f32 v[82:83], v[110:111], v[82:83] op_sel_hi:[0,1]
	v_pk_fma_f32 v[80:81], v[72:73], v[80:81], v[76:77]
	v_pk_fma_f32 v[108:109], v[64:65], v[108:109], v[68:69]
	v_pk_fma_f32 v[60:61], v[66:67], v[60:61], v[70:71]
	v_pk_fma_f32 v[82:83], v[74:75], v[82:83], v[78:79]
	v_pk_fma_f32 v[36:37], v[80:81], s[38:39], v[36:37] op_sel_hi:[1,0,1]
	v_pk_fma_f32 v[60:61], v[60:61], s[38:39], v[34:35] op_sel_hi:[1,0,1]
	v_pk_fma_f32 v[34:35], v[108:109], s[38:39], v[32:33] op_sel_hi:[1,0,1]
	v_pk_fma_f32 v[38:39], v[82:83], s[38:39], v[38:39] op_sel_hi:[1,0,1]
	v_cvt_pk_bf16_f32 v32, v36, v37
	v_cvt_pk_bf16_f32 v34, v34, v35
	v_cvt_pk_bf16_f32 v33, v38, v39
	v_cvt_pk_bf16_f32 v35, v60, v61
	v_lshlrev_b32_e32 v37, 16, v34
	v_lshlrev_b32_e32 v36, 16, v32
	v_and_b32_e32 v39, 0xffff0000, v34
	v_and_b32_e32 v38, 0xffff0000, v32
	v_and_b32_e32 v81, 0xffff0000, v35
	v_and_b32_e32 v80, 0xffff0000, v33
	v_pk_add_f32 v[82:83], v[36:37], v[38:39]
	v_pk_mul_f32 v[38:39], v[38:39], v[38:39]
	v_lshlrev_b32_e32 v61, 16, v35
	v_lshlrev_b32_e32 v60, 16, v33
	v_pk_fma_f32 v[36:37], v[36:37], v[36:37], v[38:39]
	v_pk_mul_f32 v[38:39], v[80:81], v[80:81]
	v_mov_b32_e32 v46, v59
	v_pk_fma_f32 v[38:39], v[60:61], v[60:61], v[38:39]
	v_lshl_add_u64 v[44:45], v[44:45], 0, v[200:201]
	v_pk_add_f32 v[36:37], v[36:37], v[38:39]
	global_store_dwordx4 v[44:45], v[40:43], off
	global_store_dwordx4 v[44:45], v[32:35], off offset:256
	v_pk_add_f32 v[36:37], v[36:37], v[36:37] op_sel_hi:[0,1]
	v_mov_b32_e32 v36, v58
	v_pk_add_f32 v[36:37], v[36:37], v[46:47]
	ds_bpermute_b32 v46, v216, v36
	ds_bpermute_b32 v47, v216, v37
	v_pk_add_f32 v[118:119], v[118:119], v[120:121]
	v_pk_add_f32 v[108:109], v[60:61], v[80:81]
	v_pk_add_f32 v[118:119], v[118:119], v[118:119] op_sel_hi:[0,1]
	v_pk_add_f32 v[82:83], v[82:83], v[108:109]
	s_waitcnt lgkmcnt(0)
	v_pk_add_f32 v[36:37], v[36:37], v[46:47]
	s_waitcnt vmcnt(3)
	v_pk_mul_f32 v[46:47], v[62:63], s[36:37] op_sel_hi:[1,0]
	v_add_u32_e32 v32, 0xb0, v198
	v_fma_f32 v34, -v46, v46, v47
	v_add_f32_e32 v34, 0x3727c5ac, v34
	v_rsq_f32_e32 v80, v34
	v_pk_add_f32 v[82:83], v[82:83], v[82:83] op_sel_hi:[0,1]
	v_mov_b32_e32 v118, v113
	v_ashrrev_i32_e32 v33, 31, v32
	v_pk_add_f32 v[38:39], v[118:119], 0 op_sel_hi:[1,0]
	v_mov_b32_e32 v113, v83
	v_lshl_add_u64 v[58:59], v[32:33], 3, s[10:11]
	v_lshlrev_b64 v[44:45], 11, v[32:33]
	v_pk_add_f32 v[38:39], v[112:113], v[38:39]
	ds_bpermute_b32 v60, v216, v38
	ds_bpermute_b32 v61, v216, v39
	s_waitcnt vmcnt(2)
	v_lshlrev_b32_e32 v110, 16, v55
	s_waitcnt lgkmcnt(0)
	v_pk_add_f32 v[40:41], v[38:39], v[60:61]
	v_lshl_add_u64 v[60:61], v[202:203], 0, v[44:45]
	v_and_b32_e32 v109, 0xffff0000, v55
	v_sub_f32_e32 v109, v109, v46
	global_load_dwordx4 v[32:35], v[60:61], off offset:256
	global_load_dwordx2 v[62:63], v[58:59], off
	s_nop 0
	global_load_dwordx4 v[58:61], v[60:61], off
	ds_bpermute_b32 v42, v199, v40
	ds_bpermute_b32 v38, v199, v36
	ds_bpermute_b32 v43, v199, v41
	v_lshlrev_b32_e32 v81, 16, v53
	v_and_b32_e32 v82, 0xffff0000, v53
	v_lshlrev_b32_e32 v47, 16, v52
	v_and_b32_e32 v52, 0xffff0000, v52
	v_lshlrev_b32_e32 v108, 16, v54
	v_and_b32_e32 v83, 0xffff0000, v54
	v_sub_f32_e32 v55, v82, v46
	v_sub_f32_e32 v54, v81, v46
	v_sub_f32_e32 v53, v52, v46
	v_sub_f32_e32 v52, v47, v46
	v_pk_mul_f32 v[54:55], v[80:81], v[54:55] op_sel_hi:[0,1]
	v_sub_f32_e32 v83, v83, v46
	v_sub_f32_e32 v82, v108, v46
	v_sub_f32_e32 v108, v110, v46
	v_pk_mul_f32 v[52:53], v[80:81], v[52:53] op_sel_hi:[0,1]
	v_pk_fma_f32 v[54:55], v[98:99], v[54:55], v[102:103]
	v_pk_mul_f32 v[108:109], v[80:81], v[108:109] op_sel_hi:[0,1]
	v_pk_mul_f32 v[82:83], v[80:81], v[82:83] op_sel_hi:[0,1]
	v_pk_fma_f32 v[52:53], v[96:97], v[52:53], v[100:101]
	v_pk_fma_f32 v[82:83], v[88:89], v[82:83], v[92:93]
	v_pk_fma_f32 v[108:109], v[90:91], v[108:109], v[94:95]
	v_pk_fma_f32 v[30:31], v[54:55], s[38:39], v[30:31] op_sel_hi:[1,0,1]
	v_pk_fma_f32 v[28:29], v[52:53], s[38:39], v[28:29] op_sel_hi:[1,0,1]
	v_pk_fma_f32 v[52:53], v[108:109], s[38:39], v[26:27] op_sel_hi:[1,0,1]
	v_pk_fma_f32 v[26:27], v[82:83], s[38:39], v[24:25] op_sel_hi:[1,0,1]
	v_cvt_pk_bf16_f32 v25, v30, v31
	v_lshlrev_b32_e32 v30, 16, v48
	v_and_b32_e32 v31, 0xffff0000, v48
	v_cvt_pk_bf16_f32 v26, v26, v27
	v_cvt_pk_bf16_f32 v27, v52, v53
	v_lshlrev_b32_e32 v47, 16, v49
	v_and_b32_e32 v48, 0xffff0000, v49
	v_lshlrev_b32_e32 v52, 16, v50
	v_and_b32_e32 v50, 0xffff0000, v50
	v_lshlrev_b32_e32 v53, 16, v51
	v_and_b32_e32 v54, 0xffff0000, v51
	v_sub_f32_e32 v31, v31, v46
	v_sub_f32_e32 v30, v30, v46
	v_sub_f32_e32 v49, v48, v46
	v_sub_f32_e32 v48, v47, v46
	v_pk_mul_f32 v[30:31], v[80:81], v[30:31] op_sel_hi:[0,1]
	v_sub_f32_e32 v51, v50, v46
	v_sub_f32_e32 v50, v52, v46
	v_sub_f32_e32 v47, v54, v46
	v_sub_f32_e32 v46, v53, v46
	v_pk_mul_f32 v[48:49], v[80:81], v[48:49] op_sel_hi:[0,1]
	v_pk_fma_f32 v[30:31], v[72:73], v[30:31], v[76:77]
	v_pk_mul_f32 v[46:47], v[80:81], v[46:47] op_sel_hi:[0,1]
	v_pk_mul_f32 v[50:51], v[80:81], v[50:51] op_sel_hi:[0,1]
	v_pk_fma_f32 v[48:49], v[74:75], v[48:49], v[78:79]
	v_pk_fma_f32 v[50:51], v[64:65], v[50:51], v[68:69]
	v_pk_fma_f32 v[46:47], v[66:67], v[46:47], v[70:71]
	v_pk_fma_f32 v[20:21], v[30:31], s[38:39], v[20:21] op_sel_hi:[1,0,1]
	v_cvt_pk_bf16_f32 v24, v28, v29
	v_lshl_add_u64 v[28:29], s[26:27], 0, v[56:57]
	v_pk_fma_f32 v[22:23], v[48:49], s[38:39], v[22:23] op_sel_hi:[1,0,1]
	v_pk_fma_f32 v[30:31], v[46:47], s[38:39], v[18:19] op_sel_hi:[1,0,1]
	v_pk_fma_f32 v[18:19], v[50:51], s[38:39], v[16:17] op_sel_hi:[1,0,1]
	v_cvt_pk_bf16_f32 v16, v20, v21
	v_lshl_add_u64 v[28:29], v[28:29], 0, v[200:201]
	v_cvt_pk_bf16_f32 v17, v22, v23
	v_cvt_pk_bf16_f32 v18, v18, v19
	v_cvt_pk_bf16_f32 v19, v30, v31
	v_lshlrev_b32_e32 v21, 16, v24
	v_lshlrev_b32_e32 v20, 16, v16
	v_and_b32_e32 v23, 0xffff0000, v24
	v_and_b32_e32 v22, 0xffff0000, v16
	global_store_dwordx4 v[28:29], v[24:27], off
	global_store_dwordx4 v[28:29], v[16:19], off offset:256
	v_lshlrev_b32_e32 v29, 16, v25
	v_lshlrev_b32_e32 v28, 16, v17
	v_and_b32_e32 v25, 0xffff0000, v25
	v_and_b32_e32 v24, 0xffff0000, v17
	v_lshlrev_b32_e32 v17, 16, v26
	v_lshlrev_b32_e32 v16, 16, v18
	v_and_b32_e32 v31, 0xffff0000, v26
	v_and_b32_e32 v30, 0xffff0000, v18
	v_lshlrev_b32_e32 v46, 16, v19
	v_and_b32_e32 v26, 0xffff0000, v19
	v_pk_add_f32 v[18:19], v[20:21], v[22:23]
	v_pk_mul_f32 v[22:23], v[22:23], v[22:23]
	v_pk_add_f32 v[48:49], v[28:29], v[24:25]
	v_pk_fma_f32 v[20:21], v[20:21], v[20:21], v[22:23]
	v_pk_mul_f32 v[22:23], v[24:25], v[24:25]
	s_waitcnt vmcnt(3)
	v_pk_mul_f32 v[24:25], v[62:63], s[36:37] op_sel_hi:[1,0]
	v_pk_fma_f32 v[22:23], v[28:29], v[28:29], v[22:23]
	v_fma_f32 v25, -v24, v24, v25
	v_add_f32_e32 v25, 0x3727c5ac, v25
	v_lshlrev_b32_e32 v47, 16, v27
	v_and_b32_e32 v27, 0xffff0000, v27
	v_pk_add_f32 v[20:21], v[20:21], v[22:23]
	v_pk_mul_f32 v[22:23], v[30:31], v[30:31]
	v_pk_add_f32 v[18:19], v[18:19], v[48:49]
	v_pk_add_f32 v[48:49], v[16:17], v[30:31]
	v_pk_add_f32 v[50:51], v[46:47], v[26:27]
	v_pk_fma_f32 v[16:17], v[16:17], v[16:17], v[22:23]
	v_pk_mul_f32 v[22:23], v[26:27], v[26:27]
	v_pk_fma_f32 v[22:23], v[46:47], v[46:47], v[22:23]
	v_pk_add_f32 v[16:17], v[16:17], v[22:23]
	s_waitcnt vmcnt(2)
	v_lshlrev_b32_e32 v28, 16, v60
	v_pk_add_f32 v[16:17], v[20:21], v[16:17]
	v_and_b32_e32 v29, 0xffff0000, v60
	v_lshlrev_b32_e32 v30, 16, v61
	v_and_b32_e32 v31, 0xffff0000, v61
	v_sub_f32_e32 v29, v29, v24
	v_lshlrev_b32_e32 v21, 16, v58
	v_and_b32_e32 v22, 0xffff0000, v58
	v_rsq_f32_e32 v20, v25
	v_lshlrev_b32_e32 v25, 16, v59
	v_and_b32_e32 v26, 0xffff0000, v59
	v_sub_f32_e32 v23, v22, v24
	v_sub_f32_e32 v22, v21, v24
	v_sub_f32_e32 v28, v28, v24
	v_sub_f32_e32 v31, v31, v24
	v_sub_f32_e32 v30, v30, v24
	v_sub_f32_e32 v27, v26, v24
	v_sub_f32_e32 v26, v25, v24
	v_pk_mul_f32 v[22:23], v[20:21], v[22:23] op_sel_hi:[0,1]
	v_pk_mul_f32 v[30:31], v[20:21], v[30:31] op_sel_hi:[0,1]
	v_pk_mul_f32 v[28:29], v[20:21], v[28:29] op_sel_hi:[0,1]
	v_pk_mul_f32 v[26:27], v[20:21], v[26:27] op_sel_hi:[0,1]
	v_pk_fma_f32 v[22:23], v[96:97], v[22:23], v[100:101]
	v_pk_fma_f32 v[28:29], v[88:89], v[28:29], v[92:93]
	v_pk_fma_f32 v[30:31], v[90:91], v[30:31], v[94:95]
	v_pk_fma_f32 v[26:27], v[98:99], v[26:27], v[102:103]
	v_pk_fma_f32 v[12:13], v[22:23], s[38:39], v[12:13] op_sel_hi:[1,0,1]
	v_pk_fma_f32 v[22:23], v[30:31], s[38:39], v[10:11] op_sel_hi:[1,0,1]
	v_pk_fma_f32 v[10:11], v[28:29], s[38:39], v[8:9] op_sel_hi:[1,0,1]
	v_pk_fma_f32 v[14:15], v[26:27], s[38:39], v[14:15] op_sel_hi:[1,0,1]
	v_cvt_pk_bf16_f32 v8, v12, v13
	v_cvt_pk_bf16_f32 v10, v10, v11
	v_cvt_pk_bf16_f32 v9, v14, v15
	v_cvt_pk_bf16_f32 v11, v22, v23
	v_lshlrev_b32_e32 v15, 16, v10
	v_lshlrev_b32_e32 v14, 16, v8
	v_and_b32_e32 v23, 0xffff0000, v10
	v_and_b32_e32 v22, 0xffff0000, v8
	v_and_b32_e32 v29, 0xffff0000, v11
	v_and_b32_e32 v28, 0xffff0000, v9
	v_pk_add_f32 v[30:31], v[14:15], v[22:23]
	v_pk_mul_f32 v[22:23], v[22:23], v[22:23]
	v_lshlrev_b32_e32 v27, 16, v11
	v_lshlrev_b32_e32 v26, 16, v9
	v_pk_fma_f32 v[14:15], v[14:15], v[14:15], v[22:23]
	v_pk_mul_f32 v[22:23], v[28:29], v[28:29]
	v_lshl_add_u64 v[12:13], s[26:27], 0, v[44:45]
	v_pk_add_f32 v[44:45], v[26:27], v[28:29]
	v_pk_fma_f32 v[22:23], v[26:27], v[26:27], v[22:23]
	v_pk_add_f32 v[30:31], v[30:31], v[44:45]
	v_pk_add_f32 v[14:15], v[14:15], v[22:23]
	v_pk_add_f32 v[30:31], v[30:31], v[30:31] op_sel_hi:[0,1]
	v_pk_add_f32 v[14:15], v[14:15], v[14:15] op_sel_hi:[0,1]
	v_lshlrev_b32_e32 v14, 16, v32
	v_and_b32_e32 v21, 0xffff0000, v32
	v_lshlrev_b32_e32 v25, 16, v33
	v_and_b32_e32 v26, 0xffff0000, v33
	v_lshlrev_b32_e32 v28, 16, v34
	v_and_b32_e32 v29, 0xffff0000, v34
	v_lshlrev_b32_e32 v30, 16, v35
	v_and_b32_e32 v32, 0xffff0000, v35
	v_sub_f32_e32 v23, v21, v24
	v_sub_f32_e32 v22, v14, v24
	v_sub_f32_e32 v27, v26, v24
	v_sub_f32_e32 v26, v25, v24
	v_sub_f32_e32 v29, v29, v24
	v_sub_f32_e32 v28, v28, v24
	v_sub_f32_e32 v25, v32, v24
	v_sub_f32_e32 v24, v30, v24
	v_pk_mul_f32 v[26:27], v[20:21], v[26:27] op_sel_hi:[0,1]
	v_pk_mul_f32 v[22:23], v[20:21], v[22:23] op_sel_hi:[0,1]
	v_pk_mul_f32 v[24:25], v[20:21], v[24:25] op_sel_hi:[0,1]
	v_pk_mul_f32 v[20:21], v[20:21], v[28:29] op_sel_hi:[0,1]
	v_pk_fma_f32 v[22:23], v[72:73], v[22:23], v[76:77]
	v_pk_fma_f32 v[20:21], v[64:65], v[20:21], v[68:69]
	v_pk_fma_f32 v[24:25], v[66:67], v[24:25], v[70:71]
	v_pk_fma_f32 v[26:27], v[74:75], v[26:27], v[78:79]
	v_pk_fma_f32 v[4:5], v[22:23], s[38:39], v[4:5] op_sel_hi:[1,0,1]
	v_pk_fma_f32 v[22:23], v[24:25], s[38:39], v[2:3] op_sel_hi:[1,0,1]
	v_pk_fma_f32 v[2:3], v[20:21], s[38:39], v[0:1] op_sel_hi:[1,0,1]
	v_pk_fma_f32 v[6:7], v[26:27], s[38:39], v[6:7] op_sel_hi:[1,0,1]
	v_cvt_pk_bf16_f32 v0, v4, v5
	v_cvt_pk_bf16_f32 v2, v2, v3
	v_cvt_pk_bf16_f32 v1, v6, v7
	v_cvt_pk_bf16_f32 v3, v22, v23
	v_lshlrev_b32_e32 v5, 16, v2
	v_lshlrev_b32_e32 v4, 16, v0
	v_and_b32_e32 v7, 0xffff0000, v2
	v_and_b32_e32 v6, 0xffff0000, v0
	v_lshlrev_b32_e32 v21, 16, v3
	v_lshlrev_b32_e32 v20, 16, v1
	v_and_b32_e32 v23, 0xffff0000, v3
	v_and_b32_e32 v22, 0xffff0000, v1
	v_pk_add_f32 v[24:25], v[4:5], v[6:7]
	v_pk_mul_f32 v[6:7], v[6:7], v[6:7]
	v_pk_add_f32 v[48:49], v[48:49], v[50:51]
	v_pk_add_f32 v[26:27], v[20:21], v[22:23]
	v_pk_fma_f32 v[4:5], v[4:5], v[4:5], v[6:7]
	v_pk_mul_f32 v[6:7], v[22:23], v[22:23]
	v_pk_add_f32 v[18:19], v[18:19], v[48:49]
	v_pk_add_f32 v[24:25], v[24:25], v[26:27]
	v_pk_fma_f32 v[6:7], v[20:21], v[20:21], v[6:7]
	v_pk_add_f32 v[24:25], v[24:25], v[24:25] op_sel_hi:[0,1]
	v_pk_add_f32 v[4:5], v[4:5], v[6:7]
	v_mov_b32_e32 v30, v19
	v_pk_add_f32 v[4:5], v[4:5], v[4:5] op_sel_hi:[0,1]
	v_pk_add_f32 v[6:7], v[30:31], 0 op_sel_hi:[1,0]
	v_mov_b32_e32 v19, v25
	v_pk_add_f32 v[6:7], v[18:19], v[6:7]
	v_mov_b32_e32 v4, v16
	v_mov_b32_e32 v14, v17
	ds_bpermute_b32 v18, v216, v6
	ds_bpermute_b32 v19, v216, v7
	v_pk_add_f32 v[4:5], v[4:5], v[14:15]
	ds_bpermute_b32 v14, v216, v4
	ds_bpermute_b32 v15, v216, v5
	v_lshl_add_u64 v[12:13], v[12:13], 0, v[200:201]
	global_store_dwordx4 v[12:13], v[8:11], off
	global_store_dwordx4 v[12:13], v[0:3], off offset:256
	ds_bpermute_b32 v39, v199, v37
	s_waitcnt lgkmcnt(1)
	v_pk_add_f32 v[4:5], v[4:5], v[14:15]
	v_pk_add_f32 v[0:1], v[6:7], v[18:19]
	ds_bpermute_b32 v2, v199, v0
	ds_bpermute_b32 v3, v199, v1
	ds_bpermute_b32 v6, v199, v4
	ds_bpermute_b32 v7, v199, v5
	v_pk_add_f32 v[8:9], v[136:137], v[138:139]
	v_pk_add_f32 v[10:11], v[104:105], v[106:107]
	s_waitcnt lgkmcnt(2)
	v_pk_add_f32 v[0:1], v[0:1], v[2:3]
	v_pk_add_f32 v[2:3], v[132:133], v[134:135]
	v_pk_add_f32 v[14:15], v[84:85], v[86:87]
	s_waitcnt lgkmcnt(0)
	v_pk_add_f32 v[4:5], v[4:5], v[6:7]
	v_cndmask_b32_e64 v3, v3, v9, s[4:5]
	v_cndmask_b32_e64 v2, v2, v8, s[4:5]
	v_cmp_ne_u64_e32 vcc, 0, v[180:181]
	v_cndmask_b32_e64 v4, v4, v0, s[4:5]
	v_cndmask_b32_e64 v10, v14, v10, s[4:5]
	v_cndmask_b32_e32 v0, v2, v3, vcc
	v_cmp_eq_u32_e32 vcc, 2, v180
	v_pk_add_f32 v[12:13], v[40:41], v[42:43]
	v_pk_add_f32 v[16:17], v[36:37], v[38:39]
	v_cndmask_b32_e64 v11, v15, v11, s[4:5]
	v_cndmask_b32_e32 v0, v0, v10, vcc
	v_cmp_eq_u32_e32 vcc, 3, v180
	v_cndmask_b32_e64 v7, v16, v12, s[4:5]
	v_cndmask_b32_e64 v6, v17, v13, s[4:5]
	v_cndmask_b32_e32 v0, v0, v11, vcc
	v_cmp_eq_u32_e32 vcc, 4, v180
	v_cndmask_b32_e64 v5, v5, v1, s[4:5]
	s_mov_b64 s[0:1], -1
	v_cndmask_b32_e32 v0, v0, v7, vcc
	v_cmp_eq_u32_e32 vcc, 5, v180
	s_nop 1
	v_cndmask_b32_e32 v0, v0, v6, vcc
	v_cmp_eq_u32_e32 vcc, 6, v180
	s_nop 1
	v_cndmask_b32_e32 v0, v0, v4, vcc
	v_cmp_eq_u32_e32 vcc, 7, v180
	s_nop 1
	v_cndmask_b32_e32 v8, v0, v5, vcc
	v_or_b32_e32 v0, v198, v183
	v_ashrrev_i32_e32 v1, 31, v0
	v_lshl_add_u64 v[0:1], v[0:1], 3, v[188:189]
	v_cmp_eq_u32_e32 vcc, 1, v182
	global_atomic_add_f32 v[0:1], v8, off
	s_nop 0
	v_cndmask_b32_e32 v0, v2, v3, vcc
	v_cmp_eq_u32_e32 vcc, 2, v182
	s_nop 1
	v_cndmask_b32_e32 v0, v0, v10, vcc
	v_cmp_eq_u32_e32 vcc, 3, v182
	s_nop 1
	v_cndmask_b32_e32 v0, v0, v11, vcc
	v_cmp_eq_u32_e32 vcc, 4, v182
	s_nop 1
	v_cndmask_b32_e32 v0, v0, v7, vcc
	v_cmp_eq_u32_e32 vcc, 5, v182
	s_nop 1
	v_cndmask_b32_e32 v0, v0, v6, vcc
	v_cmp_eq_u32_e32 vcc, 6, v182
	s_nop 1
	v_cndmask_b32_e32 v0, v0, v4, vcc
	v_cmp_eq_u32_e32 vcc, 7, v182
	s_nop 1
	v_cndmask_b32_e32 v8, v0, v5, vcc
	v_or_b32_e32 v0, v198, v185
	v_ashrrev_i32_e32 v1, 31, v0
	v_lshl_add_u64 v[0:1], v[0:1], 3, v[188:189]
	v_cmp_eq_u32_e32 vcc, 1, v184
	global_atomic_add_f32 v[0:1], v8, off
	s_nop 0
	v_cndmask_b32_e32 v0, v2, v3, vcc
	v_cmp_eq_u32_e32 vcc, 2, v184
	s_nop 1
	v_cndmask_b32_e32 v0, v0, v10, vcc
	v_cmp_eq_u32_e32 vcc, 3, v184
	s_nop 1
	v_cndmask_b32_e32 v0, v0, v11, vcc
	v_cmp_eq_u32_e32 vcc, 4, v184
	s_nop 1
	v_cndmask_b32_e32 v0, v0, v7, vcc
	v_cmp_eq_u32_e32 vcc, 5, v184
	s_nop 1
	v_cndmask_b32_e32 v0, v0, v6, vcc
	v_cmp_eq_u32_e32 vcc, 6, v184
	s_nop 1
	v_cndmask_b32_e32 v0, v0, v4, vcc
	v_cmp_eq_u32_e32 vcc, 7, v184
	s_nop 1
	v_cndmask_b32_e32 v8, v0, v5, vcc
	v_add_u32_e32 v0, v198, v187
	v_ashrrev_i32_e32 v1, 31, v0
	v_lshl_add_u64 v[0:1], v[0:1], 3, v[188:189]
	v_cmp_eq_u32_e32 vcc, 1, v186
	global_atomic_add_f32 v[0:1], v8, off
	s_nop 0
	v_cndmask_b32_e32 v0, v2, v3, vcc
	v_cmp_eq_u32_e32 vcc, 2, v186
	s_nop 1
	v_cndmask_b32_e32 v0, v0, v10, vcc
	v_cmp_eq_u32_e32 vcc, 3, v186
	s_nop 1
	v_cndmask_b32_e32 v0, v0, v11, vcc
	v_cmp_eq_u32_e32 vcc, 4, v186
	s_nop 1
	v_cndmask_b32_e32 v0, v0, v7, vcc
	v_cmp_eq_u32_e32 vcc, 5, v186
	s_nop 1
	v_cndmask_b32_e32 v0, v0, v6, vcc
	v_cmp_eq_u32_e32 vcc, 6, v186
	s_nop 1
	v_cndmask_b32_e32 v0, v0, v4, vcc
	v_cmp_eq_u32_e32 vcc, 7, v186
	s_nop 1
	v_cndmask_b32_e32 v2, v0, v5, vcc
	v_add_u32_e32 v0, v198, v208
	v_ashrrev_i32_e32 v1, 31, v0
	v_lshl_add_u64 v[0:1], v[0:1], 3, v[188:189]
	global_atomic_add_f32 v[0:1], v2, off
	s_and_b64 vcc, exec, s[6:7]
	s_cbranch_vccnz .LBB0_998
	s_andn2_b64 vcc, exec, s[8:9]
	s_cbranch_vccnz .LBB0_997
	s_barrier
	s_branch .LBB0_997

.LBB0_1086:
	v_lshl_add_u32 v188, s4, 8, v169
	v_ashrrev_i32_e32 v189, 31, v188
	v_lshl_add_u64 v[128:129], v[188:189], 3, s[28:29]
	global_load_dwordx2 v[182:183], v[128:129], off
	v_or_b32_e32 v194, 16, v188
	v_ashrrev_i32_e32 v195, 31, v194
	v_or_b32_e32 v192, 32, v188
	v_lshl_add_u64 v[128:129], v[194:195], 3, s[28:29]
	v_ashrrev_i32_e32 v193, 31, v192
	v_lshl_add_u64 v[130:131], v[192:193], 3, s[28:29]
	global_load_dwordx2 v[190:191], v[128:129], off
	global_load_dwordx2 v[196:197], v[130:131], off
	v_lshl_or_b32 v212, s5, 8, v187
	v_ashrrev_i32_e32 v213, 31, v212
	v_or_b32_e32 v184, 48, v188
	v_add_u32_e32 v180, 0x80, v188
	v_lshlrev_b64 v[128:129], 2, v[212:213]
	v_ashrrev_i32_e32 v185, 31, v184
	v_ashrrev_i32_e32 v181, 31, v180
	v_lshl_add_u64 v[130:131], s[30:31], 0, v[128:129]
	v_lshl_add_u64 v[136:137], s[34:35], 0, v[128:129]
	v_lshl_add_u64 v[200:201], v[184:185], 3, s[28:29]
	v_lshl_add_u64 v[202:203], v[180:181], 3, s[28:29]
	global_load_dwordx4 v[148:151], v[130:131], off offset:16
	global_load_dwordx4 v[156:159], v[130:131], off
	global_load_dwordx4 v[144:147], v[136:137], off offset:16
	global_load_dwordx4 v[152:155], v[136:137], off
	global_load_dwordx4 v[132:135], v[130:131], off offset:528
	global_load_dwordx4 v[140:143], v[130:131], off offset:512
	s_nop 0
	global_load_dwordx4 v[128:131], v[136:137], off offset:528
	s_nop 0
	global_load_dwordx4 v[136:139], v[136:137], off offset:512
	s_nop 0
	global_load_dwordx2 v[200:201], v[200:201], off
	s_nop 0
	global_load_dwordx2 v[206:207], v[202:203], off
	v_lshlrev_b64 v[212:213], 1, v[212:213]
	s_waitcnt vmcnt(0)
	v_pk_mul_f32 v[218:219], v[182:183], s[40:41] op_sel_hi:[1,0]
	s_nop 0
	v_fma_f32 v182, -v218, v218, v219
	v_add_f32_e32 v182, 0x3727c5ac, v182
	v_pk_mul_f32 v[208:209], v[190:191], s[40:41] op_sel_hi:[1,0]
	v_pk_mul_f32 v[196:197], v[196:197], s[40:41] op_sel_hi:[1,0]
	v_fma_f32 v183, -v208, v208, v209
	v_fma_f32 v186, -v196, v196, v197
	v_add_f32_e32 v183, 0x3727c5ac, v183
	v_add_f32_e32 v186, 0x3727c5ac, v186
	v_pk_mul_f32 v[206:207], v[206:207], s[40:41] op_sel_hi:[1,0]
	s_nop 0
	v_rsq_f32_e32 v222, v182
	v_rsq_f32_e32 v214, v183
	v_pk_mul_f32 v[202:203], v[200:201], s[40:41] op_sel_hi:[1,0]
	v_fma_f32 v200, -v202, v202, v203
	v_add_f32_e32 v200, 0x3727c5ac, v200
	v_rsq_f32_e32 v216, v200
	v_add_u32_e32 v182, 0x90, v188
	v_ashrrev_i32_e32 v183, 31, v182
	v_lshl_add_u64 v[182:183], v[182:183], 3, s[28:29]
	global_load_dwordx2 v[182:183], v[182:183], off
	v_rsq_f32_e32 v220, v186
	v_pk_fma_f32 v[104:105], v[148:149], v[208:209], v[104:105] op_sel_hi:[1,0,1] neg_lo:[1,0,0] neg_hi:[1,0,0]
	v_pk_fma_f32 v[108:109], v[156:157], v[208:209], v[108:109] op_sel_hi:[1,0,1] neg_lo:[1,0,0] neg_hi:[1,0,0]
	v_pk_fma_f32 v[104:105], v[104:105], v[214:215], v[144:145] op_sel_hi:[1,0,1]
	v_add_u32_e32 v190, 0xa0, v188
	v_ashrrev_i32_e32 v191, 31, v190
	v_lshl_add_u64 v[190:191], v[190:191], 3, s[28:29]
	global_load_dwordx2 v[190:191], v[190:191], off
	v_add_u32_e32 v200, 0xb0, v188
	v_ashrrev_i32_e32 v201, 31, v200
	v_lshl_add_u64 v[200:201], v[200:201], 3, s[28:29]
	global_load_dwordx2 v[224:225], v[200:201], off
	v_fma_f32 v200, -v206, v206, v207
	v_add_f32_e32 v200, 0x3727c5ac, v200
	v_rsq_f32_e32 v210, v200
	v_lshlrev_b64 v[188:189], 13, v[188:189]
	v_lshl_add_u64 v[188:189], s[24:25], 0, v[188:189]
	v_lshl_add_u64 v[188:189], v[188:189], 0, v[212:213]
	v_pk_fma_f32 v[108:109], v[108:109], v[214:215], v[152:153] op_sel_hi:[1,0,1]
	v_max_f32_e32 v104, 0, v104
	s_waitcnt vmcnt(2)
	v_pk_mul_f32 v[200:201], v[182:183], s[40:41] op_sel_hi:[1,0]
	v_fma_f32 v182, -v200, v200, v201
	v_add_f32_e32 v182, 0x3727c5ac, v182
	v_max_f32_e32 v105, 0, v105
	v_max_f32_e32 v108, 0, v108
	v_max_f32_e32 v109, 0, v109
	v_pk_fma_f32 v[96:97], v[132:133], v[208:209], v[96:97] op_sel_hi:[1,0,1] neg_lo:[1,0,0] neg_hi:[1,0,0]
	v_pk_mul_f32 v[108:109], v[108:109], v[108:109]
	s_waitcnt vmcnt(1)
	v_pk_mul_f32 v[190:191], v[190:191], s[40:41] op_sel_hi:[1,0]
	v_pk_fma_f32 v[100:101], v[140:141], v[208:209], v[100:101] op_sel_hi:[1,0,1] neg_lo:[1,0,0] neg_hi:[1,0,0]
	v_fma_f32 v204, -v190, v190, v191
	v_add_f32_e32 v204, 0x3727c5ac, v204
	v_rsq_f32_e32 v198, v204
	v_pk_fma_f32 v[96:97], v[96:97], v[214:215], v[128:129] op_sel_hi:[1,0,1]
	v_pk_fma_f32 v[100:101], v[100:101], v[214:215], v[136:137] op_sel_hi:[1,0,1]
	v_max_f32_e32 v96, 0, v96
	v_max_f32_e32 v97, 0, v97
	v_rsq_f32_e32 v204, v182
	s_waitcnt vmcnt(0)
	v_pk_mul_f32 v[182:183], v[224:225], s[40:41] op_sel_hi:[1,0]
	v_fma_f32 v224, -v182, v182, v183
	v_add_f32_e32 v224, 0x3727c5ac, v224
	v_rsq_f32_e32 v186, v224
	v_max_f32_e32 v100, 0, v100
	v_max_f32_e32 v101, 0, v101
	v_pk_fma_f32 v[88:89], v[148:149], v[196:197], v[88:89] op_sel_hi:[1,0,1] neg_lo:[1,0,0] neg_hi:[1,0,0]
	v_pk_mul_f32 v[100:101], v[100:101], v[100:101]
	v_pk_fma_f32 v[92:93], v[156:157], v[196:197], v[92:93] op_sel_hi:[1,0,1] neg_lo:[1,0,0] neg_hi:[1,0,0]
	v_pk_fma_f32 v[88:89], v[88:89], v[220:221], v[144:145] op_sel_hi:[1,0,1]
	v_pk_fma_f32 v[92:93], v[92:93], v[220:221], v[152:153] op_sel_hi:[1,0,1]
	v_max_f32_e32 v88, 0, v88
	v_pk_fma_f32 v[224:225], v[156:157], v[218:219], v[124:125] op_sel_hi:[1,0,1] neg_lo:[1,0,0] neg_hi:[1,0,0]
	v_xor_b32_e32 v125, 0x80000000, v159
	v_xor_b32_e32 v124, 0x80000000, v158
	v_pk_fma_f32 v[158:159], v[224:225], v[222:223], v[152:153] op_sel_hi:[1,0,1]
	v_pk_fma_f32 v[224:225], v[148:149], v[218:219], v[120:121] op_sel_hi:[1,0,1] neg_lo:[1,0,0] neg_hi:[1,0,0]
	v_xor_b32_e32 v121, 0x80000000, v151
	v_xor_b32_e32 v120, 0x80000000, v150
	v_pk_fma_f32 v[126:127], v[124:125], v[218:219], v[126:127] op_sel_hi:[1,0,1]
	v_pk_fma_f32 v[122:123], v[120:121], v[218:219], v[122:123] op_sel_hi:[1,0,1]
	v_pk_fma_f32 v[126:127], v[126:127], v[222:223], v[154:155] op_sel_hi:[1,0,1]
	v_pk_fma_f32 v[122:123], v[122:123], v[222:223], v[146:147] op_sel_hi:[1,0,1]
	v_max_f32_e32 v126, 0, v126
	v_max_f32_e32 v122, 0, v122
	v_max_f32_e32 v127, 0, v127
	v_max_f32_e32 v123, 0, v123
	v_pk_mul_f32 v[126:127], v[126:127], v[126:127]
	v_pk_mul_f32 v[122:123], v[122:123], v[122:123]
	v_pk_fma_f32 v[150:151], v[224:225], v[222:223], v[144:145] op_sel_hi:[1,0,1]
	v_cvt_pk_bf16_f32 v225, v126, v127
	v_cvt_pk_bf16_f32 v227, v122, v123
	v_pk_fma_f32 v[122:123], v[140:141], v[218:219], v[116:117] op_sel_hi:[1,0,1] neg_lo:[1,0,0] neg_hi:[1,0,0]
	v_xor_b32_e32 v117, 0x80000000, v143
	v_xor_b32_e32 v116, 0x80000000, v142
	v_pk_fma_f32 v[126:127], v[132:133], v[218:219], v[112:113] op_sel_hi:[1,0,1] neg_lo:[1,0,0] neg_hi:[1,0,0]
	v_xor_b32_e32 v113, 0x80000000, v135
	v_xor_b32_e32 v112, 0x80000000, v134
	v_pk_fma_f32 v[118:119], v[116:117], v[218:219], v[118:119] op_sel_hi:[1,0,1]
	v_pk_fma_f32 v[114:115], v[112:113], v[218:219], v[114:115] op_sel_hi:[1,0,1]
	v_max_f32_e32 v158, 0, v158
	v_max_f32_e32 v150, 0, v150
	v_max_f32_e32 v159, 0, v159
	v_max_f32_e32 v151, 0, v151
	v_pk_fma_f32 v[118:119], v[118:119], v[222:223], v[138:139] op_sel_hi:[1,0,1]
	v_pk_fma_f32 v[114:115], v[114:115], v[222:223], v[130:131] op_sel_hi:[1,0,1]
	v_pk_mul_f32 v[158:159], v[158:159], v[158:159]
	v_pk_mul_f32 v[150:151], v[150:151], v[150:151]
	v_pk_fma_f32 v[122:123], v[122:123], v[222:223], v[136:137] op_sel_hi:[1,0,1]
	v_max_f32_e32 v118, 0, v118
	v_max_f32_e32 v114, 0, v114
	v_max_f32_e32 v119, 0, v119
	v_max_f32_e32 v115, 0, v115
	v_pk_fma_f32 v[110:111], v[124:125], v[208:209], v[110:111] op_sel_hi:[1,0,1]
	v_pk_fma_f32 v[106:107], v[120:121], v[208:209], v[106:107] op_sel_hi:[1,0,1]
	v_cvt_pk_bf16_f32 v224, v158, v159
	v_cvt_pk_bf16_f32 v226, v150, v151
	v_max_f32_e32 v122, 0, v122
	v_max_f32_e32 v123, 0, v123
	v_pk_mul_f32 v[118:119], v[118:119], v[118:119]
	v_pk_mul_f32 v[114:115], v[114:115], v[114:115]
	v_pk_fma_f32 v[110:111], v[110:111], v[214:215], v[154:155] op_sel_hi:[1,0,1]
	v_pk_fma_f32 v[106:107], v[106:107], v[214:215], v[146:147] op_sel_hi:[1,0,1]
	global_store_dwordx4 v[188:189], v[224:227], off nt
	v_pk_fma_f32 v[126:127], v[126:127], v[222:223], v[128:129] op_sel_hi:[1,0,1]
	v_pk_mul_f32 v[122:123], v[122:123], v[122:123]
	v_cvt_pk_bf16_f32 v223, v118, v119
	v_cvt_pk_bf16_f32 v225, v114, v115
	v_lshlrev_b64 v[114:115], 13, v[194:195]
	v_pk_mul_f32 v[118:119], v[104:105], v[104:105]
	v_max_f32_e32 v104, 0, v110
	v_max_f32_e32 v106, 0, v106
	v_max_f32_e32 v105, 0, v111
	v_max_f32_e32 v107, 0, v107
	v_cvt_pk_bf16_f32 v222, v122, v123
	v_lshl_add_u64 v[114:115], s[24:25], 0, v[114:115]
	v_pk_mul_f32 v[110:111], v[104:105], v[104:105]
	v_pk_mul_f32 v[122:123], v[106:107], v[106:107]
	v_pk_fma_f32 v[102:103], v[116:117], v[208:209], v[102:103] op_sel_hi:[1,0,1]
	v_pk_fma_f32 v[98:99], v[112:113], v[208:209], v[98:99] op_sel_hi:[1,0,1]
	v_lshl_add_u64 v[114:115], v[114:115], 0, v[212:213]
	v_cvt_pk_bf16_f32 v104, v108, v109
	v_cvt_pk_bf16_f32 v105, v110, v111
	v_cvt_pk_bf16_f32 v106, v118, v119
	v_cvt_pk_bf16_f32 v107, v122, v123
	v_pk_fma_f32 v[102:103], v[102:103], v[214:215], v[138:139] op_sel_hi:[1,0,1]
	v_pk_fma_f32 v[98:99], v[98:99], v[214:215], v[130:131] op_sel_hi:[1,0,1]
	global_store_dwordx4 v[114:115], v[104:107], off nt
	v_max_f32_e32 v98, 0, v98
	v_max_f32_e32 v99, 0, v99
	v_pk_mul_f32 v[104:105], v[96:97], v[96:97]
	v_max_f32_e32 v96, 0, v102
	v_max_f32_e32 v97, 0, v103
	v_pk_mul_f32 v[102:103], v[96:97], v[96:97]
	v_pk_mul_f32 v[106:107], v[98:99], v[98:99]
	v_pk_fma_f32 v[94:95], v[124:125], v[196:197], v[94:95] op_sel_hi:[1,0,1]
	v_pk_fma_f32 v[90:91], v[120:121], v[196:197], v[90:91] op_sel_hi:[1,0,1]
	v_cvt_pk_bf16_f32 v96, v100, v101
	v_cvt_pk_bf16_f32 v97, v102, v103
	v_cvt_pk_bf16_f32 v98, v104, v105
	v_cvt_pk_bf16_f32 v99, v106, v107
	v_pk_fma_f32 v[94:95], v[94:95], v[220:221], v[154:155] op_sel_hi:[1,0,1]
	v_pk_fma_f32 v[90:91], v[90:91], v[220:221], v[146:147] op_sel_hi:[1,0,1]
	v_max_f32_e32 v89, 0, v89
	global_store_dwordx4 v[114:115], v[96:99], off offset:256 nt
	v_max_f32_e32 v92, 0, v92
	v_max_f32_e32 v93, 0, v93
	v_lshlrev_b64 v[96:97], 13, v[192:193]
	v_pk_mul_f32 v[98:99], v[88:89], v[88:89]
	v_max_f32_e32 v88, 0, v94
	v_max_f32_e32 v90, 0, v90
	v_max_f32_e32 v89, 0, v95
	v_max_f32_e32 v91, 0, v91
	v_pk_fma_f32 v[80:81], v[132:133], v[196:197], v[80:81] op_sel_hi:[1,0,1] neg_lo:[1,0,0] neg_hi:[1,0,0]
	v_lshl_add_u64 v[96:97], s[24:25], 0, v[96:97]
	v_pk_mul_f32 v[92:93], v[92:93], v[92:93]
	v_pk_mul_f32 v[94:95], v[88:89], v[88:89]
	v_pk_mul_f32 v[100:101], v[90:91], v[90:91]
	v_pk_fma_f32 v[84:85], v[140:141], v[196:197], v[84:85] op_sel_hi:[1,0,1] neg_lo:[1,0,0] neg_hi:[1,0,0]
	v_pk_fma_f32 v[86:87], v[116:117], v[196:197], v[86:87] op_sel_hi:[1,0,1]
	v_pk_fma_f32 v[82:83], v[112:113], v[196:197], v[82:83] op_sel_hi:[1,0,1]
	v_pk_fma_f32 v[80:81], v[80:81], v[220:221], v[128:129] op_sel_hi:[1,0,1]
	v_lshl_add_u64 v[96:97], v[96:97], 0, v[212:213]
	v_cvt_pk_bf16_f32 v88, v92, v93
	v_cvt_pk_bf16_f32 v89, v94, v95
	v_cvt_pk_bf16_f32 v90, v98, v99
	v_cvt_pk_bf16_f32 v91, v100, v101
	v_pk_fma_f32 v[86:87], v[86:87], v[220:221], v[138:139] op_sel_hi:[1,0,1]
	v_pk_fma_f32 v[84:85], v[84:85], v[220:221], v[136:137] op_sel_hi:[1,0,1]
	v_pk_fma_f32 v[82:83], v[82:83], v[220:221], v[130:131] op_sel_hi:[1,0,1]
	v_max_f32_e32 v80, 0, v80
	v_max_f32_e32 v81, 0, v81
	global_store_dwordx4 v[96:97], v[88:91], off nt
	v_max_f32_e32 v84, 0, v84
	v_max_f32_e32 v85, 0, v85
	v_pk_mul_f32 v[88:89], v[80:81], v[80:81]
	v_max_f32_e32 v80, 0, v86
	v_max_f32_e32 v82, 0, v82
	v_max_f32_e32 v81, 0, v87
	v_max_f32_e32 v83, 0, v83
	v_pk_fma_f32 v[72:73], v[148:149], v[202:203], v[72:73] op_sel_hi:[1,0,1] neg_lo:[1,0,0] neg_hi:[1,0,0]
	v_pk_mul_f32 v[84:85], v[84:85], v[84:85]
	v_pk_mul_f32 v[86:87], v[80:81], v[80:81]
	v_pk_mul_f32 v[90:91], v[82:83], v[82:83]
	v_pk_fma_f32 v[76:77], v[156:157], v[202:203], v[76:77] op_sel_hi:[1,0,1] neg_lo:[1,0,0] neg_hi:[1,0,0]
	v_pk_fma_f32 v[78:79], v[124:125], v[202:203], v[78:79] op_sel_hi:[1,0,1]
	v_pk_fma_f32 v[74:75], v[120:121], v[202:203], v[74:75] op_sel_hi:[1,0,1]
	v_pk_fma_f32 v[72:73], v[72:73], v[216:217], v[144:145] op_sel_hi:[1,0,1]
	v_cvt_pk_bf16_f32 v80, v84, v85
	v_cvt_pk_bf16_f32 v81, v86, v87
	v_cvt_pk_bf16_f32 v82, v88, v89
	v_cvt_pk_bf16_f32 v83, v90, v91
	v_pk_fma_f32 v[78:79], v[78:79], v[216:217], v[154:155] op_sel_hi:[1,0,1]
	v_pk_fma_f32 v[76:77], v[76:77], v[216:217], v[152:153] op_sel_hi:[1,0,1]
	v_pk_fma_f32 v[74:75], v[74:75], v[216:217], v[146:147] op_sel_hi:[1,0,1]
	v_max_f32_e32 v72, 0, v72
	v_max_f32_e32 v73, 0, v73
	global_store_dwordx4 v[96:97], v[80:83], off offset:256 nt
	v_max_f32_e32 v76, 0, v76
	v_max_f32_e32 v77, 0, v77
	v_lshlrev_b64 v[80:81], 13, v[184:185]
	v_pk_mul_f32 v[82:83], v[72:73], v[72:73]
	v_max_f32_e32 v72, 0, v78
	v_max_f32_e32 v74, 0, v74
	v_max_f32_e32 v73, 0, v79
	v_max_f32_e32 v75, 0, v75
	v_pk_fma_f32 v[64:65], v[132:133], v[202:203], v[64:65] op_sel_hi:[1,0,1] neg_lo:[1,0,0] neg_hi:[1,0,0]
	v_lshl_add_u64 v[80:81], s[24:25], 0, v[80:81]
	v_pk_mul_f32 v[76:77], v[76:77], v[76:77]
	v_pk_mul_f32 v[78:79], v[72:73], v[72:73]
	v_pk_mul_f32 v[84:85], v[74:75], v[74:75]
	v_pk_fma_f32 v[68:69], v[140:141], v[202:203], v[68:69] op_sel_hi:[1,0,1] neg_lo:[1,0,0] neg_hi:[1,0,0]
	v_pk_fma_f32 v[70:71], v[116:117], v[202:203], v[70:71] op_sel_hi:[1,0,1]
	v_pk_fma_f32 v[66:67], v[112:113], v[202:203], v[66:67] op_sel_hi:[1,0,1]
	v_pk_fma_f32 v[64:65], v[64:65], v[216:217], v[128:129] op_sel_hi:[1,0,1]
	v_lshl_add_u64 v[80:81], v[80:81], 0, v[212:213]
	v_cvt_pk_bf16_f32 v72, v76, v77
	v_cvt_pk_bf16_f32 v73, v78, v79
	v_cvt_pk_bf16_f32 v74, v82, v83
	v_cvt_pk_bf16_f32 v75, v84, v85
	v_pk_fma_f32 v[70:71], v[70:71], v[216:217], v[138:139] op_sel_hi:[1,0,1]
	v_pk_fma_f32 v[68:69], v[68:69], v[216:217], v[136:137] op_sel_hi:[1,0,1]
	v_pk_fma_f32 v[66:67], v[66:67], v[216:217], v[130:131] op_sel_hi:[1,0,1]
	v_max_f32_e32 v64, 0, v64
	v_max_f32_e32 v65, 0, v65
	global_store_dwordx4 v[80:81], v[72:75], off nt
	v_max_f32_e32 v68, 0, v68
	v_max_f32_e32 v69, 0, v69
	v_pk_mul_f32 v[72:73], v[64:65], v[64:65]
	v_max_f32_e32 v64, 0, v70
	v_max_f32_e32 v66, 0, v66
	v_max_f32_e32 v65, 0, v71
	v_max_f32_e32 v67, 0, v67
	v_pk_fma_f32 v[56:57], v[148:149], v[206:207], v[56:57] op_sel_hi:[1,0,1] neg_lo:[1,0,0] neg_hi:[1,0,0]
	v_pk_mul_f32 v[68:69], v[68:69], v[68:69]
	v_pk_mul_f32 v[70:71], v[64:65], v[64:65]
	v_pk_mul_f32 v[74:75], v[66:67], v[66:67]
	v_pk_fma_f32 v[60:61], v[156:157], v[206:207], v[60:61] op_sel_hi:[1,0,1] neg_lo:[1,0,0] neg_hi:[1,0,0]
	v_pk_fma_f32 v[62:63], v[124:125], v[206:207], v[62:63] op_sel_hi:[1,0,1]
	v_pk_fma_f32 v[58:59], v[120:121], v[206:207], v[58:59] op_sel_hi:[1,0,1]
	v_pk_fma_f32 v[56:57], v[56:57], v[210:211], v[144:145] op_sel_hi:[1,0,1]
	v_cvt_pk_bf16_f32 v64, v68, v69
	v_cvt_pk_bf16_f32 v65, v70, v71
	v_cvt_pk_bf16_f32 v66, v72, v73
	v_cvt_pk_bf16_f32 v67, v74, v75
	v_pk_fma_f32 v[62:63], v[62:63], v[210:211], v[154:155] op_sel_hi:[1,0,1]
	v_pk_fma_f32 v[60:61], v[60:61], v[210:211], v[152:153] op_sel_hi:[1,0,1]
	v_pk_fma_f32 v[58:59], v[58:59], v[210:211], v[146:147] op_sel_hi:[1,0,1]
	v_max_f32_e32 v56, 0, v56
	v_max_f32_e32 v57, 0, v57
	global_store_dwordx4 v[80:81], v[64:67], off offset:256 nt
	v_max_f32_e32 v60, 0, v60
	v_max_f32_e32 v61, 0, v61
	v_lshlrev_b64 v[64:65], 13, v[180:181]
	v_pk_mul_f32 v[66:67], v[56:57], v[56:57]
	v_max_f32_e32 v56, 0, v62
	v_max_f32_e32 v58, 0, v58
	v_max_f32_e32 v57, 0, v63
	v_max_f32_e32 v59, 0, v59
	v_pk_fma_f32 v[48:49], v[132:133], v[206:207], v[48:49] op_sel_hi:[1,0,1] neg_lo:[1,0,0] neg_hi:[1,0,0]
	v_lshl_add_u64 v[64:65], s[24:25], 0, v[64:65]
	v_pk_mul_f32 v[60:61], v[60:61], v[60:61]
	v_pk_mul_f32 v[62:63], v[56:57], v[56:57]
	v_pk_mul_f32 v[68:69], v[58:59], v[58:59]
	v_pk_fma_f32 v[52:53], v[140:141], v[206:207], v[52:53] op_sel_hi:[1,0,1] neg_lo:[1,0,0] neg_hi:[1,0,0]
	v_pk_fma_f32 v[54:55], v[116:117], v[206:207], v[54:55] op_sel_hi:[1,0,1]
	v_pk_fma_f32 v[50:51], v[112:113], v[206:207], v[50:51] op_sel_hi:[1,0,1]
	v_pk_fma_f32 v[48:49], v[48:49], v[210:211], v[128:129] op_sel_hi:[1,0,1]
	v_lshl_add_u64 v[64:65], v[64:65], 0, v[212:213]
	v_cvt_pk_bf16_f32 v56, v60, v61
	v_cvt_pk_bf16_f32 v57, v62, v63
	v_cvt_pk_bf16_f32 v58, v66, v67
	v_cvt_pk_bf16_f32 v59, v68, v69
	v_pk_fma_f32 v[54:55], v[54:55], v[210:211], v[138:139] op_sel_hi:[1,0,1]
	v_pk_fma_f32 v[52:53], v[52:53], v[210:211], v[136:137] op_sel_hi:[1,0,1]
	v_pk_fma_f32 v[50:51], v[50:51], v[210:211], v[130:131] op_sel_hi:[1,0,1]
	v_max_f32_e32 v48, 0, v48
	v_max_f32_e32 v49, 0, v49
	global_store_dwordx4 v[64:65], v[56:59], off nt
	v_max_f32_e32 v52, 0, v52
	v_max_f32_e32 v53, 0, v53
	v_pk_mul_f32 v[56:57], v[48:49], v[48:49]
	v_max_f32_e32 v48, 0, v54
	v_max_f32_e32 v50, 0, v50
	v_max_f32_e32 v49, 0, v55
	v_max_f32_e32 v51, 0, v51
	v_pk_fma_f32 v[44:45], v[156:157], v[200:201], v[44:45] op_sel_hi:[1,0,1] neg_lo:[1,0,0] neg_hi:[1,0,0]
	v_pk_fma_f32 v[40:41], v[148:149], v[200:201], v[40:41] op_sel_hi:[1,0,1] neg_lo:[1,0,0] neg_hi:[1,0,0]
	v_pk_mul_f32 v[52:53], v[52:53], v[52:53]
	v_pk_mul_f32 v[54:55], v[48:49], v[48:49]
	v_pk_mul_f32 v[58:59], v[50:51], v[50:51]
	v_pk_fma_f32 v[46:47], v[124:125], v[200:201], v[46:47] op_sel_hi:[1,0,1]
	v_pk_fma_f32 v[44:45], v[44:45], v[204:205], v[152:153] op_sel_hi:[1,0,1]
	v_pk_fma_f32 v[42:43], v[120:121], v[200:201], v[42:43] op_sel_hi:[1,0,1]
	v_pk_fma_f32 v[40:41], v[40:41], v[204:205], v[144:145] op_sel_hi:[1,0,1]
	v_cvt_pk_bf16_f32 v48, v52, v53
	v_cvt_pk_bf16_f32 v49, v54, v55
	v_cvt_pk_bf16_f32 v50, v56, v57
	v_cvt_pk_bf16_f32 v51, v58, v59
	v_pk_fma_f32 v[46:47], v[46:47], v[204:205], v[154:155] op_sel_hi:[1,0,1]
	v_pk_fma_f32 v[42:43], v[42:43], v[204:205], v[146:147] op_sel_hi:[1,0,1]
	v_max_f32_e32 v44, 0, v44
	v_max_f32_e32 v40, 0, v40
	v_max_f32_e32 v45, 0, v45
	v_max_f32_e32 v41, 0, v41
	global_store_dwordx4 v[64:65], v[48:51], off offset:256 nt
	v_pk_mul_f32 v[44:45], v[44:45], v[44:45]
	v_max_f32_e32 v42, 0, v42
	v_pk_mul_f32 v[50:51], v[40:41], v[40:41]
	v_max_f32_e32 v40, 0, v46
	v_max_f32_e32 v41, 0, v47
	v_max_f32_e32 v43, 0, v43
	v_pk_fma_f32 v[32:33], v[132:133], v[200:201], v[32:33] op_sel_hi:[1,0,1] neg_lo:[1,0,0] neg_hi:[1,0,0]
	v_pk_mul_f32 v[46:47], v[40:41], v[40:41]
	v_pk_mul_f32 v[52:53], v[42:43], v[42:43]
	v_cvt_pk_bf16_f32 v40, v44, v45
	v_add_co_u32_e32 v44, vcc, s67, v188
	v_pk_fma_f32 v[36:37], v[140:141], v[200:201], v[36:37] op_sel_hi:[1,0,1] neg_lo:[1,0,0] neg_hi:[1,0,0]
	v_pk_fma_f32 v[38:39], v[116:117], v[200:201], v[38:39] op_sel_hi:[1,0,1]
	v_pk_fma_f32 v[34:35], v[112:113], v[200:201], v[34:35] op_sel_hi:[1,0,1]
	v_pk_fma_f32 v[32:33], v[32:33], v[204:205], v[128:129] op_sel_hi:[1,0,1]
	v_cvt_pk_bf16_f32 v41, v46, v47
	v_cvt_pk_bf16_f32 v42, v50, v51
	v_cvt_pk_bf16_f32 v43, v52, v53
	v_addc_co_u32_e32 v45, vcc, 0, v189, vcc
	v_pk_fma_f32 v[38:39], v[38:39], v[204:205], v[138:139] op_sel_hi:[1,0,1]
	v_pk_fma_f32 v[36:37], v[36:37], v[204:205], v[136:137] op_sel_hi:[1,0,1]
	v_pk_fma_f32 v[34:35], v[34:35], v[204:205], v[130:131] op_sel_hi:[1,0,1]
	v_max_f32_e32 v32, 0, v32
	v_max_f32_e32 v33, 0, v33
	global_store_dwordx4 v[44:45], v[40:43], off nt
	v_max_f32_e32 v36, 0, v36
	v_max_f32_e32 v37, 0, v37
	v_pk_mul_f32 v[40:41], v[32:33], v[32:33]
	v_max_f32_e32 v32, 0, v38
	v_max_f32_e32 v34, 0, v34
	v_max_f32_e32 v33, 0, v39
	v_max_f32_e32 v35, 0, v35
	v_pk_fma_f32 v[28:29], v[156:157], v[190:191], v[28:29] op_sel_hi:[1,0,1] neg_lo:[1,0,0] neg_hi:[1,0,0]
	v_pk_fma_f32 v[24:25], v[148:149], v[190:191], v[24:25] op_sel_hi:[1,0,1] neg_lo:[1,0,0] neg_hi:[1,0,0]
	v_pk_mul_f32 v[36:37], v[36:37], v[36:37]
	v_pk_mul_f32 v[38:39], v[32:33], v[32:33]
	v_pk_mul_f32 v[42:43], v[34:35], v[34:35]
	v_pk_fma_f32 v[30:31], v[124:125], v[190:191], v[30:31] op_sel_hi:[1,0,1]
	v_pk_fma_f32 v[28:29], v[28:29], v[198:199], v[152:153] op_sel_hi:[1,0,1]
	v_pk_fma_f32 v[26:27], v[120:121], v[190:191], v[26:27] op_sel_hi:[1,0,1]
	v_pk_fma_f32 v[24:25], v[24:25], v[198:199], v[144:145] op_sel_hi:[1,0,1]
	v_lshl_add_u64 v[48:49], v[188:189], 0, s[42:43]
	v_cvt_pk_bf16_f32 v32, v36, v37
	v_cvt_pk_bf16_f32 v33, v38, v39
	v_cvt_pk_bf16_f32 v34, v40, v41
	v_cvt_pk_bf16_f32 v35, v42, v43
	v_pk_fma_f32 v[30:31], v[30:31], v[198:199], v[154:155] op_sel_hi:[1,0,1]
	v_pk_fma_f32 v[26:27], v[26:27], v[198:199], v[146:147] op_sel_hi:[1,0,1]
	v_max_f32_e32 v28, 0, v28
	v_max_f32_e32 v24, 0, v24
	v_max_f32_e32 v29, 0, v29
	v_max_f32_e32 v25, 0, v25
	global_store_dwordx4 v[48:49], v[32:35], off offset:256 nt
	v_pk_mul_f32 v[28:29], v[28:29], v[28:29]
	v_max_f32_e32 v26, 0, v26
	v_pk_mul_f32 v[34:35], v[24:25], v[24:25]
	v_max_f32_e32 v24, 0, v30
	v_max_f32_e32 v25, 0, v31
	v_max_f32_e32 v27, 0, v27
	v_pk_fma_f32 v[16:17], v[132:133], v[190:191], v[16:17] op_sel_hi:[1,0,1] neg_lo:[1,0,0] neg_hi:[1,0,0]
	v_pk_mul_f32 v[30:31], v[24:25], v[24:25]
	v_pk_mul_f32 v[36:37], v[26:27], v[26:27]
	v_cvt_pk_bf16_f32 v24, v28, v29
	v_add_co_u32_e32 v28, vcc, s68, v188
	v_pk_fma_f32 v[20:21], v[140:141], v[190:191], v[20:21] op_sel_hi:[1,0,1] neg_lo:[1,0,0] neg_hi:[1,0,0]
	v_pk_fma_f32 v[22:23], v[116:117], v[190:191], v[22:23] op_sel_hi:[1,0,1]
	v_pk_fma_f32 v[18:19], v[112:113], v[190:191], v[18:19] op_sel_hi:[1,0,1]
	v_pk_fma_f32 v[16:17], v[16:17], v[198:199], v[128:129] op_sel_hi:[1,0,1]
	v_cvt_pk_bf16_f32 v25, v30, v31
	v_cvt_pk_bf16_f32 v26, v34, v35
	v_cvt_pk_bf16_f32 v27, v36, v37
	v_addc_co_u32_e32 v29, vcc, 0, v189, vcc
	v_pk_fma_f32 v[22:23], v[22:23], v[198:199], v[138:139] op_sel_hi:[1,0,1]
	v_pk_fma_f32 v[20:21], v[20:21], v[198:199], v[136:137] op_sel_hi:[1,0,1]
	v_pk_fma_f32 v[18:19], v[18:19], v[198:199], v[130:131] op_sel_hi:[1,0,1]
	v_max_f32_e32 v16, 0, v16
	v_max_f32_e32 v17, 0, v17
	global_store_dwordx4 v[28:29], v[24:27], off nt
	v_max_f32_e32 v20, 0, v20
	v_max_f32_e32 v21, 0, v21
	v_pk_mul_f32 v[24:25], v[16:17], v[16:17]
	v_max_f32_e32 v16, 0, v22
	v_max_f32_e32 v18, 0, v18
	v_max_f32_e32 v17, 0, v23
	v_max_f32_e32 v19, 0, v19
	v_pk_fma_f32 v[12:13], v[156:157], v[182:183], v[12:13] op_sel_hi:[1,0,1] neg_lo:[1,0,0] neg_hi:[1,0,0]
	v_pk_fma_f32 v[8:9], v[148:149], v[182:183], v[8:9] op_sel_hi:[1,0,1] neg_lo:[1,0,0] neg_hi:[1,0,0]
	v_pk_mul_f32 v[20:21], v[20:21], v[20:21]
	v_pk_mul_f32 v[22:23], v[16:17], v[16:17]
	v_pk_mul_f32 v[26:27], v[18:19], v[18:19]
	v_pk_fma_f32 v[14:15], v[124:125], v[182:183], v[14:15] op_sel_hi:[1,0,1]
	v_pk_fma_f32 v[12:13], v[12:13], v[186:187], v[152:153] op_sel_hi:[1,0,1]
	v_pk_fma_f32 v[10:11], v[120:121], v[182:183], v[10:11] op_sel_hi:[1,0,1]
	v_pk_fma_f32 v[8:9], v[8:9], v[186:187], v[144:145] op_sel_hi:[1,0,1]
	v_lshl_add_u64 v[32:33], v[188:189], 0, s[44:45]
	v_cvt_pk_bf16_f32 v16, v20, v21
	v_cvt_pk_bf16_f32 v17, v22, v23
	v_cvt_pk_bf16_f32 v18, v24, v25
	v_cvt_pk_bf16_f32 v19, v26, v27
	v_pk_fma_f32 v[14:15], v[14:15], v[186:187], v[154:155] op_sel_hi:[1,0,1]
	v_pk_fma_f32 v[10:11], v[10:11], v[186:187], v[146:147] op_sel_hi:[1,0,1]
	v_max_f32_e32 v12, 0, v12
	v_max_f32_e32 v8, 0, v8
	v_max_f32_e32 v13, 0, v13
	v_max_f32_e32 v9, 0, v9
	global_store_dwordx4 v[32:33], v[16:19], off offset:256 nt
	v_pk_mul_f32 v[12:13], v[12:13], v[12:13]
	v_max_f32_e32 v10, 0, v10
	v_pk_mul_f32 v[18:19], v[8:9], v[8:9]
	v_max_f32_e32 v8, 0, v14
	v_max_f32_e32 v9, 0, v15
	v_max_f32_e32 v11, 0, v11
	v_pk_fma_f32 v[0:1], v[132:133], v[182:183], v[0:1] op_sel_hi:[1,0,1] neg_lo:[1,0,0] neg_hi:[1,0,0]
	v_pk_mul_f32 v[14:15], v[8:9], v[8:9]
	v_pk_mul_f32 v[20:21], v[10:11], v[10:11]
	v_cvt_pk_bf16_f32 v8, v12, v13
	v_add_co_u32_e32 v12, vcc, s69, v188
	v_pk_fma_f32 v[4:5], v[140:141], v[182:183], v[4:5] op_sel_hi:[1,0,1] neg_lo:[1,0,0] neg_hi:[1,0,0]
	v_pk_fma_f32 v[6:7], v[116:117], v[182:183], v[6:7] op_sel_hi:[1,0,1]
	v_pk_fma_f32 v[2:3], v[112:113], v[182:183], v[2:3] op_sel_hi:[1,0,1]
	v_pk_fma_f32 v[0:1], v[0:1], v[186:187], v[128:129] op_sel_hi:[1,0,1]
	v_cvt_pk_bf16_f32 v9, v14, v15
	v_cvt_pk_bf16_f32 v10, v18, v19
	v_cvt_pk_bf16_f32 v11, v20, v21
	v_addc_co_u32_e32 v13, vcc, 0, v189, vcc
	v_pk_fma_f32 v[6:7], v[6:7], v[186:187], v[138:139] op_sel_hi:[1,0,1]
	v_pk_fma_f32 v[4:5], v[4:5], v[186:187], v[136:137] op_sel_hi:[1,0,1]
	v_pk_fma_f32 v[2:3], v[2:3], v[186:187], v[130:131] op_sel_hi:[1,0,1]
	v_max_f32_e32 v0, 0, v0
	v_max_f32_e32 v1, 0, v1
	v_max_f32_e32 v126, 0, v126
	v_max_f32_e32 v127, 0, v127
	global_store_dwordx4 v[12:13], v[8:11], off nt
	v_max_f32_e32 v4, 0, v4
	v_max_f32_e32 v5, 0, v5
	v_pk_mul_f32 v[8:9], v[0:1], v[0:1]
	v_max_f32_e32 v0, 0, v6
	v_max_f32_e32 v2, 0, v2
	v_max_f32_e32 v1, 0, v7
	v_max_f32_e32 v3, 0, v3
	v_pk_mul_f32 v[126:127], v[126:127], v[126:127]
	v_pk_mul_f32 v[4:5], v[4:5], v[4:5]
	v_pk_mul_f32 v[6:7], v[0:1], v[0:1]
	v_pk_mul_f32 v[10:11], v[2:3], v[2:3]
	v_cvt_pk_bf16_f32 v224, v126, v127
	v_lshl_add_u64 v[16:17], v[188:189], 0, s[46:47]
	v_cvt_pk_bf16_f32 v0, v4, v5
	v_cvt_pk_bf16_f32 v1, v6, v7
	v_cvt_pk_bf16_f32 v2, v8, v9
	v_cvt_pk_bf16_f32 v3, v10, v11
	s_andn2_b64 vcc, exec, s[0:1]
	s_mov_b64 s[0:1], -1
	global_store_dwordx4 v[188:189], v[222:225], off offset:256 nt
	global_store_dwordx4 v[16:17], v[0:3], off offset:256 nt
	s_cbranch_vccnz .LBB0_1075
	s_andn2_b64 vcc, exec, s[10:11]
	s_cbranch_vccnz .LBB0_1074
	s_barrier
	s_branch .LBB0_1074

.LBB0_1159:
	v_lshl_add_u32 v198, s0, 8, v169
	v_ashrrev_i32_e32 v199, 31, v198
	v_lshl_or_b32 v64, s1, 8, v209
	v_lshl_add_u64 v[68:69], v[198:199], 3, s[28:29]
	v_lshlrev_b64 v[66:67], 11, v[198:199]
	v_ashrrev_i32_e32 v65, 31, v64
	global_load_dwordx2 v[224:225], v[68:69], off
	v_lshl_add_u64 v[66:67], s[26:27], 0, v[66:67]
	v_lshlrev_b64 v[200:201], 1, v[64:65]
	v_lshl_add_u64 v[226:227], v[66:67], 0, v[200:201]
	global_load_dwordx4 v[216:219], v[226:227], off
	global_load_dwordx4 v[220:223], v[226:227], off offset:256
	v_lshlrev_b64 v[64:65], 2, v[64:65]
	v_lshl_add_u64 v[68:69], s[10:11], 0, v[64:65]
	v_and_b32_e32 v66, 64, v213
	v_lshl_add_u64 v[76:77], s[12:13], 0, v[64:65]
	global_load_dwordx4 v[88:91], v[68:69], off offset:16
	global_load_dwordx4 v[96:99], v[68:69], off
	global_load_dwordx4 v[92:95], v[76:77], off offset:16
	global_load_dwordx4 v[100:103], v[76:77], off
	v_xor_b32_e32 v67, 16, v213
	v_add_u32_e32 v71, 64, v66
	v_xor_b32_e32 v70, 32, v213
	v_cmp_lt_i32_e32 vcc, v67, v71
	v_or_b32_e32 v66, 16, v198
	v_lshl_add_u64 v[202:203], s[26:27], 0, v[200:201]
	v_cndmask_b32_e32 v64, v213, v67, vcc
	v_cmp_lt_i32_e32 vcc, v70, v71
	v_ashrrev_i32_e32 v67, 31, v66
	v_lshlrev_b32_e32 v215, 2, v64
	v_cndmask_b32_e32 v65, v213, v70, vcc
	v_lshlrev_b32_e32 v199, 2, v65
	v_lshl_add_u64 v[160:161], v[66:67], 3, s[28:29]
	v_lshlrev_b64 v[204:205], 11, v[66:67]
	global_load_dwordx4 v[64:67], v[68:69], off offset:528
	global_load_dwordx4 v[72:75], v[68:69], off offset:512
	s_nop 0
	global_load_dwordx4 v[68:71], v[76:77], off offset:528
	s_nop 0
	global_load_dwordx4 v[76:79], v[76:77], off offset:512
	s_nop 0
	global_load_dwordx2 v[206:207], v[160:161], off
	v_lshl_add_u64 v[164:165], v[202:203], 0, v[204:205]
	global_load_dwordx4 v[160:163], v[164:165], off offset:256
	s_nop 0
	global_load_dwordx4 v[164:167], v[164:165], off
	s_waitcnt vmcnt(0)
	v_pk_mul_f32 v[224:225], v[224:225], s[36:37] op_sel_hi:[1,0]
	s_nop 0
	v_fma_f32 v225, -v224, v224, v225
	v_add_f32_e32 v225, 0x3727c5ac, v225
	v_lshlrev_b32_e32 v235, 16, v220
	v_and_b32_e32 v236, 0xffff0000, v220
	v_lshlrev_b32_e32 v228, 16, v216
	v_and_b32_e32 v216, 0xffff0000, v216
	v_lshlrev_b32_e32 v229, 16, v217
	v_and_b32_e32 v230, 0xffff0000, v217
	v_sub_f32_e32 v217, v216, v224
	v_sub_f32_e32 v216, v228, v224
	v_lshlrev_b32_e32 v231, 16, v218
	v_and_b32_e32 v232, 0xffff0000, v218
	v_sub_f32_e32 v218, v229, v224
	v_lshlrev_b32_e32 v233, 16, v219
	v_and_b32_e32 v234, 0xffff0000, v219
	v_sub_f32_e32 v219, v230, v224
	v_sub_f32_e32 v220, v231, v224
	v_lshlrev_b32_e32 v237, 16, v221
	v_and_b32_e32 v238, 0xffff0000, v221
	v_sub_f32_e32 v221, v232, v224
	v_lshlrev_b32_e32 v239, 16, v222
	v_and_b32_e32 v240, 0xffff0000, v222
	v_sub_f32_e32 v222, v233, v224
	v_lshlrev_b32_e32 v241, 16, v223
	v_and_b32_e32 v242, 0xffff0000, v223
	v_sub_f32_e32 v223, v234, v224
	v_sub_f32_e32 v229, v236, v224
	v_rsq_f32_e32 v230, v225
	s_nop 0
	v_pk_mul_f32 v[216:217], v[216:217], v[230:231] op_sel_hi:[1,0]
	v_pk_mul_f32 v[218:219], v[218:219], v[230:231] op_sel_hi:[1,0]
	v_pk_mul_f32 v[222:223], v[222:223], v[230:231] op_sel_hi:[1,0]
	v_pk_mul_f32 v[220:221], v[220:221], v[230:231] op_sel_hi:[1,0]
	v_pk_fma_f32 v[216:217], v[96:97], v[216:217], v[100:101]
	v_pk_fma_f32 v[218:219], v[98:99], v[218:219], v[102:103]
	v_pk_fma_f32 v[220:221], v[88:89], v[220:221], v[92:93]
	v_pk_fma_f32 v[222:223], v[90:91], v[222:223], v[94:95]
	v_pk_fma_f32 v[156:157], v[216:217], s[38:39], v[156:157] op_sel_hi:[1,0,1]
	v_pk_fma_f32 v[158:159], v[218:219], s[38:39], v[158:159] op_sel_hi:[1,0,1]
	v_pk_fma_f32 v[216:217], v[222:223], s[38:39], v[154:155] op_sel_hi:[1,0,1]
	v_pk_fma_f32 v[154:155], v[220:221], s[38:39], v[152:153] op_sel_hi:[1,0,1]
	v_cvt_pk_bf16_f32 v152, v156, v157
	v_sub_f32_e32 v228, v235, v224
	v_sub_f32_e32 v157, v238, v224
	v_sub_f32_e32 v156, v237, v224
	v_cvt_pk_bf16_f32 v153, v158, v159
	v_cvt_pk_bf16_f32 v154, v154, v155
	v_cvt_pk_bf16_f32 v155, v216, v217
	v_pk_mul_f32 v[156:157], v[156:157], v[230:231] op_sel_hi:[1,0]
	v_pk_mul_f32 v[158:159], v[228:229], v[230:231] op_sel_hi:[1,0]
	v_sub_f32_e32 v217, v240, v224
	v_sub_f32_e32 v216, v239, v224
	v_sub_f32_e32 v219, v242, v224
	v_sub_f32_e32 v218, v241, v224
	v_pk_fma_f32 v[158:159], v[72:73], v[158:159], v[76:77]
	v_pk_fma_f32 v[156:157], v[74:75], v[156:157], v[78:79]
	v_pk_mul_f32 v[218:219], v[218:219], v[230:231] op_sel_hi:[1,0]
	v_pk_mul_f32 v[216:217], v[216:217], v[230:231] op_sel_hi:[1,0]
	v_pk_fma_f32 v[218:219], v[66:67], v[218:219], v[70:71]
	v_pk_fma_f32 v[216:217], v[64:65], v[216:217], v[68:69]
	v_pk_fma_f32 v[150:151], v[156:157], s[38:39], v[150:151] op_sel_hi:[1,0,1]
	v_pk_fma_f32 v[148:149], v[158:159], s[38:39], v[148:149] op_sel_hi:[1,0,1]
	v_pk_fma_f32 v[156:157], v[218:219], s[38:39], v[146:147] op_sel_hi:[1,0,1]
	v_pk_fma_f32 v[146:147], v[216:217], s[38:39], v[144:145] op_sel_hi:[1,0,1]
	v_cvt_pk_bf16_f32 v144, v148, v149
	v_cvt_pk_bf16_f32 v145, v150, v151
	global_store_dwordx4 v[226:227], v[152:155], off
	v_cvt_pk_bf16_f32 v146, v146, v147
	v_cvt_pk_bf16_f32 v147, v156, v157
	v_lshlrev_b32_e32 v149, 16, v152
	v_lshlrev_b32_e32 v148, 16, v144
	v_and_b32_e32 v151, 0xffff0000, v152
	v_and_b32_e32 v150, 0xffff0000, v144
	v_lshlrev_b32_e32 v157, 16, v153
	v_lshlrev_b32_e32 v156, 16, v145
	v_and_b32_e32 v153, 0xffff0000, v153
	v_and_b32_e32 v152, 0xffff0000, v145
	global_store_dwordx4 v[226:227], v[144:147], off offset:256
	v_and_b32_e32 v159, 0xffff0000, v154
	v_and_b32_e32 v158, 0xffff0000, v146
	v_lshlrev_b32_e32 v145, 16, v154
	v_lshlrev_b32_e32 v144, 16, v146
	v_lshlrev_b32_e32 v217, 16, v155
	v_lshlrev_b32_e32 v216, 16, v147
	v_and_b32_e32 v155, 0xffff0000, v155
	v_and_b32_e32 v154, 0xffff0000, v147
	v_pk_add_f32 v[146:147], v[148:149], v[150:151]
	v_pk_add_f32 v[218:219], v[156:157], v[152:153]
	v_pk_add_f32 v[220:221], v[216:217], v[154:155]
	v_pk_add_f32 v[146:147], v[146:147], v[218:219]
	v_pk_add_f32 v[218:219], v[144:145], v[158:159]
	v_lshlrev_b32_e32 v222, 16, v167
	v_pk_add_f32 v[218:219], v[218:219], v[220:221]
	v_and_b32_e32 v221, 0xffff0000, v167
	v_pk_add_f32 v[218:219], v[146:147], v[218:219]
	v_pk_mul_f32 v[146:147], v[150:151], v[150:151]
	s_nop 0
	v_pk_fma_f32 v[146:147], v[148:149], v[148:149], v[146:147]
	v_pk_mul_f32 v[148:149], v[152:153], v[152:153]
	s_nop 0
	v_pk_fma_f32 v[148:149], v[156:157], v[156:157], v[148:149]
	v_pk_mul_f32 v[156:157], v[206:207], s[36:37] op_sel_hi:[1,0]
	v_pk_add_f32 v[146:147], v[146:147], v[148:149]
	v_pk_mul_f32 v[148:149], v[158:159], v[158:159]
	v_sub_f32_e32 v221, v221, v156
	v_pk_fma_f32 v[144:145], v[144:145], v[144:145], v[148:149]
	v_pk_mul_f32 v[148:149], v[154:155], v[154:155]
	s_nop 0
	v_pk_fma_f32 v[148:149], v[216:217], v[216:217], v[148:149]
	s_nop 0
	v_pk_add_f32 v[144:145], v[144:145], v[148:149]
	s_nop 0
	v_pk_add_f32 v[154:155], v[146:147], v[144:145]
	v_fma_f32 v146, -v156, v156, v157
	v_add_f32_e32 v146, 0x3727c5ac, v146
	v_rsq_f32_e32 v206, v146
	v_or_b32_e32 v144, 32, v198
	v_ashrrev_i32_e32 v145, 31, v144
	v_lshl_add_u64 v[148:149], v[144:145], 3, s[28:29]
	v_lshlrev_b64 v[152:153], 11, v[144:145]
	v_lshl_add_u64 v[150:151], v[202:203], 0, v[152:153]
	s_nop 0
	s_nop 1
	s_nop 1
	global_load_dwordx4 v[144:147], v[150:151], off offset:256
	global_load_dwordx2 v[158:159], v[148:149], off
	s_nop 0
	global_load_dwordx4 v[148:151], v[150:151], off
	s_nop 0
	v_lshlrev_b32_e32 v157, 16, v164
	v_and_b32_e32 v164, 0xffff0000, v164
	v_and_b32_e32 v216, 0xffff0000, v165
	v_lshlrev_b32_e32 v220, 16, v166
	v_and_b32_e32 v217, 0xffff0000, v166
	v_lshlrev_b32_e32 v207, 16, v165
	v_sub_f32_e32 v165, v164, v156
	v_sub_f32_e32 v164, v157, v156
	v_sub_f32_e32 v167, v216, v156
	v_sub_f32_e32 v217, v217, v156
	v_sub_f32_e32 v216, v220, v156
	v_sub_f32_e32 v220, v222, v156
	v_sub_f32_e32 v166, v207, v156
	v_pk_mul_f32 v[164:165], v[206:207], v[164:165] op_sel_hi:[0,1]
	v_pk_mul_f32 v[220:221], v[206:207], v[220:221] op_sel_hi:[0,1]
	v_pk_mul_f32 v[216:217], v[206:207], v[216:217] op_sel_hi:[0,1]
	v_pk_mul_f32 v[166:167], v[206:207], v[166:167] op_sel_hi:[0,1]
	v_pk_fma_f32 v[164:165], v[96:97], v[164:165], v[100:101]
	v_pk_fma_f32 v[216:217], v[88:89], v[216:217], v[92:93]
	v_pk_fma_f32 v[220:221], v[90:91], v[220:221], v[94:95]
	v_pk_fma_f32 v[166:167], v[98:99], v[166:167], v[102:103]
	v_pk_fma_f32 v[140:141], v[164:165], s[38:39], v[140:141] op_sel_hi:[1,0,1]
	v_pk_fma_f32 v[164:165], v[220:221], s[38:39], v[138:139] op_sel_hi:[1,0,1]
	v_pk_fma_f32 v[138:139], v[216:217], s[38:39], v[136:137] op_sel_hi:[1,0,1]
	v_pk_fma_f32 v[142:143], v[166:167], s[38:39], v[142:143] op_sel_hi:[1,0,1]
	v_cvt_pk_bf16_f32 v136, v140, v141
	v_cvt_pk_bf16_f32 v138, v138, v139
	v_cvt_pk_bf16_f32 v137, v142, v143
	v_cvt_pk_bf16_f32 v139, v164, v165
	v_lshlrev_b32_e32 v143, 16, v138
	v_lshlrev_b32_e32 v142, 16, v136
	v_and_b32_e32 v165, 0xffff0000, v138
	v_and_b32_e32 v164, 0xffff0000, v136
	v_lshl_add_u64 v[140:141], s[26:27], 0, v[204:205]
	v_and_b32_e32 v205, 0xffff0000, v139
	v_and_b32_e32 v204, 0xffff0000, v137
	v_pk_add_f32 v[216:217], v[142:143], v[164:165]
	v_pk_mul_f32 v[164:165], v[164:165], v[164:165]
	v_lshlrev_b32_e32 v167, 16, v139
	v_lshlrev_b32_e32 v166, 16, v137
	v_pk_fma_f32 v[142:143], v[142:143], v[142:143], v[164:165]
	v_pk_mul_f32 v[164:165], v[204:205], v[204:205]
	v_pk_add_f32 v[220:221], v[166:167], v[204:205]
	v_pk_fma_f32 v[164:165], v[166:167], v[166:167], v[164:165]
	v_and_b32_e32 v157, 0xffff0000, v160
	v_pk_add_f32 v[142:143], v[142:143], v[164:165]
	v_lshlrev_b32_e32 v164, 16, v161
	v_pk_add_f32 v[142:143], v[142:143], v[142:143] op_sel_hi:[0,1]
	v_lshlrev_b32_e32 v142, 16, v160
	v_and_b32_e32 v165, 0xffff0000, v161
	v_lshlrev_b32_e32 v166, 16, v162
	v_and_b32_e32 v167, 0xffff0000, v162
	v_lshlrev_b32_e32 v204, 16, v163
	v_and_b32_e32 v205, 0xffff0000, v163
	v_sub_f32_e32 v161, v157, v156
	v_sub_f32_e32 v160, v142, v156
	v_sub_f32_e32 v163, v165, v156
	v_sub_f32_e32 v162, v164, v156
	v_sub_f32_e32 v165, v167, v156
	v_sub_f32_e32 v164, v166, v156
	v_sub_f32_e32 v157, v205, v156
	v_sub_f32_e32 v156, v204, v156
	v_pk_mul_f32 v[160:161], v[206:207], v[160:161] op_sel_hi:[0,1]
	v_pk_mul_f32 v[156:157], v[206:207], v[156:157] op_sel_hi:[0,1]
	v_pk_mul_f32 v[164:165], v[206:207], v[164:165] op_sel_hi:[0,1]
	v_pk_mul_f32 v[162:163], v[206:207], v[162:163] op_sel_hi:[0,1]
	v_pk_fma_f32 v[160:161], v[72:73], v[160:161], v[76:77]
	v_pk_fma_f32 v[164:165], v[64:65], v[164:165], v[68:69]
	v_pk_fma_f32 v[156:157], v[66:67], v[156:157], v[70:71]
	v_pk_fma_f32 v[162:163], v[74:75], v[162:163], v[78:79]
	v_pk_fma_f32 v[132:133], v[160:161], s[38:39], v[132:133] op_sel_hi:[1,0,1]
	v_pk_fma_f32 v[156:157], v[156:157], s[38:39], v[130:131] op_sel_hi:[1,0,1]
	v_pk_fma_f32 v[130:131], v[164:165], s[38:39], v[128:129] op_sel_hi:[1,0,1]
	v_pk_fma_f32 v[134:135], v[162:163], s[38:39], v[134:135] op_sel_hi:[1,0,1]
	v_cvt_pk_bf16_f32 v128, v132, v133
	v_cvt_pk_bf16_f32 v130, v130, v131
	v_cvt_pk_bf16_f32 v129, v134, v135
	v_cvt_pk_bf16_f32 v131, v156, v157
	v_lshlrev_b32_e32 v133, 16, v130
	v_lshlrev_b32_e32 v132, 16, v128
	v_and_b32_e32 v135, 0xffff0000, v130
	v_and_b32_e32 v134, 0xffff0000, v128
	v_and_b32_e32 v161, 0xffff0000, v131
	v_and_b32_e32 v160, 0xffff0000, v129
	v_pk_add_f32 v[162:163], v[132:133], v[134:135]
	v_pk_mul_f32 v[134:135], v[134:135], v[134:135]
	v_lshlrev_b32_e32 v157, 16, v131
	v_lshlrev_b32_e32 v156, 16, v129
	v_pk_fma_f32 v[132:133], v[132:133], v[132:133], v[134:135]
	v_pk_mul_f32 v[134:135], v[160:161], v[160:161]
	v_lshl_add_u64 v[140:141], v[140:141], 0, v[200:201]
	v_pk_fma_f32 v[134:135], v[156:157], v[156:157], v[134:135]
	global_store_dwordx4 v[140:141], v[136:139], off
	global_store_dwordx4 v[140:141], v[128:131], off offset:256
	v_pk_add_f32 v[132:133], v[132:133], v[134:135]
	v_pk_add_f32 v[216:217], v[216:217], v[220:221]
	v_pk_add_f32 v[132:133], v[132:133], v[132:133] op_sel_hi:[0,1]
	v_mov_b32_e32 v132, v155
	v_mov_b32_e32 v155, v143
	v_pk_add_f32 v[132:133], v[132:133], v[154:155]
	ds_bpermute_b32 v142, v215, v132
	ds_bpermute_b32 v143, v215, v133
	v_pk_add_f32 v[164:165], v[156:157], v[160:161]
	v_pk_add_f32 v[216:217], v[216:217], v[216:217] op_sel_hi:[0,1]
	v_pk_add_f32 v[162:163], v[162:163], v[164:165]
	v_or_b32_e32 v128, 48, v198
	s_waitcnt lgkmcnt(0)
	v_pk_add_f32 v[132:133], v[132:133], v[142:143]
	s_waitcnt vmcnt(3)
	v_pk_mul_f32 v[142:143], v[158:159], s[36:37] op_sel_hi:[1,0]
	v_pk_add_f32 v[162:163], v[162:163], v[162:163] op_sel_hi:[0,1]
	v_fma_f32 v130, -v142, v142, v143
	v_add_f32_e32 v130, 0x3727c5ac, v130
	v_rsq_f32_e32 v160, v130
	v_mov_b32_e32 v216, v219
	v_ashrrev_i32_e32 v129, 31, v128
	v_pk_add_f32 v[134:135], v[216:217], 0 op_sel_hi:[1,0]
	v_mov_b32_e32 v219, v163
	v_lshl_add_u64 v[154:155], v[128:129], 3, s[28:29]
	v_lshlrev_b64 v[140:141], 11, v[128:129]
	v_pk_add_f32 v[134:135], v[218:219], v[134:135]
	ds_bpermute_b32 v156, v215, v134
	ds_bpermute_b32 v157, v215, v135
	s_waitcnt vmcnt(2)
	v_lshlrev_b32_e32 v166, 16, v151
	s_waitcnt lgkmcnt(0)
	v_pk_add_f32 v[136:137], v[134:135], v[156:157]
	v_lshl_add_u64 v[156:157], v[202:203], 0, v[140:141]
	v_and_b32_e32 v165, 0xffff0000, v151
	v_sub_f32_e32 v165, v165, v142
	global_load_dwordx4 v[128:131], v[156:157], off offset:256
	global_load_dwordx2 v[158:159], v[154:155], off
	s_nop 0
	global_load_dwordx4 v[154:157], v[156:157], off
	ds_bpermute_b32 v138, v199, v136
	ds_bpermute_b32 v134, v199, v132
	ds_bpermute_b32 v139, v199, v137
	v_lshlrev_b32_e32 v143, 16, v148
	v_and_b32_e32 v148, 0xffff0000, v148
	v_lshlrev_b32_e32 v161, 16, v149
	v_and_b32_e32 v162, 0xffff0000, v149
	v_lshlrev_b32_e32 v164, 16, v150
	v_and_b32_e32 v163, 0xffff0000, v150
	v_sub_f32_e32 v149, v148, v142
	v_sub_f32_e32 v148, v143, v142
	v_sub_f32_e32 v151, v162, v142
	v_sub_f32_e32 v150, v161, v142
	v_sub_f32_e32 v163, v163, v142
	v_sub_f32_e32 v162, v164, v142
	v_sub_f32_e32 v164, v166, v142
	v_pk_mul_f32 v[150:151], v[160:161], v[150:151] op_sel_hi:[0,1]
	v_pk_mul_f32 v[148:149], v[160:161], v[148:149] op_sel_hi:[0,1]
	v_pk_mul_f32 v[164:165], v[160:161], v[164:165] op_sel_hi:[0,1]
	v_pk_mul_f32 v[162:163], v[160:161], v[162:163] op_sel_hi:[0,1]
	v_pk_fma_f32 v[148:149], v[96:97], v[148:149], v[100:101]
	v_pk_fma_f32 v[150:151], v[98:99], v[150:151], v[102:103]
	v_pk_fma_f32 v[162:163], v[88:89], v[162:163], v[92:93]
	v_pk_fma_f32 v[164:165], v[90:91], v[164:165], v[94:95]
	v_pk_fma_f32 v[126:127], v[150:151], s[38:39], v[126:127] op_sel_hi:[1,0,1]
	v_pk_fma_f32 v[124:125], v[148:149], s[38:39], v[124:125] op_sel_hi:[1,0,1]
	v_pk_fma_f32 v[148:149], v[164:165], s[38:39], v[122:123] op_sel_hi:[1,0,1]
	v_pk_fma_f32 v[122:123], v[162:163], s[38:39], v[120:121] op_sel_hi:[1,0,1]
	v_cvt_pk_bf16_f32 v121, v126, v127
	v_cvt_pk_bf16_f32 v122, v122, v123
	v_cvt_pk_bf16_f32 v123, v148, v149
	v_lshlrev_b32_e32 v126, 16, v144
	v_and_b32_e32 v127, 0xffff0000, v144
	v_lshlrev_b32_e32 v143, 16, v145
	v_and_b32_e32 v144, 0xffff0000, v145
	v_lshlrev_b32_e32 v148, 16, v146
	v_and_b32_e32 v146, 0xffff0000, v146
	v_lshlrev_b32_e32 v149, 16, v147
	v_and_b32_e32 v150, 0xffff0000, v147
	v_sub_f32_e32 v127, v127, v142
	v_sub_f32_e32 v126, v126, v142
	v_sub_f32_e32 v145, v144, v142
	v_sub_f32_e32 v144, v143, v142
	v_sub_f32_e32 v147, v146, v142
	v_sub_f32_e32 v146, v148, v142
	v_sub_f32_e32 v143, v150, v142
	v_sub_f32_e32 v142, v149, v142
	v_pk_mul_f32 v[144:145], v[160:161], v[144:145] op_sel_hi:[0,1]
	v_pk_mul_f32 v[126:127], v[160:161], v[126:127] op_sel_hi:[0,1]
	v_pk_mul_f32 v[142:143], v[160:161], v[142:143] op_sel_hi:[0,1]
	v_pk_mul_f32 v[146:147], v[160:161], v[146:147] op_sel_hi:[0,1]
	v_pk_fma_f32 v[126:127], v[72:73], v[126:127], v[76:77]
	v_pk_fma_f32 v[144:145], v[74:75], v[144:145], v[78:79]
	v_pk_fma_f32 v[146:147], v[64:65], v[146:147], v[68:69]
	v_pk_fma_f32 v[142:143], v[66:67], v[142:143], v[70:71]
	v_cvt_pk_bf16_f32 v120, v124, v125
	v_lshl_add_u64 v[124:125], s[26:27], 0, v[152:153]
	v_pk_fma_f32 v[118:119], v[144:145], s[38:39], v[118:119] op_sel_hi:[1,0,1]
	v_pk_fma_f32 v[116:117], v[126:127], s[38:39], v[116:117] op_sel_hi:[1,0,1]
	v_pk_fma_f32 v[126:127], v[142:143], s[38:39], v[114:115] op_sel_hi:[1,0,1]
	v_pk_fma_f32 v[114:115], v[146:147], s[38:39], v[112:113] op_sel_hi:[1,0,1]
	v_lshl_add_u64 v[124:125], v[124:125], 0, v[200:201]
	v_cvt_pk_bf16_f32 v112, v116, v117
	v_cvt_pk_bf16_f32 v113, v118, v119
	v_cvt_pk_bf16_f32 v114, v114, v115
	v_cvt_pk_bf16_f32 v115, v126, v127
	global_store_dwordx4 v[124:125], v[120:123], off
	global_store_dwordx4 v[124:125], v[112:115], off offset:256
	v_lshlrev_b32_e32 v117, 16, v120
	v_lshlrev_b32_e32 v116, 16, v112
	v_and_b32_e32 v119, 0xffff0000, v120
	v_and_b32_e32 v118, 0xffff0000, v112
	v_lshlrev_b32_e32 v125, 16, v121
	v_lshlrev_b32_e32 v124, 16, v113
	v_and_b32_e32 v121, 0xffff0000, v121
	v_and_b32_e32 v120, 0xffff0000, v113
	v_lshlrev_b32_e32 v113, 16, v122
	v_lshlrev_b32_e32 v112, 16, v114
	v_and_b32_e32 v127, 0xffff0000, v122
	v_and_b32_e32 v126, 0xffff0000, v114
	v_lshlrev_b32_e32 v143, 16, v123
	v_lshlrev_b32_e32 v142, 16, v115
	v_and_b32_e32 v123, 0xffff0000, v123
	v_and_b32_e32 v122, 0xffff0000, v115
	v_pk_add_f32 v[114:115], v[116:117], v[118:119]
	v_pk_add_f32 v[144:145], v[124:125], v[120:121]
	v_pk_add_f32 v[146:147], v[142:143], v[122:123]
	v_pk_add_f32 v[114:115], v[114:115], v[144:145]
	v_pk_add_f32 v[144:145], v[112:113], v[126:127]
	s_waitcnt vmcnt(2)
	v_lshlrev_b32_e32 v150, 16, v156
	v_pk_add_f32 v[144:145], v[144:145], v[146:147]
	v_and_b32_e32 v151, 0xffff0000, v156
	v_pk_add_f32 v[144:145], v[114:115], v[144:145]
	v_pk_mul_f32 v[114:115], v[118:119], v[118:119]
	v_lshlrev_b32_e32 v152, 16, v157
	v_pk_fma_f32 v[114:115], v[116:117], v[116:117], v[114:115]
	v_pk_mul_f32 v[116:117], v[120:121], v[120:121]
	v_and_b32_e32 v153, 0xffff0000, v157
	v_pk_fma_f32 v[116:117], v[124:125], v[124:125], v[116:117]
	v_pk_mul_f32 v[124:125], v[158:159], s[36:37] op_sel_hi:[1,0]
	v_pk_add_f32 v[114:115], v[114:115], v[116:117]
	v_pk_mul_f32 v[116:117], v[126:127], v[126:127]
	v_and_b32_e32 v149, 0xffff0000, v155
	v_pk_fma_f32 v[112:113], v[112:113], v[112:113], v[116:117]
	v_pk_mul_f32 v[116:117], v[122:123], v[122:123]
	v_sub_f32_e32 v151, v151, v124
	v_pk_fma_f32 v[116:117], v[142:143], v[142:143], v[116:117]
	v_sub_f32_e32 v150, v150, v124
	v_pk_add_f32 v[112:113], v[112:113], v[116:117]
	v_sub_f32_e32 v153, v153, v124
	v_pk_add_f32 v[122:123], v[114:115], v[112:113]
	v_fma_f32 v114, -v124, v124, v125
	v_add_f32_e32 v114, 0x3727c5ac, v114
	v_rsq_f32_e32 v142, v114
	v_add_u32_e32 v112, 0x80, v198
	v_ashrrev_i32_e32 v113, 31, v112
	v_lshl_add_u64 v[116:117], v[112:113], 3, s[28:29]
	v_lshlrev_b64 v[120:121], 11, v[112:113]
	v_lshl_add_u64 v[118:119], v[202:203], 0, v[120:121]
	v_sub_f32_e32 v152, v152, v124
	v_sub_f32_e32 v149, v149, v124
	ds_bpermute_b32 v135, v199, v133
	s_nop 1
	global_load_dwordx4 v[112:115], v[118:119], off offset:256
	global_load_dwordx2 v[126:127], v[116:117], off
	s_nop 0
	global_load_dwordx4 v[116:119], v[118:119], off
	s_nop 0
	v_lshlrev_b32_e32 v125, 16, v154
	v_and_b32_e32 v143, 0xffff0000, v154
	v_lshlrev_b32_e32 v148, 16, v155
	v_sub_f32_e32 v147, v143, v124
	v_sub_f32_e32 v146, v125, v124
	v_sub_f32_e32 v148, v148, v124
	v_pk_mul_f32 v[146:147], v[142:143], v[146:147] op_sel_hi:[0,1]
	v_pk_mul_f32 v[152:153], v[142:143], v[152:153] op_sel_hi:[0,1]
	v_pk_mul_f32 v[150:151], v[142:143], v[150:151] op_sel_hi:[0,1]
	v_pk_mul_f32 v[148:149], v[142:143], v[148:149] op_sel_hi:[0,1]
	v_pk_fma_f32 v[146:147], v[96:97], v[146:147], v[100:101]
	v_pk_fma_f32 v[150:151], v[88:89], v[150:151], v[92:93]
	v_pk_fma_f32 v[152:153], v[90:91], v[152:153], v[94:95]
	v_pk_fma_f32 v[148:149], v[98:99], v[148:149], v[102:103]
	v_pk_fma_f32 v[108:109], v[146:147], s[38:39], v[108:109] op_sel_hi:[1,0,1]
	v_pk_fma_f32 v[146:147], v[152:153], s[38:39], v[106:107] op_sel_hi:[1,0,1]
	v_pk_fma_f32 v[106:107], v[150:151], s[38:39], v[104:105] op_sel_hi:[1,0,1]
	v_pk_fma_f32 v[110:111], v[148:149], s[38:39], v[110:111] op_sel_hi:[1,0,1]
	v_cvt_pk_bf16_f32 v104, v108, v109
	v_cvt_pk_bf16_f32 v106, v106, v107
	v_cvt_pk_bf16_f32 v105, v110, v111
	v_cvt_pk_bf16_f32 v107, v146, v147
	v_lshl_add_u64 v[108:109], s[26:27], 0, v[140:141]
	v_lshlrev_b32_e32 v111, 16, v106
	v_lshlrev_b32_e32 v110, 16, v104
	v_and_b32_e32 v141, 0xffff0000, v106
	v_and_b32_e32 v140, 0xffff0000, v104
	v_and_b32_e32 v149, 0xffff0000, v107
	v_and_b32_e32 v148, 0xffff0000, v105
	v_pk_add_f32 v[150:151], v[110:111], v[140:141]
	v_pk_mul_f32 v[140:141], v[140:141], v[140:141]
	v_lshlrev_b32_e32 v147, 16, v107
	v_lshlrev_b32_e32 v146, 16, v105
	v_pk_fma_f32 v[110:111], v[110:111], v[110:111], v[140:141]
	v_pk_mul_f32 v[140:141], v[148:149], v[148:149]
	v_pk_add_f32 v[152:153], v[146:147], v[148:149]
	v_pk_fma_f32 v[140:141], v[146:147], v[146:147], v[140:141]
	v_and_b32_e32 v125, 0xffff0000, v128
	v_pk_add_f32 v[110:111], v[110:111], v[140:141]
	v_lshlrev_b32_e32 v140, 16, v129
	v_pk_add_f32 v[110:111], v[110:111], v[110:111] op_sel_hi:[0,1]
	v_lshlrev_b32_e32 v110, 16, v128
	v_and_b32_e32 v141, 0xffff0000, v129
	v_lshlrev_b32_e32 v143, 16, v130
	v_and_b32_e32 v146, 0xffff0000, v130
	v_lshlrev_b32_e32 v147, 16, v131
	v_and_b32_e32 v148, 0xffff0000, v131
	v_sub_f32_e32 v129, v125, v124
	v_sub_f32_e32 v128, v110, v124
	v_sub_f32_e32 v131, v141, v124
	v_sub_f32_e32 v130, v140, v124
	v_sub_f32_e32 v141, v146, v124
	v_sub_f32_e32 v140, v143, v124
	v_sub_f32_e32 v125, v148, v124
	v_sub_f32_e32 v124, v147, v124
	v_pk_mul_f32 v[128:129], v[142:143], v[128:129] op_sel_hi:[0,1]
	v_pk_mul_f32 v[124:125], v[142:143], v[124:125] op_sel_hi:[0,1]
	v_pk_mul_f32 v[140:141], v[142:143], v[140:141] op_sel_hi:[0,1]
	v_pk_mul_f32 v[130:131], v[142:143], v[130:131] op_sel_hi:[0,1]
	v_pk_fma_f32 v[128:129], v[72:73], v[128:129], v[76:77]
	v_pk_fma_f32 v[140:141], v[64:65], v[140:141], v[68:69]
	v_pk_fma_f32 v[124:125], v[66:67], v[124:125], v[70:71]
	v_pk_fma_f32 v[130:131], v[74:75], v[130:131], v[78:79]
	v_pk_fma_f32 v[84:85], v[128:129], s[38:39], v[84:85] op_sel_hi:[1,0,1]
	v_pk_fma_f32 v[124:125], v[124:125], s[38:39], v[82:83] op_sel_hi:[1,0,1]
	v_pk_fma_f32 v[82:83], v[140:141], s[38:39], v[80:81] op_sel_hi:[1,0,1]
	v_pk_fma_f32 v[86:87], v[130:131], s[38:39], v[86:87] op_sel_hi:[1,0,1]
	v_cvt_pk_bf16_f32 v80, v84, v85
	v_cvt_pk_bf16_f32 v82, v82, v83
	v_cvt_pk_bf16_f32 v81, v86, v87
	v_cvt_pk_bf16_f32 v83, v124, v125
	v_lshlrev_b32_e32 v85, 16, v82
	v_lshlrev_b32_e32 v84, 16, v80
	v_and_b32_e32 v87, 0xffff0000, v82
	v_and_b32_e32 v86, 0xffff0000, v80
	v_and_b32_e32 v129, 0xffff0000, v83
	v_and_b32_e32 v128, 0xffff0000, v81
	v_pk_add_f32 v[130:131], v[84:85], v[86:87]
	v_pk_mul_f32 v[86:87], v[86:87], v[86:87]
	v_lshlrev_b32_e32 v125, 16, v83
	v_lshlrev_b32_e32 v124, 16, v81
	v_pk_fma_f32 v[84:85], v[84:85], v[84:85], v[86:87]
	v_pk_mul_f32 v[86:87], v[128:129], v[128:129]
	v_mov_b32_e32 v110, v123
	v_pk_fma_f32 v[86:87], v[124:125], v[124:125], v[86:87]
	v_lshl_add_u64 v[108:109], v[108:109], 0, v[200:201]
	v_pk_add_f32 v[84:85], v[84:85], v[86:87]
	global_store_dwordx4 v[108:109], v[104:107], off
	global_store_dwordx4 v[108:109], v[80:83], off offset:256
	v_pk_add_f32 v[84:85], v[84:85], v[84:85] op_sel_hi:[0,1]
	v_mov_b32_e32 v84, v122
	v_pk_add_f32 v[84:85], v[84:85], v[110:111]
	ds_bpermute_b32 v110, v215, v84
	ds_bpermute_b32 v111, v215, v85
	v_pk_add_f32 v[150:151], v[150:151], v[152:153]
	v_pk_add_f32 v[140:141], v[124:125], v[128:129]
	v_pk_add_f32 v[150:151], v[150:151], v[150:151] op_sel_hi:[0,1]
	v_pk_add_f32 v[130:131], v[130:131], v[140:141]
	s_waitcnt lgkmcnt(0)
	v_pk_add_f32 v[84:85], v[84:85], v[110:111]
	s_waitcnt vmcnt(3)
	v_pk_mul_f32 v[110:111], v[126:127], s[36:37] op_sel_hi:[1,0]
	v_add_u32_e32 v80, 0x90, v198
	v_fma_f32 v82, -v110, v110, v111
	v_add_f32_e32 v82, 0x3727c5ac, v82
	v_rsq_f32_e32 v128, v82
	v_pk_add_f32 v[130:131], v[130:131], v[130:131] op_sel_hi:[0,1]
	v_mov_b32_e32 v150, v145
	v_ashrrev_i32_e32 v81, 31, v80
	v_pk_add_f32 v[86:87], v[150:151], 0 op_sel_hi:[1,0]
	v_mov_b32_e32 v145, v131
	v_lshl_add_u64 v[122:123], v[80:81], 3, s[28:29]
	v_lshlrev_b64 v[108:109], 11, v[80:81]
	v_pk_add_f32 v[86:87], v[144:145], v[86:87]
	ds_bpermute_b32 v124, v215, v86
	ds_bpermute_b32 v125, v215, v87
	s_waitcnt vmcnt(2)
	v_lshlrev_b32_e32 v142, 16, v119
	s_waitcnt lgkmcnt(0)
	v_pk_add_f32 v[104:105], v[86:87], v[124:125]
	v_lshl_add_u64 v[124:125], v[202:203], 0, v[108:109]
	v_and_b32_e32 v141, 0xffff0000, v119
	v_sub_f32_e32 v141, v141, v110
	global_load_dwordx4 v[80:83], v[124:125], off offset:256
	global_load_dwordx2 v[126:127], v[122:123], off
	s_nop 0
	global_load_dwordx4 v[122:125], v[124:125], off
	ds_bpermute_b32 v106, v199, v104
	ds_bpermute_b32 v86, v199, v84
	ds_bpermute_b32 v107, v199, v105
	v_lshlrev_b32_e32 v111, 16, v116
	v_and_b32_e32 v116, 0xffff0000, v116
	v_lshlrev_b32_e32 v129, 16, v117
	v_and_b32_e32 v130, 0xffff0000, v117
	v_lshlrev_b32_e32 v140, 16, v118
	v_and_b32_e32 v131, 0xffff0000, v118
	v_sub_f32_e32 v117, v116, v110
	v_sub_f32_e32 v116, v111, v110
	v_sub_f32_e32 v119, v130, v110
	v_sub_f32_e32 v118, v129, v110
	v_sub_f32_e32 v131, v131, v110
	v_sub_f32_e32 v130, v140, v110
	v_sub_f32_e32 v140, v142, v110
	v_pk_mul_f32 v[118:119], v[128:129], v[118:119] op_sel_hi:[0,1]
	v_pk_mul_f32 v[116:117], v[128:129], v[116:117] op_sel_hi:[0,1]
	v_pk_mul_f32 v[140:141], v[128:129], v[140:141] op_sel_hi:[0,1]
	v_pk_mul_f32 v[130:131], v[128:129], v[130:131] op_sel_hi:[0,1]
	v_pk_fma_f32 v[116:117], v[96:97], v[116:117], v[100:101]
	v_pk_fma_f32 v[118:119], v[98:99], v[118:119], v[102:103]
	v_pk_fma_f32 v[130:131], v[88:89], v[130:131], v[92:93]
	v_pk_fma_f32 v[140:141], v[90:91], v[140:141], v[94:95]
	v_pk_fma_f32 v[62:63], v[118:119], s[38:39], v[62:63] op_sel_hi:[1,0,1]
	v_pk_fma_f32 v[60:61], v[116:117], s[38:39], v[60:61] op_sel_hi:[1,0,1]
	v_pk_fma_f32 v[116:117], v[140:141], s[38:39], v[58:59] op_sel_hi:[1,0,1]
	v_pk_fma_f32 v[58:59], v[130:131], s[38:39], v[56:57] op_sel_hi:[1,0,1]
	v_cvt_pk_bf16_f32 v57, v62, v63
	v_cvt_pk_bf16_f32 v58, v58, v59
	v_cvt_pk_bf16_f32 v59, v116, v117
	v_lshlrev_b32_e32 v62, 16, v112
	v_and_b32_e32 v63, 0xffff0000, v112
	v_lshlrev_b32_e32 v111, 16, v113
	v_and_b32_e32 v112, 0xffff0000, v113
	v_lshlrev_b32_e32 v116, 16, v114
	v_and_b32_e32 v114, 0xffff0000, v114
	v_lshlrev_b32_e32 v117, 16, v115
	v_and_b32_e32 v118, 0xffff0000, v115
	v_sub_f32_e32 v63, v63, v110
	v_sub_f32_e32 v62, v62, v110
	v_sub_f32_e32 v113, v112, v110
	v_sub_f32_e32 v112, v111, v110
	v_sub_f32_e32 v115, v114, v110
	v_sub_f32_e32 v114, v116, v110
	v_sub_f32_e32 v111, v118, v110
	v_sub_f32_e32 v110, v117, v110
	v_pk_mul_f32 v[112:113], v[128:129], v[112:113] op_sel_hi:[0,1]
	v_pk_mul_f32 v[62:63], v[128:129], v[62:63] op_sel_hi:[0,1]
	v_pk_mul_f32 v[110:111], v[128:129], v[110:111] op_sel_hi:[0,1]
	v_pk_mul_f32 v[114:115], v[128:129], v[114:115] op_sel_hi:[0,1]
	v_pk_fma_f32 v[62:63], v[72:73], v[62:63], v[76:77]
	v_pk_fma_f32 v[112:113], v[74:75], v[112:113], v[78:79]
	v_pk_fma_f32 v[114:115], v[64:65], v[114:115], v[68:69]
	v_pk_fma_f32 v[110:111], v[66:67], v[110:111], v[70:71]
	v_cvt_pk_bf16_f32 v56, v60, v61
	v_lshl_add_u64 v[60:61], s[26:27], 0, v[120:121]
	v_pk_fma_f32 v[54:55], v[112:113], s[38:39], v[54:55] op_sel_hi:[1,0,1]
	v_pk_fma_f32 v[52:53], v[62:63], s[38:39], v[52:53] op_sel_hi:[1,0,1]
	v_pk_fma_f32 v[62:63], v[110:111], s[38:39], v[50:51] op_sel_hi:[1,0,1]
	v_pk_fma_f32 v[50:51], v[114:115], s[38:39], v[48:49] op_sel_hi:[1,0,1]
	v_lshl_add_u64 v[60:61], v[60:61], 0, v[200:201]
	v_cvt_pk_bf16_f32 v48, v52, v53
	v_cvt_pk_bf16_f32 v49, v54, v55
	v_cvt_pk_bf16_f32 v50, v50, v51
	v_cvt_pk_bf16_f32 v51, v62, v63
	global_store_dwordx4 v[60:61], v[56:59], off
	global_store_dwordx4 v[60:61], v[48:51], off offset:256
	v_lshlrev_b32_e32 v53, 16, v56
	v_lshlrev_b32_e32 v52, 16, v48
	v_and_b32_e32 v55, 0xffff0000, v56
	v_and_b32_e32 v54, 0xffff0000, v48
	v_lshlrev_b32_e32 v61, 16, v57
	v_lshlrev_b32_e32 v60, 16, v49
	v_and_b32_e32 v57, 0xffff0000, v57
	v_and_b32_e32 v56, 0xffff0000, v49
	v_lshlrev_b32_e32 v49, 16, v58
	v_lshlrev_b32_e32 v48, 16, v50
	v_and_b32_e32 v63, 0xffff0000, v58
	v_and_b32_e32 v62, 0xffff0000, v50
	v_lshlrev_b32_e32 v111, 16, v59
	v_lshlrev_b32_e32 v110, 16, v51
	v_and_b32_e32 v59, 0xffff0000, v59
	v_and_b32_e32 v58, 0xffff0000, v51
	v_pk_add_f32 v[50:51], v[52:53], v[54:55]
	v_pk_add_f32 v[112:113], v[60:61], v[56:57]
	v_pk_add_f32 v[114:115], v[110:111], v[58:59]
	v_pk_add_f32 v[50:51], v[50:51], v[112:113]
	v_pk_add_f32 v[112:113], v[48:49], v[62:63]
	s_waitcnt vmcnt(2)
	v_lshlrev_b32_e32 v118, 16, v124
	v_pk_add_f32 v[112:113], v[112:113], v[114:115]
	v_and_b32_e32 v119, 0xffff0000, v124
	v_pk_add_f32 v[112:113], v[50:51], v[112:113]
	v_pk_mul_f32 v[50:51], v[54:55], v[54:55]
	v_lshlrev_b32_e32 v120, 16, v125
	v_pk_fma_f32 v[50:51], v[52:53], v[52:53], v[50:51]
	v_pk_mul_f32 v[52:53], v[56:57], v[56:57]
	v_and_b32_e32 v121, 0xffff0000, v125
	v_pk_fma_f32 v[52:53], v[60:61], v[60:61], v[52:53]
	v_pk_mul_f32 v[60:61], v[126:127], s[36:37] op_sel_hi:[1,0]
	v_pk_add_f32 v[50:51], v[50:51], v[52:53]
	v_pk_mul_f32 v[52:53], v[62:63], v[62:63]
	v_and_b32_e32 v117, 0xffff0000, v123
	v_pk_fma_f32 v[48:49], v[48:49], v[48:49], v[52:53]
	v_pk_mul_f32 v[52:53], v[58:59], v[58:59]
	v_sub_f32_e32 v119, v119, v60
	v_pk_fma_f32 v[52:53], v[110:111], v[110:111], v[52:53]
	v_sub_f32_e32 v118, v118, v60
	v_pk_add_f32 v[48:49], v[48:49], v[52:53]
	v_sub_f32_e32 v121, v121, v60
	v_pk_add_f32 v[58:59], v[50:51], v[48:49]
	v_fma_f32 v50, -v60, v60, v61
	v_add_f32_e32 v50, 0x3727c5ac, v50
	v_rsq_f32_e32 v110, v50
	v_add_u32_e32 v48, 0xa0, v198
	v_ashrrev_i32_e32 v49, 31, v48
	v_lshl_add_u64 v[52:53], v[48:49], 3, s[28:29]
	v_lshlrev_b64 v[56:57], 11, v[48:49]
	v_lshl_add_u64 v[54:55], v[202:203], 0, v[56:57]
	v_sub_f32_e32 v120, v120, v60
	v_sub_f32_e32 v117, v117, v60
	ds_bpermute_b32 v87, v199, v85
	s_nop 1
	global_load_dwordx4 v[48:51], v[54:55], off offset:256
	global_load_dwordx2 v[62:63], v[52:53], off
	s_nop 0
	global_load_dwordx4 v[52:55], v[54:55], off
	s_nop 0
	v_lshlrev_b32_e32 v61, 16, v122
	v_and_b32_e32 v111, 0xffff0000, v122
	v_lshlrev_b32_e32 v116, 16, v123
	v_sub_f32_e32 v115, v111, v60
	v_sub_f32_e32 v114, v61, v60
	v_sub_f32_e32 v116, v116, v60
	v_pk_mul_f32 v[114:115], v[110:111], v[114:115] op_sel_hi:[0,1]
	v_pk_mul_f32 v[120:121], v[110:111], v[120:121] op_sel_hi:[0,1]
	v_pk_mul_f32 v[118:119], v[110:111], v[118:119] op_sel_hi:[0,1]
	v_pk_mul_f32 v[116:117], v[110:111], v[116:117] op_sel_hi:[0,1]
	v_pk_fma_f32 v[114:115], v[96:97], v[114:115], v[100:101]
	v_pk_fma_f32 v[118:119], v[88:89], v[118:119], v[92:93]
	v_pk_fma_f32 v[120:121], v[90:91], v[120:121], v[94:95]
	v_pk_fma_f32 v[116:117], v[98:99], v[116:117], v[102:103]
	v_pk_fma_f32 v[44:45], v[114:115], s[38:39], v[44:45] op_sel_hi:[1,0,1]
	v_pk_fma_f32 v[114:115], v[120:121], s[38:39], v[42:43] op_sel_hi:[1,0,1]
	v_pk_fma_f32 v[42:43], v[118:119], s[38:39], v[40:41] op_sel_hi:[1,0,1]
	v_pk_fma_f32 v[46:47], v[116:117], s[38:39], v[46:47] op_sel_hi:[1,0,1]
	v_cvt_pk_bf16_f32 v40, v44, v45
	v_cvt_pk_bf16_f32 v42, v42, v43
	v_cvt_pk_bf16_f32 v41, v46, v47
	v_cvt_pk_bf16_f32 v43, v114, v115
	v_lshl_add_u64 v[44:45], s[26:27], 0, v[108:109]
	v_lshlrev_b32_e32 v47, 16, v42
	v_lshlrev_b32_e32 v46, 16, v40
	v_and_b32_e32 v109, 0xffff0000, v42
	v_and_b32_e32 v108, 0xffff0000, v40
	v_and_b32_e32 v117, 0xffff0000, v43
	v_and_b32_e32 v116, 0xffff0000, v41
	v_pk_add_f32 v[118:119], v[46:47], v[108:109]
	v_pk_mul_f32 v[108:109], v[108:109], v[108:109]
	v_lshlrev_b32_e32 v115, 16, v43
	v_lshlrev_b32_e32 v114, 16, v41
	v_pk_fma_f32 v[46:47], v[46:47], v[46:47], v[108:109]
	v_pk_mul_f32 v[108:109], v[116:117], v[116:117]
	v_pk_add_f32 v[120:121], v[114:115], v[116:117]
	v_pk_fma_f32 v[108:109], v[114:115], v[114:115], v[108:109]
	v_and_b32_e32 v61, 0xffff0000, v80
	v_pk_add_f32 v[46:47], v[46:47], v[108:109]
	v_lshlrev_b32_e32 v108, 16, v81
	v_pk_add_f32 v[46:47], v[46:47], v[46:47] op_sel_hi:[0,1]
	v_lshlrev_b32_e32 v46, 16, v80
	v_and_b32_e32 v109, 0xffff0000, v81
	v_lshlrev_b32_e32 v111, 16, v82
	v_and_b32_e32 v114, 0xffff0000, v82
	v_lshlrev_b32_e32 v115, 16, v83
	v_and_b32_e32 v116, 0xffff0000, v83
	v_sub_f32_e32 v81, v61, v60
	v_sub_f32_e32 v80, v46, v60
	v_sub_f32_e32 v83, v109, v60
	v_sub_f32_e32 v82, v108, v60
	v_sub_f32_e32 v109, v114, v60
	v_sub_f32_e32 v108, v111, v60
	v_sub_f32_e32 v61, v116, v60
	v_sub_f32_e32 v60, v115, v60
	v_pk_mul_f32 v[80:81], v[110:111], v[80:81] op_sel_hi:[0,1]
	v_pk_mul_f32 v[60:61], v[110:111], v[60:61] op_sel_hi:[0,1]
	v_pk_mul_f32 v[108:109], v[110:111], v[108:109] op_sel_hi:[0,1]
	v_pk_mul_f32 v[82:83], v[110:111], v[82:83] op_sel_hi:[0,1]
	v_pk_fma_f32 v[80:81], v[72:73], v[80:81], v[76:77]
	v_pk_fma_f32 v[108:109], v[64:65], v[108:109], v[68:69]
	v_pk_fma_f32 v[60:61], v[66:67], v[60:61], v[70:71]
	v_pk_fma_f32 v[82:83], v[74:75], v[82:83], v[78:79]
	v_pk_fma_f32 v[36:37], v[80:81], s[38:39], v[36:37] op_sel_hi:[1,0,1]
	v_pk_fma_f32 v[60:61], v[60:61], s[38:39], v[34:35] op_sel_hi:[1,0,1]
	v_pk_fma_f32 v[34:35], v[108:109], s[38:39], v[32:33] op_sel_hi:[1,0,1]
	v_pk_fma_f32 v[38:39], v[82:83], s[38:39], v[38:39] op_sel_hi:[1,0,1]
	v_cvt_pk_bf16_f32 v32, v36, v37
	v_cvt_pk_bf16_f32 v34, v34, v35
	v_cvt_pk_bf16_f32 v33, v38, v39
	v_cvt_pk_bf16_f32 v35, v60, v61
	v_lshlrev_b32_e32 v37, 16, v34
	v_lshlrev_b32_e32 v36, 16, v32
	v_and_b32_e32 v39, 0xffff0000, v34
	v_and_b32_e32 v38, 0xffff0000, v32
	v_and_b32_e32 v81, 0xffff0000, v35
	v_and_b32_e32 v80, 0xffff0000, v33
	v_pk_add_f32 v[82:83], v[36:37], v[38:39]
	v_pk_mul_f32 v[38:39], v[38:39], v[38:39]
	v_lshlrev_b32_e32 v61, 16, v35
	v_lshlrev_b32_e32 v60, 16, v33
	v_pk_fma_f32 v[36:37], v[36:37], v[36:37], v[38:39]
	v_pk_mul_f32 v[38:39], v[80:81], v[80:81]
	v_mov_b32_e32 v46, v59
	v_pk_fma_f32 v[38:39], v[60:61], v[60:61], v[38:39]
	v_lshl_add_u64 v[44:45], v[44:45], 0, v[200:201]
	v_pk_add_f32 v[36:37], v[36:37], v[38:39]
	global_store_dwordx4 v[44:45], v[40:43], off
	global_store_dwordx4 v[44:45], v[32:35], off offset:256
	v_pk_add_f32 v[36:37], v[36:37], v[36:37] op_sel_hi:[0,1]
	v_mov_b32_e32 v36, v58
	v_pk_add_f32 v[36:37], v[36:37], v[46:47]
	ds_bpermute_b32 v46, v215, v36
	ds_bpermute_b32 v47, v215, v37
	v_pk_add_f32 v[118:119], v[118:119], v[120:121]
	v_pk_add_f32 v[108:109], v[60:61], v[80:81]
	v_pk_add_f32 v[118:119], v[118:119], v[118:119] op_sel_hi:[0,1]
	v_pk_add_f32 v[82:83], v[82:83], v[108:109]
	s_waitcnt lgkmcnt(0)
	v_pk_add_f32 v[36:37], v[36:37], v[46:47]
	s_waitcnt vmcnt(3)
	v_pk_mul_f32 v[46:47], v[62:63], s[36:37] op_sel_hi:[1,0]
	v_add_u32_e32 v32, 0xb0, v198
	v_fma_f32 v34, -v46, v46, v47
	v_add_f32_e32 v34, 0x3727c5ac, v34
	v_rsq_f32_e32 v80, v34
	v_pk_add_f32 v[82:83], v[82:83], v[82:83] op_sel_hi:[0,1]
	v_mov_b32_e32 v118, v113
	v_ashrrev_i32_e32 v33, 31, v32
	v_pk_add_f32 v[38:39], v[118:119], 0 op_sel_hi:[1,0]
	v_mov_b32_e32 v113, v83
	v_lshl_add_u64 v[58:59], v[32:33], 3, s[28:29]
	v_lshlrev_b64 v[44:45], 11, v[32:33]
	v_pk_add_f32 v[38:39], v[112:113], v[38:39]
	ds_bpermute_b32 v60, v215, v38
	ds_bpermute_b32 v61, v215, v39
	s_waitcnt vmcnt(2)
	v_lshlrev_b32_e32 v110, 16, v55
	s_waitcnt lgkmcnt(0)
	v_pk_add_f32 v[40:41], v[38:39], v[60:61]
	v_lshl_add_u64 v[60:61], v[202:203], 0, v[44:45]
	v_and_b32_e32 v109, 0xffff0000, v55
	v_sub_f32_e32 v109, v109, v46
	global_load_dwordx4 v[32:35], v[60:61], off offset:256
	global_load_dwordx2 v[62:63], v[58:59], off
	s_nop 0
	global_load_dwordx4 v[58:61], v[60:61], off
	ds_bpermute_b32 v42, v199, v40
	ds_bpermute_b32 v38, v199, v36
	ds_bpermute_b32 v43, v199, v41
	v_lshlrev_b32_e32 v81, 16, v53
	v_and_b32_e32 v82, 0xffff0000, v53
	v_lshlrev_b32_e32 v47, 16, v52
	v_and_b32_e32 v52, 0xffff0000, v52
	v_lshlrev_b32_e32 v108, 16, v54
	v_and_b32_e32 v83, 0xffff0000, v54
	v_sub_f32_e32 v55, v82, v46
	v_sub_f32_e32 v54, v81, v46
	v_sub_f32_e32 v53, v52, v46
	v_sub_f32_e32 v52, v47, v46
	v_pk_mul_f32 v[54:55], v[80:81], v[54:55] op_sel_hi:[0,1]
	v_sub_f32_e32 v83, v83, v46
	v_sub_f32_e32 v82, v108, v46
	v_sub_f32_e32 v108, v110, v46
	v_pk_mul_f32 v[52:53], v[80:81], v[52:53] op_sel_hi:[0,1]
	v_pk_fma_f32 v[54:55], v[98:99], v[54:55], v[102:103]
	v_pk_mul_f32 v[108:109], v[80:81], v[108:109] op_sel_hi:[0,1]
	v_pk_mul_f32 v[82:83], v[80:81], v[82:83] op_sel_hi:[0,1]
	v_pk_fma_f32 v[52:53], v[96:97], v[52:53], v[100:101]
	v_pk_fma_f32 v[82:83], v[88:89], v[82:83], v[92:93]
	v_pk_fma_f32 v[108:109], v[90:91], v[108:109], v[94:95]
	v_pk_fma_f32 v[30:31], v[54:55], s[38:39], v[30:31] op_sel_hi:[1,0,1]
	v_pk_fma_f32 v[28:29], v[52:53], s[38:39], v[28:29] op_sel_hi:[1,0,1]
	v_pk_fma_f32 v[52:53], v[108:109], s[38:39], v[26:27] op_sel_hi:[1,0,1]
	v_pk_fma_f32 v[26:27], v[82:83], s[38:39], v[24:25] op_sel_hi:[1,0,1]
	v_cvt_pk_bf16_f32 v25, v30, v31
	v_lshlrev_b32_e32 v30, 16, v48
	v_and_b32_e32 v31, 0xffff0000, v48
	v_cvt_pk_bf16_f32 v26, v26, v27
	v_cvt_pk_bf16_f32 v27, v52, v53
	v_lshlrev_b32_e32 v47, 16, v49
	v_and_b32_e32 v48, 0xffff0000, v49
	v_lshlrev_b32_e32 v52, 16, v50
	v_and_b32_e32 v50, 0xffff0000, v50
	v_lshlrev_b32_e32 v53, 16, v51
	v_and_b32_e32 v54, 0xffff0000, v51
	v_sub_f32_e32 v31, v31, v46
	v_sub_f32_e32 v30, v30, v46
	v_sub_f32_e32 v49, v48, v46
	v_sub_f32_e32 v48, v47, v46
	v_pk_mul_f32 v[30:31], v[80:81], v[30:31] op_sel_hi:[0,1]
	v_sub_f32_e32 v51, v50, v46
	v_sub_f32_e32 v50, v52, v46
	v_sub_f32_e32 v47, v54, v46
	v_sub_f32_e32 v46, v53, v46
	v_pk_mul_f32 v[48:49], v[80:81], v[48:49] op_sel_hi:[0,1]
	v_pk_fma_f32 v[30:31], v[72:73], v[30:31], v[76:77]
	v_pk_mul_f32 v[46:47], v[80:81], v[46:47] op_sel_hi:[0,1]
	v_pk_mul_f32 v[50:51], v[80:81], v[50:51] op_sel_hi:[0,1]
	v_pk_fma_f32 v[48:49], v[74:75], v[48:49], v[78:79]
	v_pk_fma_f32 v[50:51], v[64:65], v[50:51], v[68:69]
	v_pk_fma_f32 v[46:47], v[66:67], v[46:47], v[70:71]
	v_pk_fma_f32 v[20:21], v[30:31], s[38:39], v[20:21] op_sel_hi:[1,0,1]
	v_cvt_pk_bf16_f32 v24, v28, v29
	v_lshl_add_u64 v[28:29], s[26:27], 0, v[56:57]
	v_pk_fma_f32 v[22:23], v[48:49], s[38:39], v[22:23] op_sel_hi:[1,0,1]
	v_pk_fma_f32 v[30:31], v[46:47], s[38:39], v[18:19] op_sel_hi:[1,0,1]
	v_pk_fma_f32 v[18:19], v[50:51], s[38:39], v[16:17] op_sel_hi:[1,0,1]
	v_cvt_pk_bf16_f32 v16, v20, v21
	v_lshl_add_u64 v[28:29], v[28:29], 0, v[200:201]
	v_cvt_pk_bf16_f32 v17, v22, v23
	v_cvt_pk_bf16_f32 v18, v18, v19
	v_cvt_pk_bf16_f32 v19, v30, v31
	v_lshlrev_b32_e32 v21, 16, v24
	v_lshlrev_b32_e32 v20, 16, v16
	v_and_b32_e32 v23, 0xffff0000, v24
	v_and_b32_e32 v22, 0xffff0000, v16
	global_store_dwordx4 v[28:29], v[24:27], off
	global_store_dwordx4 v[28:29], v[16:19], off offset:256
	v_lshlrev_b32_e32 v29, 16, v25
	v_lshlrev_b32_e32 v28, 16, v17
	v_and_b32_e32 v25, 0xffff0000, v25
	v_and_b32_e32 v24, 0xffff0000, v17
	v_lshlrev_b32_e32 v17, 16, v26
	v_lshlrev_b32_e32 v16, 16, v18
	v_and_b32_e32 v31, 0xffff0000, v26
	v_and_b32_e32 v30, 0xffff0000, v18
	v_lshlrev_b32_e32 v46, 16, v19
	v_and_b32_e32 v26, 0xffff0000, v19
	v_pk_add_f32 v[18:19], v[20:21], v[22:23]
	v_pk_mul_f32 v[22:23], v[22:23], v[22:23]
	v_pk_add_f32 v[48:49], v[28:29], v[24:25]
	v_pk_fma_f32 v[20:21], v[20:21], v[20:21], v[22:23]
	v_pk_mul_f32 v[22:23], v[24:25], v[24:25]
	s_waitcnt vmcnt(3)
	v_pk_mul_f32 v[24:25], v[62:63], s[36:37] op_sel_hi:[1,0]
	v_pk_fma_f32 v[22:23], v[28:29], v[28:29], v[22:23]
	v_fma_f32 v25, -v24, v24, v25
	v_add_f32_e32 v25, 0x3727c5ac, v25
	v_lshlrev_b32_e32 v47, 16, v27
	v_and_b32_e32 v27, 0xffff0000, v27
	v_pk_add_f32 v[20:21], v[20:21], v[22:23]
	v_pk_mul_f32 v[22:23], v[30:31], v[30:31]
	v_pk_add_f32 v[18:19], v[18:19], v[48:49]
	v_pk_add_f32 v[48:49], v[16:17], v[30:31]
	v_pk_add_f32 v[50:51], v[46:47], v[26:27]
	v_pk_fma_f32 v[16:17], v[16:17], v[16:17], v[22:23]
	v_pk_mul_f32 v[22:23], v[26:27], v[26:27]
	v_pk_fma_f32 v[22:23], v[46:47], v[46:47], v[22:23]
	v_pk_add_f32 v[16:17], v[16:17], v[22:23]
	s_waitcnt vmcnt(2)
	v_lshlrev_b32_e32 v28, 16, v60
	v_pk_add_f32 v[16:17], v[20:21], v[16:17]
	v_and_b32_e32 v29, 0xffff0000, v60
	v_lshlrev_b32_e32 v30, 16, v61
	v_and_b32_e32 v31, 0xffff0000, v61
	v_sub_f32_e32 v29, v29, v24
	v_lshlrev_b32_e32 v21, 16, v58
	v_and_b32_e32 v22, 0xffff0000, v58
	v_rsq_f32_e32 v20, v25
	v_lshlrev_b32_e32 v25, 16, v59
	v_and_b32_e32 v26, 0xffff0000, v59
	v_sub_f32_e32 v23, v22, v24
	v_sub_f32_e32 v22, v21, v24
	v_sub_f32_e32 v28, v28, v24
	v_sub_f32_e32 v31, v31, v24
	v_sub_f32_e32 v30, v30, v24
	v_sub_f32_e32 v27, v26, v24
	v_sub_f32_e32 v26, v25, v24
	v_pk_mul_f32 v[22:23], v[20:21], v[22:23] op_sel_hi:[0,1]
	v_pk_mul_f32 v[30:31], v[20:21], v[30:31] op_sel_hi:[0,1]
	v_pk_mul_f32 v[28:29], v[20:21], v[28:29] op_sel_hi:[0,1]
	v_pk_mul_f32 v[26:27], v[20:21], v[26:27] op_sel_hi:[0,1]
	v_pk_fma_f32 v[22:23], v[96:97], v[22:23], v[100:101]
	v_pk_fma_f32 v[28:29], v[88:89], v[28:29], v[92:93]
	v_pk_fma_f32 v[30:31], v[90:91], v[30:31], v[94:95]
	v_pk_fma_f32 v[26:27], v[98:99], v[26:27], v[102:103]
	v_pk_fma_f32 v[12:13], v[22:23], s[38:39], v[12:13] op_sel_hi:[1,0,1]
	v_pk_fma_f32 v[22:23], v[30:31], s[38:39], v[10:11] op_sel_hi:[1,0,1]
	v_pk_fma_f32 v[10:11], v[28:29], s[38:39], v[8:9] op_sel_hi:[1,0,1]
	v_pk_fma_f32 v[14:15], v[26:27], s[38:39], v[14:15] op_sel_hi:[1,0,1]
	v_cvt_pk_bf16_f32 v8, v12, v13
	v_cvt_pk_bf16_f32 v10, v10, v11
	v_cvt_pk_bf16_f32 v9, v14, v15
	v_cvt_pk_bf16_f32 v11, v22, v23
	v_lshlrev_b32_e32 v15, 16, v10
	v_lshlrev_b32_e32 v14, 16, v8
	v_and_b32_e32 v23, 0xffff0000, v10
	v_and_b32_e32 v22, 0xffff0000, v8
	v_and_b32_e32 v29, 0xffff0000, v11
	v_and_b32_e32 v28, 0xffff0000, v9
	v_pk_add_f32 v[30:31], v[14:15], v[22:23]
	v_pk_mul_f32 v[22:23], v[22:23], v[22:23]
	v_lshlrev_b32_e32 v27, 16, v11
	v_lshlrev_b32_e32 v26, 16, v9
	v_pk_fma_f32 v[14:15], v[14:15], v[14:15], v[22:23]
	v_pk_mul_f32 v[22:23], v[28:29], v[28:29]
	v_lshl_add_u64 v[12:13], s[26:27], 0, v[44:45]
	v_pk_add_f32 v[44:45], v[26:27], v[28:29]
	v_pk_fma_f32 v[22:23], v[26:27], v[26:27], v[22:23]
	v_pk_add_f32 v[30:31], v[30:31], v[44:45]
	v_pk_add_f32 v[14:15], v[14:15], v[22:23]
	v_pk_add_f32 v[30:31], v[30:31], v[30:31] op_sel_hi:[0,1]
	v_pk_add_f32 v[14:15], v[14:15], v[14:15] op_sel_hi:[0,1]
	v_lshlrev_b32_e32 v14, 16, v32
	v_and_b32_e32 v21, 0xffff0000, v32
	v_lshlrev_b32_e32 v25, 16, v33
	v_and_b32_e32 v26, 0xffff0000, v33
	v_lshlrev_b32_e32 v28, 16, v34
	v_and_b32_e32 v29, 0xffff0000, v34
	v_lshlrev_b32_e32 v30, 16, v35
	v_and_b32_e32 v32, 0xffff0000, v35
	v_sub_f32_e32 v23, v21, v24
	v_sub_f32_e32 v22, v14, v24
	v_sub_f32_e32 v27, v26, v24
	v_sub_f32_e32 v26, v25, v24
	v_sub_f32_e32 v29, v29, v24
	v_sub_f32_e32 v28, v28, v24
	v_sub_f32_e32 v25, v32, v24
	v_sub_f32_e32 v24, v30, v24
	v_pk_mul_f32 v[26:27], v[20:21], v[26:27] op_sel_hi:[0,1]
	v_pk_mul_f32 v[22:23], v[20:21], v[22:23] op_sel_hi:[0,1]
	v_pk_mul_f32 v[24:25], v[20:21], v[24:25] op_sel_hi:[0,1]
	v_pk_mul_f32 v[20:21], v[20:21], v[28:29] op_sel_hi:[0,1]
	v_pk_fma_f32 v[22:23], v[72:73], v[22:23], v[76:77]
	v_pk_fma_f32 v[20:21], v[64:65], v[20:21], v[68:69]
	v_pk_fma_f32 v[24:25], v[66:67], v[24:25], v[70:71]
	v_pk_fma_f32 v[26:27], v[74:75], v[26:27], v[78:79]
	v_pk_fma_f32 v[4:5], v[22:23], s[38:39], v[4:5] op_sel_hi:[1,0,1]
	v_pk_fma_f32 v[22:23], v[24:25], s[38:39], v[2:3] op_sel_hi:[1,0,1]
	v_pk_fma_f32 v[2:3], v[20:21], s[38:39], v[0:1] op_sel_hi:[1,0,1]
	v_pk_fma_f32 v[6:7], v[26:27], s[38:39], v[6:7] op_sel_hi:[1,0,1]
	v_cvt_pk_bf16_f32 v0, v4, v5
	v_cvt_pk_bf16_f32 v2, v2, v3
	v_cvt_pk_bf16_f32 v1, v6, v7
	v_cvt_pk_bf16_f32 v3, v22, v23
	v_lshlrev_b32_e32 v5, 16, v2
	v_lshlrev_b32_e32 v4, 16, v0
	v_and_b32_e32 v7, 0xffff0000, v2
	v_and_b32_e32 v6, 0xffff0000, v0
	v_lshlrev_b32_e32 v21, 16, v3
	v_lshlrev_b32_e32 v20, 16, v1
	v_and_b32_e32 v23, 0xffff0000, v3
	v_and_b32_e32 v22, 0xffff0000, v1
	v_pk_add_f32 v[24:25], v[4:5], v[6:7]
	v_pk_mul_f32 v[6:7], v[6:7], v[6:7]
	v_pk_add_f32 v[48:49], v[48:49], v[50:51]
	v_pk_add_f32 v[26:27], v[20:21], v[22:23]
	v_pk_fma_f32 v[4:5], v[4:5], v[4:5], v[6:7]
	v_pk_mul_f32 v[6:7], v[22:23], v[22:23]
	v_pk_add_f32 v[18:19], v[18:19], v[48:49]
	v_pk_add_f32 v[24:25], v[24:25], v[26:27]
	v_pk_fma_f32 v[6:7], v[20:21], v[20:21], v[6:7]
	v_pk_add_f32 v[24:25], v[24:25], v[24:25] op_sel_hi:[0,1]
	v_pk_add_f32 v[4:5], v[4:5], v[6:7]
	v_mov_b32_e32 v30, v19
	v_pk_add_f32 v[4:5], v[4:5], v[4:5] op_sel_hi:[0,1]
	v_pk_add_f32 v[6:7], v[30:31], 0 op_sel_hi:[1,0]
	v_mov_b32_e32 v19, v25
	v_pk_add_f32 v[6:7], v[18:19], v[6:7]
	v_mov_b32_e32 v4, v16
	v_mov_b32_e32 v14, v17
	ds_bpermute_b32 v18, v215, v6
	ds_bpermute_b32 v19, v215, v7
	v_pk_add_f32 v[4:5], v[4:5], v[14:15]
	ds_bpermute_b32 v14, v215, v4
	ds_bpermute_b32 v15, v215, v5
	v_lshl_add_u64 v[12:13], v[12:13], 0, v[200:201]
	global_store_dwordx4 v[12:13], v[8:11], off
	global_store_dwordx4 v[12:13], v[0:3], off offset:256
	ds_bpermute_b32 v39, v199, v37
	s_waitcnt lgkmcnt(1)
	v_pk_add_f32 v[4:5], v[4:5], v[14:15]
	v_pk_add_f32 v[0:1], v[6:7], v[18:19]
	ds_bpermute_b32 v2, v199, v0
	ds_bpermute_b32 v3, v199, v1
	ds_bpermute_b32 v6, v199, v4
	ds_bpermute_b32 v7, v199, v5
	v_pk_add_f32 v[8:9], v[136:137], v[138:139]
	v_pk_add_f32 v[10:11], v[104:105], v[106:107]
	s_waitcnt lgkmcnt(2)
	v_pk_add_f32 v[0:1], v[0:1], v[2:3]
	v_pk_add_f32 v[2:3], v[132:133], v[134:135]
	v_pk_add_f32 v[14:15], v[84:85], v[86:87]
	s_waitcnt lgkmcnt(0)
	v_pk_add_f32 v[4:5], v[4:5], v[6:7]
	v_cndmask_b32_e64 v3, v3, v9, s[4:5]
	v_cndmask_b32_e64 v2, v2, v8, s[4:5]
	v_cmp_ne_u64_e32 vcc, 0, v[180:181]
	v_cndmask_b32_e64 v4, v4, v0, s[4:5]
	v_cndmask_b32_e64 v10, v14, v10, s[4:5]
	v_cndmask_b32_e32 v0, v2, v3, vcc
	v_cmp_eq_u32_e32 vcc, 2, v180
	v_pk_add_f32 v[12:13], v[40:41], v[42:43]
	v_pk_add_f32 v[16:17], v[36:37], v[38:39]
	v_cndmask_b32_e64 v11, v15, v11, s[4:5]
	v_cndmask_b32_e32 v0, v0, v10, vcc
	v_cmp_eq_u32_e32 vcc, 3, v180
	v_cndmask_b32_e64 v7, v16, v12, s[4:5]
	v_cndmask_b32_e64 v6, v17, v13, s[4:5]
	v_cndmask_b32_e32 v0, v0, v11, vcc
	v_cmp_eq_u32_e32 vcc, 4, v180
	v_cndmask_b32_e64 v5, v5, v1, s[4:5]
	s_mov_b64 s[0:1], -1
	v_cndmask_b32_e32 v0, v0, v7, vcc
	v_cmp_eq_u32_e32 vcc, 5, v180
	s_nop 1
	v_cndmask_b32_e32 v0, v0, v6, vcc
	v_cmp_eq_u32_e32 vcc, 6, v180
	s_nop 1
	v_cndmask_b32_e32 v0, v0, v4, vcc
	v_cmp_eq_u32_e32 vcc, 7, v180
	s_nop 1
	v_cndmask_b32_e32 v8, v0, v5, vcc
	v_or_b32_e32 v0, v198, v183
	v_ashrrev_i32_e32 v1, 31, v0
	v_lshl_add_u64 v[0:1], v[0:1], 3, v[188:189]
	v_cmp_eq_u32_e32 vcc, 1, v182
	global_atomic_add_f32 v[0:1], v8, off
	s_nop 0
	v_cndmask_b32_e32 v0, v2, v3, vcc
	v_cmp_eq_u32_e32 vcc, 2, v182
	s_nop 1
	v_cndmask_b32_e32 v0, v0, v10, vcc
	v_cmp_eq_u32_e32 vcc, 3, v182
	s_nop 1
	v_cndmask_b32_e32 v0, v0, v11, vcc
	v_cmp_eq_u32_e32 vcc, 4, v182
	s_nop 1
	v_cndmask_b32_e32 v0, v0, v7, vcc
	v_cmp_eq_u32_e32 vcc, 5, v182
	s_nop 1
	v_cndmask_b32_e32 v0, v0, v6, vcc
	v_cmp_eq_u32_e32 vcc, 6, v182
	s_nop 1
	v_cndmask_b32_e32 v0, v0, v4, vcc
	v_cmp_eq_u32_e32 vcc, 7, v182
	s_nop 1
	v_cndmask_b32_e32 v8, v0, v5, vcc
	v_or_b32_e32 v0, v198, v185
	v_ashrrev_i32_e32 v1, 31, v0
	v_lshl_add_u64 v[0:1], v[0:1], 3, v[188:189]
	v_cmp_eq_u32_e32 vcc, 1, v184
	global_atomic_add_f32 v[0:1], v8, off
	s_nop 0
	v_cndmask_b32_e32 v0, v2, v3, vcc
	v_cmp_eq_u32_e32 vcc, 2, v184
	s_nop 1
	v_cndmask_b32_e32 v0, v0, v10, vcc
	v_cmp_eq_u32_e32 vcc, 3, v184
	s_nop 1
	v_cndmask_b32_e32 v0, v0, v11, vcc
	v_cmp_eq_u32_e32 vcc, 4, v184
	s_nop 1
	v_cndmask_b32_e32 v0, v0, v7, vcc
	v_cmp_eq_u32_e32 vcc, 5, v184
	s_nop 1
	v_cndmask_b32_e32 v0, v0, v6, vcc
	v_cmp_eq_u32_e32 vcc, 6, v184
	s_nop 1
	v_cndmask_b32_e32 v0, v0, v4, vcc
	v_cmp_eq_u32_e32 vcc, 7, v184
	s_nop 1
	v_cndmask_b32_e32 v8, v0, v5, vcc
	v_add_u32_e32 v0, v198, v187
	v_ashrrev_i32_e32 v1, 31, v0
	v_lshl_add_u64 v[0:1], v[0:1], 3, v[188:189]
	v_cmp_eq_u32_e32 vcc, 1, v186
	global_atomic_add_f32 v[0:1], v8, off
	s_nop 0
	v_cndmask_b32_e32 v0, v2, v3, vcc
	v_cmp_eq_u32_e32 vcc, 2, v186
	s_nop 1
	v_cndmask_b32_e32 v0, v0, v10, vcc
	v_cmp_eq_u32_e32 vcc, 3, v186
	s_nop 1
	v_cndmask_b32_e32 v0, v0, v11, vcc
	v_cmp_eq_u32_e32 vcc, 4, v186
	s_nop 1
	v_cndmask_b32_e32 v0, v0, v7, vcc
	v_cmp_eq_u32_e32 vcc, 5, v186
	s_nop 1
	v_cndmask_b32_e32 v0, v0, v6, vcc
	v_cmp_eq_u32_e32 vcc, 6, v186
	s_nop 1
	v_cndmask_b32_e32 v0, v0, v4, vcc
	v_cmp_eq_u32_e32 vcc, 7, v186
	s_nop 1
	v_cndmask_b32_e32 v2, v0, v5, vcc
	v_add_u32_e32 v0, v198, v208
	v_ashrrev_i32_e32 v1, 31, v0
	v_lshl_add_u64 v[0:1], v[0:1], 3, v[188:189]
	global_atomic_add_f32 v[0:1], v2, off
	s_andn2_b64 vcc, exec, s[6:7]
	s_cbranch_vccnz .LBB0_1148
	s_andn2_b64 vcc, exec, s[8:9]
	s_cbranch_vccnz .LBB0_1147
	s_barrier
	s_branch .LBB0_1147

	.amdhsa_kernel _Z10hybrid_fwd4Args
		.amdhsa_group_segment_fixed_size 0
		.amdhsa_private_segment_fixed_size 0
		.amdhsa_kernarg_size 368
		.amdhsa_user_sgpr_count 2
		.amdhsa_user_sgpr_dispatch_ptr 0
		.amdhsa_user_sgpr_queue_ptr 0
		.amdhsa_user_sgpr_kernarg_segment_ptr 1
		.amdhsa_user_sgpr_dispatch_id 0
		.amdhsa_user_sgpr_kernarg_preload_length 0
		.amdhsa_user_sgpr_kernarg_preload_offset 0
		.amdhsa_user_sgpr_private_segment_size 0
		.amdhsa_uses_dynamic_stack 0
		.amdhsa_enable_private_segment 0
		.amdhsa_system_sgpr_workgroup_id_x 1
		.amdhsa_system_sgpr_workgroup_id_y 0
		.amdhsa_system_sgpr_workgroup_id_z 0
		.amdhsa_system_sgpr_workgroup_info 0
		.amdhsa_system_vgpr_workitem_id 2
		.amdhsa_next_free_vgpr 256
		.amdhsa_next_free_sgpr 98
		.amdhsa_accum_offset 256
		.amdhsa_reserve_vcc 1
		.amdhsa_float_round_mode_32 0
		.amdhsa_float_round_mode_16_64 0
		.amdhsa_float_denorm_mode_32 3
		.amdhsa_float_denorm_mode_16_64 3
		.amdhsa_dx10_clamp 1
		.amdhsa_ieee_mode 1
		.amdhsa_fp16_overflow 0
		.amdhsa_tg_split 0
		.amdhsa_exception_fp_ieee_invalid_op 0
		.amdhsa_exception_fp_denorm_src 0
		.amdhsa_exception_fp_ieee_div_zero 0
		.amdhsa_exception_fp_ieee_overflow 0
		.amdhsa_exception_fp_ieee_underflow 0
		.amdhsa_exception_fp_ieee_inexact 0
		.amdhsa_exception_int_div_zero 0
	.end_amdhsa_kernel

amdhsa.kernels:
  - .agpr_count:     0
    .args:
      - .offset:         0
        .size:           112
        .value_kind:     by_value
      - .offset:         112
        .size:           4
        .value_kind:     hidden_block_count_x
      - .offset:         116
        .size:           4
        .value_kind:     hidden_block_count_y
      - .offset:         120
        .size:           4
        .value_kind:     hidden_block_count_z
      - .offset:         124
        .size:           2
        .value_kind:     hidden_group_size_x
      - .offset:         126
        .size:           2
        .value_kind:     hidden_group_size_y
      - .offset:         128
        .size:           2
        .value_kind:     hidden_group_size_z
      - .offset:         130
        .size:           2
        .value_kind:     hidden_remainder_x
      - .offset:         132
        .size:           2
        .value_kind:     hidden_remainder_y
      - .offset:         134
        .size:           2
        .value_kind:     hidden_remainder_z
      - .offset:         152
        .size:           8
        .value_kind:     hidden_global_offset_x
      - .offset:         160
        .size:           8
        .value_kind:     hidden_global_offset_y
      - .offset:         168
        .size:           8
        .value_kind:     hidden_global_offset_z
      - .offset:         176
        .size:           2
        .value_kind:     hidden_grid_dims
      - .offset:         200
        .size:           8
        .value_kind:     hidden_multigrid_sync_arg
      - .offset:         232
        .size:           4
        .value_kind:     hidden_dynamic_lds_size
    .group_segment_fixed_size: 0
    .kernarg_segment_align: 8
    .kernarg_segment_size: 368
    .language:       OpenCL C
    .language_version:
      - 2
      - 0
    .max_flat_workgroup_size: 512
    .name:           _Z10hybrid_fwd4Args
    .private_segment_fixed_size: 0
    .sgpr_count:     104
    .sgpr_spill_count: 196
    .symbol:         _Z10hybrid_fwd4Args.kd
    .uniform_work_group_size: 1
    .uses_dynamic_stack: false
    .vgpr_count:     256
    .vgpr_spill_count: 0
    .wavefront_size: 64
